# speedup vs baseline: 1.1021x; 1.0140x over previous
; __device__ __forceinline__ void phase_prep(const Params& p, char* smraw) {
;     ...
;       for (int j = 0; j < 4; ++j) {
;         v[j] = vin[j];
;         if (!tbl) { f32x4 g = *(const f32x4*)(p.norm_ffn + ly * D + (j * 64 + l) * 4); v[j] *= g; }
;         m = fmaxf(m, fmaxf(fmaxf(fabsf(v[j][0]), fabsf(v[j][1])), fmaxf(fabsf(v[j][2]), fabsf(v[j][3]))));
;       }
; #pragma unroll
;       for (int mm = 32; mm >= 1; mm >>= 1) m = fmaxf(m, __shfl_xor(m, mm));
;       const float qmax = tbl ? 6.f : 7.f;
;       const float inv = m > 0.f ? qmax / m : 0.f;
.LBB0_70:
	v_mov_b32_e32 v61, 0x40e00000
	v_pk_mul_f32 v[20:21], v[20:21], v[78:79]
	v_pk_mul_f32 v[18:19], v[18:19], v[76:77]

; __device__ __forceinline__ void phase_prep(const Params& p, char* smraw) {
;     ...
;       for (int j = 0; j < 4; ++j) {
;         v[j] = vin[j];
;         if (!tbl) { f32x4 g = *(const f32x4*)(p.norm_ffn + ly * D + (j * 64 + l) * 4); v[j] *= g; }
;         m = fmaxf(m, fmaxf(fmaxf(fabsf(v[j][0]), fabsf(v[j][1])), fmaxf(fabsf(v[j][2]), fabsf(v[j][3]))));
.LBB0_93:
	global_load_dwordx4 v[62:65], v[44:45], off
	global_load_dwordx4 v[68:71], v[44:45], off offset:1024
	global_load_dwordx4 v[72:75], v[44:45], off offset:2048
	global_load_dwordx4 v[76:79], v[44:45], off offset:3072
	s_waitcnt vmcnt(0)
	v_pk_mul_f32 v[32:33], v[32:33], v[64:65]
	v_pk_mul_f32 v[30:31], v[30:31], v[62:63]
	s_or_b64 exec, exec, s[14:15]
	s_and_saveexec_b64 s[14:15], s[8:9]
	s_cbranch_execz .LBB0_68
.LBB0_94:
	v_pk_mul_f32 v[28:29], v[28:29], v[70:71]
	v_pk_mul_f32 v[26:27], v[26:27], v[68:69]
	s_or_b64 exec, exec, s[14:15]
	s_and_saveexec_b64 s[14:15], s[8:9]
	s_cbranch_execz .LBB0_69
.LBB0_95:
	v_pk_mul_f32 v[24:25], v[24:25], v[74:75]
	v_pk_mul_f32 v[22:23], v[22:23], v[72:73]
	s_or_b64 exec, exec, s[14:15]
	v_mov_b32_e32 v61, 0x40c00000
	s_and_saveexec_b64 s[14:15], s[8:9]
	s_cbranch_execnz .LBB0_70
	s_branch .LBB0_71

; __device__ __forceinline__ void phase_prep(const Params& p, char* smraw) {
;     ...
;       for (int j = 0; j < 4; ++j) {
;         v[j] = vin[j];
;         if (!tbl) { f32x4 g = *(const f32x4*)(p.norm_ffn + ly * D + (j * 64 + l) * 4); v[j] *= g; }
;         m = fmaxf(m, fmaxf(fmaxf(fabsf(v[j][0]), fabsf(v[j][1])), fmaxf(fabsf(v[j][2]), fabsf(v[j][3]))));
.LBB0_105:
	v_mov_b32_e32 v19, 0x40e00000
	v_pk_mul_f32 v[4:5], v[4:5], v[78:79]
	v_pk_mul_f32 v[2:3], v[2:3], v[76:77]

; __device__ __forceinline__ void phase_prep(const Params& p, char* smraw) {
;     ...
;       for (int j = 0; j < 4; ++j) {
;         v[j] = vin[j];
;         if (!tbl) { f32x4 g = *(const f32x4*)(p.norm_ffn + ly * D + (j * 64 + l) * 4); v[j] *= g; }
;         m = fmaxf(m, fmaxf(fmaxf(fabsf(v[j][0]), fabsf(v[j][1])), fmaxf(fabsf(v[j][2]), fabsf(v[j][3]))));
.LBB0_127:
	global_load_dwordx4 v[24:27], v[20:21], off
	global_load_dwordx4 v[68:71], v[20:21], off offset:1024
	global_load_dwordx4 v[72:75], v[20:21], off offset:2048
	global_load_dwordx4 v[76:79], v[20:21], off offset:3072
	s_waitcnt vmcnt(0)
	v_pk_mul_f32 v[16:17], v[16:17], v[26:27]
	v_pk_mul_f32 v[14:15], v[14:15], v[24:25]
	s_or_b64 exec, exec, s[12:13]
	s_and_saveexec_b64 s[12:13], s[8:9]
	s_cbranch_execz .LBB0_103
.LBB0_128:
	v_pk_mul_f32 v[12:13], v[12:13], v[70:71]
	v_pk_mul_f32 v[10:11], v[10:11], v[68:69]
	s_or_b64 exec, exec, s[12:13]
	s_and_saveexec_b64 s[12:13], s[8:9]
	s_cbranch_execz .LBB0_104
.LBB0_129:
	v_pk_mul_f32 v[8:9], v[8:9], v[74:75]
	v_pk_mul_f32 v[6:7], v[6:7], v[72:73]
	s_or_b64 exec, exec, s[12:13]
	v_mov_b32_e32 v19, 0x40c00000
	s_and_saveexec_b64 s[12:13], s[8:9]
	s_cbranch_execnz .LBB0_105
	s_branch .LBB0_106

; __device__ __forceinline__ void phase_prep(const Params& p, char* smraw) {
;     ...
;   for (size_t i = gtid; i < (size_t)T * 256; i += gstride) {
;     int t = (int)(i >> 8), c4 = (int)(i & 255);
;     int b = t / L, pp = t - b * L;
;     const float* src = pp < NM ? p.meta + (size_t)pp * D : p.x + (size_t)(b * SEQ + pp - NM) * D;
;     f32x4 v = *(const f32x4*)(src + c4 * 4);
;     u32x2 o; o[0] = cvtpk(v[0], v[1]); o[1] = cvtpk(v[2], v[3]);
;     *(u32x2*)(p.hb + (size_t)t * D + c4 * 4) = o;
;   }
.LBB0_138:
	s_or_b64 exec, exec, s[4:5]
	s_mov_b64 s[4:5], 0x804000
	v_cmp_gt_u64_e32 vcc, s[4:5], v[2:3]
	s_and_saveexec_b64 s[4:5], vcc
	s_cbranch_execz .LBB0_141
	s_lshl_b64 s[6:7], s[2:3], 10
	v_lshl_add_u64 v[4:5], v[34:35], 2, s[6:7]
	s_lshl_b64 s[6:7], s[96:97], 10
	s_mov_b64 s[8:9], 0
	v_mov_b32_e32 v7, 0
	v_mov_b32_e32 v1, s37
	v_mov_b32_e32 v10, s39
	v_mov_b32_e32 v11, s36
	v_mov_b32_e32 v12, s38
	s_mov_b64 s[10:11], 0x803fff
	v_mov_b64_e32 v[8:9], v[2:3]
	v_and_b32_e32 v40, 0xff, v2
	v_lshrrev_b32_e32 v41, 8, v2
	v_lshlrev_b32_e32 v42, 4, v40
	v_mov_b32_e32 v43, 0
	v_lshlrev_b32_e32 v44, 3, v40
	s_sub_u32 s12, s36, 0x10000
	s_subb_u32 s13, s37, 0
	v_lshrrev_b32_e32 v45, 6, v34
	v_mov_b32_e32 v46, s12
	v_mov_b32_e32 v47, s13
	v_mov_b32_e32 v48, s38
	v_mov_b32_e32 v49, s39
	v_mov_b32_e32 v57, 0
	v_lshl_add_u64 v[46:47], v[42:43], 0, v[46:47]
	v_lshl_add_u64 v[48:49], v[42:43], 0, v[48:49]
	s_lshl_b32 s14, s96, 8
	s_mul_i32 s15, s14, 7
	s_lshl_b32 s16, s14, 3
	s_lshl_b32 s17, s96, 3
	v_readfirstlane_b32 s18, v45
	s_lshl_b32 s18, s18, 6
	s_lshl_b32 s19, s2, 8
	s_add_u32 s18, s18, s19
	s_add_u32 s18, s18, 63
	s_mov_b32 s20, 0x7fc02
	s_movk_i32 s21, 0xdff0
	s_mov_b32 s22, 0x804000
.Lmy_hinit_loop:
	s_add_u32 s23, s18, s15
	s_cmp_lt_u32 s23, s22
	s_cbranch_scc0 .Lmy_hinit_done
	v_mov_b32_e32 v64, v41
	v_mul_hi_u32 v52, v64, s20
	v_mad_i32_i24 v53, v52, s21, v64
	v_cmp_gt_u32_e32 vcc, 16, v53
	v_lshlrev_b32_e32 v54, 12, v53
	v_lshl_add_u32 v55, v52, 25, v54
	v_lshl_add_u32 v65, v64, 11, v44
	v_cndmask_b32_e32 v56, v55, v54, vcc
	v_cndmask_b32_e32 v58, v46, v48, vcc
	v_cndmask_b32_e32 v59, v47, v49, vcc
	v_lshl_add_u64 v[66:67], v[56:57], 0, v[58:59]
	global_load_dwordx4 v[68:71], v[66:67], off
	v_add_u32_e32 v72, s96, v64
	v_mul_hi_u32 v52, v72, s20
	v_mad_i32_i24 v53, v52, s21, v72
	v_cmp_gt_u32_e32 vcc, 16, v53
	v_lshlrev_b32_e32 v54, 12, v53
	v_lshl_add_u32 v55, v52, 25, v54
	v_lshl_add_u32 v73, v72, 11, v44
	v_cndmask_b32_e32 v56, v55, v54, vcc
	v_cndmask_b32_e32 v58, v46, v48, vcc
	v_cndmask_b32_e32 v59, v47, v49, vcc
	v_lshl_add_u64 v[74:75], v[56:57], 0, v[58:59]
	global_load_dwordx4 v[76:79], v[74:75], off
	v_add_u32_e32 v80, s96, v72
	v_mul_hi_u32 v52, v80, s20
	v_mad_i32_i24 v53, v52, s21, v80
	v_cmp_gt_u32_e32 vcc, 16, v53
	v_lshlrev_b32_e32 v54, 12, v53
	v_lshl_add_u32 v55, v52, 25, v54
	v_lshl_add_u32 v81, v80, 11, v44
	v_cndmask_b32_e32 v56, v55, v54, vcc
	v_cndmask_b32_e32 v58, v46, v48, vcc
	v_cndmask_b32_e32 v59, v47, v49, vcc
	v_lshl_add_u64 v[82:83], v[56:57], 0, v[58:59]
	global_load_dwordx4 v[84:87], v[82:83], off
	v_add_u32_e32 v88, s96, v80
	v_mul_hi_u32 v52, v88, s20
	v_mad_i32_i24 v53, v52, s21, v88
	v_cmp_gt_u32_e32 vcc, 16, v53
	v_lshlrev_b32_e32 v54, 12, v53
	v_lshl_add_u32 v55, v52, 25, v54
	v_lshl_add_u32 v89, v88, 11, v44
	v_cndmask_b32_e32 v56, v55, v54, vcc
	v_cndmask_b32_e32 v58, v46, v48, vcc
	v_cndmask_b32_e32 v59, v47, v49, vcc
	v_lshl_add_u64 v[90:91], v[56:57], 0, v[58:59]
	global_load_dwordx4 v[92:95], v[90:91], off
	v_add_u32_e32 v96, s96, v88
	v_mul_hi_u32 v52, v96, s20
	v_mad_i32_i24 v53, v52, s21, v96
	v_cmp_gt_u32_e32 vcc, 16, v53
	v_lshlrev_b32_e32 v54, 12, v53
	v_lshl_add_u32 v55, v52, 25, v54
	v_lshl_add_u32 v97, v96, 11, v44
	v_cndmask_b32_e32 v56, v55, v54, vcc
	v_cndmask_b32_e32 v58, v46, v48, vcc
	v_cndmask_b32_e32 v59, v47, v49, vcc
	v_lshl_add_u64 v[98:99], v[56:57], 0, v[58:59]
	global_load_dwordx4 v[100:103], v[98:99], off
	v_add_u32_e32 v104, s96, v96
	v_mul_hi_u32 v52, v104, s20
	v_mad_i32_i24 v53, v52, s21, v104
	v_cmp_gt_u32_e32 vcc, 16, v53
	v_lshlrev_b32_e32 v54, 12, v53
	v_lshl_add_u32 v55, v52, 25, v54
	v_lshl_add_u32 v105, v104, 11, v44
	v_cndmask_b32_e32 v56, v55, v54, vcc
	v_cndmask_b32_e32 v58, v46, v48, vcc
	v_cndmask_b32_e32 v59, v47, v49, vcc
	v_lshl_add_u64 v[106:107], v[56:57], 0, v[58:59]
	global_load_dwordx4 v[108:111], v[106:107], off
	v_add_u32_e32 v112, s96, v104
	v_mul_hi_u32 v52, v112, s20
	v_mad_i32_i24 v53, v52, s21, v112
	v_cmp_gt_u32_e32 vcc, 16, v53
	v_lshlrev_b32_e32 v54, 12, v53
	v_lshl_add_u32 v55, v52, 25, v54
	v_lshl_add_u32 v113, v112, 11, v44
	v_cndmask_b32_e32 v56, v55, v54, vcc
	v_cndmask_b32_e32 v58, v46, v48, vcc
	v_cndmask_b32_e32 v59, v47, v49, vcc
	v_lshl_add_u64 v[114:115], v[56:57], 0, v[58:59]
	global_load_dwordx4 v[116:119], v[114:115], off
	v_add_u32_e32 v120, s96, v112
	v_mul_hi_u32 v52, v120, s20
	v_mad_i32_i24 v53, v52, s21, v120
	v_cmp_gt_u32_e32 vcc, 16, v53
	v_lshlrev_b32_e32 v54, 12, v53
	v_lshl_add_u32 v55, v52, 25, v54
	v_lshl_add_u32 v121, v120, 11, v44
	v_cndmask_b32_e32 v56, v55, v54, vcc
	v_cndmask_b32_e32 v58, v46, v48, vcc
	v_cndmask_b32_e32 v59, v47, v49, vcc
	v_lshl_add_u64 v[122:123], v[56:57], 0, v[58:59]
	global_load_dwordx4 v[124:127], v[122:123], off
	s_waitcnt vmcnt(7)
	v_cvt_pk_bf16_f32 v68, v68, v69
	v_cvt_pk_bf16_f32 v69, v70, v71
	global_store_dwordx2 v65, v[68:69], s[76:77]
	s_waitcnt vmcnt(7)
	v_cvt_pk_bf16_f32 v76, v76, v77
	v_cvt_pk_bf16_f32 v77, v78, v79
	global_store_dwordx2 v73, v[76:77], s[76:77]
	s_waitcnt vmcnt(7)
	v_cvt_pk_bf16_f32 v84, v84, v85
	v_cvt_pk_bf16_f32 v85, v86, v87
	global_store_dwordx2 v81, v[84:85], s[76:77]
	s_waitcnt vmcnt(7)
	v_cvt_pk_bf16_f32 v92, v92, v93
	v_cvt_pk_bf16_f32 v93, v94, v95
	global_store_dwordx2 v89, v[92:93], s[76:77]
	s_waitcnt vmcnt(7)
	v_cvt_pk_bf16_f32 v100, v100, v101
	v_cvt_pk_bf16_f32 v101, v102, v103
	global_store_dwordx2 v97, v[100:101], s[76:77]
	s_waitcnt vmcnt(7)
	v_cvt_pk_bf16_f32 v108, v108, v109
	v_cvt_pk_bf16_f32 v109, v110, v111
	global_store_dwordx2 v105, v[108:109], s[76:77]
	s_waitcnt vmcnt(7)
	v_cvt_pk_bf16_f32 v116, v116, v117
	v_cvt_pk_bf16_f32 v117, v118, v119
	global_store_dwordx2 v113, v[116:117], s[76:77]
	s_waitcnt vmcnt(7)
	v_cvt_pk_bf16_f32 v124, v124, v125
	v_cvt_pk_bf16_f32 v125, v126, v127
	global_store_dwordx2 v121, v[124:125], s[76:77]
	v_add_u32_e32 v41, s17, v41
	v_add_u32_e32 v8, s16, v8
	s_add_u32 s18, s18, s16
	s_branch .Lmy_hinit_loop
.Lmy_hinit_done:
	v_cmp_gt_u32_e32 vcc, s22, v8
	s_and_b64 exec, exec, vcc
	s_cbranch_execz .LBB0_141

; template <bool SWAP, bool SS>
; __device__ __forceinline__ void gemm_main(const u16* __restrict__ A, int lda, int M, int m0,
;                                           const u16* __restrict__ Bt, int ldb, int n0, int K,
;                                           char* smraw, f32x16 (&acc)[2][2]) {
;     ...
;   unsigned aoff[4], boff[4];
; #pragma unroll
;   for (int j = 0; j < 4; ++j) {
;     int r = lrow + 32 * j;
;     int ar = m0 + r; ar = ar < M ? ar : M - 1;
;     aoff[j] = ((unsigned)ar * (unsigned)lda + (unsigned)kc * 8u) * 2u;
;     boff[j] = ((unsigned)(n0 + r) * (unsigned)ldb + (unsigned)kc * 8u) * 2u;
;   }
; #pragma unroll
;   for (int i = 0; i < 2; ++i)
; #pragma unroll
;     for (int j = 0; j < 2; ++j)
; #pragma unroll
;       for (int r = 0; r < 16; ++r) acc[i][j][r] = 0.f;
;   float ss[4] = {0.f, 0.f, 0.f, 0.f};
;   const int nk = K / 64;
;   auto gload = [&](u32x4 (&ga)[4], u32x4 (&gb)[4], int kt) {
; #pragma unroll
;     for (int j = 0; j < 4; ++j) { ga[j] = *(const u32x4*)(Ab + (aoff[j] + (unsigned)kt * 128u)); gb[j] = *(const u32x4*)(Bb + (boff[j] + (unsigned)kt * 128u)); }
;   };
;   auto lwrite = [&](const u32x4 (&ga)[4], const u32x4 (&gb)[4], int buf) {
;     u16* As = sm + buf * (2 * 128 * TSTR);
;     u16* Bs = As + 128 * TSTR;
; #pragma unroll
;     for (int j = 0; j < 4; ++j) {
;       *(u32x4*)(As + (lrow + 32 * j) * TSTR + kc * 8) = ga[j];
;       *(u32x4*)(Bs + (lrow + 32 * j) * TSTR + kc * 8) = gb[j];
;       if (SS) ss[j] += sumsq8(ga[j]);
;     }
;   };
;   auto compute = [&](int buf) {
;     const u16* As = sm + buf * (2 * 128 * TSTR);
;     const u16* Bs = As + 128 * TSTR;
; #pragma unroll
;     for (int ks = 0; ks < 4; ++ks) {
;       bf16x8 af[2], bf[2];
; #pragma unroll
;       for (int i = 0; i < 2; ++i) af[i] = *(const bf16x8*)(As + (wm * 64 + i * 32 + lc) * TSTR + ks * 16 + hf * 8);
; #pragma unroll
;       for (int j = 0; j < 2; ++j) bf[j] = *(const bf16x8*)(Bs + (wn * 64 + j * 32 + lc) * TSTR + ks * 16 + hf * 8);
; #pragma unroll
;       for (int i = 0; i < 2; ++i)
; #pragma unroll
;         for (int j = 0; j < 2; ++j)
;           acc[i][j] = SWAP ? mfma32(bf[j], af[i], acc[i][j]) : mfma32(af[i], bf[j], acc[i][j]);
;     }
;   };
;   u32x4 ga0[4], gb0[4], ga1[4], gb1[4];
;   gload(ga0, gb0, 0);
;   if (nk > 1) gload(ga1, gb1, 1);
;   lwrite(ga0, gb0, 0);
;   if (nk > 2) gload(ga0, gb0, 2);
;   __syncthreads();
.LBB0_185:
	s_mul_hi_i32 s0, s24, 0x2aaaaaab
	s_lshr_b32 s1, s0, 31
	s_ashr_i32 s0, s0, 2
	s_add_i32 s0, s0, s1
	v_mov_b32_e32 v1, v189
	s_lshl_b32 s25, s0, 7
	s_mul_i32 s6, s0, 0xffffffe8
	v_ashrrev_i32_e32 v167, 3, v1
	v_and_b32_e32 v169, 7, v1
	v_add_u32_e32 v2, s25, v167
	s_add_i32 s6, s6, s24
	v_lshlrev_b32_e32 v0, 4, v169
	v_min_i32_e32 v2, 0x803f, v2
	v_add_u32_e32 v10, 32, v167
	s_lshl_b32 s7, s6, 7
	v_lshl_or_b32 v146, v2, 11, v0
	v_add_u32_e32 v2, s25, v10
	v_add_u32_e32 v10, s7, v10
	v_add_u32_e32 v22, 64, v167
	v_add_u32_e32 v26, 0x60, v167
	v_lshl_or_b32 v48, v10, 11, v0
	v_add_u32_e32 v10, s25, v22
	v_add_u32_e32 v27, s25, v26
	v_min_i32_e32 v10, 0x803f, v10
	v_add_u32_e32 v22, s7, v22
	v_min_i32_e32 v27, 0x803f, v27
	v_add_u32_e32 v30, s7, v26
	v_min_i32_e32 v2, 0x803f, v2
	v_add_u32_e32 v11, s7, v167
	v_lshl_or_b32 v36, v10, 11, v0
	v_lshl_or_b32 v49, v22, 11, v0
	v_lshl_or_b32 v38, v27, 11, v0
	v_lshl_or_b32 v50, v30, 11, v0
	s_waitcnt lgkmcnt(0)
	v_lshl_or_b32 v34, v2, 11, v0
	global_load_dwordx4 v[2:5], v146, s[76:77]
	global_load_dwordx4 v[6:9], v34, s[76:77]
	v_lshl_or_b32 v40, v11, 11, v0
	global_load_dwordx4 v[10:13], v36, s[76:77]
	global_load_dwordx4 v[14:17], v40, s[78:79]
	global_load_dwordx4 v[18:21], v48, s[78:79]
	global_load_dwordx4 v[22:25], v49, s[78:79]
	global_load_dwordx4 v[30:33], v50, s[78:79]
	global_load_dwordx4 v[26:29], v38, s[76:77]
	v_mad_u64_u32 v[210:211], s[4:5], v167, s17, v[0:1]
	global_load_dwordx4 v[132:135], v146, s[76:77] offset:128
	global_load_dwordx4 v[128:131], v36, s[76:77] offset:128
	global_load_dwordx4 v[64:67], v40, s[78:79] offset:128
	global_load_dwordx4 v[76:79], v49, s[78:79] offset:128
	global_load_dwordx4 v[140:143], v34, s[76:77] offset:128
	global_load_dwordx4 v[92:95], v48, s[78:79] offset:128
	v_mov_b32_e32 v37, v147
	v_lshl_add_u64 v[216:217], s[76:77], 0, v[36:37]
	v_and_b32_e32 v51, 31, v1
	s_mulk_i32 s0, 0xc00
	v_lshl_add_u64 v[212:213], s[76:77], 0, v[146:147]
	v_mov_b32_e32 v35, v147
	v_mov_b32_e32 v39, v147
	v_lshl_add_u64 v[214:215], s[76:77], 0, v[34:35]
	v_lshl_add_u64 v[218:219], s[76:77], 0, v[38:39]
	v_add_u32_e32 v173, 0xd800, v210
	s_mov_b32 s8, 0
	v_mov_b32_e32 v52, v147
	v_mov_b32_e32 v53, v147
	v_mov_b32_e32 v54, v147
	v_mov_b32_e32 v55, v147
	v_mov_b32_e32 v56, v147
	v_mov_b32_e32 v57, v147
	v_mov_b32_e32 v58, v147
	v_mov_b32_e32 v59, v147
	v_mov_b32_e32 v60, v147
	v_mov_b32_e32 v61, v147
	v_mov_b32_e32 v62, v147
	v_mov_b32_e32 v63, v147
	s_waitcnt vmcnt(13)
	ds_write_b128 v210, v[2:5]
	s_waitcnt vmcnt(12)
	ds_write_b128 v210, v[6:9] offset:4608
	s_waitcnt vmcnt(11)
	ds_write_b128 v210, v[10:13] offset:9216
	s_waitcnt vmcnt(10)
	ds_write_b128 v210, v[14:17] offset:18432
	s_waitcnt vmcnt(9)
	ds_write_b128 v210, v[18:21] offset:23040
	s_waitcnt vmcnt(8)
	ds_write_b128 v210, v[22:25] offset:27648
	s_waitcnt vmcnt(7)
	ds_write_b128 v210, v[30:33] offset:32256
	s_waitcnt vmcnt(6)
	ds_write_b128 v210, v[26:29] offset:13824
	global_load_dwordx4 v[136:139], v38, s[76:77] offset:128
	global_load_dwordx4 v[104:107], v50, s[78:79] offset:128
	global_load_dwordx4 v[68:71], v36, s[76:77] offset:256
	global_load_dwordx4 v[72:75], v40, s[78:79] offset:256
	global_load_dwordx4 v[80:83], v146, s[76:77] offset:256
	global_load_dwordx4 v[84:87], v49, s[78:79] offset:256
	global_load_dwordx4 v[88:91], v34, s[76:77] offset:256
	global_load_dwordx4 v[96:99], v48, s[78:79] offset:256
	global_load_dwordx4 v[100:103], v38, s[76:77] offset:256
	global_load_dwordx4 v[108:111], v50, s[78:79] offset:256
	v_lshlrev_b32_e32 v37, 16, v6
	v_and_b32_e32 v41, 0xffff0000, v6
	v_and_b32_e32 v40, 0xffff0000, v2
	v_lshlrev_b32_e32 v43, 16, v7
	v_and_b32_e32 v7, 0xffff0000, v7
	v_and_b32_e32 v6, 0xffff0000, v3
	v_lshlrev_b32_e32 v36, 16, v2
	v_lshlrev_b32_e32 v42, 16, v3
	v_lshlrev_b32_e32 v3, 16, v8
	v_lshlrev_b32_e32 v2, 16, v4
	v_and_b32_e32 v45, 0xffff0000, v8
	v_and_b32_e32 v44, 0xffff0000, v4
	v_lshlrev_b32_e32 v46, 16, v5
	v_and_b32_e32 v8, 0xffff0000, v5
	v_pk_mul_f32 v[4:5], v[40:41], v[40:41]
	v_pk_mul_f32 v[6:7], v[6:7], v[6:7]
	v_lshlrev_b32_e32 v47, 16, v9
	v_and_b32_e32 v9, 0xffff0000, v9
	v_pk_mul_f32 v[14:15], v[44:45], v[44:45]
	v_pk_fma_f32 v[4:5], v[36:37], v[36:37], v[4:5]
	v_pk_fma_f32 v[6:7], v[42:43], v[42:43], v[6:7]
	v_pk_mul_f32 v[8:9], v[8:9], v[8:9]
	v_pk_fma_f32 v[2:3], v[2:3], v[2:3], v[14:15]
	v_pk_add_f32 v[4:5], v[4:5], v[6:7]
	v_pk_fma_f32 v[8:9], v[46:47], v[46:47], v[8:9]
	v_pk_add_f32 v[2:3], v[2:3], v[4:5]
	v_and_b32_e32 v5, 0xffff0000, v26
	v_and_b32_e32 v4, 0xffff0000, v10
	v_pk_add_f32 v[222:223], v[8:9], v[2:3]
	v_lshlrev_b32_e32 v3, 16, v26
	v_lshlrev_b32_e32 v2, 16, v10
	v_pk_mul_f32 v[4:5], v[4:5], v[4:5]
	v_and_b32_e32 v7, 0xffff0000, v27
	v_and_b32_e32 v6, 0xffff0000, v11
	v_pk_fma_f32 v[2:3], v[2:3], v[2:3], v[4:5]
	v_lshlrev_b32_e32 v5, 16, v27
	v_lshlrev_b32_e32 v4, 16, v11
	v_pk_mul_f32 v[6:7], v[6:7], v[6:7]
	v_mov_b32_e32 v8, v147
	v_pk_fma_f32 v[4:5], v[4:5], v[4:5], v[6:7]
	v_and_b32_e32 v7, 0xffff0000, v28
	v_and_b32_e32 v6, 0xffff0000, v12
	v_pk_add_f32 v[2:3], v[2:3], v[4:5]
	v_lshlrev_b32_e32 v5, 16, v28
	v_lshlrev_b32_e32 v4, 16, v12
	v_pk_mul_f32 v[6:7], v[6:7], v[6:7]
	v_mov_b32_e32 v9, v147
	v_pk_fma_f32 v[4:5], v[4:5], v[4:5], v[6:7]
	v_and_b32_e32 v7, 0xffff0000, v29
	v_and_b32_e32 v6, 0xffff0000, v13
	v_pk_add_f32 v[2:3], v[4:5], v[2:3]
	v_lshlrev_b32_e32 v5, 16, v29
	v_lshlrev_b32_e32 v4, 16, v13
	v_pk_mul_f32 v[6:7], v[6:7], v[6:7]
	v_mov_b32_e32 v10, v147
	v_pk_fma_f32 v[4:5], v[4:5], v[4:5], v[6:7]
	v_mov_b32_e32 v6, v147
	v_pk_add_f32 v[220:221], v[4:5], v[2:3]
	v_lshrrev_b32_e32 v2, 1, v1
	v_and_b32_e32 v1, 0x5f, v1
; template <bool SWAP, bool SS>
; __device__ __forceinline__ void gemm_main(const u16* __restrict__ A, int lda, int M, int m0,
;                                           const u16* __restrict__ Bt, int ldb, int n0, int K,
;                                           char* smraw, f32x16 (&acc)[2][2]) {
;     ...
;   auto lwrite = [&](const u32x4 (&ga)[4], const u32x4 (&gb)[4], int buf) {
;     u16* As = sm + buf * (2 * 128 * TSTR);
;     u16* Bs = As + 128 * TSTR;
; #pragma unroll
;     for (int j = 0; j < 4; ++j) {
;       *(u32x4*)(As + (lrow + 32 * j) * TSTR + kc * 8) = ga[j];
;       *(u32x4*)(Bs + (lrow + 32 * j) * TSTR + kc * 8) = gb[j];
;       if (SS) ss[j] += sumsq8(ga[j]);
;     }
;   };
;   auto compute = [&](int buf) {
;     const u16* As = sm + buf * (2 * 128 * TSTR);
;     const u16* Bs = As + 128 * TSTR;
; #pragma unroll
;     for (int ks = 0; ks < 4; ++ks) {
;       bf16x8 af[2], bf[2];
; #pragma unroll
;       for (int i = 0; i < 2; ++i) af[i] = *(const bf16x8*)(As + (wm * 64 + i * 32 + lc) * TSTR + ks * 16 + hf * 8);
; #pragma unroll
;       for (int j = 0; j < 2; ++j) bf[j] = *(const bf16x8*)(Bs + (wn * 64 + j * 32 + lc) * TSTR + ks * 16 + hf * 8);
; #pragma unroll
;       for (int i = 0; i < 2; ++i)
; #pragma unroll
;         for (int j = 0; j < 2; ++j)
;           acc[i][j] = SWAP ? mfma32(bf[j], af[i], acc[i][j]) : mfma32(af[i], bf[j], acc[i][j]);
;     }
;   };
;   u32x4 ga0[4], gb0[4], ga1[4], gb1[4];
;   gload(ga0, gb0, 0);
;   if (nk > 1) gload(ga1, gb1, 1);
;   lwrite(ga0, gb0, 0);
;   if (nk > 2) gload(ga0, gb0, 2);
;   __syncthreads();
;   for (int kt = 0; kt < nk; kt += 2) {
;     compute(0);
;     if (kt + 1 < nk) lwrite(ga1, gb1, 1);
;     if (kt + 3 < nk) gload(ga1, gb1, kt + 3);
;     __syncthreads();
	v_and_or_b32 v3, v2, s18, v51
	v_and_b32_e32 v2, 16, v2
	v_mul_u32_u24_e32 v1, 0x48, v1
	v_lshl_add_u32 v171, v1, 1, v2
	v_add_u32_e32 v1, s13, v167
	v_subrev_u32_e32 v1, s0, v1
	v_lshl_or_b32 v146, v1, 11, v0
	v_add_u32_e32 v1, s15, v167
	v_subrev_u32_e32 v1, s0, v1
	v_lshl_add_u64 v[226:227], s[78:79], 0, v[146:147]
	v_lshl_or_b32 v146, v1, 11, v0
	v_add_u32_e32 v1, s16, v167
	v_subrev_u32_e32 v1, s0, v1
	v_lshl_add_u64 v[228:229], s[78:79], 0, v[146:147]
	v_lshl_or_b32 v146, v1, 11, v0
	v_add_u32_e32 v1, s12, v167
	v_subrev_u32_e32 v1, s0, v1
	v_lshl_add_u64 v[230:231], s[78:79], 0, v[146:147]
	v_lshl_or_b32 v146, v1, 11, v0
	v_mad_u64_u32 v[224:225], s[4:5], v3, s17, v[2:3]
	v_lshl_add_u64 v[232:233], s[78:79], 0, v[146:147]
	s_mov_b64 s[0:1], 0
	v_mov_b32_e32 v0, 0
	v_mov_b32_e32 v1, v147
	v_mov_b32_e32 v2, v147
	v_mov_b32_e32 v3, v147
	v_mov_b32_e32 v4, v147
	v_mov_b32_e32 v5, v147
	v_mov_b32_e32 v7, v147
	v_mov_b32_e32 v11, v147
	v_mov_b32_e32 v12, v147
	v_mov_b32_e32 v13, v147
	v_mov_b32_e32 v14, v147
	v_mov_b32_e32 v15, v147
	v_mov_b32_e32 v16, 0
	v_mov_b32_e32 v17, v147
	v_mov_b32_e32 v18, v147
	v_mov_b32_e32 v19, v147
	v_mov_b32_e32 v20, v147
	v_mov_b32_e32 v21, v147
	v_mov_b32_e32 v22, v147
	v_mov_b32_e32 v23, v147
	v_mov_b32_e32 v24, v147
	v_mov_b32_e32 v25, v147
	v_mov_b32_e32 v26, v147
	v_mov_b32_e32 v27, v147
	v_mov_b32_e32 v28, v147
	v_mov_b32_e32 v29, v147
	v_mov_b32_e32 v30, v147
	v_mov_b32_e32 v31, v147
	v_mov_b32_e32 v32, 0
	v_mov_b32_e32 v33, v147
	v_mov_b32_e32 v34, v147
	v_mov_b32_e32 v36, v147
	v_mov_b32_e32 v37, v147
	v_mov_b32_e32 v38, v147
	v_mov_b32_e32 v40, v147
	v_mov_b32_e32 v41, v147
	v_mov_b32_e32 v42, v147
	v_mov_b32_e32 v43, v147
	v_mov_b32_e32 v44, v147
	v_mov_b32_e32 v45, v147
	v_mov_b32_e32 v46, v147
	v_mov_b32_e32 v47, v147
	v_mov_b32_e32 v48, 0
	v_mov_b32_e32 v49, v147
	v_mov_b32_e32 v50, v147
	v_mov_b32_e32 v51, v147
	s_waitcnt lgkmcnt(0)
	s_barrier
.LBB0_186:
	s_cmp_lt_u32 s8, 14
	s_cbranch_scc1 .Lmy_qkv_nolast
	s_waitcnt vmcnt(0)
.Lmy_qkv_nolast:
	ds_read_b128 v[112:115], v171 offset:18432
	ds_read_b128 v[116:119], v224
	ds_read_b128 v[120:123], v224 offset:32
	ds_read_b128 v[124:127], v171 offset:18464
	ds_read_b128 v[234:237], v171 offset:23040
	ds_read_b128 v[238:241], v171 offset:23072
	s_cmp_gt_u32 s8, 12
	s_waitcnt lgkmcnt(4)
	v_mfma_f32_32x32x16_bf16 v[48:63], v[112:115], v[116:119], v[48:63]
	v_lshl_add_u64 v[246:247], v[218:219], 0, s[0:1]
	v_lshl_add_u64 v[248:249], v[226:227], 0, s[0:1]
	s_waitcnt lgkmcnt(1)
	v_mfma_f32_32x32x16_bf16 v[32:47], v[234:237], v[116:119], v[32:47]
	ds_read_b128 v[116:119], v224 offset:4608
	ds_read_b128 v[242:245], v224 offset:4640
	s_waitcnt lgkmcnt(1)
	v_mfma_f32_32x32x16_bf16 v[16:31], v[112:115], v[116:119], v[16:31]
	v_mfma_f32_32x32x16_bf16 v[0:15], v[234:237], v[116:119], v[0:15]
	v_mfma_f32_32x32x16_bf16 v[48:63], v[124:127], v[120:123], v[48:63]
	v_mfma_f32_32x32x16_bf16 v[32:47], v[238:241], v[120:123], v[32:47]
	s_waitcnt lgkmcnt(0)
	v_mfma_f32_32x32x16_bf16 v[16:31], v[124:127], v[242:245], v[16:31]
	ds_read_b128 v[112:115], v171 offset:18496
	ds_read_b128 v[116:119], v224 offset:64
	ds_read_b128 v[120:123], v224 offset:96
	ds_read_b128 v[124:127], v171 offset:18528
	ds_read_b128 v[234:237], v171 offset:23104
	ds_read_b128 v[250:253], v171 offset:23136
	v_mfma_f32_32x32x16_bf16 v[0:15], v[238:241], v[242:245], v[0:15]
	v_lshl_add_u64 v[238:239], v[214:215], 0, s[0:1]
	v_lshl_add_u64 v[240:241], v[230:231], 0, s[0:1]
	v_lshl_add_u64 v[242:243], v[216:217], 0, s[0:1]
	v_lshl_add_u64 v[244:245], v[228:229], 0, s[0:1]
	s_waitcnt lgkmcnt(4)
	v_mfma_f32_32x32x16_bf16 v[48:63], v[112:115], v[116:119], v[48:63]
	s_waitcnt lgkmcnt(1)
	v_mfma_f32_32x32x16_bf16 v[32:47], v[234:237], v[116:119], v[32:47]
	ds_read_b128 v[116:119], v224 offset:4672
	ds_read_b128 v[174:177], v224 offset:4704
	s_waitcnt vmcnt(8)
	ds_write_b128 v210, v[132:135] offset:36864
	ds_write_b128 v210, v[64:67] offset:55296
	ds_write_b128 v210, v[140:143] offset:41472
	ds_write_b128 v210, v[92:95] offset:59904
	ds_write_b128 v210, v[128:131] offset:46080
	ds_write_b128 v210, v[76:79] offset:64512
	ds_write_b128 v210, v[136:139] offset:50688
	ds_write_b128 v173, v[104:107] offset:13824
	s_waitcnt lgkmcnt(9)
	v_mfma_f32_32x32x16_bf16 v[16:31], v[112:115], v[116:119], v[16:31]
	v_mfma_f32_32x32x16_bf16 v[0:15], v[234:237], v[116:119], v[0:15]
	v_lshl_add_u64 v[234:235], v[212:213], 0, s[0:1]
	v_lshl_add_u64 v[236:237], v[232:233], 0, s[0:1]
	v_mfma_f32_32x32x16_bf16 v[48:63], v[124:127], v[120:123], v[48:63]
	v_mfma_f32_32x32x16_bf16 v[32:47], v[250:253], v[120:123], v[32:47]
	s_waitcnt lgkmcnt(8)
	v_mfma_f32_32x32x16_bf16 v[16:31], v[124:127], v[174:177], v[16:31]
	v_mfma_f32_32x32x16_bf16 v[0:15], v[250:253], v[174:177], v[0:15]
	v_and_b32_e32 v177, 0xffff0000, v140
	v_and_b32_e32 v176, 0xffff0000, v132
	v_lshlrev_b32_e32 v175, 16, v140
	v_lshlrev_b32_e32 v174, 16, v132
	v_pk_mul_f32 v[176:177], v[176:177], v[176:177]
	v_and_b32_e32 v140, 0xffff0000, v133
	v_pk_fma_f32 v[174:175], v[174:175], v[174:175], v[176:177]
	v_lshlrev_b32_e32 v177, 16, v141
	v_and_b32_e32 v141, 0xffff0000, v141
	v_lshlrev_b32_e32 v176, 16, v133
	v_pk_mul_f32 v[132:133], v[140:141], v[140:141]
	v_lshlrev_b32_e32 v141, 16, v142
	v_pk_fma_f32 v[132:133], v[176:177], v[176:177], v[132:133]
	v_lshlrev_b32_e32 v140, 16, v134
	v_pk_add_f32 v[132:133], v[174:175], v[132:133]
	v_and_b32_e32 v175, 0xffff0000, v142
	v_and_b32_e32 v174, 0xffff0000, v134
	v_pk_mul_f32 v[174:175], v[174:175], v[174:175]
	v_and_b32_e32 v142, 0xffff0000, v135
	v_pk_fma_f32 v[140:141], v[140:141], v[140:141], v[174:175]
	s_waitcnt lgkmcnt(0)
	v_pk_add_f32 v[132:133], v[140:141], v[132:133]
	v_lshlrev_b32_e32 v141, 16, v143
	v_and_b32_e32 v143, 0xffff0000, v143
	v_lshlrev_b32_e32 v140, 16, v135
	v_pk_mul_f32 v[134:135], v[142:143], v[142:143]
	s_barrier
; template <bool SWAP, bool SS>
; __device__ __forceinline__ void gemm_main(const u16* __restrict__ A, int lda, int M, int m0,
;                                           const u16* __restrict__ Bt, int ldb, int n0, int K,
;                                           char* smraw, f32x16 (&acc)[2][2]) {
;     ...
;   auto gload = [&](u32x4 (&ga)[4], u32x4 (&gb)[4], int kt) {
; #pragma unroll
;     for (int j = 0; j < 4; ++j) { ga[j] = *(const u32x4*)(Ab + (aoff[j] + (unsigned)kt * 128u)); gb[j] = *(const u32x4*)(Bb + (boff[j] + (unsigned)kt * 128u)); }
;   };
;   auto lwrite = [&](const u32x4 (&ga)[4], const u32x4 (&gb)[4], int buf) {
;     u16* As = sm + buf * (2 * 128 * TSTR);
;     u16* Bs = As + 128 * TSTR;
; #pragma unroll
;     for (int j = 0; j < 4; ++j) {
;       *(u32x4*)(As + (lrow + 32 * j) * TSTR + kc * 8) = ga[j];
;       *(u32x4*)(Bs + (lrow + 32 * j) * TSTR + kc * 8) = gb[j];
;       if (SS) ss[j] += sumsq8(ga[j]);
;     }
;   };
;   auto compute = [&](int buf) {
;     const u16* As = sm + buf * (2 * 128 * TSTR);
;     const u16* Bs = As + 128 * TSTR;
; #pragma unroll
;     for (int ks = 0; ks < 4; ++ks) {
;       bf16x8 af[2], bf[2];
; #pragma unroll
;       for (int i = 0; i < 2; ++i) af[i] = *(const bf16x8*)(As + (wm * 64 + i * 32 + lc) * TSTR + ks * 16 + hf * 8);
; #pragma unroll
;       for (int j = 0; j < 2; ++j) bf[j] = *(const bf16x8*)(Bs + (wn * 64 + j * 32 + lc) * TSTR + ks * 16 + hf * 8);
; #pragma unroll
;       for (int i = 0; i < 2; ++i)
; #pragma unroll
;         for (int j = 0; j < 2; ++j)
;           acc[i][j] = SWAP ? mfma32(bf[j], af[i], acc[i][j]) : mfma32(af[i], bf[j], acc[i][j]);
;     }
;     ...
;   for (int kt = 0; kt < nk; kt += 2) {
;     compute(0);
;     if (kt + 1 < nk) lwrite(ga1, gb1, 1);
;     if (kt + 3 < nk) gload(ga1, gb1, kt + 3);
;     __syncthreads();
;     if (kt + 1 < nk) {
;       compute(1);
;       if (kt + 2 < nk) lwrite(ga0, gb0, 0);
;       if (kt + 4 < nk) gload(ga0, gb0, kt + 4);
	v_pk_fma_f32 v[134:135], v[140:141], v[140:141], v[134:135]
	s_nop 0
	v_pk_add_f32 v[132:133], v[134:135], v[132:133]
	v_and_b32_e32 v135, 0xffff0000, v136
	v_and_b32_e32 v134, 0xffff0000, v128
	v_pk_add_f32 v[222:223], v[222:223], v[132:133]
	v_lshlrev_b32_e32 v133, 16, v136
	v_lshlrev_b32_e32 v132, 16, v128
	v_pk_mul_f32 v[134:135], v[134:135], v[134:135]
	v_and_b32_e32 v136, 0xffff0000, v129
	v_pk_fma_f32 v[132:133], v[132:133], v[132:133], v[134:135]
	v_lshlrev_b32_e32 v135, 16, v137
	v_and_b32_e32 v137, 0xffff0000, v137
	v_lshlrev_b32_e32 v134, 16, v129
	v_pk_mul_f32 v[128:129], v[136:137], v[136:137]
	s_cmp_gt_u32 s8, 13
	v_pk_fma_f32 v[128:129], v[134:135], v[134:135], v[128:129]
	v_and_b32_e32 v135, 0xffff0000, v138
	v_and_b32_e32 v134, 0xffff0000, v130
	v_pk_add_f32 v[128:129], v[132:133], v[128:129]
	v_lshlrev_b32_e32 v133, 16, v138
	v_lshlrev_b32_e32 v132, 16, v130
	v_pk_mul_f32 v[134:135], v[134:135], v[134:135]
	s_cselect_b64 s[4:5], -1, 0
	v_pk_fma_f32 v[132:133], v[132:133], v[132:133], v[134:135]
	v_and_b32_e32 v135, 0xffff0000, v139
	v_and_b32_e32 v134, 0xffff0000, v131
	v_pk_add_f32 v[128:129], v[132:133], v[128:129]
	v_lshlrev_b32_e32 v133, 16, v139
	v_lshlrev_b32_e32 v132, 16, v131
	v_pk_mul_f32 v[130:131], v[134:135], v[134:135]
	s_and_b64 vcc, exec, s[4:5]
	v_pk_fma_f32 v[130:131], v[132:133], v[132:133], v[130:131]
	s_nop 0
	v_pk_add_f32 v[128:129], v[130:131], v[128:129]
	s_nop 0
	v_pk_add_f32 v[220:221], v[220:221], v[128:129]
	s_cmp_gt_u32 s8, 12
	s_cbranch_scc1 .Lmy_qkv_skipL
	global_load_dwordx4 v[132:135], v[234:235], off offset:384
	global_load_dwordx4 v[64:67], v[236:237], off offset:384
	global_load_dwordx4 v[140:143], v[238:239], off offset:384
	global_load_dwordx4 v[92:95], v[240:241], off offset:384
	global_load_dwordx4 v[128:131], v[242:243], off offset:384
	global_load_dwordx4 v[76:79], v[244:245], off offset:384
	global_load_dwordx4 v[136:139], v[246:247], off offset:384
	global_load_dwordx4 v[104:107], v[248:249], off offset:384
.Lmy_qkv_skipL:
	ds_read_b128 v[112:115], v224 offset:41472
	ds_read_b128 v[116:119], v171 offset:59904
	ds_read_b128 v[120:123], v224 offset:36864
	ds_read_b128 v[124:127], v224 offset:36896
	ds_read_b128 v[174:177], v171 offset:55296
	ds_read_b128 v[250:253], v171 offset:55328
	s_waitcnt lgkmcnt(1)
	v_mfma_f32_32x32x16_bf16 v[48:63], v[174:177], v[120:123], v[48:63]
	v_mfma_f32_32x32x16_bf16 v[32:47], v[116:119], v[120:123], v[32:47]
	v_mfma_f32_32x32x16_bf16 v[16:31], v[174:177], v[112:115], v[16:31]
	v_mfma_f32_32x32x16_bf16 v[0:15], v[116:119], v[112:115], v[0:15]
	ds_read_b128 v[112:115], v224 offset:41504
	ds_read_b128 v[116:119], v171 offset:59936
	s_waitcnt lgkmcnt(2)
	v_mfma_f32_32x32x16_bf16 v[48:63], v[250:253], v[124:127], v[48:63]
	s_waitcnt lgkmcnt(0)
	v_mfma_f32_32x32x16_bf16 v[32:47], v[116:119], v[124:127], v[32:47]
	v_mfma_f32_32x32x16_bf16 v[16:31], v[250:253], v[112:115], v[16:31]
	v_mfma_f32_32x32x16_bf16 v[0:15], v[116:119], v[112:115], v[0:15]
	ds_read_b128 v[112:115], v224 offset:36928
	ds_read_b128 v[116:119], v224 offset:41536
	ds_read_b128 v[120:123], v171 offset:55360
	ds_read_b128 v[124:127], v171 offset:59968
	s_waitcnt lgkmcnt(1)
	v_mfma_f32_32x32x16_bf16 v[48:63], v[120:123], v[112:115], v[48:63]
	s_waitcnt lgkmcnt(0)
	v_mfma_f32_32x32x16_bf16 v[32:47], v[124:127], v[112:115], v[32:47]
	v_mfma_f32_32x32x16_bf16 v[16:31], v[120:123], v[116:119], v[16:31]
	v_mfma_f32_32x32x16_bf16 v[0:15], v[124:127], v[116:119], v[0:15]
	ds_read_b128 v[112:115], v224 offset:36960
	ds_read_b128 v[116:119], v224 offset:41568
	ds_read_b128 v[120:123], v171 offset:55392
	ds_read_b128 v[124:127], v171 offset:60000
	s_waitcnt lgkmcnt(1)
	v_mfma_f32_32x32x16_bf16 v[48:63], v[120:123], v[112:115], v[48:63]
	s_waitcnt lgkmcnt(0)
	v_mfma_f32_32x32x16_bf16 v[32:47], v[124:127], v[112:115], v[32:47]
	v_mfma_f32_32x32x16_bf16 v[16:31], v[120:123], v[116:119], v[16:31]
	v_mfma_f32_32x32x16_bf16 v[0:15], v[124:127], v[116:119], v[0:15]
	s_cbranch_vccnz .LBB0_190
	s_waitcnt vmcnt(8)
	v_and_b32_e32 v115, 0xffff0000, v88
	v_and_b32_e32 v114, 0xffff0000, v80
	v_lshlrev_b32_e32 v113, 16, v88
	v_lshlrev_b32_e32 v112, 16, v80
	v_pk_mul_f32 v[114:115], v[114:115], v[114:115]
	v_and_b32_e32 v117, 0xffff0000, v89
	v_and_b32_e32 v116, 0xffff0000, v81
	v_pk_fma_f32 v[112:113], v[112:113], v[112:113], v[114:115]
	v_lshlrev_b32_e32 v115, 16, v89
	v_lshlrev_b32_e32 v114, 16, v81
	v_pk_mul_f32 v[116:117], v[116:117], v[116:117]
	ds_write_b128 v210, v[80:83]
	ds_write_b128 v210, v[72:75] offset:18432
	ds_write_b128 v210, v[88:91] offset:4608
	ds_write_b128 v210, v[96:99] offset:23040
	v_pk_fma_f32 v[114:115], v[114:115], v[114:115], v[116:117]
	v_and_b32_e32 v117, 0xffff0000, v90
	v_and_b32_e32 v116, 0xffff0000, v82
	v_pk_add_f32 v[112:113], v[112:113], v[114:115]
	v_lshlrev_b32_e32 v115, 16, v90
	v_lshlrev_b32_e32 v114, 16, v82
	v_pk_mul_f32 v[116:117], v[116:117], v[116:117]
	ds_write_b128 v210, v[68:71] offset:9216
	ds_write_b128 v210, v[84:87] offset:27648
	ds_write_b128 v210, v[100:103] offset:13824
	ds_write_b128 v210, v[108:111] offset:32256
	v_pk_fma_f32 v[114:115], v[114:115], v[114:115], v[116:117]
	v_and_b32_e32 v117, 0xffff0000, v91
	v_and_b32_e32 v116, 0xffff0000, v83
	v_pk_add_f32 v[112:113], v[114:115], v[112:113]
	v_lshlrev_b32_e32 v115, 16, v91
	v_lshlrev_b32_e32 v114, 16, v83
	v_pk_mul_f32 v[116:117], v[116:117], v[116:117]
	s_nop 0
	v_pk_fma_f32 v[114:115], v[114:115], v[114:115], v[116:117]
	v_and_b32_e32 v117, 0xffff0000, v101
	v_pk_add_f32 v[112:113], v[114:115], v[112:113]
	v_and_b32_e32 v115, 0xffff0000, v100
	v_and_b32_e32 v114, 0xffff0000, v68
	v_pk_add_f32 v[222:223], v[112:113], v[222:223]
	v_lshlrev_b32_e32 v113, 16, v100
	v_lshlrev_b32_e32 v112, 16, v68
	v_pk_mul_f32 v[114:115], v[114:115], v[114:115]
	v_and_b32_e32 v116, 0xffff0000, v69
	v_pk_fma_f32 v[112:113], v[112:113], v[112:113], v[114:115]
	v_lshlrev_b32_e32 v115, 16, v101
	v_lshlrev_b32_e32 v114, 16, v69
	v_pk_mul_f32 v[116:117], v[116:117], v[116:117]
	s_nop 0
	v_pk_fma_f32 v[114:115], v[114:115], v[114:115], v[116:117]
	v_and_b32_e32 v117, 0xffff0000, v102
	v_and_b32_e32 v116, 0xffff0000, v70
	v_pk_add_f32 v[112:113], v[112:113], v[114:115]
	v_lshlrev_b32_e32 v115, 16, v102
	v_lshlrev_b32_e32 v114, 16, v70
	v_pk_mul_f32 v[116:117], v[116:117], v[116:117]
	s_nop 0
	v_pk_fma_f32 v[114:115], v[114:115], v[114:115], v[116:117]
	v_and_b32_e32 v117, 0xffff0000, v103
	v_and_b32_e32 v116, 0xffff0000, v71
	v_pk_add_f32 v[112:113], v[114:115], v[112:113]
	v_lshlrev_b32_e32 v115, 16, v103
	v_lshlrev_b32_e32 v114, 16, v71
	v_pk_mul_f32 v[116:117], v[116:117], v[116:117]
	s_nop 0
	v_pk_fma_f32 v[114:115], v[114:115], v[114:115], v[116:117]
	s_nop 0
	v_pk_add_f32 v[112:113], v[114:115], v[112:113]
	s_nop 0
	v_pk_add_f32 v[220:221], v[112:113], v[220:221]

; template <bool SWAP, bool SS>
; __device__ __forceinline__ void gemm_main(const u16* __restrict__ A, int lda, int M, int m0,
;                                           const u16* __restrict__ Bt, int ldb, int n0, int K,
;                                           char* smraw, f32x16 (&acc)[2][2]) {
;     ...
;   for (int kt = 0; kt < nk; kt += 2) {
;     compute(0);
;     if (kt + 1 < nk) lwrite(ga1, gb1, 1);
;     if (kt + 3 < nk) gload(ga1, gb1, kt + 3);
;     __syncthreads();
;     if (kt + 1 < nk) {
;       compute(1);
;       if (kt + 2 < nk) lwrite(ga0, gb0, 0);
;       if (kt + 4 < nk) gload(ga0, gb0, kt + 4);
;       __syncthreads();
;     }
;   }
.LBB0_192:
	s_add_i32 s8, s8, 2
	s_add_u32 s0, s0, 0x100
	s_addc_u32 s1, s1, 0
	s_and_b64 vcc, exec, s[4:5]
	s_waitcnt lgkmcnt(0)
	s_barrier
	s_cbranch_vccnz .LBB0_194
	s_branch .LBB0_186

; __device__ __forceinline__ void phase_qkv(const Params& p, char* smraw) {
;     ...
;       if (sec < 2) {
;         float ssq = 0.f;
; #pragma unroll
;         for (int j = 0; j < 2; ++j)
; #pragma unroll
;           for (int r = 0; r < 16; ++r) { float v = acc[i][j][r] * rs; ssq += v * v; }
;         ssq += __shfl_xor(ssq, 32);
.LBB0_206:
	v_cndmask_b32_e64 v65, v159, v66, s[8:9]
	v_lshlrev_b32_e32 v67, 2, v65
	s_andn2_b64 vcc, exec, s[10:11]
	v_cndmask_b32_e64 v66, 1.0, v165, s[4:5]
	s_cbranch_vccnz .LBB0_210
	s_waitcnt lgkmcnt(0)
	v_mul_f32_e32 v71, v49, v69
	v_mul_f32_e32 v65, v48, v69
	v_mul_f32_e32 v71, v71, v71
	v_fmac_f32_e32 v71, v65, v65
	v_mul_f32_e32 v65, v50, v69
	v_fmac_f32_e32 v71, v65, v65
	v_mul_f32_e32 v65, v51, v69
	v_fmac_f32_e32 v71, v65, v65
	v_mul_f32_e32 v65, v52, v69
	v_fmac_f32_e32 v71, v65, v65
	v_mul_f32_e32 v65, v53, v69
	v_fmac_f32_e32 v71, v65, v65
	v_mul_f32_e32 v65, v54, v69
	v_fmac_f32_e32 v71, v65, v65
	v_mul_f32_e32 v65, v55, v69
	v_fmac_f32_e32 v71, v65, v65
	v_mul_f32_e32 v65, v56, v69
	v_fmac_f32_e32 v71, v65, v65
	v_mul_f32_e32 v65, v57, v69
	v_fmac_f32_e32 v71, v65, v65
	v_mul_f32_e32 v65, v58, v69
	v_fmac_f32_e32 v71, v65, v65
	v_mul_f32_e32 v65, v59, v69
	v_fmac_f32_e32 v71, v65, v65
	v_mul_f32_e32 v65, v60, v69
	v_fmac_f32_e32 v71, v65, v65
	v_mul_f32_e32 v65, v61, v69
	v_fmac_f32_e32 v71, v65, v65
	v_mul_f32_e32 v65, v62, v69
	v_fmac_f32_e32 v71, v65, v65
	v_mul_f32_e32 v65, v63, v69
	v_fmac_f32_e32 v71, v65, v65
	v_mul_f32_e32 v65, v32, v69
	v_fmac_f32_e32 v71, v65, v65
	v_mul_f32_e32 v65, v33, v69
	v_fmac_f32_e32 v71, v65, v65
	v_mul_f32_e32 v65, v34, v69
	v_fmac_f32_e32 v71, v65, v65
	v_mul_f32_e32 v65, v35, v69
	v_fmac_f32_e32 v71, v65, v65
	v_mul_f32_e32 v65, v36, v69
	v_fmac_f32_e32 v71, v65, v65
	v_mul_f32_e32 v65, v37, v69
	v_fmac_f32_e32 v71, v65, v65
	v_mul_f32_e32 v65, v38, v69
	v_fmac_f32_e32 v71, v65, v65
	v_mul_f32_e32 v65, v39, v69
	v_fmac_f32_e32 v71, v65, v65
	v_mul_f32_e32 v65, v40, v69
	v_fmac_f32_e32 v71, v65, v65
	v_mul_f32_e32 v65, v41, v69
	v_fmac_f32_e32 v71, v65, v65
	v_mul_f32_e32 v65, v42, v69
	v_fmac_f32_e32 v71, v65, v65
	v_mul_f32_e32 v65, v43, v69
	v_fmac_f32_e32 v71, v65, v65
	v_mul_f32_e32 v65, v44, v69
	v_fmac_f32_e32 v71, v65, v65
	v_mul_f32_e32 v65, v45, v69
	v_fmac_f32_e32 v71, v65, v65
	v_mul_f32_e32 v65, v46, v69
	v_fmac_f32_e32 v71, v65, v65
	v_mul_f32_e32 v65, v47, v69
	v_fmac_f32_e32 v71, v65, v65
	ds_bpermute_b32 v72, v67, v71
	s_and_saveexec_b64 s[8:9], s[6:7]
	s_cbranch_execz .LBB0_209
; __device__ __forceinline__ void phase_qkv(const Params& p, char* smraw) {
;     ...
;         const float mult = rsqrtf(ssq * (1.f / 64.f) + EPS) * rs * (sec == 0 ? QS : 1.f);
;         const float* gain = sec == 0 ? p.qgain : p.kgain;
;         u16* dst = (sec == 0 ? p.qbuf : p.kbuf) + ((size_t)bh * LP + pos) * 64;
;         if (valid) {
; #pragma unroll
;           for (int j = 0; j < 2; ++j)
; #pragma unroll
;             for (int rg = 0; rg < 4; ++rg) {
;               const int d0 = j * 32 + 8 * rg + 4 * hf;
;               f32x4 g = *(const f32x4*)(gain + d0);
;               u32x2 o;
;               o[0] = cvtpk(acc[i][j][rg * 4 + 0] * mult * g[0], acc[i][j][rg * 4 + 1] * mult * g[1]);
;               o[1] = cvtpk(acc[i][j][rg * 4 + 2] * mult * g[2], acc[i][j][rg * 4 + 3] * mult * g[3]);
;               *(u32x2*)(dst + d0) = o;
;             }
	s_and_b64 s[6:7], s[4:5], exec
	s_cselect_b32 s7, s47, s49
	s_cselect_b32 s6, s46, s48
	v_lshlrev_b32_e32 v73, 2, v144
	global_load_dwordx4 v[74:77], v73, s[6:7]
	s_waitcnt vmcnt(3)
	global_load_dwordx4 v[96:99], v73, s[6:7] offset:32
	global_load_dwordx4 v[100:103], v73, s[6:7] offset:64
	global_load_dwordx4 v[104:107], v73, s[6:7] offset:96
	global_load_dwordx4 v[108:111], v73, s[6:7] offset:128
	global_load_dwordx4 v[112:115], v73, s[6:7] offset:160
	global_load_dwordx4 v[116:119], v73, s[6:7] offset:192
	global_load_dwordx4 v[120:123], v73, s[6:7] offset:224
	v_mul_hi_i32_i24_e32 v79, 0x2080, v70
	v_mul_i32_i24_e32 v78, 0x2080, v70
	s_waitcnt lgkmcnt(0)
	v_add_f32_e32 v70, v71, v72
	v_fmamk_f32 v70, v70, 0x3c800000, v161
	v_mul_f32_e32 v71, 0x4b800000, v70
	v_cmp_gt_f32_e32 vcc, s19, v70
	v_ashrrev_i32_e32 v65, 31, v64
	v_readlane_b32 s36, v254, 0
	v_cndmask_b32_e32 v70, v70, v71, vcc
	v_rsq_f32_e32 v70, v70
	v_readlane_b32 s48, v254, 12
	v_readlane_b32 s49, v254, 13
	v_readlane_b32 s50, v254, 14
	v_mul_f32_e32 v71, 0x45800000, v70
	v_cndmask_b32_e32 v70, v70, v71, vcc
	v_readlane_b32 s51, v254, 15
	v_lshl_add_u64 v[64:65], v[78:79], 0, v[64:65]
	v_mul_f32_e32 v69, v69, v70
	s_cselect_b32 s11, s49, s51
	s_cselect_b32 s10, s48, s50
	v_lshlrev_b64 v[64:65], 7, v[64:65]
	v_mul_f32_e32 v69, v66, v69
	v_lshlrev_b32_e32 v146, 1, v144
	v_lshl_add_u64 v[64:65], s[10:11], 0, v[64:65]
	v_mul_f32_e32 v48, v48, v69
	v_mul_f32_e32 v49, v49, v69
	v_lshl_add_u64 v[64:65], v[64:65], 0, v[146:147]
	v_mul_f32_e32 v50, v50, v69
	v_mul_f32_e32 v51, v51, v69
	v_mul_f32_e32 v52, v52, v69
	v_mul_f32_e32 v53, v53, v69
	v_mul_f32_e32 v54, v54, v69
	v_mul_f32_e32 v55, v55, v69
	v_mul_f32_e32 v32, v32, v69
	v_mul_f32_e32 v33, v33, v69
	v_mul_f32_e32 v34, v34, v69
	v_mul_f32_e32 v35, v35, v69
	v_mul_f32_e32 v36, v36, v69
	v_mul_f32_e32 v37, v37, v69
	v_mul_f32_e32 v38, v38, v69
	v_mul_f32_e32 v39, v39, v69
	v_readlane_b32 s37, v254, 1
	v_readlane_b32 s38, v254, 2
	v_readlane_b32 s39, v254, 3
	v_readlane_b32 s40, v254, 4
	v_readlane_b32 s41, v254, 5
	v_readlane_b32 s42, v254, 6
	v_readlane_b32 s43, v254, 7
	v_readlane_b32 s44, v254, 8
	v_readlane_b32 s45, v254, 9
	v_readlane_b32 s46, v254, 10
	v_readlane_b32 s47, v254, 11
	v_readlane_b32 s36, v254, 42
	v_readlane_b32 s37, v254, 43
	v_readlane_b32 s38, v254, 44
	v_readlane_b32 s39, v254, 45
	v_readlane_b32 s46, v254, 52
	v_readlane_b32 s47, v254, 53
	v_readlane_b32 s48, v254, 54
	v_readlane_b32 s49, v254, 55
	v_readlane_b32 s40, v254, 46
	v_readlane_b32 s41, v254, 47
	v_readlane_b32 s42, v254, 48
	v_readlane_b32 s43, v254, 49
	v_readlane_b32 s44, v254, 50
	v_readlane_b32 s45, v254, 51
	v_readlane_b32 s50, v254, 56
	v_readlane_b32 s51, v254, 57
	s_waitcnt vmcnt(0)
	v_mul_f32_e32 v48, v48, v74
	v_mul_f32_e32 v49, v49, v75
	v_mul_f32_e32 v50, v50, v76
	v_mul_f32_e32 v51, v51, v77
	v_cvt_pk_bf16_f32 v48, v48, v49
	v_cvt_pk_bf16_f32 v49, v50, v51
	global_store_dwordx2 v[64:65], v[48:49], off
	v_mul_f32_e32 v48, v52, v96
	v_mul_f32_e32 v49, v53, v97
	v_mul_f32_e32 v50, v54, v98
	v_mul_f32_e32 v51, v55, v99
	v_cvt_pk_bf16_f32 v48, v48, v49
	v_cvt_pk_bf16_f32 v49, v50, v51
	global_store_dwordx2 v[64:65], v[48:49], off offset:16
	v_mul_f32_e32 v52, v56, v69
	v_mul_f32_e32 v53, v57, v69
	v_mul_f32_e32 v54, v58, v69
	v_mul_f32_e32 v55, v59, v69
	v_mul_f32_e32 v48, v52, v100
	v_mul_f32_e32 v49, v53, v101
	v_mul_f32_e32 v50, v54, v102
	v_mul_f32_e32 v51, v55, v103
	v_cvt_pk_bf16_f32 v48, v48, v49
	v_cvt_pk_bf16_f32 v49, v50, v51
	global_store_dwordx2 v[64:65], v[48:49], off offset:32
	v_mul_f32_e32 v52, v60, v69
	v_mul_f32_e32 v53, v61, v69
	v_mul_f32_e32 v54, v62, v69
	v_mul_f32_e32 v55, v63, v69
	v_mul_f32_e32 v48, v52, v104
	v_mul_f32_e32 v49, v53, v105
	v_mul_f32_e32 v50, v54, v106
	v_mul_f32_e32 v51, v55, v107
	v_cvt_pk_bf16_f32 v48, v48, v49
	v_cvt_pk_bf16_f32 v49, v50, v51
	global_store_dwordx2 v[64:65], v[48:49], off offset:48
	v_mul_f32_e32 v32, v32, v108
	v_mul_f32_e32 v33, v33, v109
	v_mul_f32_e32 v34, v34, v110
	v_mul_f32_e32 v35, v35, v111
	v_cvt_pk_bf16_f32 v32, v32, v33
	v_cvt_pk_bf16_f32 v33, v34, v35
	global_store_dwordx2 v[64:65], v[32:33], off offset:64
	v_mul_f32_e32 v32, v36, v112
	v_mul_f32_e32 v33, v37, v113
	v_mul_f32_e32 v34, v38, v114
	v_mul_f32_e32 v35, v39, v115
	v_cvt_pk_bf16_f32 v32, v32, v33
	v_cvt_pk_bf16_f32 v33, v34, v35
	global_store_dwordx2 v[64:65], v[32:33], off offset:80
	v_mul_f32_e32 v36, v40, v69
	v_mul_f32_e32 v37, v41, v69
	v_mul_f32_e32 v38, v42, v69
	v_mul_f32_e32 v39, v43, v69
	v_mul_f32_e32 v32, v36, v116
	v_mul_f32_e32 v33, v37, v117
	v_mul_f32_e32 v34, v38, v118
	v_mul_f32_e32 v35, v39, v119
	v_cvt_pk_bf16_f32 v32, v32, v33
	v_cvt_pk_bf16_f32 v33, v34, v35
	global_store_dwordx2 v[64:65], v[32:33], off offset:96
	v_mul_f32_e32 v36, v44, v69
	v_mul_f32_e32 v37, v45, v69
	v_mul_f32_e32 v38, v46, v69
	v_mul_f32_e32 v39, v47, v69
	v_mul_f32_e32 v32, v36, v120
	v_mul_f32_e32 v33, v37, v121
	v_mul_f32_e32 v34, v38, v122
	v_mul_f32_e32 v35, v39, v123
	v_cvt_pk_bf16_f32 v32, v32, v33
	v_cvt_pk_bf16_f32 v33, v34, v35
	global_store_dwordx2 v[64:65], v[32:33], off offset:112

; __device__ __forceinline__ void phase_qkv(const Params& p, char* smraw) {
;     ...
;       if (sec < 2) {
;         float ssq = 0.f;
; #pragma unroll
;         for (int j = 0; j < 2; ++j)
; #pragma unroll
;           for (int r = 0; r < 16; ++r) { float v = acc[i][j][r] * rs; ssq += v * v; }
;         ssq += __shfl_xor(ssq, 32);
.LBB0_214:
	s_andn2_b64 vcc, exec, s[0:1]
	s_cbranch_vccnz .LBB0_184
	s_waitcnt lgkmcnt(0)
	v_mul_f32_e32 v36, v17, v34
	v_mul_f32_e32 v33, v16, v34
	v_mul_f32_e32 v36, v36, v36
	v_fmac_f32_e32 v36, v33, v33
	v_mul_f32_e32 v33, v18, v34
	v_fmac_f32_e32 v36, v33, v33
	v_mul_f32_e32 v33, v19, v34
	v_fmac_f32_e32 v36, v33, v33
	v_mul_f32_e32 v33, v20, v34
	v_fmac_f32_e32 v36, v33, v33
	v_mul_f32_e32 v33, v21, v34
	v_fmac_f32_e32 v36, v33, v33
	v_mul_f32_e32 v33, v22, v34
	v_fmac_f32_e32 v36, v33, v33
	v_mul_f32_e32 v33, v23, v34
	v_fmac_f32_e32 v36, v33, v33
	v_mul_f32_e32 v33, v24, v34
	v_fmac_f32_e32 v36, v33, v33
	v_mul_f32_e32 v33, v25, v34
	v_fmac_f32_e32 v36, v33, v33
	v_mul_f32_e32 v33, v26, v34
	v_fmac_f32_e32 v36, v33, v33
	v_mul_f32_e32 v33, v27, v34
	v_fmac_f32_e32 v36, v33, v33
	v_mul_f32_e32 v33, v28, v34
	v_fmac_f32_e32 v36, v33, v33
	v_mul_f32_e32 v33, v29, v34
	v_fmac_f32_e32 v36, v33, v33
	v_mul_f32_e32 v33, v30, v34
	v_fmac_f32_e32 v36, v33, v33
	v_mul_f32_e32 v33, v31, v34
	v_fmac_f32_e32 v36, v33, v33
	v_mul_f32_e32 v33, v0, v34
	v_fmac_f32_e32 v36, v33, v33
	v_mul_f32_e32 v33, v1, v34
	v_fmac_f32_e32 v36, v33, v33
	v_mul_f32_e32 v33, v2, v34
	v_fmac_f32_e32 v36, v33, v33
	v_mul_f32_e32 v33, v3, v34
	v_fmac_f32_e32 v36, v33, v33
	v_mul_f32_e32 v33, v4, v34
	v_fmac_f32_e32 v36, v33, v33
	v_mul_f32_e32 v33, v5, v34
	v_fmac_f32_e32 v36, v33, v33
	v_mul_f32_e32 v33, v6, v34
	v_fmac_f32_e32 v36, v33, v33
	v_mul_f32_e32 v33, v7, v34
	v_fmac_f32_e32 v36, v33, v33
	v_mul_f32_e32 v33, v8, v34
	v_fmac_f32_e32 v36, v33, v33
	v_mul_f32_e32 v33, v9, v34
	v_fmac_f32_e32 v36, v33, v33
	v_mul_f32_e32 v33, v10, v34
	v_fmac_f32_e32 v36, v33, v33
	v_mul_f32_e32 v33, v11, v34
	v_fmac_f32_e32 v36, v33, v33
	v_mul_f32_e32 v33, v12, v34
	v_fmac_f32_e32 v36, v33, v33
	v_mul_f32_e32 v33, v13, v34
	v_fmac_f32_e32 v36, v33, v33
	v_mul_f32_e32 v33, v14, v34
	v_fmac_f32_e32 v36, v33, v33
	v_mul_f32_e32 v33, v15, v34
	v_fmac_f32_e32 v36, v33, v33
	ds_bpermute_b32 v37, v67, v36
	s_and_saveexec_b64 s[0:1], s[6:7]
	s_cbranch_execz .LBB0_183
; __device__ __forceinline__ void phase_qkv(const Params& p, char* smraw) {
;     ...
;         const float mult = rsqrtf(ssq * (1.f / 64.f) + EPS) * rs * (sec == 0 ? QS : 1.f);
;         const float* gain = sec == 0 ? p.qgain : p.kgain;
;         u16* dst = (sec == 0 ? p.qbuf : p.kbuf) + ((size_t)bh * LP + pos) * 64;
;         if (valid) {
; #pragma unroll
;           for (int j = 0; j < 2; ++j)
; #pragma unroll
;             for (int rg = 0; rg < 4; ++rg) {
;               const int d0 = j * 32 + 8 * rg + 4 * hf;
;               f32x4 g = *(const f32x4*)(gain + d0);
;               u32x2 o;
;               o[0] = cvtpk(acc[i][j][rg * 4 + 0] * mult * g[0], acc[i][j][rg * 4 + 1] * mult * g[1]);
;               o[1] = cvtpk(acc[i][j][rg * 4 + 2] * mult * g[2], acc[i][j][rg * 4 + 3] * mult * g[3]);
;               *(u32x2*)(dst + d0) = o;
;             }
	s_and_b64 s[4:5], s[4:5], exec
	s_cselect_b32 s5, s47, s49
	s_cselect_b32 s4, s46, s48
	v_lshlrev_b32_e32 v44, 2, v144
	global_load_dwordx4 v[38:41], v44, s[4:5]
	global_load_dwordx4 v[96:99], v44, s[4:5] offset:32
	global_load_dwordx4 v[100:103], v44, s[4:5] offset:64
	global_load_dwordx4 v[104:107], v44, s[4:5] offset:96
	global_load_dwordx4 v[108:111], v44, s[4:5] offset:128
	global_load_dwordx4 v[112:115], v44, s[4:5] offset:160
	global_load_dwordx4 v[116:119], v44, s[4:5] offset:192
	global_load_dwordx4 v[120:123], v44, s[4:5] offset:224
	v_mul_hi_i32_i24_e32 v43, 0x2080, v35
	v_mul_i32_i24_e32 v42, 0x2080, v35
	s_waitcnt lgkmcnt(0)
	v_add_f32_e32 v35, v36, v37
	v_fmamk_f32 v35, v35, 0x3c800000, v161
	v_mul_f32_e32 v36, 0x4b800000, v35
	v_cmp_gt_f32_e32 vcc, s19, v35
	v_ashrrev_i32_e32 v33, 31, v32
	v_readlane_b32 s36, v254, 0
	v_cndmask_b32_e32 v35, v35, v36, vcc
	v_rsq_f32_e32 v35, v35
	v_readlane_b32 s48, v254, 12
	v_readlane_b32 s49, v254, 13
	v_readlane_b32 s50, v254, 14
	v_mul_f32_e32 v36, 0x45800000, v35
	v_cndmask_b32_e32 v35, v35, v36, vcc
	v_readlane_b32 s51, v254, 15
	v_lshl_add_u64 v[32:33], v[42:43], 0, v[32:33]
	v_mul_f32_e32 v34, v34, v35
	s_cselect_b32 s7, s49, s51
	s_cselect_b32 s6, s48, s50
	v_lshlrev_b64 v[32:33], 7, v[32:33]
	v_mul_f32_e32 v34, v66, v34
	v_lshlrev_b32_e32 v146, 1, v144
	v_lshl_add_u64 v[32:33], s[6:7], 0, v[32:33]
	v_mul_f32_e32 v16, v16, v34
	v_mul_f32_e32 v17, v17, v34
	v_lshl_add_u64 v[32:33], v[32:33], 0, v[146:147]
	v_mul_f32_e32 v18, v18, v34
	v_mul_f32_e32 v19, v19, v34
	v_mul_f32_e32 v20, v20, v34
	v_mul_f32_e32 v21, v21, v34
	v_mul_f32_e32 v22, v22, v34
	v_mul_f32_e32 v23, v23, v34
	v_mul_f32_e32 v0, v0, v34
	v_mul_f32_e32 v1, v1, v34
	v_mul_f32_e32 v2, v2, v34
	v_mul_f32_e32 v3, v3, v34
	v_mul_f32_e32 v4, v4, v34
	v_mul_f32_e32 v5, v5, v34
	v_mul_f32_e32 v6, v6, v34
	v_mul_f32_e32 v7, v7, v34
	v_readlane_b32 s37, v254, 1
	v_readlane_b32 s38, v254, 2
	v_readlane_b32 s39, v254, 3
	v_readlane_b32 s40, v254, 4
	v_readlane_b32 s41, v254, 5
	v_readlane_b32 s42, v254, 6
	v_readlane_b32 s43, v254, 7
	v_readlane_b32 s44, v254, 8
	v_readlane_b32 s45, v254, 9
	v_readlane_b32 s46, v254, 10
	v_readlane_b32 s47, v254, 11
	v_readlane_b32 s36, v254, 42
	v_readlane_b32 s37, v254, 43
	v_readlane_b32 s38, v254, 44
	v_readlane_b32 s39, v254, 45
	v_readlane_b32 s46, v254, 52
	v_readlane_b32 s47, v254, 53
	v_readlane_b32 s48, v254, 54
	v_readlane_b32 s49, v254, 55
	v_readlane_b32 s40, v254, 46
	v_readlane_b32 s41, v254, 47
	v_readlane_b32 s42, v254, 48
	v_readlane_b32 s43, v254, 49
	v_readlane_b32 s44, v254, 50
	v_readlane_b32 s45, v254, 51
	v_readlane_b32 s50, v254, 56
	v_readlane_b32 s51, v254, 57
	s_waitcnt vmcnt(0)
	v_mul_f32_e32 v16, v16, v38
	v_mul_f32_e32 v17, v17, v39
	v_mul_f32_e32 v18, v18, v40
	v_mul_f32_e32 v19, v19, v41
	v_cvt_pk_bf16_f32 v16, v16, v17
	v_cvt_pk_bf16_f32 v17, v18, v19
	global_store_dwordx2 v[32:33], v[16:17], off
	v_mul_f32_e32 v16, v20, v96
	v_mul_f32_e32 v17, v21, v97
	v_mul_f32_e32 v18, v22, v98
	v_mul_f32_e32 v19, v23, v99
	v_cvt_pk_bf16_f32 v16, v16, v17
	v_cvt_pk_bf16_f32 v17, v18, v19
	global_store_dwordx2 v[32:33], v[16:17], off offset:16
	v_mul_f32_e32 v20, v24, v34
	v_mul_f32_e32 v21, v25, v34
	v_mul_f32_e32 v22, v26, v34
	v_mul_f32_e32 v23, v27, v34
	v_mul_f32_e32 v16, v20, v100
	v_mul_f32_e32 v17, v21, v101
	v_mul_f32_e32 v18, v22, v102
	v_mul_f32_e32 v19, v23, v103
	v_cvt_pk_bf16_f32 v16, v16, v17
	v_cvt_pk_bf16_f32 v17, v18, v19
	global_store_dwordx2 v[32:33], v[16:17], off offset:32
	v_mul_f32_e32 v20, v28, v34
	v_mul_f32_e32 v21, v29, v34
	v_mul_f32_e32 v22, v30, v34
	v_mul_f32_e32 v23, v31, v34
	v_mul_f32_e32 v16, v20, v104
	v_mul_f32_e32 v17, v21, v105
	v_mul_f32_e32 v18, v22, v106
	v_mul_f32_e32 v19, v23, v107
	v_cvt_pk_bf16_f32 v16, v16, v17
	v_cvt_pk_bf16_f32 v17, v18, v19
	global_store_dwordx2 v[32:33], v[16:17], off offset:48
	v_mul_f32_e32 v0, v0, v108
	v_mul_f32_e32 v1, v1, v109
	v_mul_f32_e32 v2, v2, v110
	v_mul_f32_e32 v3, v3, v111
	v_cvt_pk_bf16_f32 v0, v0, v1
	v_cvt_pk_bf16_f32 v1, v2, v3
	global_store_dwordx2 v[32:33], v[0:1], off offset:64
	v_mul_f32_e32 v0, v4, v112
	v_mul_f32_e32 v1, v5, v113
	v_mul_f32_e32 v2, v6, v114
	v_mul_f32_e32 v3, v7, v115
	v_cvt_pk_bf16_f32 v0, v0, v1
	v_cvt_pk_bf16_f32 v1, v2, v3
	global_store_dwordx2 v[32:33], v[0:1], off offset:80
	v_mul_f32_e32 v4, v8, v34
	v_mul_f32_e32 v5, v9, v34
	v_mul_f32_e32 v6, v10, v34
	v_mul_f32_e32 v7, v11, v34
	v_mul_f32_e32 v0, v4, v116
	v_mul_f32_e32 v1, v5, v117
	v_mul_f32_e32 v2, v6, v118
	v_mul_f32_e32 v3, v7, v119
	v_cvt_pk_bf16_f32 v0, v0, v1
	v_cvt_pk_bf16_f32 v1, v2, v3
	global_store_dwordx2 v[32:33], v[0:1], off offset:96
	v_mul_f32_e32 v4, v12, v34
	v_mul_f32_e32 v5, v13, v34
	v_mul_f32_e32 v6, v14, v34
	v_mul_f32_e32 v7, v15, v34
	v_mul_f32_e32 v0, v4, v120
	v_mul_f32_e32 v1, v5, v121
	v_mul_f32_e32 v2, v6, v122
	v_mul_f32_e32 v3, v7, v123
	v_cvt_pk_bf16_f32 v0, v0, v1
	v_cvt_pk_bf16_f32 v1, v2, v3
	global_store_dwordx2 v[32:33], v[0:1], off offset:112
	s_branch .LBB0_183

; __device__ __forceinline__ void phase_pool(const Params& p, char* smraw) {
;     ...
;   for (int item = blockIdx.x; item < Bn * NCH; item += gridDim.x) {
;     const int b = item / NCH, c0 = (item - b * NCH) * CH;
;     __syncthreads();
;     for (int r = w; r < CH + 15; r += 4) {
;       const int pp = c0 - 15 + r;
;       if (pp >= 0) {
;         const u16* row = p.hb + (size_t)(b * L + pp) * D;
;         u32x4 a = *(const u32x4*)(row + l * 8), c = *(const u32x4*)(row + 512 + l * 8);
;         float s = wave_sum(sumsq8(a) + sumsq8(c));
;         if (l == 0) rstd_s[r] = rsqrtf(s * (1.f / 1024.f) + EPS);
;       }
;     }
.LBB0_828:
	s_or_b64 exec, exec, s[0:1]
	v_mov_b32_e32 v0, v189
	s_cmpk_gt_i32 s2, 0x2ab
	s_barrier
	s_cbranch_scc1 .LBB0_876
	v_and_b32_e32 v0, 63, v189
	v_lshrrev_b32_e32 v10, 6, v189
	v_lshlrev_b32_e32 v1, 3, v189
	v_xor_b32_e32 v2, 32, v0
	v_xor_b32_e32 v3, 16, v0
	v_xor_b32_e32 v4, 8, v0
	v_xor_b32_e32 v5, 4, v0
	v_xor_b32_e32 v6, 2, v0
	v_xor_b32_e32 v7, 1, v0
	v_lshlrev_b32_e32 v2, 2, v2
	v_lshlrev_b32_e32 v3, 2, v3
	v_lshlrev_b32_e32 v4, 2, v4
	v_lshlrev_b32_e32 v5, 2, v5
	v_lshlrev_b32_e32 v6, 2, v6
	v_lshlrev_b32_e32 v7, 2, v7
	v_readfirstlane_b32 s6, v10
	v_lshlrev_b32_e32 v0, 4, v0
	v_mov_b32_e32 v9, 0x358637bd
	v_mov_b32_e32 v59, 0
	s_mov_b32 s25, 0x800000
	s_mul_i32 s3, s2, 48
	s_mul_i32 s24, s96, 48
	s_mov_b32 s26, s2
.Lmy_pool_item:
	s_mul_hi_u32 s0, s26, 0x17f4060
	s_mul_i32 s27, s0, 0x2010
	s_sub_u32 s9, s3, s27
	s_barrier
	s_add_u32 s0, s6, 0
	s_min_u32 s0, s0, 62
	s_add_u32 s1, s9, s0
	s_sub_u32 s1, s1, 15
	s_max_i32 s1, s1, 0
	s_add_u32 s1, s1, s27
	s_lshl_b32 s1, s1, 11
	v_add_u32_e32 v30, s1, v0
	global_load_dwordx4 v[100:103], v30, s[76:77]
	global_load_dwordx4 v[104:107], v30, s[76:77] offset:1024
	s_add_u32 s0, s6, 4
	s_min_u32 s0, s0, 62
	s_add_u32 s1, s9, s0
	s_sub_u32 s1, s1, 15
	s_max_i32 s1, s1, 0
	s_add_u32 s1, s1, s27
	s_lshl_b32 s1, s1, 11
	v_add_u32_e32 v31, s1, v0
	global_load_dwordx4 v[108:111], v31, s[76:77]
	global_load_dwordx4 v[112:115], v31, s[76:77] offset:1024
	s_add_u32 s0, s6, 8
	s_min_u32 s0, s0, 62
	s_add_u32 s1, s9, s0
	s_sub_u32 s1, s1, 15
	s_max_i32 s1, s1, 0
	s_add_u32 s1, s1, s27
	s_lshl_b32 s1, s1, 11
	v_add_u32_e32 v32, s1, v0
	global_load_dwordx4 v[116:119], v32, s[76:77]
	global_load_dwordx4 v[120:123], v32, s[76:77] offset:1024
	s_add_u32 s0, s6, 12
	s_min_u32 s0, s0, 62
	s_add_u32 s1, s9, s0
	s_sub_u32 s1, s1, 15
	s_max_i32 s1, s1, 0
	s_add_u32 s1, s1, s27
	s_lshl_b32 s1, s1, 11
	v_add_u32_e32 v33, s1, v0
	global_load_dwordx4 v[124:127], v33, s[76:77]
	global_load_dwordx4 v[128:131], v33, s[76:77] offset:1024
	s_add_u32 s0, s6, 16
	s_min_u32 s0, s0, 62
	s_add_u32 s1, s9, s0
	s_sub_u32 s1, s1, 15
	s_max_i32 s1, s1, 0
	s_add_u32 s1, s1, s27
	s_lshl_b32 s1, s1, 11
	v_add_u32_e32 v34, s1, v0
	global_load_dwordx4 v[132:135], v34, s[76:77]
	global_load_dwordx4 v[136:139], v34, s[76:77] offset:1024
	s_add_u32 s0, s6, 20
	s_min_u32 s0, s0, 62
	s_add_u32 s1, s9, s0
	s_sub_u32 s1, s1, 15
	s_max_i32 s1, s1, 0
	s_add_u32 s1, s1, s27
	s_lshl_b32 s1, s1, 11
	v_add_u32_e32 v35, s1, v0
	global_load_dwordx4 v[140:143], v35, s[76:77]
	global_load_dwordx4 v[144:147], v35, s[76:77] offset:1024
	s_add_u32 s0, s6, 24
	s_min_u32 s0, s0, 62
	s_add_u32 s1, s9, s0
	s_sub_u32 s1, s1, 15
	s_max_i32 s1, s1, 0
	s_add_u32 s1, s1, s27
	s_lshl_b32 s1, s1, 11
	v_add_u32_e32 v36, s1, v0
	global_load_dwordx4 v[148:151], v36, s[76:77]
	global_load_dwordx4 v[152:155], v36, s[76:77] offset:1024
	s_add_u32 s0, s6, 28
	s_min_u32 s0, s0, 62
	s_add_u32 s1, s9, s0
	s_sub_u32 s1, s1, 15
	s_max_i32 s1, s1, 0
	s_add_u32 s1, s1, s27
	s_lshl_b32 s1, s1, 11
	v_add_u32_e32 v37, s1, v0
	global_load_dwordx4 v[156:159], v37, s[76:77]
	global_load_dwordx4 v[160:163], v37, s[76:77] offset:1024
	s_waitcnt vmcnt(14)
	v_lshlrev_b32_e32 v10, 16, v100
	v_and_b32_e32 v100, 0xffff0000, v100
	v_lshlrev_b32_e32 v14, 16, v104
	v_and_b32_e32 v104, 0xffff0000, v104
	v_lshlrev_b32_e32 v11, 16, v101
	v_and_b32_e32 v101, 0xffff0000, v101
	v_lshlrev_b32_e32 v15, 16, v105
	v_and_b32_e32 v105, 0xffff0000, v105
	v_lshlrev_b32_e32 v12, 16, v102
	v_and_b32_e32 v102, 0xffff0000, v102
	v_lshlrev_b32_e32 v16, 16, v106
	v_and_b32_e32 v106, 0xffff0000, v106
	v_lshlrev_b32_e32 v13, 16, v103
	v_and_b32_e32 v103, 0xffff0000, v103
	v_lshlrev_b32_e32 v17, 16, v107
	v_and_b32_e32 v107, 0xffff0000, v107
	v_mul_f32_e32 v100, v100, v100
	v_mul_f32_e32 v104, v104, v104
	v_mul_f32_e32 v101, v101, v101
	v_mul_f32_e32 v105, v105, v105
	v_mul_f32_e32 v102, v102, v102
	v_mul_f32_e32 v106, v106, v106
	v_mul_f32_e32 v103, v103, v103
	v_mul_f32_e32 v107, v107, v107
	v_fmac_f32_e32 v100, v10, v10
	v_fmac_f32_e32 v104, v14, v14
	v_fmac_f32_e32 v101, v11, v11
	v_fmac_f32_e32 v105, v15, v15
	v_fmac_f32_e32 v102, v12, v12
	v_fmac_f32_e32 v106, v16, v16
	v_fmac_f32_e32 v103, v13, v13
	v_fmac_f32_e32 v107, v17, v17
	v_add_f32_e32 v100, v100, v101
	v_add_f32_e32 v104, v104, v105
	v_add_f32_e32 v100, v102, v100
	v_add_f32_e32 v104, v106, v104
	v_add_f32_e32 v100, v103, v100
	v_add_f32_e32 v104, v107, v104
	v_add_f32_e32 v40, v100, v104
	s_waitcnt vmcnt(12)
	v_lshlrev_b32_e32 v10, 16, v108
	v_and_b32_e32 v108, 0xffff0000, v108
	v_lshlrev_b32_e32 v14, 16, v112
	v_and_b32_e32 v112, 0xffff0000, v112
	v_lshlrev_b32_e32 v11, 16, v109
	v_and_b32_e32 v109, 0xffff0000, v109
	v_lshlrev_b32_e32 v15, 16, v113
	v_and_b32_e32 v113, 0xffff0000, v113
	v_lshlrev_b32_e32 v12, 16, v110
	v_and_b32_e32 v110, 0xffff0000, v110
	v_lshlrev_b32_e32 v16, 16, v114
	v_and_b32_e32 v114, 0xffff0000, v114
	v_lshlrev_b32_e32 v13, 16, v111
	v_and_b32_e32 v111, 0xffff0000, v111
	v_lshlrev_b32_e32 v17, 16, v115
	v_and_b32_e32 v115, 0xffff0000, v115
	v_mul_f32_e32 v108, v108, v108
	v_mul_f32_e32 v112, v112, v112
	v_mul_f32_e32 v109, v109, v109
	v_mul_f32_e32 v113, v113, v113
	v_mul_f32_e32 v110, v110, v110
	v_mul_f32_e32 v114, v114, v114
	v_mul_f32_e32 v111, v111, v111
	v_mul_f32_e32 v115, v115, v115
	v_fmac_f32_e32 v108, v10, v10
	v_fmac_f32_e32 v112, v14, v14
	v_fmac_f32_e32 v109, v11, v11
	v_fmac_f32_e32 v113, v15, v15
	v_fmac_f32_e32 v110, v12, v12
	v_fmac_f32_e32 v114, v16, v16
	v_fmac_f32_e32 v111, v13, v13
	v_fmac_f32_e32 v115, v17, v17
	v_add_f32_e32 v108, v108, v109
	v_add_f32_e32 v112, v112, v113
	v_add_f32_e32 v108, v110, v108
	v_add_f32_e32 v112, v114, v112
	v_add_f32_e32 v108, v111, v108
	v_add_f32_e32 v112, v115, v112
	v_add_f32_e32 v41, v108, v112
	s_waitcnt vmcnt(10)
; __device__ __forceinline__ void phase_pool(const Params& p, char* smraw) {
;     ...
;     for (int r = w; r < CH + 15; r += 4) {
;       const int pp = c0 - 15 + r;
;       if (pp >= 0) {
;         const u16* row = p.hb + (size_t)(b * L + pp) * D;
;         u32x4 a = *(const u32x4*)(row + l * 8), c = *(const u32x4*)(row + 512 + l * 8);
;         float s = wave_sum(sumsq8(a) + sumsq8(c));
;         if (l == 0) rstd_s[r] = rsqrtf(s * (1.f / 1024.f) + EPS);
;       }
	v_lshlrev_b32_e32 v10, 16, v116
	v_and_b32_e32 v116, 0xffff0000, v116
	v_lshlrev_b32_e32 v14, 16, v120
	v_and_b32_e32 v120, 0xffff0000, v120
	v_lshlrev_b32_e32 v11, 16, v117
	v_and_b32_e32 v117, 0xffff0000, v117
	v_lshlrev_b32_e32 v15, 16, v121
	v_and_b32_e32 v121, 0xffff0000, v121
	v_lshlrev_b32_e32 v12, 16, v118
	v_and_b32_e32 v118, 0xffff0000, v118
	v_lshlrev_b32_e32 v16, 16, v122
	v_and_b32_e32 v122, 0xffff0000, v122
	v_lshlrev_b32_e32 v13, 16, v119
	v_and_b32_e32 v119, 0xffff0000, v119
	v_lshlrev_b32_e32 v17, 16, v123
	v_and_b32_e32 v123, 0xffff0000, v123
	v_mul_f32_e32 v116, v116, v116
	v_mul_f32_e32 v120, v120, v120
	v_mul_f32_e32 v117, v117, v117
	v_mul_f32_e32 v121, v121, v121
	v_mul_f32_e32 v118, v118, v118
	v_mul_f32_e32 v122, v122, v122
	v_mul_f32_e32 v119, v119, v119
	v_mul_f32_e32 v123, v123, v123
	v_fmac_f32_e32 v116, v10, v10
	v_fmac_f32_e32 v120, v14, v14
	v_fmac_f32_e32 v117, v11, v11
	v_fmac_f32_e32 v121, v15, v15
	v_fmac_f32_e32 v118, v12, v12
	v_fmac_f32_e32 v122, v16, v16
	v_fmac_f32_e32 v119, v13, v13
	v_fmac_f32_e32 v123, v17, v17
	v_add_f32_e32 v116, v116, v117
	v_add_f32_e32 v120, v120, v121
	v_add_f32_e32 v116, v118, v116
	v_add_f32_e32 v120, v122, v120
	v_add_f32_e32 v116, v119, v116
	v_add_f32_e32 v120, v123, v120
	v_add_f32_e32 v42, v116, v120
	s_waitcnt vmcnt(8)
	v_lshlrev_b32_e32 v10, 16, v124
	v_and_b32_e32 v124, 0xffff0000, v124
	v_lshlrev_b32_e32 v14, 16, v128
	v_and_b32_e32 v128, 0xffff0000, v128
	v_lshlrev_b32_e32 v11, 16, v125
	v_and_b32_e32 v125, 0xffff0000, v125
	v_lshlrev_b32_e32 v15, 16, v129
	v_and_b32_e32 v129, 0xffff0000, v129
	v_lshlrev_b32_e32 v12, 16, v126
	v_and_b32_e32 v126, 0xffff0000, v126
	v_lshlrev_b32_e32 v16, 16, v130
	v_and_b32_e32 v130, 0xffff0000, v130
	v_lshlrev_b32_e32 v13, 16, v127
	v_and_b32_e32 v127, 0xffff0000, v127
	v_lshlrev_b32_e32 v17, 16, v131
	v_and_b32_e32 v131, 0xffff0000, v131
	v_mul_f32_e32 v124, v124, v124
	v_mul_f32_e32 v128, v128, v128
	v_mul_f32_e32 v125, v125, v125
	v_mul_f32_e32 v129, v129, v129
	v_mul_f32_e32 v126, v126, v126
	v_mul_f32_e32 v130, v130, v130
	v_mul_f32_e32 v127, v127, v127
	v_mul_f32_e32 v131, v131, v131
	v_fmac_f32_e32 v124, v10, v10
	v_fmac_f32_e32 v128, v14, v14
	v_fmac_f32_e32 v125, v11, v11
	v_fmac_f32_e32 v129, v15, v15
	v_fmac_f32_e32 v126, v12, v12
	v_fmac_f32_e32 v130, v16, v16
	v_fmac_f32_e32 v127, v13, v13
	v_fmac_f32_e32 v131, v17, v17
	v_add_f32_e32 v124, v124, v125
	v_add_f32_e32 v128, v128, v129
	v_add_f32_e32 v124, v126, v124
	v_add_f32_e32 v128, v130, v128
	v_add_f32_e32 v124, v127, v124
	v_add_f32_e32 v128, v131, v128
	v_add_f32_e32 v43, v124, v128
	s_waitcnt vmcnt(6)
	v_lshlrev_b32_e32 v10, 16, v132
	v_and_b32_e32 v132, 0xffff0000, v132
	v_lshlrev_b32_e32 v14, 16, v136
	v_and_b32_e32 v136, 0xffff0000, v136
	v_lshlrev_b32_e32 v11, 16, v133
	v_and_b32_e32 v133, 0xffff0000, v133
	v_lshlrev_b32_e32 v15, 16, v137
	v_and_b32_e32 v137, 0xffff0000, v137
	v_lshlrev_b32_e32 v12, 16, v134
	v_and_b32_e32 v134, 0xffff0000, v134
	v_lshlrev_b32_e32 v16, 16, v138
	v_and_b32_e32 v138, 0xffff0000, v138
	v_lshlrev_b32_e32 v13, 16, v135
	v_and_b32_e32 v135, 0xffff0000, v135
	v_lshlrev_b32_e32 v17, 16, v139
	v_and_b32_e32 v139, 0xffff0000, v139
	v_mul_f32_e32 v132, v132, v132
	v_mul_f32_e32 v136, v136, v136
	v_mul_f32_e32 v133, v133, v133
	v_mul_f32_e32 v137, v137, v137
	v_mul_f32_e32 v134, v134, v134
	v_mul_f32_e32 v138, v138, v138
	v_mul_f32_e32 v135, v135, v135
	v_mul_f32_e32 v139, v139, v139
	v_fmac_f32_e32 v132, v10, v10
	v_fmac_f32_e32 v136, v14, v14
	v_fmac_f32_e32 v133, v11, v11
	v_fmac_f32_e32 v137, v15, v15
	v_fmac_f32_e32 v134, v12, v12
	v_fmac_f32_e32 v138, v16, v16
	v_fmac_f32_e32 v135, v13, v13
	v_fmac_f32_e32 v139, v17, v17
	v_add_f32_e32 v132, v132, v133
	v_add_f32_e32 v136, v136, v137
	v_add_f32_e32 v132, v134, v132
	v_add_f32_e32 v136, v138, v136
	v_add_f32_e32 v132, v135, v132
	v_add_f32_e32 v136, v139, v136
	v_add_f32_e32 v44, v132, v136
	s_waitcnt vmcnt(4)
	v_lshlrev_b32_e32 v10, 16, v140
	v_and_b32_e32 v140, 0xffff0000, v140
	v_lshlrev_b32_e32 v14, 16, v144
	v_and_b32_e32 v144, 0xffff0000, v144
	v_lshlrev_b32_e32 v11, 16, v141
	v_and_b32_e32 v141, 0xffff0000, v141
	v_lshlrev_b32_e32 v15, 16, v145
	v_and_b32_e32 v145, 0xffff0000, v145
	v_lshlrev_b32_e32 v12, 16, v142
	v_and_b32_e32 v142, 0xffff0000, v142
	v_lshlrev_b32_e32 v16, 16, v146
	v_and_b32_e32 v146, 0xffff0000, v146
	v_lshlrev_b32_e32 v13, 16, v143
	v_and_b32_e32 v143, 0xffff0000, v143
	v_lshlrev_b32_e32 v17, 16, v147
	v_and_b32_e32 v147, 0xffff0000, v147
	v_mul_f32_e32 v140, v140, v140
	v_mul_f32_e32 v144, v144, v144
	v_mul_f32_e32 v141, v141, v141
	v_mul_f32_e32 v145, v145, v145
	v_mul_f32_e32 v142, v142, v142
	v_mul_f32_e32 v146, v146, v146
	v_mul_f32_e32 v143, v143, v143
	v_mul_f32_e32 v147, v147, v147
	v_fmac_f32_e32 v140, v10, v10
	v_fmac_f32_e32 v144, v14, v14
	v_fmac_f32_e32 v141, v11, v11
	v_fmac_f32_e32 v145, v15, v15
	v_fmac_f32_e32 v142, v12, v12
	v_fmac_f32_e32 v146, v16, v16
	v_fmac_f32_e32 v143, v13, v13
	v_fmac_f32_e32 v147, v17, v17
	v_add_f32_e32 v140, v140, v141
	v_add_f32_e32 v144, v144, v145
	v_add_f32_e32 v140, v142, v140
	v_add_f32_e32 v144, v146, v144
	v_add_f32_e32 v140, v143, v140
	v_add_f32_e32 v144, v147, v144
	v_add_f32_e32 v45, v140, v144
	s_waitcnt vmcnt(2)
; __device__ __forceinline__ void phase_pool(const Params& p, char* smraw) {
;     ...
;     for (int r = w; r < CH + 15; r += 4) {
;       const int pp = c0 - 15 + r;
;       if (pp >= 0) {
;         const u16* row = p.hb + (size_t)(b * L + pp) * D;
;         u32x4 a = *(const u32x4*)(row + l * 8), c = *(const u32x4*)(row + 512 + l * 8);
;         float s = wave_sum(sumsq8(a) + sumsq8(c));
;         if (l == 0) rstd_s[r] = rsqrtf(s * (1.f / 1024.f) + EPS);
;       }
	v_lshlrev_b32_e32 v10, 16, v148
	v_and_b32_e32 v148, 0xffff0000, v148
	v_lshlrev_b32_e32 v14, 16, v152
	v_and_b32_e32 v152, 0xffff0000, v152
	v_lshlrev_b32_e32 v11, 16, v149
	v_and_b32_e32 v149, 0xffff0000, v149
	v_lshlrev_b32_e32 v15, 16, v153
	v_and_b32_e32 v153, 0xffff0000, v153
	v_lshlrev_b32_e32 v12, 16, v150
	v_and_b32_e32 v150, 0xffff0000, v150
	v_lshlrev_b32_e32 v16, 16, v154
	v_and_b32_e32 v154, 0xffff0000, v154
	v_lshlrev_b32_e32 v13, 16, v151
	v_and_b32_e32 v151, 0xffff0000, v151
	v_lshlrev_b32_e32 v17, 16, v155
	v_and_b32_e32 v155, 0xffff0000, v155
	v_mul_f32_e32 v148, v148, v148
	v_mul_f32_e32 v152, v152, v152
	v_mul_f32_e32 v149, v149, v149
	v_mul_f32_e32 v153, v153, v153
	v_mul_f32_e32 v150, v150, v150
	v_mul_f32_e32 v154, v154, v154
	v_mul_f32_e32 v151, v151, v151
	v_mul_f32_e32 v155, v155, v155
	v_fmac_f32_e32 v148, v10, v10
	v_fmac_f32_e32 v152, v14, v14
	v_fmac_f32_e32 v149, v11, v11
	v_fmac_f32_e32 v153, v15, v15
	v_fmac_f32_e32 v150, v12, v12
	v_fmac_f32_e32 v154, v16, v16
	v_fmac_f32_e32 v151, v13, v13
	v_fmac_f32_e32 v155, v17, v17
	v_add_f32_e32 v148, v148, v149
	v_add_f32_e32 v152, v152, v153
	v_add_f32_e32 v148, v150, v148
	v_add_f32_e32 v152, v154, v152
	v_add_f32_e32 v148, v151, v148
	v_add_f32_e32 v152, v155, v152
	v_add_f32_e32 v46, v148, v152
	s_waitcnt vmcnt(0)
	v_lshlrev_b32_e32 v10, 16, v156
	v_and_b32_e32 v156, 0xffff0000, v156
	v_lshlrev_b32_e32 v14, 16, v160
	v_and_b32_e32 v160, 0xffff0000, v160
	v_lshlrev_b32_e32 v11, 16, v157
	v_and_b32_e32 v157, 0xffff0000, v157
	v_lshlrev_b32_e32 v15, 16, v161
	v_and_b32_e32 v161, 0xffff0000, v161
	v_lshlrev_b32_e32 v12, 16, v158
	v_and_b32_e32 v158, 0xffff0000, v158
	v_lshlrev_b32_e32 v16, 16, v162
	v_and_b32_e32 v162, 0xffff0000, v162
	v_lshlrev_b32_e32 v13, 16, v159
	v_and_b32_e32 v159, 0xffff0000, v159
	v_lshlrev_b32_e32 v17, 16, v163
	v_and_b32_e32 v163, 0xffff0000, v163
	v_mul_f32_e32 v156, v156, v156
	v_mul_f32_e32 v160, v160, v160
	v_mul_f32_e32 v157, v157, v157
	v_mul_f32_e32 v161, v161, v161
	v_mul_f32_e32 v158, v158, v158
	v_mul_f32_e32 v162, v162, v162
	v_mul_f32_e32 v159, v159, v159
	v_mul_f32_e32 v163, v163, v163
	v_fmac_f32_e32 v156, v10, v10
	v_fmac_f32_e32 v160, v14, v14
	v_fmac_f32_e32 v157, v11, v11
	v_fmac_f32_e32 v161, v15, v15
	v_fmac_f32_e32 v158, v12, v12
	v_fmac_f32_e32 v162, v16, v16
	v_fmac_f32_e32 v159, v13, v13
	v_fmac_f32_e32 v163, v17, v17
	v_add_f32_e32 v156, v156, v157
	v_add_f32_e32 v160, v160, v161
	v_add_f32_e32 v156, v158, v156
	v_add_f32_e32 v160, v162, v160
	v_add_f32_e32 v156, v159, v156
	v_add_f32_e32 v160, v163, v160
	v_add_f32_e32 v47, v156, v160
	ds_bpermute_b32 v48, v2, v40
	ds_bpermute_b32 v49, v2, v41
	ds_bpermute_b32 v50, v2, v42
	ds_bpermute_b32 v51, v2, v43
	ds_bpermute_b32 v52, v2, v44
	ds_bpermute_b32 v53, v2, v45
	ds_bpermute_b32 v54, v2, v46
	ds_bpermute_b32 v55, v2, v47
	s_waitcnt lgkmcnt(0)
	v_add_f32_e32 v40, v40, v48
	v_add_f32_e32 v41, v41, v49
	v_add_f32_e32 v42, v42, v50
	v_add_f32_e32 v43, v43, v51
	v_add_f32_e32 v44, v44, v52
	v_add_f32_e32 v45, v45, v53
	v_add_f32_e32 v46, v46, v54
	v_add_f32_e32 v47, v47, v55
	ds_bpermute_b32 v48, v3, v40
	ds_bpermute_b32 v49, v3, v41
	ds_bpermute_b32 v50, v3, v42
	ds_bpermute_b32 v51, v3, v43
	ds_bpermute_b32 v52, v3, v44
	ds_bpermute_b32 v53, v3, v45
	ds_bpermute_b32 v54, v3, v46
	ds_bpermute_b32 v55, v3, v47
	s_waitcnt lgkmcnt(0)
	v_add_f32_e32 v40, v40, v48
	v_add_f32_e32 v41, v41, v49
	v_add_f32_e32 v42, v42, v50
	v_add_f32_e32 v43, v43, v51
	v_add_f32_e32 v44, v44, v52
	v_add_f32_e32 v45, v45, v53
	v_add_f32_e32 v46, v46, v54
	v_add_f32_e32 v47, v47, v55
	ds_bpermute_b32 v48, v4, v40
	ds_bpermute_b32 v49, v4, v41
	ds_bpermute_b32 v50, v4, v42
	ds_bpermute_b32 v51, v4, v43
	ds_bpermute_b32 v52, v4, v44
	ds_bpermute_b32 v53, v4, v45
	ds_bpermute_b32 v54, v4, v46
	ds_bpermute_b32 v55, v4, v47
	s_waitcnt lgkmcnt(0)
	v_add_f32_e32 v40, v40, v48
	v_add_f32_e32 v41, v41, v49
	v_add_f32_e32 v42, v42, v50
	v_add_f32_e32 v43, v43, v51
	v_add_f32_e32 v44, v44, v52
	v_add_f32_e32 v45, v45, v53
	v_add_f32_e32 v46, v46, v54
	v_add_f32_e32 v47, v47, v55
	ds_bpermute_b32 v48, v5, v40
	ds_bpermute_b32 v49, v5, v41
	ds_bpermute_b32 v50, v5, v42
	ds_bpermute_b32 v51, v5, v43
	ds_bpermute_b32 v52, v5, v44
	ds_bpermute_b32 v53, v5, v45
	ds_bpermute_b32 v54, v5, v46
	ds_bpermute_b32 v55, v5, v47
	s_waitcnt lgkmcnt(0)
	v_add_f32_e32 v40, v40, v48
	v_add_f32_e32 v41, v41, v49
	v_add_f32_e32 v42, v42, v50
	v_add_f32_e32 v43, v43, v51
	v_add_f32_e32 v44, v44, v52
	v_add_f32_e32 v45, v45, v53
	v_add_f32_e32 v46, v46, v54
	v_add_f32_e32 v47, v47, v55
	ds_bpermute_b32 v48, v6, v40
	ds_bpermute_b32 v49, v6, v41
	ds_bpermute_b32 v50, v6, v42
	ds_bpermute_b32 v51, v6, v43
	ds_bpermute_b32 v52, v6, v44
	ds_bpermute_b32 v53, v6, v45
	ds_bpermute_b32 v54, v6, v46
	ds_bpermute_b32 v55, v6, v47
	s_waitcnt lgkmcnt(0)
	v_add_f32_e32 v40, v40, v48
	v_add_f32_e32 v41, v41, v49
	v_add_f32_e32 v42, v42, v50
	v_add_f32_e32 v43, v43, v51
	v_add_f32_e32 v44, v44, v52
	v_add_f32_e32 v45, v45, v53
	v_add_f32_e32 v46, v46, v54
	v_add_f32_e32 v47, v47, v55
	ds_bpermute_b32 v48, v7, v40
	ds_bpermute_b32 v49, v7, v41
	ds_bpermute_b32 v50, v7, v42
	ds_bpermute_b32 v51, v7, v43
	ds_bpermute_b32 v52, v7, v44
	ds_bpermute_b32 v53, v7, v45
	ds_bpermute_b32 v54, v7, v46
	ds_bpermute_b32 v55, v7, v47
	s_waitcnt lgkmcnt(0)
; __device__ __forceinline__ void phase_pool(const Params& p, char* smraw) {
;     ...
;     for (int r = w; r < CH + 15; r += 4) {
;       const int pp = c0 - 15 + r;
;       if (pp >= 0) {
;         const u16* row = p.hb + (size_t)(b * L + pp) * D;
;         u32x4 a = *(const u32x4*)(row + l * 8), c = *(const u32x4*)(row + 512 + l * 8);
;         float s = wave_sum(sumsq8(a) + sumsq8(c));
;         if (l == 0) rstd_s[r] = rsqrtf(s * (1.f / 1024.f) + EPS);
;       }
;     }
	v_add_f32_e32 v40, v40, v48
	v_add_f32_e32 v41, v41, v49
	v_add_f32_e32 v42, v42, v50
	v_add_f32_e32 v43, v43, v51
	v_add_f32_e32 v44, v44, v52
	v_add_f32_e32 v45, v45, v53
	v_add_f32_e32 v46, v46, v54
	v_add_f32_e32 v47, v47, v55
	v_fmamk_f32 v40, v40, 0x3a800000, v9
	v_mul_f32_e32 v48, 0x4b800000, v40
	v_cmp_gt_f32_e32 vcc, s25, v40
	s_nop 1
	v_cndmask_b32_e32 v40, v40, v48, vcc
	v_rsq_f32_e32 v40, v40
	s_nop 0
	v_mul_f32_e32 v48, 0x45800000, v40
	v_cndmask_b32_e32 v40, v40, v48, vcc
	v_fmamk_f32 v41, v41, 0x3a800000, v9
	v_mul_f32_e32 v49, 0x4b800000, v41
	v_cmp_gt_f32_e32 vcc, s25, v41
	s_nop 1
	v_cndmask_b32_e32 v41, v41, v49, vcc
	v_rsq_f32_e32 v41, v41
	s_nop 0
	v_mul_f32_e32 v49, 0x45800000, v41
	v_cndmask_b32_e32 v41, v41, v49, vcc
	v_fmamk_f32 v42, v42, 0x3a800000, v9
	v_mul_f32_e32 v50, 0x4b800000, v42
	v_cmp_gt_f32_e32 vcc, s25, v42
	s_nop 1
	v_cndmask_b32_e32 v42, v42, v50, vcc
	v_rsq_f32_e32 v42, v42
	s_nop 0
	v_mul_f32_e32 v50, 0x45800000, v42
	v_cndmask_b32_e32 v42, v42, v50, vcc
	v_fmamk_f32 v43, v43, 0x3a800000, v9
	v_mul_f32_e32 v51, 0x4b800000, v43
	v_cmp_gt_f32_e32 vcc, s25, v43
	s_nop 1
	v_cndmask_b32_e32 v43, v43, v51, vcc
	v_rsq_f32_e32 v43, v43
	s_nop 0
	v_mul_f32_e32 v51, 0x45800000, v43
	v_cndmask_b32_e32 v43, v43, v51, vcc
	v_fmamk_f32 v44, v44, 0x3a800000, v9
	v_mul_f32_e32 v52, 0x4b800000, v44
	v_cmp_gt_f32_e32 vcc, s25, v44
	s_nop 1
	v_cndmask_b32_e32 v44, v44, v52, vcc
	v_rsq_f32_e32 v44, v44
	s_nop 0
	v_mul_f32_e32 v52, 0x45800000, v44
	v_cndmask_b32_e32 v44, v44, v52, vcc
	v_fmamk_f32 v45, v45, 0x3a800000, v9
	v_mul_f32_e32 v53, 0x4b800000, v45
	v_cmp_gt_f32_e32 vcc, s25, v45
	s_nop 1
	v_cndmask_b32_e32 v45, v45, v53, vcc
	v_rsq_f32_e32 v45, v45
	s_nop 0
	v_mul_f32_e32 v53, 0x45800000, v45
	v_cndmask_b32_e32 v45, v45, v53, vcc
	v_fmamk_f32 v46, v46, 0x3a800000, v9
	v_mul_f32_e32 v54, 0x4b800000, v46
	v_cmp_gt_f32_e32 vcc, s25, v46
	s_nop 1
	v_cndmask_b32_e32 v46, v46, v54, vcc
	v_rsq_f32_e32 v46, v46
	s_nop 0
	v_mul_f32_e32 v54, 0x45800000, v46
	v_cndmask_b32_e32 v46, v46, v54, vcc
	v_fmamk_f32 v47, v47, 0x3a800000, v9
	v_mul_f32_e32 v55, 0x4b800000, v47
	v_cmp_gt_f32_e32 vcc, s25, v47
	s_nop 1
	v_cndmask_b32_e32 v47, v47, v55, vcc
	v_rsq_f32_e32 v47, v47
	s_nop 0
	v_mul_f32_e32 v55, 0x45800000, v47
	v_cndmask_b32_e32 v47, v47, v55, vcc
	s_mov_b64 s[10:11], exec
	s_mov_b64 exec, 1
	s_add_u32 s0, s6, 0
	s_min_u32 s0, s0, 62
	s_lshl_b32 s0, s0, 2
	v_mov_b32_e32 v48, s0
	ds_write_b32 v48, v40
	s_add_u32 s0, s6, 4
	s_min_u32 s0, s0, 62
	s_lshl_b32 s0, s0, 2
	v_mov_b32_e32 v49, s0
	ds_write_b32 v49, v41
	s_add_u32 s0, s6, 8
	s_min_u32 s0, s0, 62
	s_lshl_b32 s0, s0, 2
	v_mov_b32_e32 v50, s0
	ds_write_b32 v50, v42
	s_add_u32 s0, s6, 12
	s_min_u32 s0, s0, 62
	s_lshl_b32 s0, s0, 2
	v_mov_b32_e32 v51, s0
	ds_write_b32 v51, v43
	s_add_u32 s0, s6, 16
	s_min_u32 s0, s0, 62
	s_lshl_b32 s0, s0, 2
	v_mov_b32_e32 v52, s0
	ds_write_b32 v52, v44
	s_add_u32 s0, s6, 20
	s_min_u32 s0, s0, 62
	s_lshl_b32 s0, s0, 2
	v_mov_b32_e32 v53, s0
	ds_write_b32 v53, v45
	s_add_u32 s0, s6, 24
	s_min_u32 s0, s0, 62
	s_lshl_b32 s0, s0, 2
	v_mov_b32_e32 v54, s0
	ds_write_b32 v54, v46
	s_add_u32 s0, s6, 28
	s_min_u32 s0, s0, 62
	s_lshl_b32 s0, s0, 2
	v_mov_b32_e32 v55, s0
	ds_write_b32 v55, v47
	s_mov_b64 exec, s[10:11]
	s_add_u32 s0, s6, 32
	s_min_u32 s0, s0, 62
	s_add_u32 s1, s9, s0
	s_sub_u32 s1, s1, 15
	s_max_i32 s1, s1, 0
	s_add_u32 s1, s1, s27
	s_lshl_b32 s1, s1, 11
	v_add_u32_e32 v30, s1, v0
	global_load_dwordx4 v[100:103], v30, s[76:77]
	global_load_dwordx4 v[104:107], v30, s[76:77] offset:1024
	s_add_u32 s0, s6, 36
	s_min_u32 s0, s0, 62
	s_add_u32 s1, s9, s0
	s_sub_u32 s1, s1, 15
	s_max_i32 s1, s1, 0
	s_add_u32 s1, s1, s27
	s_lshl_b32 s1, s1, 11
	v_add_u32_e32 v31, s1, v0
	global_load_dwordx4 v[108:111], v31, s[76:77]
	global_load_dwordx4 v[112:115], v31, s[76:77] offset:1024
	s_add_u32 s0, s6, 40
	s_min_u32 s0, s0, 62
	s_add_u32 s1, s9, s0
	s_sub_u32 s1, s1, 15
	s_max_i32 s1, s1, 0
	s_add_u32 s1, s1, s27
	s_lshl_b32 s1, s1, 11
	v_add_u32_e32 v32, s1, v0
	global_load_dwordx4 v[116:119], v32, s[76:77]
	global_load_dwordx4 v[120:123], v32, s[76:77] offset:1024
	s_add_u32 s0, s6, 44
	s_min_u32 s0, s0, 62
	s_add_u32 s1, s9, s0
	s_sub_u32 s1, s1, 15
	s_max_i32 s1, s1, 0
	s_add_u32 s1, s1, s27
	s_lshl_b32 s1, s1, 11
	v_add_u32_e32 v33, s1, v0
	global_load_dwordx4 v[124:127], v33, s[76:77]
	global_load_dwordx4 v[128:131], v33, s[76:77] offset:1024
	s_add_u32 s0, s6, 48
	s_min_u32 s0, s0, 62
	s_add_u32 s1, s9, s0
	s_sub_u32 s1, s1, 15
	s_max_i32 s1, s1, 0
	s_add_u32 s1, s1, s27
	s_lshl_b32 s1, s1, 11
	v_add_u32_e32 v34, s1, v0
	global_load_dwordx4 v[132:135], v34, s[76:77]
	global_load_dwordx4 v[136:139], v34, s[76:77] offset:1024
	s_add_u32 s0, s6, 52
	s_min_u32 s0, s0, 62
	s_add_u32 s1, s9, s0
	s_sub_u32 s1, s1, 15
	s_max_i32 s1, s1, 0
	s_add_u32 s1, s1, s27
	s_lshl_b32 s1, s1, 11
	v_add_u32_e32 v35, s1, v0
	global_load_dwordx4 v[140:143], v35, s[76:77]
	global_load_dwordx4 v[144:147], v35, s[76:77] offset:1024
	s_add_u32 s0, s6, 56
	s_min_u32 s0, s0, 62
	s_add_u32 s1, s9, s0
	s_sub_u32 s1, s1, 15
	s_max_i32 s1, s1, 0
	s_add_u32 s1, s1, s27
	s_lshl_b32 s1, s1, 11
	v_add_u32_e32 v36, s1, v0
	global_load_dwordx4 v[148:151], v36, s[76:77]
	global_load_dwordx4 v[152:155], v36, s[76:77] offset:1024
	s_add_u32 s0, s6, 60
	s_min_u32 s0, s0, 62
	s_add_u32 s1, s9, s0
	s_sub_u32 s1, s1, 15
	s_max_i32 s1, s1, 0
	s_add_u32 s1, s1, s27
	s_lshl_b32 s1, s1, 11
	v_add_u32_e32 v37, s1, v0
	global_load_dwordx4 v[156:159], v37, s[76:77]
	global_load_dwordx4 v[160:163], v37, s[76:77] offset:1024
	s_waitcnt vmcnt(14)
; __device__ __forceinline__ void phase_pool(const Params& p, char* smraw) {
;     ...
;     for (int r = w; r < CH + 15; r += 4) {
;       const int pp = c0 - 15 + r;
;       if (pp >= 0) {
;         const u16* row = p.hb + (size_t)(b * L + pp) * D;
;         u32x4 a = *(const u32x4*)(row + l * 8), c = *(const u32x4*)(row + 512 + l * 8);
;         float s = wave_sum(sumsq8(a) + sumsq8(c));
;         if (l == 0) rstd_s[r] = rsqrtf(s * (1.f / 1024.f) + EPS);
;       }
	v_lshlrev_b32_e32 v10, 16, v100
	v_and_b32_e32 v100, 0xffff0000, v100
	v_lshlrev_b32_e32 v14, 16, v104
	v_and_b32_e32 v104, 0xffff0000, v104
	v_lshlrev_b32_e32 v11, 16, v101
	v_and_b32_e32 v101, 0xffff0000, v101
	v_lshlrev_b32_e32 v15, 16, v105
	v_and_b32_e32 v105, 0xffff0000, v105
	v_lshlrev_b32_e32 v12, 16, v102
	v_and_b32_e32 v102, 0xffff0000, v102
	v_lshlrev_b32_e32 v16, 16, v106
	v_and_b32_e32 v106, 0xffff0000, v106
	v_lshlrev_b32_e32 v13, 16, v103
	v_and_b32_e32 v103, 0xffff0000, v103
	v_lshlrev_b32_e32 v17, 16, v107
	v_and_b32_e32 v107, 0xffff0000, v107
	v_mul_f32_e32 v100, v100, v100
	v_mul_f32_e32 v104, v104, v104
	v_mul_f32_e32 v101, v101, v101
	v_mul_f32_e32 v105, v105, v105
	v_mul_f32_e32 v102, v102, v102
	v_mul_f32_e32 v106, v106, v106
	v_mul_f32_e32 v103, v103, v103
	v_mul_f32_e32 v107, v107, v107
	v_fmac_f32_e32 v100, v10, v10
	v_fmac_f32_e32 v104, v14, v14
	v_fmac_f32_e32 v101, v11, v11
	v_fmac_f32_e32 v105, v15, v15
	v_fmac_f32_e32 v102, v12, v12
	v_fmac_f32_e32 v106, v16, v16
	v_fmac_f32_e32 v103, v13, v13
	v_fmac_f32_e32 v107, v17, v17
	v_add_f32_e32 v100, v100, v101
	v_add_f32_e32 v104, v104, v105
	v_add_f32_e32 v100, v102, v100
	v_add_f32_e32 v104, v106, v104
	v_add_f32_e32 v100, v103, v100
	v_add_f32_e32 v104, v107, v104
	v_add_f32_e32 v40, v100, v104
	s_waitcnt vmcnt(12)
	v_lshlrev_b32_e32 v10, 16, v108
	v_and_b32_e32 v108, 0xffff0000, v108
	v_lshlrev_b32_e32 v14, 16, v112
	v_and_b32_e32 v112, 0xffff0000, v112
	v_lshlrev_b32_e32 v11, 16, v109
	v_and_b32_e32 v109, 0xffff0000, v109
	v_lshlrev_b32_e32 v15, 16, v113
	v_and_b32_e32 v113, 0xffff0000, v113
	v_lshlrev_b32_e32 v12, 16, v110
	v_and_b32_e32 v110, 0xffff0000, v110
	v_lshlrev_b32_e32 v16, 16, v114
	v_and_b32_e32 v114, 0xffff0000, v114
	v_lshlrev_b32_e32 v13, 16, v111
	v_and_b32_e32 v111, 0xffff0000, v111
	v_lshlrev_b32_e32 v17, 16, v115
	v_and_b32_e32 v115, 0xffff0000, v115
	v_mul_f32_e32 v108, v108, v108
	v_mul_f32_e32 v112, v112, v112
	v_mul_f32_e32 v109, v109, v109
	v_mul_f32_e32 v113, v113, v113
	v_mul_f32_e32 v110, v110, v110
	v_mul_f32_e32 v114, v114, v114
	v_mul_f32_e32 v111, v111, v111
	v_mul_f32_e32 v115, v115, v115
	v_fmac_f32_e32 v108, v10, v10
	v_fmac_f32_e32 v112, v14, v14
	v_fmac_f32_e32 v109, v11, v11
	v_fmac_f32_e32 v113, v15, v15
	v_fmac_f32_e32 v110, v12, v12
	v_fmac_f32_e32 v114, v16, v16
	v_fmac_f32_e32 v111, v13, v13
	v_fmac_f32_e32 v115, v17, v17
	v_add_f32_e32 v108, v108, v109
	v_add_f32_e32 v112, v112, v113
	v_add_f32_e32 v108, v110, v108
	v_add_f32_e32 v112, v114, v112
	v_add_f32_e32 v108, v111, v108
	v_add_f32_e32 v112, v115, v112
	v_add_f32_e32 v41, v108, v112
	s_waitcnt vmcnt(10)
	v_lshlrev_b32_e32 v10, 16, v116
	v_and_b32_e32 v116, 0xffff0000, v116
	v_lshlrev_b32_e32 v14, 16, v120
	v_and_b32_e32 v120, 0xffff0000, v120
	v_lshlrev_b32_e32 v11, 16, v117
	v_and_b32_e32 v117, 0xffff0000, v117
	v_lshlrev_b32_e32 v15, 16, v121
	v_and_b32_e32 v121, 0xffff0000, v121
	v_lshlrev_b32_e32 v12, 16, v118
	v_and_b32_e32 v118, 0xffff0000, v118
	v_lshlrev_b32_e32 v16, 16, v122
	v_and_b32_e32 v122, 0xffff0000, v122
	v_lshlrev_b32_e32 v13, 16, v119
	v_and_b32_e32 v119, 0xffff0000, v119
	v_lshlrev_b32_e32 v17, 16, v123
	v_and_b32_e32 v123, 0xffff0000, v123
	v_mul_f32_e32 v116, v116, v116
	v_mul_f32_e32 v120, v120, v120
	v_mul_f32_e32 v117, v117, v117
	v_mul_f32_e32 v121, v121, v121
	v_mul_f32_e32 v118, v118, v118
	v_mul_f32_e32 v122, v122, v122
	v_mul_f32_e32 v119, v119, v119
	v_mul_f32_e32 v123, v123, v123
	v_fmac_f32_e32 v116, v10, v10
	v_fmac_f32_e32 v120, v14, v14
	v_fmac_f32_e32 v117, v11, v11
	v_fmac_f32_e32 v121, v15, v15
	v_fmac_f32_e32 v118, v12, v12
	v_fmac_f32_e32 v122, v16, v16
	v_fmac_f32_e32 v119, v13, v13
	v_fmac_f32_e32 v123, v17, v17
	v_add_f32_e32 v116, v116, v117
	v_add_f32_e32 v120, v120, v121
	v_add_f32_e32 v116, v118, v116
	v_add_f32_e32 v120, v122, v120
	v_add_f32_e32 v116, v119, v116
	v_add_f32_e32 v120, v123, v120
	v_add_f32_e32 v42, v116, v120
	s_waitcnt vmcnt(8)
	v_lshlrev_b32_e32 v10, 16, v124
	v_and_b32_e32 v124, 0xffff0000, v124
	v_lshlrev_b32_e32 v14, 16, v128
	v_and_b32_e32 v128, 0xffff0000, v128
	v_lshlrev_b32_e32 v11, 16, v125
	v_and_b32_e32 v125, 0xffff0000, v125
	v_lshlrev_b32_e32 v15, 16, v129
	v_and_b32_e32 v129, 0xffff0000, v129
	v_lshlrev_b32_e32 v12, 16, v126
	v_and_b32_e32 v126, 0xffff0000, v126
	v_lshlrev_b32_e32 v16, 16, v130
	v_and_b32_e32 v130, 0xffff0000, v130
	v_lshlrev_b32_e32 v13, 16, v127
	v_and_b32_e32 v127, 0xffff0000, v127
	v_lshlrev_b32_e32 v17, 16, v131
	v_and_b32_e32 v131, 0xffff0000, v131
	v_mul_f32_e32 v124, v124, v124
	v_mul_f32_e32 v128, v128, v128
	v_mul_f32_e32 v125, v125, v125
	v_mul_f32_e32 v129, v129, v129
	v_mul_f32_e32 v126, v126, v126
	v_mul_f32_e32 v130, v130, v130
	v_mul_f32_e32 v127, v127, v127
	v_mul_f32_e32 v131, v131, v131
	v_fmac_f32_e32 v124, v10, v10
	v_fmac_f32_e32 v128, v14, v14
	v_fmac_f32_e32 v125, v11, v11
	v_fmac_f32_e32 v129, v15, v15
	v_fmac_f32_e32 v126, v12, v12
	v_fmac_f32_e32 v130, v16, v16
	v_fmac_f32_e32 v127, v13, v13
	v_fmac_f32_e32 v131, v17, v17
	v_add_f32_e32 v124, v124, v125
	v_add_f32_e32 v128, v128, v129
	v_add_f32_e32 v124, v126, v124
	v_add_f32_e32 v128, v130, v128
	v_add_f32_e32 v124, v127, v124
	v_add_f32_e32 v128, v131, v128
	v_add_f32_e32 v43, v124, v128
	s_waitcnt vmcnt(6)
; __device__ __forceinline__ void phase_pool(const Params& p, char* smraw) {
;     ...
;     for (int r = w; r < CH + 15; r += 4) {
;       const int pp = c0 - 15 + r;
;       if (pp >= 0) {
;         const u16* row = p.hb + (size_t)(b * L + pp) * D;
;         u32x4 a = *(const u32x4*)(row + l * 8), c = *(const u32x4*)(row + 512 + l * 8);
;         float s = wave_sum(sumsq8(a) + sumsq8(c));
;         if (l == 0) rstd_s[r] = rsqrtf(s * (1.f / 1024.f) + EPS);
;       }
	v_lshlrev_b32_e32 v10, 16, v132
	v_and_b32_e32 v132, 0xffff0000, v132
	v_lshlrev_b32_e32 v14, 16, v136
	v_and_b32_e32 v136, 0xffff0000, v136
	v_lshlrev_b32_e32 v11, 16, v133
	v_and_b32_e32 v133, 0xffff0000, v133
	v_lshlrev_b32_e32 v15, 16, v137
	v_and_b32_e32 v137, 0xffff0000, v137
	v_lshlrev_b32_e32 v12, 16, v134
	v_and_b32_e32 v134, 0xffff0000, v134
	v_lshlrev_b32_e32 v16, 16, v138
	v_and_b32_e32 v138, 0xffff0000, v138
	v_lshlrev_b32_e32 v13, 16, v135
	v_and_b32_e32 v135, 0xffff0000, v135
	v_lshlrev_b32_e32 v17, 16, v139
	v_and_b32_e32 v139, 0xffff0000, v139
	v_mul_f32_e32 v132, v132, v132
	v_mul_f32_e32 v136, v136, v136
	v_mul_f32_e32 v133, v133, v133
	v_mul_f32_e32 v137, v137, v137
	v_mul_f32_e32 v134, v134, v134
	v_mul_f32_e32 v138, v138, v138
	v_mul_f32_e32 v135, v135, v135
	v_mul_f32_e32 v139, v139, v139
	v_fmac_f32_e32 v132, v10, v10
	v_fmac_f32_e32 v136, v14, v14
	v_fmac_f32_e32 v133, v11, v11
	v_fmac_f32_e32 v137, v15, v15
	v_fmac_f32_e32 v134, v12, v12
	v_fmac_f32_e32 v138, v16, v16
	v_fmac_f32_e32 v135, v13, v13
	v_fmac_f32_e32 v139, v17, v17
	v_add_f32_e32 v132, v132, v133
	v_add_f32_e32 v136, v136, v137
	v_add_f32_e32 v132, v134, v132
	v_add_f32_e32 v136, v138, v136
	v_add_f32_e32 v132, v135, v132
	v_add_f32_e32 v136, v139, v136
	v_add_f32_e32 v44, v132, v136
	s_waitcnt vmcnt(4)
	v_lshlrev_b32_e32 v10, 16, v140
	v_and_b32_e32 v140, 0xffff0000, v140
	v_lshlrev_b32_e32 v14, 16, v144
	v_and_b32_e32 v144, 0xffff0000, v144
	v_lshlrev_b32_e32 v11, 16, v141
	v_and_b32_e32 v141, 0xffff0000, v141
	v_lshlrev_b32_e32 v15, 16, v145
	v_and_b32_e32 v145, 0xffff0000, v145
	v_lshlrev_b32_e32 v12, 16, v142
	v_and_b32_e32 v142, 0xffff0000, v142
	v_lshlrev_b32_e32 v16, 16, v146
	v_and_b32_e32 v146, 0xffff0000, v146
	v_lshlrev_b32_e32 v13, 16, v143
	v_and_b32_e32 v143, 0xffff0000, v143
	v_lshlrev_b32_e32 v17, 16, v147
	v_and_b32_e32 v147, 0xffff0000, v147
	v_mul_f32_e32 v140, v140, v140
	v_mul_f32_e32 v144, v144, v144
	v_mul_f32_e32 v141, v141, v141
	v_mul_f32_e32 v145, v145, v145
	v_mul_f32_e32 v142, v142, v142
	v_mul_f32_e32 v146, v146, v146
	v_mul_f32_e32 v143, v143, v143
	v_mul_f32_e32 v147, v147, v147
	v_fmac_f32_e32 v140, v10, v10
	v_fmac_f32_e32 v144, v14, v14
	v_fmac_f32_e32 v141, v11, v11
	v_fmac_f32_e32 v145, v15, v15
	v_fmac_f32_e32 v142, v12, v12
	v_fmac_f32_e32 v146, v16, v16
	v_fmac_f32_e32 v143, v13, v13
	v_fmac_f32_e32 v147, v17, v17
	v_add_f32_e32 v140, v140, v141
	v_add_f32_e32 v144, v144, v145
	v_add_f32_e32 v140, v142, v140
	v_add_f32_e32 v144, v146, v144
	v_add_f32_e32 v140, v143, v140
	v_add_f32_e32 v144, v147, v144
	v_add_f32_e32 v45, v140, v144
	s_waitcnt vmcnt(2)
	v_lshlrev_b32_e32 v10, 16, v148
	v_and_b32_e32 v148, 0xffff0000, v148
	v_lshlrev_b32_e32 v14, 16, v152
	v_and_b32_e32 v152, 0xffff0000, v152
	v_lshlrev_b32_e32 v11, 16, v149
	v_and_b32_e32 v149, 0xffff0000, v149
	v_lshlrev_b32_e32 v15, 16, v153
	v_and_b32_e32 v153, 0xffff0000, v153
	v_lshlrev_b32_e32 v12, 16, v150
	v_and_b32_e32 v150, 0xffff0000, v150
	v_lshlrev_b32_e32 v16, 16, v154
	v_and_b32_e32 v154, 0xffff0000, v154
	v_lshlrev_b32_e32 v13, 16, v151
	v_and_b32_e32 v151, 0xffff0000, v151
	v_lshlrev_b32_e32 v17, 16, v155
	v_and_b32_e32 v155, 0xffff0000, v155
	v_mul_f32_e32 v148, v148, v148
	v_mul_f32_e32 v152, v152, v152
	v_mul_f32_e32 v149, v149, v149
	v_mul_f32_e32 v153, v153, v153
	v_mul_f32_e32 v150, v150, v150
	v_mul_f32_e32 v154, v154, v154
	v_mul_f32_e32 v151, v151, v151
	v_mul_f32_e32 v155, v155, v155
	v_fmac_f32_e32 v148, v10, v10
	v_fmac_f32_e32 v152, v14, v14
	v_fmac_f32_e32 v149, v11, v11
	v_fmac_f32_e32 v153, v15, v15
	v_fmac_f32_e32 v150, v12, v12
	v_fmac_f32_e32 v154, v16, v16
	v_fmac_f32_e32 v151, v13, v13
	v_fmac_f32_e32 v155, v17, v17
	v_add_f32_e32 v148, v148, v149
	v_add_f32_e32 v152, v152, v153
	v_add_f32_e32 v148, v150, v148
	v_add_f32_e32 v152, v154, v152
	v_add_f32_e32 v148, v151, v148
	v_add_f32_e32 v152, v155, v152
	v_add_f32_e32 v46, v148, v152
	s_waitcnt vmcnt(0)
	v_lshlrev_b32_e32 v10, 16, v156
	v_and_b32_e32 v156, 0xffff0000, v156
	v_lshlrev_b32_e32 v14, 16, v160
	v_and_b32_e32 v160, 0xffff0000, v160
	v_lshlrev_b32_e32 v11, 16, v157
	v_and_b32_e32 v157, 0xffff0000, v157
	v_lshlrev_b32_e32 v15, 16, v161
	v_and_b32_e32 v161, 0xffff0000, v161
	v_lshlrev_b32_e32 v12, 16, v158
	v_and_b32_e32 v158, 0xffff0000, v158
	v_lshlrev_b32_e32 v16, 16, v162
	v_and_b32_e32 v162, 0xffff0000, v162
	v_lshlrev_b32_e32 v13, 16, v159
	v_and_b32_e32 v159, 0xffff0000, v159
	v_lshlrev_b32_e32 v17, 16, v163
	v_and_b32_e32 v163, 0xffff0000, v163
	v_mul_f32_e32 v156, v156, v156
	v_mul_f32_e32 v160, v160, v160
	v_mul_f32_e32 v157, v157, v157
	v_mul_f32_e32 v161, v161, v161
	v_mul_f32_e32 v158, v158, v158
	v_mul_f32_e32 v162, v162, v162
	v_mul_f32_e32 v159, v159, v159
	v_mul_f32_e32 v163, v163, v163
	v_fmac_f32_e32 v156, v10, v10
	v_fmac_f32_e32 v160, v14, v14
	v_fmac_f32_e32 v157, v11, v11
	v_fmac_f32_e32 v161, v15, v15
	v_fmac_f32_e32 v158, v12, v12
	v_fmac_f32_e32 v162, v16, v16
	v_fmac_f32_e32 v159, v13, v13
	v_fmac_f32_e32 v163, v17, v17
	v_add_f32_e32 v156, v156, v157
	v_add_f32_e32 v160, v160, v161
	v_add_f32_e32 v156, v158, v156
	v_add_f32_e32 v160, v162, v160
	v_add_f32_e32 v156, v159, v156
	v_add_f32_e32 v160, v163, v160
	v_add_f32_e32 v47, v156, v160
	ds_bpermute_b32 v48, v2, v40
	ds_bpermute_b32 v49, v2, v41
	ds_bpermute_b32 v50, v2, v42
	ds_bpermute_b32 v51, v2, v43
	ds_bpermute_b32 v52, v2, v44
	ds_bpermute_b32 v53, v2, v45
	ds_bpermute_b32 v54, v2, v46
	ds_bpermute_b32 v55, v2, v47
	s_waitcnt lgkmcnt(0)
; __device__ __forceinline__ void phase_pool(const Params& p, char* smraw) {
;     ...
;     for (int r = w; r < CH + 15; r += 4) {
;       const int pp = c0 - 15 + r;
;       if (pp >= 0) {
;         const u16* row = p.hb + (size_t)(b * L + pp) * D;
;         u32x4 a = *(const u32x4*)(row + l * 8), c = *(const u32x4*)(row + 512 + l * 8);
;         float s = wave_sum(sumsq8(a) + sumsq8(c));
;         if (l == 0) rstd_s[r] = rsqrtf(s * (1.f / 1024.f) + EPS);
;       }
;     }
;     __syncthreads();
;     const int c = tid * 4;
;     const int win = 2 << (tid >> 6);
;     const u16* base = p.hb + (size_t)(b * L) * D + c;
	v_add_f32_e32 v40, v40, v48
	v_add_f32_e32 v41, v41, v49
	v_add_f32_e32 v42, v42, v50
	v_add_f32_e32 v43, v43, v51
	v_add_f32_e32 v44, v44, v52
	v_add_f32_e32 v45, v45, v53
	v_add_f32_e32 v46, v46, v54
	v_add_f32_e32 v47, v47, v55
	ds_bpermute_b32 v48, v3, v40
	ds_bpermute_b32 v49, v3, v41
	ds_bpermute_b32 v50, v3, v42
	ds_bpermute_b32 v51, v3, v43
	ds_bpermute_b32 v52, v3, v44
	ds_bpermute_b32 v53, v3, v45
	ds_bpermute_b32 v54, v3, v46
	ds_bpermute_b32 v55, v3, v47
	s_waitcnt lgkmcnt(0)
	v_add_f32_e32 v40, v40, v48
	v_add_f32_e32 v41, v41, v49
	v_add_f32_e32 v42, v42, v50
	v_add_f32_e32 v43, v43, v51
	v_add_f32_e32 v44, v44, v52
	v_add_f32_e32 v45, v45, v53
	v_add_f32_e32 v46, v46, v54
	v_add_f32_e32 v47, v47, v55
	ds_bpermute_b32 v48, v4, v40
	ds_bpermute_b32 v49, v4, v41
	ds_bpermute_b32 v50, v4, v42
	ds_bpermute_b32 v51, v4, v43
	ds_bpermute_b32 v52, v4, v44
	ds_bpermute_b32 v53, v4, v45
	ds_bpermute_b32 v54, v4, v46
	ds_bpermute_b32 v55, v4, v47
	s_waitcnt lgkmcnt(0)
	v_add_f32_e32 v40, v40, v48
	v_add_f32_e32 v41, v41, v49
	v_add_f32_e32 v42, v42, v50
	v_add_f32_e32 v43, v43, v51
	v_add_f32_e32 v44, v44, v52
	v_add_f32_e32 v45, v45, v53
	v_add_f32_e32 v46, v46, v54
	v_add_f32_e32 v47, v47, v55
	ds_bpermute_b32 v48, v5, v40
	ds_bpermute_b32 v49, v5, v41
	ds_bpermute_b32 v50, v5, v42
	ds_bpermute_b32 v51, v5, v43
	ds_bpermute_b32 v52, v5, v44
	ds_bpermute_b32 v53, v5, v45
	ds_bpermute_b32 v54, v5, v46
	ds_bpermute_b32 v55, v5, v47
	s_waitcnt lgkmcnt(0)
	v_add_f32_e32 v40, v40, v48
	v_add_f32_e32 v41, v41, v49
	v_add_f32_e32 v42, v42, v50
	v_add_f32_e32 v43, v43, v51
	v_add_f32_e32 v44, v44, v52
	v_add_f32_e32 v45, v45, v53
	v_add_f32_e32 v46, v46, v54
	v_add_f32_e32 v47, v47, v55
	ds_bpermute_b32 v48, v6, v40
	ds_bpermute_b32 v49, v6, v41
	ds_bpermute_b32 v50, v6, v42
	ds_bpermute_b32 v51, v6, v43
	ds_bpermute_b32 v52, v6, v44
	ds_bpermute_b32 v53, v6, v45
	ds_bpermute_b32 v54, v6, v46
	ds_bpermute_b32 v55, v6, v47
	s_waitcnt lgkmcnt(0)
	v_add_f32_e32 v40, v40, v48
	v_add_f32_e32 v41, v41, v49
	v_add_f32_e32 v42, v42, v50
	v_add_f32_e32 v43, v43, v51
	v_add_f32_e32 v44, v44, v52
	v_add_f32_e32 v45, v45, v53
	v_add_f32_e32 v46, v46, v54
	v_add_f32_e32 v47, v47, v55
	ds_bpermute_b32 v48, v7, v40
	ds_bpermute_b32 v49, v7, v41
	ds_bpermute_b32 v50, v7, v42
	ds_bpermute_b32 v51, v7, v43
	ds_bpermute_b32 v52, v7, v44
	ds_bpermute_b32 v53, v7, v45
	ds_bpermute_b32 v54, v7, v46
	ds_bpermute_b32 v55, v7, v47
	s_waitcnt lgkmcnt(0)
	v_add_f32_e32 v40, v40, v48
	v_add_f32_e32 v41, v41, v49
	v_add_f32_e32 v42, v42, v50
	v_add_f32_e32 v43, v43, v51
	v_add_f32_e32 v44, v44, v52
	v_add_f32_e32 v45, v45, v53
	v_add_f32_e32 v46, v46, v54
	v_add_f32_e32 v47, v47, v55
	v_fmamk_f32 v40, v40, 0x3a800000, v9
	v_mul_f32_e32 v48, 0x4b800000, v40
	v_cmp_gt_f32_e32 vcc, s25, v40
	s_nop 1
	v_cndmask_b32_e32 v40, v40, v48, vcc
	v_rsq_f32_e32 v40, v40
	s_nop 0
	v_mul_f32_e32 v48, 0x45800000, v40
	v_cndmask_b32_e32 v40, v40, v48, vcc
	v_fmamk_f32 v41, v41, 0x3a800000, v9
	v_mul_f32_e32 v49, 0x4b800000, v41
	v_cmp_gt_f32_e32 vcc, s25, v41
	s_nop 1
	v_cndmask_b32_e32 v41, v41, v49, vcc
	v_rsq_f32_e32 v41, v41
	s_nop 0
	v_mul_f32_e32 v49, 0x45800000, v41
	v_cndmask_b32_e32 v41, v41, v49, vcc
	v_fmamk_f32 v42, v42, 0x3a800000, v9
	v_mul_f32_e32 v50, 0x4b800000, v42
	v_cmp_gt_f32_e32 vcc, s25, v42
	s_nop 1
	v_cndmask_b32_e32 v42, v42, v50, vcc
	v_rsq_f32_e32 v42, v42
	s_nop 0
	v_mul_f32_e32 v50, 0x45800000, v42
	v_cndmask_b32_e32 v42, v42, v50, vcc
	v_fmamk_f32 v43, v43, 0x3a800000, v9
	v_mul_f32_e32 v51, 0x4b800000, v43
	v_cmp_gt_f32_e32 vcc, s25, v43
	s_nop 1
	v_cndmask_b32_e32 v43, v43, v51, vcc
	v_rsq_f32_e32 v43, v43
	s_nop 0
	v_mul_f32_e32 v51, 0x45800000, v43
	v_cndmask_b32_e32 v43, v43, v51, vcc
	v_fmamk_f32 v44, v44, 0x3a800000, v9
	v_mul_f32_e32 v52, 0x4b800000, v44
	v_cmp_gt_f32_e32 vcc, s25, v44
	s_nop 1
	v_cndmask_b32_e32 v44, v44, v52, vcc
	v_rsq_f32_e32 v44, v44
	s_nop 0
	v_mul_f32_e32 v52, 0x45800000, v44
	v_cndmask_b32_e32 v44, v44, v52, vcc
	v_fmamk_f32 v45, v45, 0x3a800000, v9
	v_mul_f32_e32 v53, 0x4b800000, v45
	v_cmp_gt_f32_e32 vcc, s25, v45
	s_nop 1
	v_cndmask_b32_e32 v45, v45, v53, vcc
	v_rsq_f32_e32 v45, v45
	s_nop 0
	v_mul_f32_e32 v53, 0x45800000, v45
	v_cndmask_b32_e32 v45, v45, v53, vcc
	v_fmamk_f32 v46, v46, 0x3a800000, v9
	v_mul_f32_e32 v54, 0x4b800000, v46
	v_cmp_gt_f32_e32 vcc, s25, v46
	s_nop 1
	v_cndmask_b32_e32 v46, v46, v54, vcc
	v_rsq_f32_e32 v46, v46
	s_nop 0
	v_mul_f32_e32 v54, 0x45800000, v46
	v_cndmask_b32_e32 v46, v46, v54, vcc
	v_fmamk_f32 v47, v47, 0x3a800000, v9
	v_mul_f32_e32 v55, 0x4b800000, v47
	v_cmp_gt_f32_e32 vcc, s25, v47
	s_nop 1
	v_cndmask_b32_e32 v47, v47, v55, vcc
	v_rsq_f32_e32 v47, v47
	s_nop 0
	v_mul_f32_e32 v55, 0x45800000, v47
	v_cndmask_b32_e32 v47, v47, v55, vcc
	s_mov_b64 s[10:11], exec
	s_mov_b64 exec, 1
	s_add_u32 s0, s6, 32
	s_min_u32 s0, s0, 62
	s_lshl_b32 s0, s0, 2
	v_mov_b32_e32 v48, s0
	ds_write_b32 v48, v40
	s_add_u32 s0, s6, 36
	s_min_u32 s0, s0, 62
	s_lshl_b32 s0, s0, 2
	v_mov_b32_e32 v49, s0
	ds_write_b32 v49, v41
	s_add_u32 s0, s6, 40
	s_min_u32 s0, s0, 62
	s_lshl_b32 s0, s0, 2
	v_mov_b32_e32 v50, s0
	ds_write_b32 v50, v42
	s_add_u32 s0, s6, 44
	s_min_u32 s0, s0, 62
	s_lshl_b32 s0, s0, 2
	v_mov_b32_e32 v51, s0
	ds_write_b32 v51, v43
	s_add_u32 s0, s6, 48
	s_min_u32 s0, s0, 62
	s_lshl_b32 s0, s0, 2
	v_mov_b32_e32 v52, s0
	ds_write_b32 v52, v44
	s_add_u32 s0, s6, 52
	s_min_u32 s0, s0, 62
	s_lshl_b32 s0, s0, 2
	v_mov_b32_e32 v53, s0
	ds_write_b32 v53, v45
	s_add_u32 s0, s6, 56
	s_min_u32 s0, s0, 62
	s_lshl_b32 s0, s0, 2
	v_mov_b32_e32 v54, s0
	ds_write_b32 v54, v46
	s_add_u32 s0, s6, 60
	s_min_u32 s0, s0, 62
	s_lshl_b32 s0, s0, 2
	v_mov_b32_e32 v55, s0
	ds_write_b32 v55, v47
	s_mov_b64 exec, s[10:11]
	s_waitcnt lgkmcnt(0)
	s_barrier
	s_lshl_b32 s0, s3, 11
	v_add_u32_e32 v8, s0, v1
	s_cmp_eq_u32 s6, 0
	s_cbranch_scc1 .Lmy_pool_w0
	s_cmp_eq_u32 s6, 1
	s_cbranch_scc1 .Lmy_pool_w1
	s_cmp_eq_u32 s6, 2
	s_cbranch_scc1 .Lmy_pool_w2
; __device__ __forceinline__ float bflo(unsigned u) { return __uint_as_float(u << 16); }
; __device__ __forceinline__ float bfhi(unsigned u) { return __uint_as_float(u & 0xffff0000u); }
; __device__ __forceinline__ void phase_pool(const Params& p, char* smraw) {
;     ...
;     const int c = tid * 4;
;     const int win = 2 << (tid >> 6);
;     const u16* base = p.hb + (size_t)(b * L) * D + c;
;     float s0 = 0.f, s1 = 0.f, s2 = 0.f, s3 = 0.f;
;     for (int i = 1; i < win; ++i) {
;       const int pp = c0 - i;
;       if (pp >= 0) {
;         u32x2 v = *(const u32x2*)(base + (size_t)pp * D);
;         const float rs = rstd_s[15 - i];
;         s0 += bflo(v[0]) * rs; s1 += bfhi(v[0]) * rs; s2 += bflo(v[1]) * rs; s3 += bfhi(v[1]) * rs;
;       }
;     }
;     for (int t8 = 0; t8 < CH; t8 += 8) {
;       u32x2 cur[8], old[8];
; #pragma unroll
;       for (int k = 0; k < 8; ++k) {
;         const int pp = c0 + t8 + k;
;         cur[k] = *(const u32x2*)(base + (size_t)pp * D);
;         const int po = pp - win + 1;
;         old[k] = *(const u32x2*)(base + (size_t)(po >= 0 ? po : 0) * D);
;       }
.Lmy_pool_w3:
	s_mov_b32 s35, 0x3d800000
	ds_read_b128 v[192:195], v59 offset:0
	ds_read_b128 v[196:199], v59 offset:16
	ds_read_b128 v[200:203], v59 offset:32
	ds_read_b128 v[204:207], v59 offset:48
	ds_read_b128 v[208:211], v59 offset:64
	ds_read_b128 v[212:215], v59 offset:80
	ds_read_b128 v[216:219], v59 offset:96
	ds_read_b128 v[220:223], v59 offset:112
	ds_read_b128 v[224:227], v59 offset:128
	ds_read_b128 v[228:231], v59 offset:144
	ds_read_b128 v[232:235], v59 offset:160
	ds_read_b128 v[236:239], v59 offset:176
	ds_read_b128 v[240:243], v59 offset:192
	ds_read_b128 v[244:247], v59 offset:208
	ds_read_b128 v[248:251], v59 offset:224
	ds_read_b64 v[252:253], v59 offset:240
	ds_read_b32 v186, v59 offset:248
	s_add_i32 s1, s9, -15
	s_max_i32 s1, s1, 0
	s_add_u32 s1, s1, s27
	s_lshl_b32 s1, s1, 11
	v_add_u32_e32 v30, s1, v1
	global_load_dwordx2 v[60:61], v30, s[76:77]
	s_add_i32 s1, s9, -14
	s_max_i32 s1, s1, 0
	s_add_u32 s1, s1, s27
	s_lshl_b32 s1, s1, 11
	v_add_u32_e32 v31, s1, v1
	global_load_dwordx2 v[62:63], v31, s[76:77]
	s_add_i32 s1, s9, -13
	s_max_i32 s1, s1, 0
	s_add_u32 s1, s1, s27
	s_lshl_b32 s1, s1, 11
	v_add_u32_e32 v32, s1, v1
	global_load_dwordx2 v[64:65], v32, s[76:77]
	s_add_i32 s1, s9, -12
	s_max_i32 s1, s1, 0
	s_add_u32 s1, s1, s27
	s_lshl_b32 s1, s1, 11
	v_add_u32_e32 v33, s1, v1
	global_load_dwordx2 v[66:67], v33, s[76:77]
	s_add_i32 s1, s9, -11
	s_max_i32 s1, s1, 0
	s_add_u32 s1, s1, s27
	s_lshl_b32 s1, s1, 11
	v_add_u32_e32 v34, s1, v1
	global_load_dwordx2 v[68:69], v34, s[76:77]
	s_add_i32 s1, s9, -10
	s_max_i32 s1, s1, 0
	s_add_u32 s1, s1, s27
	s_lshl_b32 s1, s1, 11
	v_add_u32_e32 v35, s1, v1
	global_load_dwordx2 v[70:71], v35, s[76:77]
	s_add_i32 s1, s9, -9
	s_max_i32 s1, s1, 0
	s_add_u32 s1, s1, s27
	s_lshl_b32 s1, s1, 11
	v_add_u32_e32 v36, s1, v1
	global_load_dwordx2 v[72:73], v36, s[76:77]
	s_add_i32 s1, s9, -8
	s_max_i32 s1, s1, 0
	s_add_u32 s1, s1, s27
	s_lshl_b32 s1, s1, 11
	v_add_u32_e32 v37, s1, v1
	global_load_dwordx2 v[74:75], v37, s[76:77]
	s_add_i32 s1, s9, -7
	s_max_i32 s1, s1, 0
	s_add_u32 s1, s1, s27
	s_lshl_b32 s1, s1, 11
	v_add_u32_e32 v30, s1, v1
	global_load_dwordx2 v[76:77], v30, s[76:77]
	s_add_i32 s1, s9, -6
	s_max_i32 s1, s1, 0
	s_add_u32 s1, s1, s27
	s_lshl_b32 s1, s1, 11
	v_add_u32_e32 v31, s1, v1
	global_load_dwordx2 v[78:79], v31, s[76:77]
	s_add_i32 s1, s9, -5
	s_max_i32 s1, s1, 0
	s_add_u32 s1, s1, s27
	s_lshl_b32 s1, s1, 11
	v_add_u32_e32 v32, s1, v1
	global_load_dwordx2 v[80:81], v32, s[76:77]
	s_add_i32 s1, s9, -4
	s_max_i32 s1, s1, 0
	s_add_u32 s1, s1, s27
	s_lshl_b32 s1, s1, 11
	v_add_u32_e32 v33, s1, v1
	global_load_dwordx2 v[82:83], v33, s[76:77]
	s_add_i32 s1, s9, -3
	s_max_i32 s1, s1, 0
	s_add_u32 s1, s1, s27
	s_lshl_b32 s1, s1, 11
	v_add_u32_e32 v34, s1, v1
	global_load_dwordx2 v[84:85], v34, s[76:77]
	s_add_i32 s1, s9, -2
	s_max_i32 s1, s1, 0
	s_add_u32 s1, s1, s27
	s_lshl_b32 s1, s1, 11
	v_add_u32_e32 v35, s1, v1
	global_load_dwordx2 v[86:87], v35, s[76:77]
	s_add_i32 s1, s9, -1
	s_max_i32 s1, s1, 0
	s_add_u32 s1, s1, s27
	s_lshl_b32 s1, s1, 11
	v_add_u32_e32 v36, s1, v1
	global_load_dwordx2 v[88:89], v36, s[76:77]
	global_load_dwordx2 v[90:91], v8, s[76:77]
	v_add_u32_e32 v30, 0x800, v8
	global_load_dwordx2 v[92:93], v30, s[76:77]
	v_add_u32_e32 v31, 0x1000, v8
	global_load_dwordx2 v[94:95], v31, s[76:77]
	v_add_u32_e32 v32, 0x1800, v8
	global_load_dwordx2 v[96:97], v32, s[76:77]
	v_add_u32_e32 v33, 0x2000, v8
	global_load_dwordx2 v[98:99], v33, s[76:77]
	v_add_u32_e32 v34, 0x2800, v8
	global_load_dwordx2 v[100:101], v34, s[76:77]
	v_add_u32_e32 v35, 0x3000, v8
	global_load_dwordx2 v[102:103], v35, s[76:77]
	v_add_u32_e32 v36, 0x3800, v8
	global_load_dwordx2 v[104:105], v36, s[76:77]
	v_add_u32_e32 v37, 0x4000, v8
	global_load_dwordx2 v[106:107], v37, s[76:77]
	v_add_u32_e32 v30, 0x4800, v8
	global_load_dwordx2 v[108:109], v30, s[76:77]
	v_add_u32_e32 v31, 0x5000, v8
	global_load_dwordx2 v[110:111], v31, s[76:77]
	v_add_u32_e32 v32, 0x5800, v8
	global_load_dwordx2 v[112:113], v32, s[76:77]
	v_add_u32_e32 v33, 0x6000, v8
	global_load_dwordx2 v[114:115], v33, s[76:77]
	v_add_u32_e32 v34, 0x6800, v8
	global_load_dwordx2 v[116:117], v34, s[76:77]
	v_add_u32_e32 v35, 0x7000, v8
	global_load_dwordx2 v[118:119], v35, s[76:77]
	v_add_u32_e32 v36, 0x7800, v8
	global_load_dwordx2 v[120:121], v36, s[76:77]
	v_add_u32_e32 v37, 0x8000, v8
	global_load_dwordx2 v[122:123], v37, s[76:77]
	v_add_u32_e32 v30, 0x8800, v8
	global_load_dwordx2 v[124:125], v30, s[76:77]
	v_add_u32_e32 v31, 0x9000, v8
	global_load_dwordx2 v[126:127], v31, s[76:77]
	v_add_u32_e32 v32, 0x9800, v8
	global_load_dwordx2 v[128:129], v32, s[76:77]
	v_add_u32_e32 v33, 0xa000, v8
	global_load_dwordx2 v[130:131], v33, s[76:77]
	v_add_u32_e32 v34, 0xa800, v8
	global_load_dwordx2 v[132:133], v34, s[76:77]
	v_add_u32_e32 v35, 0xb000, v8
	global_load_dwordx2 v[134:135], v35, s[76:77]
	v_add_u32_e32 v36, 0xb800, v8
	global_load_dwordx2 v[136:137], v36, s[76:77]
	v_add_u32_e32 v37, 0xc000, v8
	global_load_dwordx2 v[138:139], v37, s[76:77]
	v_add_u32_e32 v30, 0xc800, v8
	global_load_dwordx2 v[140:141], v30, s[76:77]
	v_add_u32_e32 v31, 0xd000, v8
	global_load_dwordx2 v[142:143], v31, s[76:77]
	v_add_u32_e32 v32, 0xd800, v8
	global_load_dwordx2 v[144:145], v32, s[76:77]
	v_add_u32_e32 v33, 0xe000, v8
	global_load_dwordx2 v[146:147], v33, s[76:77]
	v_add_u32_e32 v34, 0xe800, v8
	global_load_dwordx2 v[148:149], v34, s[76:77]
	v_add_u32_e32 v35, 0xf000, v8
	global_load_dwordx2 v[150:151], v35, s[76:77]
	v_add_u32_e32 v36, 0xf800, v8
	global_load_dwordx2 v[152:153], v36, s[76:77]
	v_add_u32_e32 v37, 0x10000, v8
	global_load_dwordx2 v[154:155], v37, s[76:77]
	v_add_u32_e32 v30, 0x10800, v8
	global_load_dwordx2 v[156:157], v30, s[76:77]
	v_add_u32_e32 v31, 0x11000, v8
	global_load_dwordx2 v[158:159], v31, s[76:77]
	v_add_u32_e32 v32, 0x11800, v8
	global_load_dwordx2 v[160:161], v32, s[76:77]
	v_add_u32_e32 v33, 0x12000, v8
	global_load_dwordx2 v[162:163], v33, s[76:77]
	v_add_u32_e32 v34, 0x12800, v8
	global_load_dwordx2 v[164:165], v34, s[76:77]
	v_add_u32_e32 v35, 0x13000, v8
	global_load_dwordx2 v[166:167], v35, s[76:77]
	v_add_u32_e32 v36, 0x13800, v8
	global_load_dwordx2 v[168:169], v36, s[76:77]
	v_add_u32_e32 v37, 0x14000, v8
	global_load_dwordx2 v[170:171], v37, s[76:77]
	v_add_u32_e32 v30, 0x14800, v8
	global_load_dwordx2 v[172:173], v30, s[76:77]
	v_add_u32_e32 v31, 0x15000, v8
	global_load_dwordx2 v[174:175], v31, s[76:77]
	v_add_u32_e32 v32, 0x15800, v8
	global_load_dwordx2 v[176:177], v32, s[76:77]
	v_add_u32_e32 v33, 0x16000, v8
	global_load_dwordx2 v[178:179], v33, s[76:77]
	v_add_u32_e32 v34, 0x16800, v8
	global_load_dwordx2 v[180:181], v34, s[76:77]
	v_add_u32_e32 v35, 0x17000, v8
	global_load_dwordx2 v[182:183], v35, s[76:77]
	v_add_u32_e32 v36, 0x17800, v8
	global_load_dwordx2 v[184:185], v36, s[76:77]
	s_waitcnt lgkmcnt(0)
	s_cmp_lg_u32 s9, 0
	s_cbranch_scc1 .Lmy_pool_w3_nz
; __device__ __forceinline__ float bflo(unsigned u) { return __uint_as_float(u << 16); }
; __device__ __forceinline__ float bfhi(unsigned u) { return __uint_as_float(u & 0xffff0000u); }
; __device__ __forceinline__ void phase_pool(const Params& p, char* smraw) {
;     ...
;     float s0 = 0.f, s1 = 0.f, s2 = 0.f, s3 = 0.f;
;     for (int i = 1; i < win; ++i) {
;       const int pp = c0 - i;
;       if (pp >= 0) {
;         u32x2 v = *(const u32x2*)(base + (size_t)pp * D);
;         const float rs = rstd_s[15 - i];
;         s0 += bflo(v[0]) * rs; s1 += bfhi(v[0]) * rs; s2 += bflo(v[1]) * rs; s3 += bfhi(v[1]) * rs;
;       }
;     }
;     for (int t8 = 0; t8 < CH; t8 += 8) {
;       u32x2 cur[8], old[8];
; #pragma unroll
;       for (int k = 0; k < 8; ++k) {
;         const int pp = c0 + t8 + k;
;         cur[k] = *(const u32x2*)(base + (size_t)pp * D);
;         const int po = pp - win + 1;
;         old[k] = *(const u32x2*)(base + (size_t)(po >= 0 ? po : 0) * D);
;       }
; #pragma unroll
;       for (int k = 0; k < 8; ++k) {
;         const int tt = t8 + k, pp = c0 + tt;
;         const float rs = rstd_s[tt + 15];
;         const float x0 = bflo(cur[k][0]) * rs, x1 = bfhi(cur[k][0]) * rs, x2 = bflo(cur[k][1]) * rs, x3 = bfhi(cur[k][1]) * rs;
;         s0 += x0; s1 += x1; s2 += x2; s3 += x3;
;         const int cnt = (pp + 1 < win) ? pp + 1 : win;
;         const float inv = 1.f / (float)cnt;
;         u32x2 o; o[0] = cvtpk(s0 * inv - x0, s1 * inv - x1); o[1] = cvtpk(s2 * inv - x2, s3 * inv - x3);
;         *(u32x2*)(p.pooled + (size_t)(b * L + pp) * D + c) = o;
;         const int po = pp - win + 1;
;         if (po >= 0) {
;           const float ro = rstd_s[tt + 15 - win + 1];
;           s0 -= bflo(old[k][0]) * ro; s1 -= bfhi(old[k][0]) * ro; s2 -= bflo(old[k][1]) * ro; s3 -= bfhi(old[k][1]) * ro;
;         }
	v_mov_b32_e32 v192, 0
	v_mov_b32_e32 v193, 0
	v_mov_b32_e32 v194, 0
	v_mov_b32_e32 v195, 0
	v_mov_b32_e32 v196, 0
	v_mov_b32_e32 v197, 0
	v_mov_b32_e32 v198, 0
	v_mov_b32_e32 v199, 0
	v_mov_b32_e32 v200, 0
	v_mov_b32_e32 v201, 0
	v_mov_b32_e32 v202, 0
	v_mov_b32_e32 v203, 0
	v_mov_b32_e32 v204, 0
	v_mov_b32_e32 v205, 0
	v_mov_b32_e32 v206, 0
.Lmy_pool_w3_nz:
	v_mov_b32_e32 v10, 0
	v_mov_b32_e32 v11, 0
	v_mov_b32_e32 v12, 0
	v_mov_b32_e32 v13, 0
	s_waitcnt vmcnt(48)
	v_and_b32_e32 v14, 0xffff0000, v88
	v_lshlrev_b32_e32 v15, 16, v88
	v_and_b32_e32 v16, 0xffff0000, v89
	v_lshlrev_b32_e32 v17, 16, v89
	v_pk_fma_f32 v[10:11], v[206:207], v[14:15], v[10:11] op_sel_hi:[0,1,1]
	v_pk_fma_f32 v[12:13], v[206:207], v[16:17], v[12:13] op_sel_hi:[0,1,1]
	v_and_b32_e32 v14, 0xffff0000, v86
	v_lshlrev_b32_e32 v15, 16, v86
	v_and_b32_e32 v16, 0xffff0000, v87
	v_lshlrev_b32_e32 v17, 16, v87
	v_pk_fma_f32 v[10:11], v[204:205], v[14:15], v[10:11] op_sel:[1,0,0] op_sel_hi:[1,1,1]
	v_pk_fma_f32 v[12:13], v[204:205], v[16:17], v[12:13] op_sel:[1,0,0] op_sel_hi:[1,1,1]
	v_and_b32_e32 v14, 0xffff0000, v84
	v_lshlrev_b32_e32 v15, 16, v84
	v_and_b32_e32 v16, 0xffff0000, v85
	v_lshlrev_b32_e32 v17, 16, v85
	v_pk_fma_f32 v[10:11], v[204:205], v[14:15], v[10:11] op_sel_hi:[0,1,1]
	v_pk_fma_f32 v[12:13], v[204:205], v[16:17], v[12:13] op_sel_hi:[0,1,1]
	v_and_b32_e32 v14, 0xffff0000, v82
	v_lshlrev_b32_e32 v15, 16, v82
	v_and_b32_e32 v16, 0xffff0000, v83
	v_lshlrev_b32_e32 v17, 16, v83
	v_pk_fma_f32 v[10:11], v[202:203], v[14:15], v[10:11] op_sel:[1,0,0] op_sel_hi:[1,1,1]
	v_pk_fma_f32 v[12:13], v[202:203], v[16:17], v[12:13] op_sel:[1,0,0] op_sel_hi:[1,1,1]
	v_and_b32_e32 v14, 0xffff0000, v80
	v_lshlrev_b32_e32 v15, 16, v80
	v_and_b32_e32 v16, 0xffff0000, v81
	v_lshlrev_b32_e32 v17, 16, v81
	v_pk_fma_f32 v[10:11], v[202:203], v[14:15], v[10:11] op_sel_hi:[0,1,1]
	v_pk_fma_f32 v[12:13], v[202:203], v[16:17], v[12:13] op_sel_hi:[0,1,1]
	v_and_b32_e32 v14, 0xffff0000, v78
	v_lshlrev_b32_e32 v15, 16, v78
	v_and_b32_e32 v16, 0xffff0000, v79
	v_lshlrev_b32_e32 v17, 16, v79
	v_pk_fma_f32 v[10:11], v[200:201], v[14:15], v[10:11] op_sel:[1,0,0] op_sel_hi:[1,1,1]
	v_pk_fma_f32 v[12:13], v[200:201], v[16:17], v[12:13] op_sel:[1,0,0] op_sel_hi:[1,1,1]
	v_and_b32_e32 v14, 0xffff0000, v76
	v_lshlrev_b32_e32 v15, 16, v76
	v_and_b32_e32 v16, 0xffff0000, v77
	v_lshlrev_b32_e32 v17, 16, v77
	v_pk_fma_f32 v[10:11], v[200:201], v[14:15], v[10:11] op_sel_hi:[0,1,1]
	v_pk_fma_f32 v[12:13], v[200:201], v[16:17], v[12:13] op_sel_hi:[0,1,1]
	v_and_b32_e32 v14, 0xffff0000, v74
	v_lshlrev_b32_e32 v15, 16, v74
	v_and_b32_e32 v16, 0xffff0000, v75
	v_lshlrev_b32_e32 v17, 16, v75
	v_pk_fma_f32 v[10:11], v[198:199], v[14:15], v[10:11] op_sel:[1,0,0] op_sel_hi:[1,1,1]
	v_pk_fma_f32 v[12:13], v[198:199], v[16:17], v[12:13] op_sel:[1,0,0] op_sel_hi:[1,1,1]
	v_and_b32_e32 v14, 0xffff0000, v72
	v_lshlrev_b32_e32 v15, 16, v72
	v_and_b32_e32 v16, 0xffff0000, v73
	v_lshlrev_b32_e32 v17, 16, v73
	v_pk_fma_f32 v[10:11], v[198:199], v[14:15], v[10:11] op_sel_hi:[0,1,1]
	v_pk_fma_f32 v[12:13], v[198:199], v[16:17], v[12:13] op_sel_hi:[0,1,1]
	v_and_b32_e32 v14, 0xffff0000, v70
	v_lshlrev_b32_e32 v15, 16, v70
	v_and_b32_e32 v16, 0xffff0000, v71
	v_lshlrev_b32_e32 v17, 16, v71
	v_pk_fma_f32 v[10:11], v[196:197], v[14:15], v[10:11] op_sel:[1,0,0] op_sel_hi:[1,1,1]
	v_pk_fma_f32 v[12:13], v[196:197], v[16:17], v[12:13] op_sel:[1,0,0] op_sel_hi:[1,1,1]
	v_and_b32_e32 v14, 0xffff0000, v68
	v_lshlrev_b32_e32 v15, 16, v68
	v_and_b32_e32 v16, 0xffff0000, v69
	v_lshlrev_b32_e32 v17, 16, v69
	v_pk_fma_f32 v[10:11], v[196:197], v[14:15], v[10:11] op_sel_hi:[0,1,1]
	v_pk_fma_f32 v[12:13], v[196:197], v[16:17], v[12:13] op_sel_hi:[0,1,1]
	v_and_b32_e32 v14, 0xffff0000, v66
	v_lshlrev_b32_e32 v15, 16, v66
	v_and_b32_e32 v16, 0xffff0000, v67
	v_lshlrev_b32_e32 v17, 16, v67
	v_pk_fma_f32 v[10:11], v[194:195], v[14:15], v[10:11] op_sel:[1,0,0] op_sel_hi:[1,1,1]
	v_pk_fma_f32 v[12:13], v[194:195], v[16:17], v[12:13] op_sel:[1,0,0] op_sel_hi:[1,1,1]
	v_and_b32_e32 v14, 0xffff0000, v64
	v_lshlrev_b32_e32 v15, 16, v64
	v_and_b32_e32 v16, 0xffff0000, v65
	v_lshlrev_b32_e32 v17, 16, v65
	v_pk_fma_f32 v[10:11], v[194:195], v[14:15], v[10:11] op_sel_hi:[0,1,1]
	v_pk_fma_f32 v[12:13], v[194:195], v[16:17], v[12:13] op_sel_hi:[0,1,1]
	v_and_b32_e32 v14, 0xffff0000, v62
	v_lshlrev_b32_e32 v15, 16, v62
	v_and_b32_e32 v16, 0xffff0000, v63
	v_lshlrev_b32_e32 v17, 16, v63
	v_pk_fma_f32 v[10:11], v[192:193], v[14:15], v[10:11] op_sel:[1,0,0] op_sel_hi:[1,1,1]
	v_pk_fma_f32 v[12:13], v[192:193], v[16:17], v[12:13] op_sel:[1,0,0] op_sel_hi:[1,1,1]
	v_and_b32_e32 v14, 0xffff0000, v60
	v_lshlrev_b32_e32 v15, 16, v60
	v_and_b32_e32 v16, 0xffff0000, v61
	v_lshlrev_b32_e32 v17, 16, v61
	v_pk_fma_f32 v[10:11], v[192:193], v[14:15], v[10:11] op_sel_hi:[0,1,1]
	v_pk_fma_f32 v[12:13], v[192:193], v[16:17], v[12:13] op_sel_hi:[0,1,1]
	s_waitcnt vmcnt(47)
	v_and_b32_e32 v14, 0xffff0000, v90
	v_lshlrev_b32_e32 v15, 16, v90
	v_and_b32_e32 v16, 0xffff0000, v91
	v_lshlrev_b32_e32 v17, 16, v91
	v_pk_mul_f32 v[18:19], v[206:207], v[14:15] op_sel:[1,0] op_sel_hi:[1,1]
	v_pk_mul_f32 v[20:21], v[206:207], v[16:17] op_sel:[1,0] op_sel_hi:[1,1]
	v_pk_fma_f32 v[10:11], v[206:207], v[14:15], v[10:11] op_sel:[1,0,0] op_sel_hi:[1,1,1]
	v_pk_fma_f32 v[12:13], v[206:207], v[16:17], v[12:13] op_sel:[1,0,0] op_sel_hi:[1,1,1]
	s_cmp_eq_u32 s9, 0
	s_cselect_b32 s0, 0x3f800000, s35
	v_fma_f32 v22, s0, v11, -v19
	v_fma_f32 v23, s0, v10, -v18
	v_fma_f32 v24, s0, v13, -v21
	v_fma_f32 v25, s0, v12, -v20
	v_cvt_pk_bf16_f32 v22, v22, v23
	v_cvt_pk_bf16_f32 v23, v24, v25
	global_store_dwordx2 v8, v[22:23], s[62:63]
	v_and_b32_e32 v14, 0xffff0000, v60
	v_lshlrev_b32_e32 v15, 16, v60
	v_and_b32_e32 v16, 0xffff0000, v61
	v_lshlrev_b32_e32 v17, 16, v61
	v_pk_fma_f32 v[10:11], v[192:193], v[14:15], v[10:11] op_sel_hi:[0,1,1] neg_lo:[1,0,0] neg_hi:[1,0,0]
	v_pk_fma_f32 v[12:13], v[192:193], v[16:17], v[12:13] op_sel_hi:[0,1,1] neg_lo:[1,0,0] neg_hi:[1,0,0]
	s_waitcnt vmcnt(47)
; __device__ __forceinline__ float bflo(unsigned u) { return __uint_as_float(u << 16); }
; __device__ __forceinline__ float bfhi(unsigned u) { return __uint_as_float(u & 0xffff0000u); }
; __device__ __forceinline__ void phase_pool(const Params& p, char* smraw) {
;     ...
;       for (int k = 0; k < 8; ++k) {
;         const int tt = t8 + k, pp = c0 + tt;
;         const float rs = rstd_s[tt + 15];
;         const float x0 = bflo(cur[k][0]) * rs, x1 = bfhi(cur[k][0]) * rs, x2 = bflo(cur[k][1]) * rs, x3 = bfhi(cur[k][1]) * rs;
;         s0 += x0; s1 += x1; s2 += x2; s3 += x3;
;         const int cnt = (pp + 1 < win) ? pp + 1 : win;
;         const float inv = 1.f / (float)cnt;
;         u32x2 o; o[0] = cvtpk(s0 * inv - x0, s1 * inv - x1); o[1] = cvtpk(s2 * inv - x2, s3 * inv - x3);
;         *(u32x2*)(p.pooled + (size_t)(b * L + pp) * D + c) = o;
;         const int po = pp - win + 1;
;         if (po >= 0) {
;           const float ro = rstd_s[tt + 15 - win + 1];
;           s0 -= bflo(old[k][0]) * ro; s1 -= bfhi(old[k][0]) * ro; s2 -= bflo(old[k][1]) * ro; s3 -= bfhi(old[k][1]) * ro;
;         }
	v_and_b32_e32 v14, 0xffff0000, v92
	v_lshlrev_b32_e32 v15, 16, v92
	v_and_b32_e32 v16, 0xffff0000, v93
	v_lshlrev_b32_e32 v17, 16, v93
	v_pk_mul_f32 v[18:19], v[208:209], v[14:15] op_sel_hi:[0,1]
	v_pk_mul_f32 v[20:21], v[208:209], v[16:17] op_sel_hi:[0,1]
	v_pk_fma_f32 v[10:11], v[208:209], v[14:15], v[10:11] op_sel_hi:[0,1,1]
	v_pk_fma_f32 v[12:13], v[208:209], v[16:17], v[12:13] op_sel_hi:[0,1,1]
	s_cmp_eq_u32 s9, 0
	s_cselect_b32 s0, 0x3f000000, s35
	v_fma_f32 v26, s0, v11, -v19
	v_fma_f32 v27, s0, v10, -v18
	v_fma_f32 v28, s0, v13, -v21
	v_fma_f32 v29, s0, v12, -v20
	v_cvt_pk_bf16_f32 v26, v26, v27
	v_cvt_pk_bf16_f32 v27, v28, v29
	v_add_u32_e32 v31, 0x800, v8
	global_store_dwordx2 v31, v[26:27], s[62:63]
	v_and_b32_e32 v14, 0xffff0000, v62
	v_lshlrev_b32_e32 v15, 16, v62
	v_and_b32_e32 v16, 0xffff0000, v63
	v_lshlrev_b32_e32 v17, 16, v63
	v_pk_fma_f32 v[10:11], v[192:193], v[14:15], v[10:11] op_sel:[1,0,0] op_sel_hi:[1,1,1] neg_lo:[1,0,0] neg_hi:[1,0,0]
	v_pk_fma_f32 v[12:13], v[192:193], v[16:17], v[12:13] op_sel:[1,0,0] op_sel_hi:[1,1,1] neg_lo:[1,0,0] neg_hi:[1,0,0]
	s_waitcnt vmcnt(47)
	v_and_b32_e32 v14, 0xffff0000, v94
	v_lshlrev_b32_e32 v15, 16, v94
	v_and_b32_e32 v16, 0xffff0000, v95
	v_lshlrev_b32_e32 v17, 16, v95
	v_pk_mul_f32 v[18:19], v[208:209], v[14:15] op_sel:[1,0] op_sel_hi:[1,1]
	v_pk_mul_f32 v[20:21], v[208:209], v[16:17] op_sel:[1,0] op_sel_hi:[1,1]
	v_pk_fma_f32 v[10:11], v[208:209], v[14:15], v[10:11] op_sel:[1,0,0] op_sel_hi:[1,1,1]
	v_pk_fma_f32 v[12:13], v[208:209], v[16:17], v[12:13] op_sel:[1,0,0] op_sel_hi:[1,1,1]
	s_cmp_eq_u32 s9, 0
	s_cselect_b32 s0, 0x3eaaaaab, s35
	v_fma_f32 v22, s0, v11, -v19
	v_fma_f32 v23, s0, v10, -v18
	v_fma_f32 v24, s0, v13, -v21
	v_fma_f32 v25, s0, v12, -v20
	v_cvt_pk_bf16_f32 v22, v22, v23
	v_cvt_pk_bf16_f32 v23, v24, v25
	v_add_u32_e32 v32, 0x1000, v8
	global_store_dwordx2 v32, v[22:23], s[62:63]
	v_and_b32_e32 v14, 0xffff0000, v64
	v_lshlrev_b32_e32 v15, 16, v64
	v_and_b32_e32 v16, 0xffff0000, v65
	v_lshlrev_b32_e32 v17, 16, v65
	v_pk_fma_f32 v[10:11], v[194:195], v[14:15], v[10:11] op_sel_hi:[0,1,1] neg_lo:[1,0,0] neg_hi:[1,0,0]
	v_pk_fma_f32 v[12:13], v[194:195], v[16:17], v[12:13] op_sel_hi:[0,1,1] neg_lo:[1,0,0] neg_hi:[1,0,0]
	s_waitcnt vmcnt(47)
	v_and_b32_e32 v14, 0xffff0000, v96
	v_lshlrev_b32_e32 v15, 16, v96
	v_and_b32_e32 v16, 0xffff0000, v97
	v_lshlrev_b32_e32 v17, 16, v97
	v_pk_mul_f32 v[18:19], v[210:211], v[14:15] op_sel_hi:[0,1]
	v_pk_mul_f32 v[20:21], v[210:211], v[16:17] op_sel_hi:[0,1]
	v_pk_fma_f32 v[10:11], v[210:211], v[14:15], v[10:11] op_sel_hi:[0,1,1]
	v_pk_fma_f32 v[12:13], v[210:211], v[16:17], v[12:13] op_sel_hi:[0,1,1]
	s_cmp_eq_u32 s9, 0
	s_cselect_b32 s0, 0x3e800000, s35
	v_fma_f32 v26, s0, v11, -v19
	v_fma_f32 v27, s0, v10, -v18
	v_fma_f32 v28, s0, v13, -v21
	v_fma_f32 v29, s0, v12, -v20
	v_cvt_pk_bf16_f32 v26, v26, v27
	v_cvt_pk_bf16_f32 v27, v28, v29
	v_add_u32_e32 v33, 0x1800, v8
	global_store_dwordx2 v33, v[26:27], s[62:63]
	v_and_b32_e32 v14, 0xffff0000, v66
	v_lshlrev_b32_e32 v15, 16, v66
	v_and_b32_e32 v16, 0xffff0000, v67
	v_lshlrev_b32_e32 v17, 16, v67
	v_pk_fma_f32 v[10:11], v[194:195], v[14:15], v[10:11] op_sel:[1,0,0] op_sel_hi:[1,1,1] neg_lo:[1,0,0] neg_hi:[1,0,0]
	v_pk_fma_f32 v[12:13], v[194:195], v[16:17], v[12:13] op_sel:[1,0,0] op_sel_hi:[1,1,1] neg_lo:[1,0,0] neg_hi:[1,0,0]
	s_waitcnt vmcnt(47)
	v_and_b32_e32 v14, 0xffff0000, v98
	v_lshlrev_b32_e32 v15, 16, v98
	v_and_b32_e32 v16, 0xffff0000, v99
	v_lshlrev_b32_e32 v17, 16, v99
	v_pk_mul_f32 v[18:19], v[210:211], v[14:15] op_sel:[1,0] op_sel_hi:[1,1]
	v_pk_mul_f32 v[20:21], v[210:211], v[16:17] op_sel:[1,0] op_sel_hi:[1,1]
	v_pk_fma_f32 v[10:11], v[210:211], v[14:15], v[10:11] op_sel:[1,0,0] op_sel_hi:[1,1,1]
	v_pk_fma_f32 v[12:13], v[210:211], v[16:17], v[12:13] op_sel:[1,0,0] op_sel_hi:[1,1,1]
	s_cmp_eq_u32 s9, 0
	s_cselect_b32 s0, 0x3e4ccccd, s35
	v_fma_f32 v22, s0, v11, -v19
	v_fma_f32 v23, s0, v10, -v18
	v_fma_f32 v24, s0, v13, -v21
	v_fma_f32 v25, s0, v12, -v20
	v_cvt_pk_bf16_f32 v22, v22, v23
	v_cvt_pk_bf16_f32 v23, v24, v25
	v_add_u32_e32 v34, 0x2000, v8
	global_store_dwordx2 v34, v[22:23], s[62:63]
	v_and_b32_e32 v14, 0xffff0000, v68
	v_lshlrev_b32_e32 v15, 16, v68
	v_and_b32_e32 v16, 0xffff0000, v69
	v_lshlrev_b32_e32 v17, 16, v69
	v_pk_fma_f32 v[10:11], v[196:197], v[14:15], v[10:11] op_sel_hi:[0,1,1] neg_lo:[1,0,0] neg_hi:[1,0,0]
	v_pk_fma_f32 v[12:13], v[196:197], v[16:17], v[12:13] op_sel_hi:[0,1,1] neg_lo:[1,0,0] neg_hi:[1,0,0]
	s_waitcnt vmcnt(47)
	v_and_b32_e32 v14, 0xffff0000, v100
	v_lshlrev_b32_e32 v15, 16, v100
	v_and_b32_e32 v16, 0xffff0000, v101
	v_lshlrev_b32_e32 v17, 16, v101
	v_pk_mul_f32 v[18:19], v[212:213], v[14:15] op_sel_hi:[0,1]
	v_pk_mul_f32 v[20:21], v[212:213], v[16:17] op_sel_hi:[0,1]
	v_pk_fma_f32 v[10:11], v[212:213], v[14:15], v[10:11] op_sel_hi:[0,1,1]
	v_pk_fma_f32 v[12:13], v[212:213], v[16:17], v[12:13] op_sel_hi:[0,1,1]
	s_cmp_eq_u32 s9, 0
	s_cselect_b32 s0, 0x3e2aaaab, s35
	v_fma_f32 v26, s0, v11, -v19
	v_fma_f32 v27, s0, v10, -v18
	v_fma_f32 v28, s0, v13, -v21
	v_fma_f32 v29, s0, v12, -v20
	v_cvt_pk_bf16_f32 v26, v26, v27
	v_cvt_pk_bf16_f32 v27, v28, v29
	v_add_u32_e32 v35, 0x2800, v8
	global_store_dwordx2 v35, v[26:27], s[62:63]
	v_and_b32_e32 v14, 0xffff0000, v70
	v_lshlrev_b32_e32 v15, 16, v70
	v_and_b32_e32 v16, 0xffff0000, v71
	v_lshlrev_b32_e32 v17, 16, v71
	v_pk_fma_f32 v[10:11], v[196:197], v[14:15], v[10:11] op_sel:[1,0,0] op_sel_hi:[1,1,1] neg_lo:[1,0,0] neg_hi:[1,0,0]
	v_pk_fma_f32 v[12:13], v[196:197], v[16:17], v[12:13] op_sel:[1,0,0] op_sel_hi:[1,1,1] neg_lo:[1,0,0] neg_hi:[1,0,0]
	s_waitcnt vmcnt(47)
; __device__ __forceinline__ float bflo(unsigned u) { return __uint_as_float(u << 16); }
; __device__ __forceinline__ float bfhi(unsigned u) { return __uint_as_float(u & 0xffff0000u); }
; __device__ __forceinline__ void phase_pool(const Params& p, char* smraw) {
;     ...
; #pragma unroll
;       for (int k = 0; k < 8; ++k) {
;         const int tt = t8 + k, pp = c0 + tt;
;         const float rs = rstd_s[tt + 15];
;         const float x0 = bflo(cur[k][0]) * rs, x1 = bfhi(cur[k][0]) * rs, x2 = bflo(cur[k][1]) * rs, x3 = bfhi(cur[k][1]) * rs;
;         s0 += x0; s1 += x1; s2 += x2; s3 += x3;
;         const int cnt = (pp + 1 < win) ? pp + 1 : win;
;         const float inv = 1.f / (float)cnt;
;         u32x2 o; o[0] = cvtpk(s0 * inv - x0, s1 * inv - x1); o[1] = cvtpk(s2 * inv - x2, s3 * inv - x3);
;         *(u32x2*)(p.pooled + (size_t)(b * L + pp) * D + c) = o;
;         const int po = pp - win + 1;
;         if (po >= 0) {
;           const float ro = rstd_s[tt + 15 - win + 1];
;           s0 -= bflo(old[k][0]) * ro; s1 -= bfhi(old[k][0]) * ro; s2 -= bflo(old[k][1]) * ro; s3 -= bfhi(old[k][1]) * ro;
;         }
;       }
	v_and_b32_e32 v14, 0xffff0000, v102
	v_lshlrev_b32_e32 v15, 16, v102
	v_and_b32_e32 v16, 0xffff0000, v103
	v_lshlrev_b32_e32 v17, 16, v103
	v_pk_mul_f32 v[18:19], v[212:213], v[14:15] op_sel:[1,0] op_sel_hi:[1,1]
	v_pk_mul_f32 v[20:21], v[212:213], v[16:17] op_sel:[1,0] op_sel_hi:[1,1]
	v_pk_fma_f32 v[10:11], v[212:213], v[14:15], v[10:11] op_sel:[1,0,0] op_sel_hi:[1,1,1]
	v_pk_fma_f32 v[12:13], v[212:213], v[16:17], v[12:13] op_sel:[1,0,0] op_sel_hi:[1,1,1]
	s_cmp_eq_u32 s9, 0
	s_cselect_b32 s0, 0x3e124925, s35
	v_fma_f32 v22, s0, v11, -v19
	v_fma_f32 v23, s0, v10, -v18
	v_fma_f32 v24, s0, v13, -v21
	v_fma_f32 v25, s0, v12, -v20
	v_cvt_pk_bf16_f32 v22, v22, v23
	v_cvt_pk_bf16_f32 v23, v24, v25
	v_add_u32_e32 v36, 0x3000, v8
	global_store_dwordx2 v36, v[22:23], s[62:63]
	v_and_b32_e32 v14, 0xffff0000, v72
	v_lshlrev_b32_e32 v15, 16, v72
	v_and_b32_e32 v16, 0xffff0000, v73
	v_lshlrev_b32_e32 v17, 16, v73
	v_pk_fma_f32 v[10:11], v[198:199], v[14:15], v[10:11] op_sel_hi:[0,1,1] neg_lo:[1,0,0] neg_hi:[1,0,0]
	v_pk_fma_f32 v[12:13], v[198:199], v[16:17], v[12:13] op_sel_hi:[0,1,1] neg_lo:[1,0,0] neg_hi:[1,0,0]
	s_waitcnt vmcnt(47)
	v_and_b32_e32 v14, 0xffff0000, v104
	v_lshlrev_b32_e32 v15, 16, v104
	v_and_b32_e32 v16, 0xffff0000, v105
	v_lshlrev_b32_e32 v17, 16, v105
	v_pk_mul_f32 v[18:19], v[214:215], v[14:15] op_sel_hi:[0,1]
	v_pk_mul_f32 v[20:21], v[214:215], v[16:17] op_sel_hi:[0,1]
	v_pk_fma_f32 v[10:11], v[214:215], v[14:15], v[10:11] op_sel_hi:[0,1,1]
	v_pk_fma_f32 v[12:13], v[214:215], v[16:17], v[12:13] op_sel_hi:[0,1,1]
	s_cmp_eq_u32 s9, 0
	s_cselect_b32 s0, 0x3e000000, s35
	v_fma_f32 v26, s0, v11, -v19
	v_fma_f32 v27, s0, v10, -v18
	v_fma_f32 v28, s0, v13, -v21
	v_fma_f32 v29, s0, v12, -v20
	v_cvt_pk_bf16_f32 v26, v26, v27
	v_cvt_pk_bf16_f32 v27, v28, v29
	v_add_u32_e32 v37, 0x3800, v8
	global_store_dwordx2 v37, v[26:27], s[62:63]
	v_and_b32_e32 v14, 0xffff0000, v74
	v_lshlrev_b32_e32 v15, 16, v74
	v_and_b32_e32 v16, 0xffff0000, v75
	v_lshlrev_b32_e32 v17, 16, v75
	v_pk_fma_f32 v[10:11], v[198:199], v[14:15], v[10:11] op_sel:[1,0,0] op_sel_hi:[1,1,1] neg_lo:[1,0,0] neg_hi:[1,0,0]
	v_pk_fma_f32 v[12:13], v[198:199], v[16:17], v[12:13] op_sel:[1,0,0] op_sel_hi:[1,1,1] neg_lo:[1,0,0] neg_hi:[1,0,0]
	s_waitcnt vmcnt(47)
	v_and_b32_e32 v14, 0xffff0000, v106
	v_lshlrev_b32_e32 v15, 16, v106
	v_and_b32_e32 v16, 0xffff0000, v107
	v_lshlrev_b32_e32 v17, 16, v107
	v_pk_mul_f32 v[18:19], v[214:215], v[14:15] op_sel:[1,0] op_sel_hi:[1,1]
	v_pk_mul_f32 v[20:21], v[214:215], v[16:17] op_sel:[1,0] op_sel_hi:[1,1]
	v_pk_fma_f32 v[10:11], v[214:215], v[14:15], v[10:11] op_sel:[1,0,0] op_sel_hi:[1,1,1]
	v_pk_fma_f32 v[12:13], v[214:215], v[16:17], v[12:13] op_sel:[1,0,0] op_sel_hi:[1,1,1]
	s_cmp_eq_u32 s9, 0
	s_cselect_b32 s0, 0x3de38e39, s35
	v_fma_f32 v22, s0, v11, -v19
	v_fma_f32 v23, s0, v10, -v18
	v_fma_f32 v24, s0, v13, -v21
	v_fma_f32 v25, s0, v12, -v20
	v_cvt_pk_bf16_f32 v22, v22, v23
	v_cvt_pk_bf16_f32 v23, v24, v25
	v_add_u32_e32 v30, 0x4000, v8
	global_store_dwordx2 v30, v[22:23], s[62:63]
	v_and_b32_e32 v14, 0xffff0000, v76
	v_lshlrev_b32_e32 v15, 16, v76
	v_and_b32_e32 v16, 0xffff0000, v77
	v_lshlrev_b32_e32 v17, 16, v77
	v_pk_fma_f32 v[10:11], v[200:201], v[14:15], v[10:11] op_sel_hi:[0,1,1] neg_lo:[1,0,0] neg_hi:[1,0,0]
	v_pk_fma_f32 v[12:13], v[200:201], v[16:17], v[12:13] op_sel_hi:[0,1,1] neg_lo:[1,0,0] neg_hi:[1,0,0]
	s_waitcnt vmcnt(47)
	v_and_b32_e32 v14, 0xffff0000, v108
	v_lshlrev_b32_e32 v15, 16, v108
	v_and_b32_e32 v16, 0xffff0000, v109
	v_lshlrev_b32_e32 v17, 16, v109
	v_pk_mul_f32 v[18:19], v[216:217], v[14:15] op_sel_hi:[0,1]
	v_pk_mul_f32 v[20:21], v[216:217], v[16:17] op_sel_hi:[0,1]
	v_pk_fma_f32 v[10:11], v[216:217], v[14:15], v[10:11] op_sel_hi:[0,1,1]
	v_pk_fma_f32 v[12:13], v[216:217], v[16:17], v[12:13] op_sel_hi:[0,1,1]
	s_cmp_eq_u32 s9, 0
	s_cselect_b32 s0, 0x3dcccccd, s35
	v_fma_f32 v26, s0, v11, -v19
	v_fma_f32 v27, s0, v10, -v18
	v_fma_f32 v28, s0, v13, -v21
	v_fma_f32 v29, s0, v12, -v20
	v_cvt_pk_bf16_f32 v26, v26, v27
	v_cvt_pk_bf16_f32 v27, v28, v29
	v_add_u32_e32 v31, 0x4800, v8
	global_store_dwordx2 v31, v[26:27], s[62:63]
	v_and_b32_e32 v14, 0xffff0000, v78
	v_lshlrev_b32_e32 v15, 16, v78
	v_and_b32_e32 v16, 0xffff0000, v79
	v_lshlrev_b32_e32 v17, 16, v79
	v_pk_fma_f32 v[10:11], v[200:201], v[14:15], v[10:11] op_sel:[1,0,0] op_sel_hi:[1,1,1] neg_lo:[1,0,0] neg_hi:[1,0,0]
	v_pk_fma_f32 v[12:13], v[200:201], v[16:17], v[12:13] op_sel:[1,0,0] op_sel_hi:[1,1,1] neg_lo:[1,0,0] neg_hi:[1,0,0]
	s_waitcnt vmcnt(47)
	v_and_b32_e32 v14, 0xffff0000, v110
	v_lshlrev_b32_e32 v15, 16, v110
	v_and_b32_e32 v16, 0xffff0000, v111
	v_lshlrev_b32_e32 v17, 16, v111
	v_pk_mul_f32 v[18:19], v[216:217], v[14:15] op_sel:[1,0] op_sel_hi:[1,1]
	v_pk_mul_f32 v[20:21], v[216:217], v[16:17] op_sel:[1,0] op_sel_hi:[1,1]
	v_pk_fma_f32 v[10:11], v[216:217], v[14:15], v[10:11] op_sel:[1,0,0] op_sel_hi:[1,1,1]
	v_pk_fma_f32 v[12:13], v[216:217], v[16:17], v[12:13] op_sel:[1,0,0] op_sel_hi:[1,1,1]
	s_cmp_eq_u32 s9, 0
	s_cselect_b32 s0, 0x3dba2e8c, s35
	v_fma_f32 v22, s0, v11, -v19
	v_fma_f32 v23, s0, v10, -v18
	v_fma_f32 v24, s0, v13, -v21
	v_fma_f32 v25, s0, v12, -v20
	v_cvt_pk_bf16_f32 v22, v22, v23
	v_cvt_pk_bf16_f32 v23, v24, v25
	v_add_u32_e32 v32, 0x5000, v8
	global_store_dwordx2 v32, v[22:23], s[62:63]
	v_and_b32_e32 v14, 0xffff0000, v80
	v_lshlrev_b32_e32 v15, 16, v80
	v_and_b32_e32 v16, 0xffff0000, v81
	v_lshlrev_b32_e32 v17, 16, v81
	v_pk_fma_f32 v[10:11], v[202:203], v[14:15], v[10:11] op_sel_hi:[0,1,1] neg_lo:[1,0,0] neg_hi:[1,0,0]
	v_pk_fma_f32 v[12:13], v[202:203], v[16:17], v[12:13] op_sel_hi:[0,1,1] neg_lo:[1,0,0] neg_hi:[1,0,0]
	s_waitcnt vmcnt(47)
; __device__ __forceinline__ float bflo(unsigned u) { return __uint_as_float(u << 16); }
; __device__ __forceinline__ float bfhi(unsigned u) { return __uint_as_float(u & 0xffff0000u); }
; __device__ __forceinline__ void phase_pool(const Params& p, char* smraw) {
;     ...
; #pragma unroll
;       for (int k = 0; k < 8; ++k) {
;         const int tt = t8 + k, pp = c0 + tt;
;         const float rs = rstd_s[tt + 15];
;         const float x0 = bflo(cur[k][0]) * rs, x1 = bfhi(cur[k][0]) * rs, x2 = bflo(cur[k][1]) * rs, x3 = bfhi(cur[k][1]) * rs;
;         s0 += x0; s1 += x1; s2 += x2; s3 += x3;
;         const int cnt = (pp + 1 < win) ? pp + 1 : win;
;         const float inv = 1.f / (float)cnt;
;         u32x2 o; o[0] = cvtpk(s0 * inv - x0, s1 * inv - x1); o[1] = cvtpk(s2 * inv - x2, s3 * inv - x3);
;         *(u32x2*)(p.pooled + (size_t)(b * L + pp) * D + c) = o;
;         const int po = pp - win + 1;
;         if (po >= 0) {
;           const float ro = rstd_s[tt + 15 - win + 1];
;           s0 -= bflo(old[k][0]) * ro; s1 -= bfhi(old[k][0]) * ro; s2 -= bflo(old[k][1]) * ro; s3 -= bfhi(old[k][1]) * ro;
;         }
;       }
	v_and_b32_e32 v14, 0xffff0000, v112
	v_lshlrev_b32_e32 v15, 16, v112
	v_and_b32_e32 v16, 0xffff0000, v113
	v_lshlrev_b32_e32 v17, 16, v113
	v_pk_mul_f32 v[18:19], v[218:219], v[14:15] op_sel_hi:[0,1]
	v_pk_mul_f32 v[20:21], v[218:219], v[16:17] op_sel_hi:[0,1]
	v_pk_fma_f32 v[10:11], v[218:219], v[14:15], v[10:11] op_sel_hi:[0,1,1]
	v_pk_fma_f32 v[12:13], v[218:219], v[16:17], v[12:13] op_sel_hi:[0,1,1]
	s_cmp_eq_u32 s9, 0
	s_cselect_b32 s0, 0x3daaaaab, s35
	v_fma_f32 v26, s0, v11, -v19
	v_fma_f32 v27, s0, v10, -v18
	v_fma_f32 v28, s0, v13, -v21
	v_fma_f32 v29, s0, v12, -v20
	v_cvt_pk_bf16_f32 v26, v26, v27
	v_cvt_pk_bf16_f32 v27, v28, v29
	v_add_u32_e32 v33, 0x5800, v8
	global_store_dwordx2 v33, v[26:27], s[62:63]
	v_and_b32_e32 v14, 0xffff0000, v82
	v_lshlrev_b32_e32 v15, 16, v82
	v_and_b32_e32 v16, 0xffff0000, v83
	v_lshlrev_b32_e32 v17, 16, v83
	v_pk_fma_f32 v[10:11], v[202:203], v[14:15], v[10:11] op_sel:[1,0,0] op_sel_hi:[1,1,1] neg_lo:[1,0,0] neg_hi:[1,0,0]
	v_pk_fma_f32 v[12:13], v[202:203], v[16:17], v[12:13] op_sel:[1,0,0] op_sel_hi:[1,1,1] neg_lo:[1,0,0] neg_hi:[1,0,0]
	s_waitcnt vmcnt(47)
	v_and_b32_e32 v14, 0xffff0000, v114
	v_lshlrev_b32_e32 v15, 16, v114
	v_and_b32_e32 v16, 0xffff0000, v115
	v_lshlrev_b32_e32 v17, 16, v115
	v_pk_mul_f32 v[18:19], v[218:219], v[14:15] op_sel:[1,0] op_sel_hi:[1,1]
	v_pk_mul_f32 v[20:21], v[218:219], v[16:17] op_sel:[1,0] op_sel_hi:[1,1]
	v_pk_fma_f32 v[10:11], v[218:219], v[14:15], v[10:11] op_sel:[1,0,0] op_sel_hi:[1,1,1]
	v_pk_fma_f32 v[12:13], v[218:219], v[16:17], v[12:13] op_sel:[1,0,0] op_sel_hi:[1,1,1]
	s_cmp_eq_u32 s9, 0
	s_cselect_b32 s0, 0x3d9d89d9, s35
	v_fma_f32 v22, s0, v11, -v19
	v_fma_f32 v23, s0, v10, -v18
	v_fma_f32 v24, s0, v13, -v21
	v_fma_f32 v25, s0, v12, -v20
	v_cvt_pk_bf16_f32 v22, v22, v23
	v_cvt_pk_bf16_f32 v23, v24, v25
	v_add_u32_e32 v34, 0x6000, v8
	global_store_dwordx2 v34, v[22:23], s[62:63]
	v_and_b32_e32 v14, 0xffff0000, v84
	v_lshlrev_b32_e32 v15, 16, v84
	v_and_b32_e32 v16, 0xffff0000, v85
	v_lshlrev_b32_e32 v17, 16, v85
	v_pk_fma_f32 v[10:11], v[204:205], v[14:15], v[10:11] op_sel_hi:[0,1,1] neg_lo:[1,0,0] neg_hi:[1,0,0]
	v_pk_fma_f32 v[12:13], v[204:205], v[16:17], v[12:13] op_sel_hi:[0,1,1] neg_lo:[1,0,0] neg_hi:[1,0,0]
	s_waitcnt vmcnt(47)
	v_and_b32_e32 v14, 0xffff0000, v116
	v_lshlrev_b32_e32 v15, 16, v116
	v_and_b32_e32 v16, 0xffff0000, v117
	v_lshlrev_b32_e32 v17, 16, v117
	v_pk_mul_f32 v[18:19], v[220:221], v[14:15] op_sel_hi:[0,1]
	v_pk_mul_f32 v[20:21], v[220:221], v[16:17] op_sel_hi:[0,1]
	v_pk_fma_f32 v[10:11], v[220:221], v[14:15], v[10:11] op_sel_hi:[0,1,1]
	v_pk_fma_f32 v[12:13], v[220:221], v[16:17], v[12:13] op_sel_hi:[0,1,1]
	s_cmp_eq_u32 s9, 0
	s_cselect_b32 s0, 0x3d924925, s35
	v_fma_f32 v26, s0, v11, -v19
	v_fma_f32 v27, s0, v10, -v18
	v_fma_f32 v28, s0, v13, -v21
	v_fma_f32 v29, s0, v12, -v20
	v_cvt_pk_bf16_f32 v26, v26, v27
	v_cvt_pk_bf16_f32 v27, v28, v29
	v_add_u32_e32 v35, 0x6800, v8
	global_store_dwordx2 v35, v[26:27], s[62:63]
	v_and_b32_e32 v14, 0xffff0000, v86
	v_lshlrev_b32_e32 v15, 16, v86
	v_and_b32_e32 v16, 0xffff0000, v87
	v_lshlrev_b32_e32 v17, 16, v87
	v_pk_fma_f32 v[10:11], v[204:205], v[14:15], v[10:11] op_sel:[1,0,0] op_sel_hi:[1,1,1] neg_lo:[1,0,0] neg_hi:[1,0,0]
	v_pk_fma_f32 v[12:13], v[204:205], v[16:17], v[12:13] op_sel:[1,0,0] op_sel_hi:[1,1,1] neg_lo:[1,0,0] neg_hi:[1,0,0]
	s_waitcnt vmcnt(47)
	v_and_b32_e32 v14, 0xffff0000, v118
	v_lshlrev_b32_e32 v15, 16, v118
	v_and_b32_e32 v16, 0xffff0000, v119
	v_lshlrev_b32_e32 v17, 16, v119
	v_pk_mul_f32 v[18:19], v[220:221], v[14:15] op_sel:[1,0] op_sel_hi:[1,1]
	v_pk_mul_f32 v[20:21], v[220:221], v[16:17] op_sel:[1,0] op_sel_hi:[1,1]
	v_pk_fma_f32 v[10:11], v[220:221], v[14:15], v[10:11] op_sel:[1,0,0] op_sel_hi:[1,1,1]
	v_pk_fma_f32 v[12:13], v[220:221], v[16:17], v[12:13] op_sel:[1,0,0] op_sel_hi:[1,1,1]
	s_cmp_eq_u32 s9, 0
	s_cselect_b32 s0, 0x3d888889, s35
	v_fma_f32 v22, s0, v11, -v19
	v_fma_f32 v23, s0, v10, -v18
	v_fma_f32 v24, s0, v13, -v21
	v_fma_f32 v25, s0, v12, -v20
	v_cvt_pk_bf16_f32 v22, v22, v23
	v_cvt_pk_bf16_f32 v23, v24, v25
	v_add_u32_e32 v36, 0x7000, v8
	global_store_dwordx2 v36, v[22:23], s[62:63]
	v_and_b32_e32 v14, 0xffff0000, v88
	v_lshlrev_b32_e32 v15, 16, v88
	v_and_b32_e32 v16, 0xffff0000, v89
	v_lshlrev_b32_e32 v17, 16, v89
	v_pk_fma_f32 v[10:11], v[206:207], v[14:15], v[10:11] op_sel_hi:[0,1,1] neg_lo:[1,0,0] neg_hi:[1,0,0]
	v_pk_fma_f32 v[12:13], v[206:207], v[16:17], v[12:13] op_sel_hi:[0,1,1] neg_lo:[1,0,0] neg_hi:[1,0,0]
	s_waitcnt vmcnt(47)
	v_and_b32_e32 v14, 0xffff0000, v120
	v_lshlrev_b32_e32 v15, 16, v120
	v_and_b32_e32 v16, 0xffff0000, v121
	v_lshlrev_b32_e32 v17, 16, v121
	v_pk_mul_f32 v[18:19], v[222:223], v[14:15] op_sel_hi:[0,1]
	v_pk_mul_f32 v[20:21], v[222:223], v[16:17] op_sel_hi:[0,1]
	v_pk_fma_f32 v[10:11], v[222:223], v[14:15], v[10:11] op_sel_hi:[0,1,1]
	v_pk_fma_f32 v[12:13], v[222:223], v[16:17], v[12:13] op_sel_hi:[0,1,1]
	s_mov_b32 s0, s35
	v_fma_f32 v26, s0, v11, -v19
	v_fma_f32 v27, s0, v10, -v18
	v_fma_f32 v28, s0, v13, -v21
	v_fma_f32 v29, s0, v12, -v20
	v_cvt_pk_bf16_f32 v26, v26, v27
	v_cvt_pk_bf16_f32 v27, v28, v29
	v_add_u32_e32 v37, 0x7800, v8
	global_store_dwordx2 v37, v[26:27], s[62:63]
	v_and_b32_e32 v14, 0xffff0000, v90
	v_lshlrev_b32_e32 v15, 16, v90
	v_and_b32_e32 v16, 0xffff0000, v91
	v_lshlrev_b32_e32 v17, 16, v91
	v_pk_fma_f32 v[10:11], v[206:207], v[14:15], v[10:11] op_sel:[1,0,0] op_sel_hi:[1,1,1] neg_lo:[1,0,0] neg_hi:[1,0,0]
	v_pk_fma_f32 v[12:13], v[206:207], v[16:17], v[12:13] op_sel:[1,0,0] op_sel_hi:[1,1,1] neg_lo:[1,0,0] neg_hi:[1,0,0]
	s_waitcnt vmcnt(47)
; __device__ __forceinline__ float bflo(unsigned u) { return __uint_as_float(u << 16); }
; __device__ __forceinline__ float bfhi(unsigned u) { return __uint_as_float(u & 0xffff0000u); }
; __device__ __forceinline__ void phase_pool(const Params& p, char* smraw) {
;     ...
; #pragma unroll
;       for (int k = 0; k < 8; ++k) {
;         const int tt = t8 + k, pp = c0 + tt;
;         const float rs = rstd_s[tt + 15];
;         const float x0 = bflo(cur[k][0]) * rs, x1 = bfhi(cur[k][0]) * rs, x2 = bflo(cur[k][1]) * rs, x3 = bfhi(cur[k][1]) * rs;
;         s0 += x0; s1 += x1; s2 += x2; s3 += x3;
;         const int cnt = (pp + 1 < win) ? pp + 1 : win;
;         const float inv = 1.f / (float)cnt;
;         u32x2 o; o[0] = cvtpk(s0 * inv - x0, s1 * inv - x1); o[1] = cvtpk(s2 * inv - x2, s3 * inv - x3);
;         *(u32x2*)(p.pooled + (size_t)(b * L + pp) * D + c) = o;
;         const int po = pp - win + 1;
;         if (po >= 0) {
;           const float ro = rstd_s[tt + 15 - win + 1];
;           s0 -= bflo(old[k][0]) * ro; s1 -= bfhi(old[k][0]) * ro; s2 -= bflo(old[k][1]) * ro; s3 -= bfhi(old[k][1]) * ro;
;         }
;       }
	v_and_b32_e32 v14, 0xffff0000, v122
	v_lshlrev_b32_e32 v15, 16, v122
	v_and_b32_e32 v16, 0xffff0000, v123
	v_lshlrev_b32_e32 v17, 16, v123
	v_pk_mul_f32 v[18:19], v[222:223], v[14:15] op_sel:[1,0] op_sel_hi:[1,1]
	v_pk_mul_f32 v[20:21], v[222:223], v[16:17] op_sel:[1,0] op_sel_hi:[1,1]
	v_pk_fma_f32 v[10:11], v[222:223], v[14:15], v[10:11] op_sel:[1,0,0] op_sel_hi:[1,1,1]
	v_pk_fma_f32 v[12:13], v[222:223], v[16:17], v[12:13] op_sel:[1,0,0] op_sel_hi:[1,1,1]
	v_fma_f32 v22, s0, v11, -v19
	v_fma_f32 v23, s0, v10, -v18
	v_fma_f32 v24, s0, v13, -v21
	v_fma_f32 v25, s0, v12, -v20
	v_cvt_pk_bf16_f32 v22, v22, v23
	v_cvt_pk_bf16_f32 v23, v24, v25
	v_add_u32_e32 v30, 0x8000, v8
	global_store_dwordx2 v30, v[22:23], s[62:63]
	v_and_b32_e32 v14, 0xffff0000, v92
	v_lshlrev_b32_e32 v15, 16, v92
	v_and_b32_e32 v16, 0xffff0000, v93
	v_lshlrev_b32_e32 v17, 16, v93
	v_pk_fma_f32 v[10:11], v[208:209], v[14:15], v[10:11] op_sel_hi:[0,1,1] neg_lo:[1,0,0] neg_hi:[1,0,0]
	v_pk_fma_f32 v[12:13], v[208:209], v[16:17], v[12:13] op_sel_hi:[0,1,1] neg_lo:[1,0,0] neg_hi:[1,0,0]
	s_waitcnt vmcnt(47)
	v_and_b32_e32 v14, 0xffff0000, v124
	v_lshlrev_b32_e32 v15, 16, v124
	v_and_b32_e32 v16, 0xffff0000, v125
	v_lshlrev_b32_e32 v17, 16, v125
	v_pk_mul_f32 v[18:19], v[224:225], v[14:15] op_sel_hi:[0,1]
	v_pk_mul_f32 v[20:21], v[224:225], v[16:17] op_sel_hi:[0,1]
	v_pk_fma_f32 v[10:11], v[224:225], v[14:15], v[10:11] op_sel_hi:[0,1,1]
	v_pk_fma_f32 v[12:13], v[224:225], v[16:17], v[12:13] op_sel_hi:[0,1,1]
	v_fma_f32 v26, s0, v11, -v19
	v_fma_f32 v27, s0, v10, -v18
	v_fma_f32 v28, s0, v13, -v21
	v_fma_f32 v29, s0, v12, -v20
	v_cvt_pk_bf16_f32 v26, v26, v27
	v_cvt_pk_bf16_f32 v27, v28, v29
	v_add_u32_e32 v31, 0x8800, v8
	global_store_dwordx2 v31, v[26:27], s[62:63]
	v_and_b32_e32 v14, 0xffff0000, v94
	v_lshlrev_b32_e32 v15, 16, v94
	v_and_b32_e32 v16, 0xffff0000, v95
	v_lshlrev_b32_e32 v17, 16, v95
	v_pk_fma_f32 v[10:11], v[208:209], v[14:15], v[10:11] op_sel:[1,0,0] op_sel_hi:[1,1,1] neg_lo:[1,0,0] neg_hi:[1,0,0]
	v_pk_fma_f32 v[12:13], v[208:209], v[16:17], v[12:13] op_sel:[1,0,0] op_sel_hi:[1,1,1] neg_lo:[1,0,0] neg_hi:[1,0,0]
	s_waitcnt vmcnt(47)
	v_and_b32_e32 v14, 0xffff0000, v126
	v_lshlrev_b32_e32 v15, 16, v126
	v_and_b32_e32 v16, 0xffff0000, v127
	v_lshlrev_b32_e32 v17, 16, v127
	v_pk_mul_f32 v[18:19], v[224:225], v[14:15] op_sel:[1,0] op_sel_hi:[1,1]
	v_pk_mul_f32 v[20:21], v[224:225], v[16:17] op_sel:[1,0] op_sel_hi:[1,1]
	v_pk_fma_f32 v[10:11], v[224:225], v[14:15], v[10:11] op_sel:[1,0,0] op_sel_hi:[1,1,1]
	v_pk_fma_f32 v[12:13], v[224:225], v[16:17], v[12:13] op_sel:[1,0,0] op_sel_hi:[1,1,1]
	v_fma_f32 v22, s0, v11, -v19
	v_fma_f32 v23, s0, v10, -v18
	v_fma_f32 v24, s0, v13, -v21
	v_fma_f32 v25, s0, v12, -v20
	v_cvt_pk_bf16_f32 v22, v22, v23
	v_cvt_pk_bf16_f32 v23, v24, v25
	v_add_u32_e32 v32, 0x9000, v8
	global_store_dwordx2 v32, v[22:23], s[62:63]
	v_and_b32_e32 v14, 0xffff0000, v96
	v_lshlrev_b32_e32 v15, 16, v96
	v_and_b32_e32 v16, 0xffff0000, v97
	v_lshlrev_b32_e32 v17, 16, v97
	v_pk_fma_f32 v[10:11], v[210:211], v[14:15], v[10:11] op_sel_hi:[0,1,1] neg_lo:[1,0,0] neg_hi:[1,0,0]
	v_pk_fma_f32 v[12:13], v[210:211], v[16:17], v[12:13] op_sel_hi:[0,1,1] neg_lo:[1,0,0] neg_hi:[1,0,0]
	s_waitcnt vmcnt(47)
	v_and_b32_e32 v14, 0xffff0000, v128
	v_lshlrev_b32_e32 v15, 16, v128
	v_and_b32_e32 v16, 0xffff0000, v129
	v_lshlrev_b32_e32 v17, 16, v129
	v_pk_mul_f32 v[18:19], v[226:227], v[14:15] op_sel_hi:[0,1]
	v_pk_mul_f32 v[20:21], v[226:227], v[16:17] op_sel_hi:[0,1]
	v_pk_fma_f32 v[10:11], v[226:227], v[14:15], v[10:11] op_sel_hi:[0,1,1]
	v_pk_fma_f32 v[12:13], v[226:227], v[16:17], v[12:13] op_sel_hi:[0,1,1]
	v_fma_f32 v26, s0, v11, -v19
	v_fma_f32 v27, s0, v10, -v18
	v_fma_f32 v28, s0, v13, -v21
	v_fma_f32 v29, s0, v12, -v20
	v_cvt_pk_bf16_f32 v26, v26, v27
	v_cvt_pk_bf16_f32 v27, v28, v29
	v_add_u32_e32 v33, 0x9800, v8
	global_store_dwordx2 v33, v[26:27], s[62:63]
	v_and_b32_e32 v14, 0xffff0000, v98
	v_lshlrev_b32_e32 v15, 16, v98
	v_and_b32_e32 v16, 0xffff0000, v99
	v_lshlrev_b32_e32 v17, 16, v99
	v_pk_fma_f32 v[10:11], v[210:211], v[14:15], v[10:11] op_sel:[1,0,0] op_sel_hi:[1,1,1] neg_lo:[1,0,0] neg_hi:[1,0,0]
	v_pk_fma_f32 v[12:13], v[210:211], v[16:17], v[12:13] op_sel:[1,0,0] op_sel_hi:[1,1,1] neg_lo:[1,0,0] neg_hi:[1,0,0]
	s_waitcnt vmcnt(47)
	v_and_b32_e32 v14, 0xffff0000, v130
	v_lshlrev_b32_e32 v15, 16, v130
	v_and_b32_e32 v16, 0xffff0000, v131
	v_lshlrev_b32_e32 v17, 16, v131
	v_pk_mul_f32 v[18:19], v[226:227], v[14:15] op_sel:[1,0] op_sel_hi:[1,1]
	v_pk_mul_f32 v[20:21], v[226:227], v[16:17] op_sel:[1,0] op_sel_hi:[1,1]
	v_pk_fma_f32 v[10:11], v[226:227], v[14:15], v[10:11] op_sel:[1,0,0] op_sel_hi:[1,1,1]
	v_pk_fma_f32 v[12:13], v[226:227], v[16:17], v[12:13] op_sel:[1,0,0] op_sel_hi:[1,1,1]
	v_fma_f32 v22, s0, v11, -v19
	v_fma_f32 v23, s0, v10, -v18
	v_fma_f32 v24, s0, v13, -v21
	v_fma_f32 v25, s0, v12, -v20
	v_cvt_pk_bf16_f32 v22, v22, v23
	v_cvt_pk_bf16_f32 v23, v24, v25
	v_add_u32_e32 v34, 0xa000, v8
	global_store_dwordx2 v34, v[22:23], s[62:63]
	v_and_b32_e32 v14, 0xffff0000, v100
	v_lshlrev_b32_e32 v15, 16, v100
	v_and_b32_e32 v16, 0xffff0000, v101
	v_lshlrev_b32_e32 v17, 16, v101
	v_pk_fma_f32 v[10:11], v[212:213], v[14:15], v[10:11] op_sel_hi:[0,1,1] neg_lo:[1,0,0] neg_hi:[1,0,0]
	v_pk_fma_f32 v[12:13], v[212:213], v[16:17], v[12:13] op_sel_hi:[0,1,1] neg_lo:[1,0,0] neg_hi:[1,0,0]
	s_waitcnt vmcnt(47)
; __device__ __forceinline__ float bflo(unsigned u) { return __uint_as_float(u << 16); }
; __device__ __forceinline__ float bfhi(unsigned u) { return __uint_as_float(u & 0xffff0000u); }
; __device__ __forceinline__ void phase_pool(const Params& p, char* smraw) {
;     ...
; #pragma unroll
;       for (int k = 0; k < 8; ++k) {
;         const int tt = t8 + k, pp = c0 + tt;
;         const float rs = rstd_s[tt + 15];
;         const float x0 = bflo(cur[k][0]) * rs, x1 = bfhi(cur[k][0]) * rs, x2 = bflo(cur[k][1]) * rs, x3 = bfhi(cur[k][1]) * rs;
;         s0 += x0; s1 += x1; s2 += x2; s3 += x3;
;         const int cnt = (pp + 1 < win) ? pp + 1 : win;
;         const float inv = 1.f / (float)cnt;
;         u32x2 o; o[0] = cvtpk(s0 * inv - x0, s1 * inv - x1); o[1] = cvtpk(s2 * inv - x2, s3 * inv - x3);
;         *(u32x2*)(p.pooled + (size_t)(b * L + pp) * D + c) = o;
;         const int po = pp - win + 1;
;         if (po >= 0) {
;           const float ro = rstd_s[tt + 15 - win + 1];
;           s0 -= bflo(old[k][0]) * ro; s1 -= bfhi(old[k][0]) * ro; s2 -= bflo(old[k][1]) * ro; s3 -= bfhi(old[k][1]) * ro;
;         }
;       }
	v_and_b32_e32 v14, 0xffff0000, v132
	v_lshlrev_b32_e32 v15, 16, v132
	v_and_b32_e32 v16, 0xffff0000, v133
	v_lshlrev_b32_e32 v17, 16, v133
	v_pk_mul_f32 v[18:19], v[228:229], v[14:15] op_sel_hi:[0,1]
	v_pk_mul_f32 v[20:21], v[228:229], v[16:17] op_sel_hi:[0,1]
	v_pk_fma_f32 v[10:11], v[228:229], v[14:15], v[10:11] op_sel_hi:[0,1,1]
	v_pk_fma_f32 v[12:13], v[228:229], v[16:17], v[12:13] op_sel_hi:[0,1,1]
	v_fma_f32 v26, s0, v11, -v19
	v_fma_f32 v27, s0, v10, -v18
	v_fma_f32 v28, s0, v13, -v21
	v_fma_f32 v29, s0, v12, -v20
	v_cvt_pk_bf16_f32 v26, v26, v27
	v_cvt_pk_bf16_f32 v27, v28, v29
	v_add_u32_e32 v35, 0xa800, v8
	global_store_dwordx2 v35, v[26:27], s[62:63]
	v_and_b32_e32 v14, 0xffff0000, v102
	v_lshlrev_b32_e32 v15, 16, v102
	v_and_b32_e32 v16, 0xffff0000, v103
	v_lshlrev_b32_e32 v17, 16, v103
	v_pk_fma_f32 v[10:11], v[212:213], v[14:15], v[10:11] op_sel:[1,0,0] op_sel_hi:[1,1,1] neg_lo:[1,0,0] neg_hi:[1,0,0]
	v_pk_fma_f32 v[12:13], v[212:213], v[16:17], v[12:13] op_sel:[1,0,0] op_sel_hi:[1,1,1] neg_lo:[1,0,0] neg_hi:[1,0,0]
	s_waitcnt vmcnt(47)
	v_and_b32_e32 v14, 0xffff0000, v134
	v_lshlrev_b32_e32 v15, 16, v134
	v_and_b32_e32 v16, 0xffff0000, v135
	v_lshlrev_b32_e32 v17, 16, v135
	v_pk_mul_f32 v[18:19], v[228:229], v[14:15] op_sel:[1,0] op_sel_hi:[1,1]
	v_pk_mul_f32 v[20:21], v[228:229], v[16:17] op_sel:[1,0] op_sel_hi:[1,1]
	v_pk_fma_f32 v[10:11], v[228:229], v[14:15], v[10:11] op_sel:[1,0,0] op_sel_hi:[1,1,1]
	v_pk_fma_f32 v[12:13], v[228:229], v[16:17], v[12:13] op_sel:[1,0,0] op_sel_hi:[1,1,1]
	v_fma_f32 v22, s0, v11, -v19
	v_fma_f32 v23, s0, v10, -v18
	v_fma_f32 v24, s0, v13, -v21
	v_fma_f32 v25, s0, v12, -v20
	v_cvt_pk_bf16_f32 v22, v22, v23
	v_cvt_pk_bf16_f32 v23, v24, v25
	v_add_u32_e32 v36, 0xb000, v8
	global_store_dwordx2 v36, v[22:23], s[62:63]
	v_and_b32_e32 v14, 0xffff0000, v104
	v_lshlrev_b32_e32 v15, 16, v104
	v_and_b32_e32 v16, 0xffff0000, v105
	v_lshlrev_b32_e32 v17, 16, v105
	v_pk_fma_f32 v[10:11], v[214:215], v[14:15], v[10:11] op_sel_hi:[0,1,1] neg_lo:[1,0,0] neg_hi:[1,0,0]
	v_pk_fma_f32 v[12:13], v[214:215], v[16:17], v[12:13] op_sel_hi:[0,1,1] neg_lo:[1,0,0] neg_hi:[1,0,0]
	s_waitcnt vmcnt(47)
	v_and_b32_e32 v14, 0xffff0000, v136
	v_lshlrev_b32_e32 v15, 16, v136
	v_and_b32_e32 v16, 0xffff0000, v137
	v_lshlrev_b32_e32 v17, 16, v137
	v_pk_mul_f32 v[18:19], v[230:231], v[14:15] op_sel_hi:[0,1]
	v_pk_mul_f32 v[20:21], v[230:231], v[16:17] op_sel_hi:[0,1]
	v_pk_fma_f32 v[10:11], v[230:231], v[14:15], v[10:11] op_sel_hi:[0,1,1]
	v_pk_fma_f32 v[12:13], v[230:231], v[16:17], v[12:13] op_sel_hi:[0,1,1]
	v_fma_f32 v26, s0, v11, -v19
	v_fma_f32 v27, s0, v10, -v18
	v_fma_f32 v28, s0, v13, -v21
	v_fma_f32 v29, s0, v12, -v20
	v_cvt_pk_bf16_f32 v26, v26, v27
	v_cvt_pk_bf16_f32 v27, v28, v29
	v_add_u32_e32 v37, 0xb800, v8
	global_store_dwordx2 v37, v[26:27], s[62:63]
	v_and_b32_e32 v14, 0xffff0000, v106
	v_lshlrev_b32_e32 v15, 16, v106
	v_and_b32_e32 v16, 0xffff0000, v107
	v_lshlrev_b32_e32 v17, 16, v107
	v_pk_fma_f32 v[10:11], v[214:215], v[14:15], v[10:11] op_sel:[1,0,0] op_sel_hi:[1,1,1] neg_lo:[1,0,0] neg_hi:[1,0,0]
	v_pk_fma_f32 v[12:13], v[214:215], v[16:17], v[12:13] op_sel:[1,0,0] op_sel_hi:[1,1,1] neg_lo:[1,0,0] neg_hi:[1,0,0]
	s_waitcnt vmcnt(47)
	v_and_b32_e32 v14, 0xffff0000, v138
	v_lshlrev_b32_e32 v15, 16, v138
	v_and_b32_e32 v16, 0xffff0000, v139
	v_lshlrev_b32_e32 v17, 16, v139
	v_pk_mul_f32 v[18:19], v[230:231], v[14:15] op_sel:[1,0] op_sel_hi:[1,1]
	v_pk_mul_f32 v[20:21], v[230:231], v[16:17] op_sel:[1,0] op_sel_hi:[1,1]
	v_pk_fma_f32 v[10:11], v[230:231], v[14:15], v[10:11] op_sel:[1,0,0] op_sel_hi:[1,1,1]
	v_pk_fma_f32 v[12:13], v[230:231], v[16:17], v[12:13] op_sel:[1,0,0] op_sel_hi:[1,1,1]
	v_fma_f32 v22, s0, v11, -v19
	v_fma_f32 v23, s0, v10, -v18
	v_fma_f32 v24, s0, v13, -v21
	v_fma_f32 v25, s0, v12, -v20
	v_cvt_pk_bf16_f32 v22, v22, v23
	v_cvt_pk_bf16_f32 v23, v24, v25
	v_add_u32_e32 v30, 0xc000, v8
	global_store_dwordx2 v30, v[22:23], s[62:63]
	v_and_b32_e32 v14, 0xffff0000, v108
	v_lshlrev_b32_e32 v15, 16, v108
	v_and_b32_e32 v16, 0xffff0000, v109
	v_lshlrev_b32_e32 v17, 16, v109
	v_pk_fma_f32 v[10:11], v[216:217], v[14:15], v[10:11] op_sel_hi:[0,1,1] neg_lo:[1,0,0] neg_hi:[1,0,0]
	v_pk_fma_f32 v[12:13], v[216:217], v[16:17], v[12:13] op_sel_hi:[0,1,1] neg_lo:[1,0,0] neg_hi:[1,0,0]
	s_waitcnt vmcnt(47)
	v_and_b32_e32 v14, 0xffff0000, v140
	v_lshlrev_b32_e32 v15, 16, v140
	v_and_b32_e32 v16, 0xffff0000, v141
	v_lshlrev_b32_e32 v17, 16, v141
	v_pk_mul_f32 v[18:19], v[232:233], v[14:15] op_sel_hi:[0,1]
	v_pk_mul_f32 v[20:21], v[232:233], v[16:17] op_sel_hi:[0,1]
	v_pk_fma_f32 v[10:11], v[232:233], v[14:15], v[10:11] op_sel_hi:[0,1,1]
	v_pk_fma_f32 v[12:13], v[232:233], v[16:17], v[12:13] op_sel_hi:[0,1,1]
	v_fma_f32 v26, s0, v11, -v19
	v_fma_f32 v27, s0, v10, -v18
	v_fma_f32 v28, s0, v13, -v21
	v_fma_f32 v29, s0, v12, -v20
	v_cvt_pk_bf16_f32 v26, v26, v27
	v_cvt_pk_bf16_f32 v27, v28, v29
	v_add_u32_e32 v31, 0xc800, v8
	global_store_dwordx2 v31, v[26:27], s[62:63]
	v_and_b32_e32 v14, 0xffff0000, v110
	v_lshlrev_b32_e32 v15, 16, v110
	v_and_b32_e32 v16, 0xffff0000, v111
	v_lshlrev_b32_e32 v17, 16, v111
	v_pk_fma_f32 v[10:11], v[216:217], v[14:15], v[10:11] op_sel:[1,0,0] op_sel_hi:[1,1,1] neg_lo:[1,0,0] neg_hi:[1,0,0]
	v_pk_fma_f32 v[12:13], v[216:217], v[16:17], v[12:13] op_sel:[1,0,0] op_sel_hi:[1,1,1] neg_lo:[1,0,0] neg_hi:[1,0,0]
	s_waitcnt vmcnt(47)
; __device__ __forceinline__ float bflo(unsigned u) { return __uint_as_float(u << 16); }
; __device__ __forceinline__ float bfhi(unsigned u) { return __uint_as_float(u & 0xffff0000u); }
; __device__ __forceinline__ void phase_pool(const Params& p, char* smraw) {
;     ...
; #pragma unroll
;       for (int k = 0; k < 8; ++k) {
;         const int tt = t8 + k, pp = c0 + tt;
;         const float rs = rstd_s[tt + 15];
;         const float x0 = bflo(cur[k][0]) * rs, x1 = bfhi(cur[k][0]) * rs, x2 = bflo(cur[k][1]) * rs, x3 = bfhi(cur[k][1]) * rs;
;         s0 += x0; s1 += x1; s2 += x2; s3 += x3;
;         const int cnt = (pp + 1 < win) ? pp + 1 : win;
;         const float inv = 1.f / (float)cnt;
;         u32x2 o; o[0] = cvtpk(s0 * inv - x0, s1 * inv - x1); o[1] = cvtpk(s2 * inv - x2, s3 * inv - x3);
;         *(u32x2*)(p.pooled + (size_t)(b * L + pp) * D + c) = o;
;         const int po = pp - win + 1;
;         if (po >= 0) {
;           const float ro = rstd_s[tt + 15 - win + 1];
;           s0 -= bflo(old[k][0]) * ro; s1 -= bfhi(old[k][0]) * ro; s2 -= bflo(old[k][1]) * ro; s3 -= bfhi(old[k][1]) * ro;
;         }
;       }
	v_and_b32_e32 v14, 0xffff0000, v142
	v_lshlrev_b32_e32 v15, 16, v142
	v_and_b32_e32 v16, 0xffff0000, v143
	v_lshlrev_b32_e32 v17, 16, v143
	v_pk_mul_f32 v[18:19], v[232:233], v[14:15] op_sel:[1,0] op_sel_hi:[1,1]
	v_pk_mul_f32 v[20:21], v[232:233], v[16:17] op_sel:[1,0] op_sel_hi:[1,1]
	v_pk_fma_f32 v[10:11], v[232:233], v[14:15], v[10:11] op_sel:[1,0,0] op_sel_hi:[1,1,1]
	v_pk_fma_f32 v[12:13], v[232:233], v[16:17], v[12:13] op_sel:[1,0,0] op_sel_hi:[1,1,1]
	v_fma_f32 v22, s0, v11, -v19
	v_fma_f32 v23, s0, v10, -v18
	v_fma_f32 v24, s0, v13, -v21
	v_fma_f32 v25, s0, v12, -v20
	v_cvt_pk_bf16_f32 v22, v22, v23
	v_cvt_pk_bf16_f32 v23, v24, v25
	v_add_u32_e32 v32, 0xd000, v8
	global_store_dwordx2 v32, v[22:23], s[62:63]
	v_and_b32_e32 v14, 0xffff0000, v112
	v_lshlrev_b32_e32 v15, 16, v112
	v_and_b32_e32 v16, 0xffff0000, v113
	v_lshlrev_b32_e32 v17, 16, v113
	v_pk_fma_f32 v[10:11], v[218:219], v[14:15], v[10:11] op_sel_hi:[0,1,1] neg_lo:[1,0,0] neg_hi:[1,0,0]
	v_pk_fma_f32 v[12:13], v[218:219], v[16:17], v[12:13] op_sel_hi:[0,1,1] neg_lo:[1,0,0] neg_hi:[1,0,0]
	s_waitcnt vmcnt(47)
	v_and_b32_e32 v14, 0xffff0000, v144
	v_lshlrev_b32_e32 v15, 16, v144
	v_and_b32_e32 v16, 0xffff0000, v145
	v_lshlrev_b32_e32 v17, 16, v145
	v_pk_mul_f32 v[18:19], v[234:235], v[14:15] op_sel_hi:[0,1]
	v_pk_mul_f32 v[20:21], v[234:235], v[16:17] op_sel_hi:[0,1]
	v_pk_fma_f32 v[10:11], v[234:235], v[14:15], v[10:11] op_sel_hi:[0,1,1]
	v_pk_fma_f32 v[12:13], v[234:235], v[16:17], v[12:13] op_sel_hi:[0,1,1]
	v_fma_f32 v26, s0, v11, -v19
	v_fma_f32 v27, s0, v10, -v18
	v_fma_f32 v28, s0, v13, -v21
	v_fma_f32 v29, s0, v12, -v20
	v_cvt_pk_bf16_f32 v26, v26, v27
	v_cvt_pk_bf16_f32 v27, v28, v29
	v_add_u32_e32 v33, 0xd800, v8
	global_store_dwordx2 v33, v[26:27], s[62:63]
	v_and_b32_e32 v14, 0xffff0000, v114
	v_lshlrev_b32_e32 v15, 16, v114
	v_and_b32_e32 v16, 0xffff0000, v115
	v_lshlrev_b32_e32 v17, 16, v115
	v_pk_fma_f32 v[10:11], v[218:219], v[14:15], v[10:11] op_sel:[1,0,0] op_sel_hi:[1,1,1] neg_lo:[1,0,0] neg_hi:[1,0,0]
	v_pk_fma_f32 v[12:13], v[218:219], v[16:17], v[12:13] op_sel:[1,0,0] op_sel_hi:[1,1,1] neg_lo:[1,0,0] neg_hi:[1,0,0]
	s_waitcnt vmcnt(47)
	v_and_b32_e32 v14, 0xffff0000, v146
	v_lshlrev_b32_e32 v15, 16, v146
	v_and_b32_e32 v16, 0xffff0000, v147
	v_lshlrev_b32_e32 v17, 16, v147
	v_pk_mul_f32 v[18:19], v[234:235], v[14:15] op_sel:[1,0] op_sel_hi:[1,1]
	v_pk_mul_f32 v[20:21], v[234:235], v[16:17] op_sel:[1,0] op_sel_hi:[1,1]
	v_pk_fma_f32 v[10:11], v[234:235], v[14:15], v[10:11] op_sel:[1,0,0] op_sel_hi:[1,1,1]
	v_pk_fma_f32 v[12:13], v[234:235], v[16:17], v[12:13] op_sel:[1,0,0] op_sel_hi:[1,1,1]
	v_fma_f32 v22, s0, v11, -v19
	v_fma_f32 v23, s0, v10, -v18
	v_fma_f32 v24, s0, v13, -v21
	v_fma_f32 v25, s0, v12, -v20
	v_cvt_pk_bf16_f32 v22, v22, v23
	v_cvt_pk_bf16_f32 v23, v24, v25
	v_add_u32_e32 v34, 0xe000, v8
	global_store_dwordx2 v34, v[22:23], s[62:63]
	v_and_b32_e32 v14, 0xffff0000, v116
	v_lshlrev_b32_e32 v15, 16, v116
	v_and_b32_e32 v16, 0xffff0000, v117
	v_lshlrev_b32_e32 v17, 16, v117
	v_pk_fma_f32 v[10:11], v[220:221], v[14:15], v[10:11] op_sel_hi:[0,1,1] neg_lo:[1,0,0] neg_hi:[1,0,0]
	v_pk_fma_f32 v[12:13], v[220:221], v[16:17], v[12:13] op_sel_hi:[0,1,1] neg_lo:[1,0,0] neg_hi:[1,0,0]
	s_waitcnt vmcnt(47)
	v_and_b32_e32 v14, 0xffff0000, v148
	v_lshlrev_b32_e32 v15, 16, v148
	v_and_b32_e32 v16, 0xffff0000, v149
	v_lshlrev_b32_e32 v17, 16, v149
	v_pk_mul_f32 v[18:19], v[236:237], v[14:15] op_sel_hi:[0,1]
	v_pk_mul_f32 v[20:21], v[236:237], v[16:17] op_sel_hi:[0,1]
	v_pk_fma_f32 v[10:11], v[236:237], v[14:15], v[10:11] op_sel_hi:[0,1,1]
	v_pk_fma_f32 v[12:13], v[236:237], v[16:17], v[12:13] op_sel_hi:[0,1,1]
	v_fma_f32 v26, s0, v11, -v19
	v_fma_f32 v27, s0, v10, -v18
	v_fma_f32 v28, s0, v13, -v21
	v_fma_f32 v29, s0, v12, -v20
	v_cvt_pk_bf16_f32 v26, v26, v27
	v_cvt_pk_bf16_f32 v27, v28, v29
	v_add_u32_e32 v35, 0xe800, v8
	global_store_dwordx2 v35, v[26:27], s[62:63]
	v_and_b32_e32 v14, 0xffff0000, v118
	v_lshlrev_b32_e32 v15, 16, v118
	v_and_b32_e32 v16, 0xffff0000, v119
	v_lshlrev_b32_e32 v17, 16, v119
	v_pk_fma_f32 v[10:11], v[220:221], v[14:15], v[10:11] op_sel:[1,0,0] op_sel_hi:[1,1,1] neg_lo:[1,0,0] neg_hi:[1,0,0]
	v_pk_fma_f32 v[12:13], v[220:221], v[16:17], v[12:13] op_sel:[1,0,0] op_sel_hi:[1,1,1] neg_lo:[1,0,0] neg_hi:[1,0,0]
	s_waitcnt vmcnt(47)
	v_and_b32_e32 v14, 0xffff0000, v150
	v_lshlrev_b32_e32 v15, 16, v150
	v_and_b32_e32 v16, 0xffff0000, v151
	v_lshlrev_b32_e32 v17, 16, v151
	v_pk_mul_f32 v[18:19], v[236:237], v[14:15] op_sel:[1,0] op_sel_hi:[1,1]
	v_pk_mul_f32 v[20:21], v[236:237], v[16:17] op_sel:[1,0] op_sel_hi:[1,1]
	v_pk_fma_f32 v[10:11], v[236:237], v[14:15], v[10:11] op_sel:[1,0,0] op_sel_hi:[1,1,1]
	v_pk_fma_f32 v[12:13], v[236:237], v[16:17], v[12:13] op_sel:[1,0,0] op_sel_hi:[1,1,1]
	v_fma_f32 v22, s0, v11, -v19
	v_fma_f32 v23, s0, v10, -v18
	v_fma_f32 v24, s0, v13, -v21
	v_fma_f32 v25, s0, v12, -v20
	v_cvt_pk_bf16_f32 v22, v22, v23
	v_cvt_pk_bf16_f32 v23, v24, v25
	v_add_u32_e32 v36, 0xf000, v8
	global_store_dwordx2 v36, v[22:23], s[62:63]
	v_and_b32_e32 v14, 0xffff0000, v120
	v_lshlrev_b32_e32 v15, 16, v120
	v_and_b32_e32 v16, 0xffff0000, v121
	v_lshlrev_b32_e32 v17, 16, v121
	v_pk_fma_f32 v[10:11], v[222:223], v[14:15], v[10:11] op_sel_hi:[0,1,1] neg_lo:[1,0,0] neg_hi:[1,0,0]
	v_pk_fma_f32 v[12:13], v[222:223], v[16:17], v[12:13] op_sel_hi:[0,1,1] neg_lo:[1,0,0] neg_hi:[1,0,0]
	s_waitcnt vmcnt(47)
; __device__ __forceinline__ float bflo(unsigned u) { return __uint_as_float(u << 16); }
; __device__ __forceinline__ float bfhi(unsigned u) { return __uint_as_float(u & 0xffff0000u); }
; __device__ __forceinline__ void phase_pool(const Params& p, char* smraw) {
;     ...
; #pragma unroll
;       for (int k = 0; k < 8; ++k) {
;         const int tt = t8 + k, pp = c0 + tt;
;         const float rs = rstd_s[tt + 15];
;         const float x0 = bflo(cur[k][0]) * rs, x1 = bfhi(cur[k][0]) * rs, x2 = bflo(cur[k][1]) * rs, x3 = bfhi(cur[k][1]) * rs;
;         s0 += x0; s1 += x1; s2 += x2; s3 += x3;
;         const int cnt = (pp + 1 < win) ? pp + 1 : win;
;         const float inv = 1.f / (float)cnt;
;         u32x2 o; o[0] = cvtpk(s0 * inv - x0, s1 * inv - x1); o[1] = cvtpk(s2 * inv - x2, s3 * inv - x3);
;         *(u32x2*)(p.pooled + (size_t)(b * L + pp) * D + c) = o;
;         const int po = pp - win + 1;
;         if (po >= 0) {
;           const float ro = rstd_s[tt + 15 - win + 1];
;           s0 -= bflo(old[k][0]) * ro; s1 -= bfhi(old[k][0]) * ro; s2 -= bflo(old[k][1]) * ro; s3 -= bfhi(old[k][1]) * ro;
;         }
;       }
	v_and_b32_e32 v14, 0xffff0000, v152
	v_lshlrev_b32_e32 v15, 16, v152
	v_and_b32_e32 v16, 0xffff0000, v153
	v_lshlrev_b32_e32 v17, 16, v153
	v_pk_mul_f32 v[18:19], v[238:239], v[14:15] op_sel_hi:[0,1]
	v_pk_mul_f32 v[20:21], v[238:239], v[16:17] op_sel_hi:[0,1]
	v_pk_fma_f32 v[10:11], v[238:239], v[14:15], v[10:11] op_sel_hi:[0,1,1]
	v_pk_fma_f32 v[12:13], v[238:239], v[16:17], v[12:13] op_sel_hi:[0,1,1]
	v_fma_f32 v26, s0, v11, -v19
	v_fma_f32 v27, s0, v10, -v18
	v_fma_f32 v28, s0, v13, -v21
	v_fma_f32 v29, s0, v12, -v20
	v_cvt_pk_bf16_f32 v26, v26, v27
	v_cvt_pk_bf16_f32 v27, v28, v29
	v_add_u32_e32 v37, 0xf800, v8
	global_store_dwordx2 v37, v[26:27], s[62:63]
	v_and_b32_e32 v14, 0xffff0000, v122
	v_lshlrev_b32_e32 v15, 16, v122
	v_and_b32_e32 v16, 0xffff0000, v123
	v_lshlrev_b32_e32 v17, 16, v123
	v_pk_fma_f32 v[10:11], v[222:223], v[14:15], v[10:11] op_sel:[1,0,0] op_sel_hi:[1,1,1] neg_lo:[1,0,0] neg_hi:[1,0,0]
	v_pk_fma_f32 v[12:13], v[222:223], v[16:17], v[12:13] op_sel:[1,0,0] op_sel_hi:[1,1,1] neg_lo:[1,0,0] neg_hi:[1,0,0]
	s_waitcnt vmcnt(47)
	v_and_b32_e32 v14, 0xffff0000, v154
	v_lshlrev_b32_e32 v15, 16, v154
	v_and_b32_e32 v16, 0xffff0000, v155
	v_lshlrev_b32_e32 v17, 16, v155
	v_pk_mul_f32 v[18:19], v[238:239], v[14:15] op_sel:[1,0] op_sel_hi:[1,1]
	v_pk_mul_f32 v[20:21], v[238:239], v[16:17] op_sel:[1,0] op_sel_hi:[1,1]
	v_pk_fma_f32 v[10:11], v[238:239], v[14:15], v[10:11] op_sel:[1,0,0] op_sel_hi:[1,1,1]
	v_pk_fma_f32 v[12:13], v[238:239], v[16:17], v[12:13] op_sel:[1,0,0] op_sel_hi:[1,1,1]
	v_fma_f32 v22, s0, v11, -v19
	v_fma_f32 v23, s0, v10, -v18
	v_fma_f32 v24, s0, v13, -v21
	v_fma_f32 v25, s0, v12, -v20
	v_cvt_pk_bf16_f32 v22, v22, v23
	v_cvt_pk_bf16_f32 v23, v24, v25
	v_add_u32_e32 v30, 0x10000, v8
	global_store_dwordx2 v30, v[22:23], s[62:63]
	v_and_b32_e32 v14, 0xffff0000, v124
	v_lshlrev_b32_e32 v15, 16, v124
	v_and_b32_e32 v16, 0xffff0000, v125
	v_lshlrev_b32_e32 v17, 16, v125
	v_pk_fma_f32 v[10:11], v[224:225], v[14:15], v[10:11] op_sel_hi:[0,1,1] neg_lo:[1,0,0] neg_hi:[1,0,0]
	v_pk_fma_f32 v[12:13], v[224:225], v[16:17], v[12:13] op_sel_hi:[0,1,1] neg_lo:[1,0,0] neg_hi:[1,0,0]
	s_waitcnt vmcnt(47)
	v_and_b32_e32 v14, 0xffff0000, v156
	v_lshlrev_b32_e32 v15, 16, v156
	v_and_b32_e32 v16, 0xffff0000, v157
	v_lshlrev_b32_e32 v17, 16, v157
	v_pk_mul_f32 v[18:19], v[240:241], v[14:15] op_sel_hi:[0,1]
	v_pk_mul_f32 v[20:21], v[240:241], v[16:17] op_sel_hi:[0,1]
	v_pk_fma_f32 v[10:11], v[240:241], v[14:15], v[10:11] op_sel_hi:[0,1,1]
	v_pk_fma_f32 v[12:13], v[240:241], v[16:17], v[12:13] op_sel_hi:[0,1,1]
	v_fma_f32 v26, s0, v11, -v19
	v_fma_f32 v27, s0, v10, -v18
	v_fma_f32 v28, s0, v13, -v21
	v_fma_f32 v29, s0, v12, -v20
	v_cvt_pk_bf16_f32 v26, v26, v27
	v_cvt_pk_bf16_f32 v27, v28, v29
	v_add_u32_e32 v31, 0x10800, v8
	global_store_dwordx2 v31, v[26:27], s[62:63]
	v_and_b32_e32 v14, 0xffff0000, v126
	v_lshlrev_b32_e32 v15, 16, v126
	v_and_b32_e32 v16, 0xffff0000, v127
	v_lshlrev_b32_e32 v17, 16, v127
	v_pk_fma_f32 v[10:11], v[224:225], v[14:15], v[10:11] op_sel:[1,0,0] op_sel_hi:[1,1,1] neg_lo:[1,0,0] neg_hi:[1,0,0]
	v_pk_fma_f32 v[12:13], v[224:225], v[16:17], v[12:13] op_sel:[1,0,0] op_sel_hi:[1,1,1] neg_lo:[1,0,0] neg_hi:[1,0,0]
	s_waitcnt vmcnt(47)
	v_and_b32_e32 v14, 0xffff0000, v158
	v_lshlrev_b32_e32 v15, 16, v158
	v_and_b32_e32 v16, 0xffff0000, v159
	v_lshlrev_b32_e32 v17, 16, v159
	v_pk_mul_f32 v[18:19], v[240:241], v[14:15] op_sel:[1,0] op_sel_hi:[1,1]
	v_pk_mul_f32 v[20:21], v[240:241], v[16:17] op_sel:[1,0] op_sel_hi:[1,1]
	v_pk_fma_f32 v[10:11], v[240:241], v[14:15], v[10:11] op_sel:[1,0,0] op_sel_hi:[1,1,1]
	v_pk_fma_f32 v[12:13], v[240:241], v[16:17], v[12:13] op_sel:[1,0,0] op_sel_hi:[1,1,1]
	v_fma_f32 v22, s0, v11, -v19
	v_fma_f32 v23, s0, v10, -v18
	v_fma_f32 v24, s0, v13, -v21
	v_fma_f32 v25, s0, v12, -v20
	v_cvt_pk_bf16_f32 v22, v22, v23
	v_cvt_pk_bf16_f32 v23, v24, v25
	v_add_u32_e32 v32, 0x11000, v8
	global_store_dwordx2 v32, v[22:23], s[62:63]
	v_and_b32_e32 v14, 0xffff0000, v128
	v_lshlrev_b32_e32 v15, 16, v128
	v_and_b32_e32 v16, 0xffff0000, v129
	v_lshlrev_b32_e32 v17, 16, v129
	v_pk_fma_f32 v[10:11], v[226:227], v[14:15], v[10:11] op_sel_hi:[0,1,1] neg_lo:[1,0,0] neg_hi:[1,0,0]
	v_pk_fma_f32 v[12:13], v[226:227], v[16:17], v[12:13] op_sel_hi:[0,1,1] neg_lo:[1,0,0] neg_hi:[1,0,0]
	s_waitcnt vmcnt(47)
	v_and_b32_e32 v14, 0xffff0000, v160
	v_lshlrev_b32_e32 v15, 16, v160
	v_and_b32_e32 v16, 0xffff0000, v161
	v_lshlrev_b32_e32 v17, 16, v161
	v_pk_mul_f32 v[18:19], v[242:243], v[14:15] op_sel_hi:[0,1]
	v_pk_mul_f32 v[20:21], v[242:243], v[16:17] op_sel_hi:[0,1]
	v_pk_fma_f32 v[10:11], v[242:243], v[14:15], v[10:11] op_sel_hi:[0,1,1]
	v_pk_fma_f32 v[12:13], v[242:243], v[16:17], v[12:13] op_sel_hi:[0,1,1]
	v_fma_f32 v26, s0, v11, -v19
	v_fma_f32 v27, s0, v10, -v18
	v_fma_f32 v28, s0, v13, -v21
	v_fma_f32 v29, s0, v12, -v20
	v_cvt_pk_bf16_f32 v26, v26, v27
	v_cvt_pk_bf16_f32 v27, v28, v29
	v_add_u32_e32 v33, 0x11800, v8
	global_store_dwordx2 v33, v[26:27], s[62:63]
	v_and_b32_e32 v14, 0xffff0000, v130
	v_lshlrev_b32_e32 v15, 16, v130
	v_and_b32_e32 v16, 0xffff0000, v131
	v_lshlrev_b32_e32 v17, 16, v131
	v_pk_fma_f32 v[10:11], v[226:227], v[14:15], v[10:11] op_sel:[1,0,0] op_sel_hi:[1,1,1] neg_lo:[1,0,0] neg_hi:[1,0,0]
	v_pk_fma_f32 v[12:13], v[226:227], v[16:17], v[12:13] op_sel:[1,0,0] op_sel_hi:[1,1,1] neg_lo:[1,0,0] neg_hi:[1,0,0]
	s_waitcnt vmcnt(47)
; __device__ __forceinline__ float bflo(unsigned u) { return __uint_as_float(u << 16); }
; __device__ __forceinline__ float bfhi(unsigned u) { return __uint_as_float(u & 0xffff0000u); }
; __device__ __forceinline__ void phase_pool(const Params& p, char* smraw) {
;     ...
; #pragma unroll
;       for (int k = 0; k < 8; ++k) {
;         const int tt = t8 + k, pp = c0 + tt;
;         const float rs = rstd_s[tt + 15];
;         const float x0 = bflo(cur[k][0]) * rs, x1 = bfhi(cur[k][0]) * rs, x2 = bflo(cur[k][1]) * rs, x3 = bfhi(cur[k][1]) * rs;
;         s0 += x0; s1 += x1; s2 += x2; s3 += x3;
;         const int cnt = (pp + 1 < win) ? pp + 1 : win;
;         const float inv = 1.f / (float)cnt;
;         u32x2 o; o[0] = cvtpk(s0 * inv - x0, s1 * inv - x1); o[1] = cvtpk(s2 * inv - x2, s3 * inv - x3);
;         *(u32x2*)(p.pooled + (size_t)(b * L + pp) * D + c) = o;
;         const int po = pp - win + 1;
;         if (po >= 0) {
;           const float ro = rstd_s[tt + 15 - win + 1];
;           s0 -= bflo(old[k][0]) * ro; s1 -= bfhi(old[k][0]) * ro; s2 -= bflo(old[k][1]) * ro; s3 -= bfhi(old[k][1]) * ro;
;         }
;       }
	v_and_b32_e32 v14, 0xffff0000, v162
	v_lshlrev_b32_e32 v15, 16, v162
	v_and_b32_e32 v16, 0xffff0000, v163
	v_lshlrev_b32_e32 v17, 16, v163
	v_pk_mul_f32 v[18:19], v[242:243], v[14:15] op_sel:[1,0] op_sel_hi:[1,1]
	v_pk_mul_f32 v[20:21], v[242:243], v[16:17] op_sel:[1,0] op_sel_hi:[1,1]
	v_pk_fma_f32 v[10:11], v[242:243], v[14:15], v[10:11] op_sel:[1,0,0] op_sel_hi:[1,1,1]
	v_pk_fma_f32 v[12:13], v[242:243], v[16:17], v[12:13] op_sel:[1,0,0] op_sel_hi:[1,1,1]
	v_fma_f32 v22, s0, v11, -v19
	v_fma_f32 v23, s0, v10, -v18
	v_fma_f32 v24, s0, v13, -v21
	v_fma_f32 v25, s0, v12, -v20
	v_cvt_pk_bf16_f32 v22, v22, v23
	v_cvt_pk_bf16_f32 v23, v24, v25
	v_add_u32_e32 v34, 0x12000, v8
	global_store_dwordx2 v34, v[22:23], s[62:63]
	v_and_b32_e32 v14, 0xffff0000, v132
	v_lshlrev_b32_e32 v15, 16, v132
	v_and_b32_e32 v16, 0xffff0000, v133
	v_lshlrev_b32_e32 v17, 16, v133
	v_pk_fma_f32 v[10:11], v[228:229], v[14:15], v[10:11] op_sel_hi:[0,1,1] neg_lo:[1,0,0] neg_hi:[1,0,0]
	v_pk_fma_f32 v[12:13], v[228:229], v[16:17], v[12:13] op_sel_hi:[0,1,1] neg_lo:[1,0,0] neg_hi:[1,0,0]
	s_waitcnt vmcnt(47)
	v_and_b32_e32 v14, 0xffff0000, v164
	v_lshlrev_b32_e32 v15, 16, v164
	v_and_b32_e32 v16, 0xffff0000, v165
	v_lshlrev_b32_e32 v17, 16, v165
	v_pk_mul_f32 v[18:19], v[244:245], v[14:15] op_sel_hi:[0,1]
	v_pk_mul_f32 v[20:21], v[244:245], v[16:17] op_sel_hi:[0,1]
	v_pk_fma_f32 v[10:11], v[244:245], v[14:15], v[10:11] op_sel_hi:[0,1,1]
	v_pk_fma_f32 v[12:13], v[244:245], v[16:17], v[12:13] op_sel_hi:[0,1,1]
	v_fma_f32 v26, s0, v11, -v19
	v_fma_f32 v27, s0, v10, -v18
	v_fma_f32 v28, s0, v13, -v21
	v_fma_f32 v29, s0, v12, -v20
	v_cvt_pk_bf16_f32 v26, v26, v27
	v_cvt_pk_bf16_f32 v27, v28, v29
	v_add_u32_e32 v35, 0x12800, v8
	global_store_dwordx2 v35, v[26:27], s[62:63]
	v_and_b32_e32 v14, 0xffff0000, v134
	v_lshlrev_b32_e32 v15, 16, v134
	v_and_b32_e32 v16, 0xffff0000, v135
	v_lshlrev_b32_e32 v17, 16, v135
	v_pk_fma_f32 v[10:11], v[228:229], v[14:15], v[10:11] op_sel:[1,0,0] op_sel_hi:[1,1,1] neg_lo:[1,0,0] neg_hi:[1,0,0]
	v_pk_fma_f32 v[12:13], v[228:229], v[16:17], v[12:13] op_sel:[1,0,0] op_sel_hi:[1,1,1] neg_lo:[1,0,0] neg_hi:[1,0,0]
	s_waitcnt vmcnt(47)
	v_and_b32_e32 v14, 0xffff0000, v166
	v_lshlrev_b32_e32 v15, 16, v166
	v_and_b32_e32 v16, 0xffff0000, v167
	v_lshlrev_b32_e32 v17, 16, v167
	v_pk_mul_f32 v[18:19], v[244:245], v[14:15] op_sel:[1,0] op_sel_hi:[1,1]
	v_pk_mul_f32 v[20:21], v[244:245], v[16:17] op_sel:[1,0] op_sel_hi:[1,1]
	v_pk_fma_f32 v[10:11], v[244:245], v[14:15], v[10:11] op_sel:[1,0,0] op_sel_hi:[1,1,1]
	v_pk_fma_f32 v[12:13], v[244:245], v[16:17], v[12:13] op_sel:[1,0,0] op_sel_hi:[1,1,1]
	v_fma_f32 v22, s0, v11, -v19
	v_fma_f32 v23, s0, v10, -v18
	v_fma_f32 v24, s0, v13, -v21
	v_fma_f32 v25, s0, v12, -v20
	v_cvt_pk_bf16_f32 v22, v22, v23
	v_cvt_pk_bf16_f32 v23, v24, v25
	v_add_u32_e32 v36, 0x13000, v8
	global_store_dwordx2 v36, v[22:23], s[62:63]
	v_and_b32_e32 v14, 0xffff0000, v136
	v_lshlrev_b32_e32 v15, 16, v136
	v_and_b32_e32 v16, 0xffff0000, v137
	v_lshlrev_b32_e32 v17, 16, v137
	v_pk_fma_f32 v[10:11], v[230:231], v[14:15], v[10:11] op_sel_hi:[0,1,1] neg_lo:[1,0,0] neg_hi:[1,0,0]
	v_pk_fma_f32 v[12:13], v[230:231], v[16:17], v[12:13] op_sel_hi:[0,1,1] neg_lo:[1,0,0] neg_hi:[1,0,0]
	s_waitcnt vmcnt(47)
	v_and_b32_e32 v14, 0xffff0000, v168
	v_lshlrev_b32_e32 v15, 16, v168
	v_and_b32_e32 v16, 0xffff0000, v169
	v_lshlrev_b32_e32 v17, 16, v169
	v_pk_mul_f32 v[18:19], v[246:247], v[14:15] op_sel_hi:[0,1]
	v_pk_mul_f32 v[20:21], v[246:247], v[16:17] op_sel_hi:[0,1]
	v_pk_fma_f32 v[10:11], v[246:247], v[14:15], v[10:11] op_sel_hi:[0,1,1]
	v_pk_fma_f32 v[12:13], v[246:247], v[16:17], v[12:13] op_sel_hi:[0,1,1]
	v_fma_f32 v26, s0, v11, -v19
	v_fma_f32 v27, s0, v10, -v18
	v_fma_f32 v28, s0, v13, -v21
	v_fma_f32 v29, s0, v12, -v20
	v_cvt_pk_bf16_f32 v26, v26, v27
	v_cvt_pk_bf16_f32 v27, v28, v29
	v_add_u32_e32 v37, 0x13800, v8
	global_store_dwordx2 v37, v[26:27], s[62:63]
	v_and_b32_e32 v14, 0xffff0000, v138
	v_lshlrev_b32_e32 v15, 16, v138
	v_and_b32_e32 v16, 0xffff0000, v139
	v_lshlrev_b32_e32 v17, 16, v139
	v_pk_fma_f32 v[10:11], v[230:231], v[14:15], v[10:11] op_sel:[1,0,0] op_sel_hi:[1,1,1] neg_lo:[1,0,0] neg_hi:[1,0,0]
	v_pk_fma_f32 v[12:13], v[230:231], v[16:17], v[12:13] op_sel:[1,0,0] op_sel_hi:[1,1,1] neg_lo:[1,0,0] neg_hi:[1,0,0]
	s_waitcnt vmcnt(47)
	v_and_b32_e32 v14, 0xffff0000, v170
	v_lshlrev_b32_e32 v15, 16, v170
	v_and_b32_e32 v16, 0xffff0000, v171
	v_lshlrev_b32_e32 v17, 16, v171
	v_pk_mul_f32 v[18:19], v[246:247], v[14:15] op_sel:[1,0] op_sel_hi:[1,1]
	v_pk_mul_f32 v[20:21], v[246:247], v[16:17] op_sel:[1,0] op_sel_hi:[1,1]
	v_pk_fma_f32 v[10:11], v[246:247], v[14:15], v[10:11] op_sel:[1,0,0] op_sel_hi:[1,1,1]
	v_pk_fma_f32 v[12:13], v[246:247], v[16:17], v[12:13] op_sel:[1,0,0] op_sel_hi:[1,1,1]
	v_fma_f32 v22, s0, v11, -v19
	v_fma_f32 v23, s0, v10, -v18
	v_fma_f32 v24, s0, v13, -v21
	v_fma_f32 v25, s0, v12, -v20
	v_cvt_pk_bf16_f32 v22, v22, v23
	v_cvt_pk_bf16_f32 v23, v24, v25
	v_add_u32_e32 v30, 0x14000, v8
	global_store_dwordx2 v30, v[22:23], s[62:63]
	v_and_b32_e32 v14, 0xffff0000, v140
	v_lshlrev_b32_e32 v15, 16, v140
	v_and_b32_e32 v16, 0xffff0000, v141
	v_lshlrev_b32_e32 v17, 16, v141
	v_pk_fma_f32 v[10:11], v[232:233], v[14:15], v[10:11] op_sel_hi:[0,1,1] neg_lo:[1,0,0] neg_hi:[1,0,0]
	v_pk_fma_f32 v[12:13], v[232:233], v[16:17], v[12:13] op_sel_hi:[0,1,1] neg_lo:[1,0,0] neg_hi:[1,0,0]
	s_waitcnt vmcnt(47)
; __device__ __forceinline__ float bflo(unsigned u) { return __uint_as_float(u << 16); }
; __device__ __forceinline__ float bfhi(unsigned u) { return __uint_as_float(u & 0xffff0000u); }
; __device__ __forceinline__ void phase_pool(const Params& p, char* smraw) {
;     ...
; #pragma unroll
;       for (int k = 0; k < 8; ++k) {
;         const int tt = t8 + k, pp = c0 + tt;
;         const float rs = rstd_s[tt + 15];
;         const float x0 = bflo(cur[k][0]) * rs, x1 = bfhi(cur[k][0]) * rs, x2 = bflo(cur[k][1]) * rs, x3 = bfhi(cur[k][1]) * rs;
;         s0 += x0; s1 += x1; s2 += x2; s3 += x3;
;         const int cnt = (pp + 1 < win) ? pp + 1 : win;
;         const float inv = 1.f / (float)cnt;
;         u32x2 o; o[0] = cvtpk(s0 * inv - x0, s1 * inv - x1); o[1] = cvtpk(s2 * inv - x2, s3 * inv - x3);
;         *(u32x2*)(p.pooled + (size_t)(b * L + pp) * D + c) = o;
;         const int po = pp - win + 1;
;         if (po >= 0) {
;           const float ro = rstd_s[tt + 15 - win + 1];
;           s0 -= bflo(old[k][0]) * ro; s1 -= bfhi(old[k][0]) * ro; s2 -= bflo(old[k][1]) * ro; s3 -= bfhi(old[k][1]) * ro;
;         }
;       }
	v_and_b32_e32 v14, 0xffff0000, v172
	v_lshlrev_b32_e32 v15, 16, v172
	v_and_b32_e32 v16, 0xffff0000, v173
	v_lshlrev_b32_e32 v17, 16, v173
	v_pk_mul_f32 v[18:19], v[248:249], v[14:15] op_sel_hi:[0,1]
	v_pk_mul_f32 v[20:21], v[248:249], v[16:17] op_sel_hi:[0,1]
	v_pk_fma_f32 v[10:11], v[248:249], v[14:15], v[10:11] op_sel_hi:[0,1,1]
	v_pk_fma_f32 v[12:13], v[248:249], v[16:17], v[12:13] op_sel_hi:[0,1,1]
	v_fma_f32 v26, s0, v11, -v19
	v_fma_f32 v27, s0, v10, -v18
	v_fma_f32 v28, s0, v13, -v21
	v_fma_f32 v29, s0, v12, -v20
	v_cvt_pk_bf16_f32 v26, v26, v27
	v_cvt_pk_bf16_f32 v27, v28, v29
	v_add_u32_e32 v31, 0x14800, v8
	global_store_dwordx2 v31, v[26:27], s[62:63]
	v_and_b32_e32 v14, 0xffff0000, v142
	v_lshlrev_b32_e32 v15, 16, v142
	v_and_b32_e32 v16, 0xffff0000, v143
	v_lshlrev_b32_e32 v17, 16, v143
	v_pk_fma_f32 v[10:11], v[232:233], v[14:15], v[10:11] op_sel:[1,0,0] op_sel_hi:[1,1,1] neg_lo:[1,0,0] neg_hi:[1,0,0]
	v_pk_fma_f32 v[12:13], v[232:233], v[16:17], v[12:13] op_sel:[1,0,0] op_sel_hi:[1,1,1] neg_lo:[1,0,0] neg_hi:[1,0,0]
	s_waitcnt vmcnt(47)
	v_and_b32_e32 v14, 0xffff0000, v174
	v_lshlrev_b32_e32 v15, 16, v174
	v_and_b32_e32 v16, 0xffff0000, v175
	v_lshlrev_b32_e32 v17, 16, v175
	v_pk_mul_f32 v[18:19], v[248:249], v[14:15] op_sel:[1,0] op_sel_hi:[1,1]
	v_pk_mul_f32 v[20:21], v[248:249], v[16:17] op_sel:[1,0] op_sel_hi:[1,1]
	v_pk_fma_f32 v[10:11], v[248:249], v[14:15], v[10:11] op_sel:[1,0,0] op_sel_hi:[1,1,1]
	v_pk_fma_f32 v[12:13], v[248:249], v[16:17], v[12:13] op_sel:[1,0,0] op_sel_hi:[1,1,1]
	v_fma_f32 v22, s0, v11, -v19
	v_fma_f32 v23, s0, v10, -v18
	v_fma_f32 v24, s0, v13, -v21
	v_fma_f32 v25, s0, v12, -v20
	v_cvt_pk_bf16_f32 v22, v22, v23
	v_cvt_pk_bf16_f32 v23, v24, v25
	v_add_u32_e32 v32, 0x15000, v8
	global_store_dwordx2 v32, v[22:23], s[62:63]
	v_and_b32_e32 v14, 0xffff0000, v144
	v_lshlrev_b32_e32 v15, 16, v144
	v_and_b32_e32 v16, 0xffff0000, v145
	v_lshlrev_b32_e32 v17, 16, v145
	v_pk_fma_f32 v[10:11], v[234:235], v[14:15], v[10:11] op_sel_hi:[0,1,1] neg_lo:[1,0,0] neg_hi:[1,0,0]
	v_pk_fma_f32 v[12:13], v[234:235], v[16:17], v[12:13] op_sel_hi:[0,1,1] neg_lo:[1,0,0] neg_hi:[1,0,0]
	s_waitcnt vmcnt(47)
	v_and_b32_e32 v14, 0xffff0000, v176
	v_lshlrev_b32_e32 v15, 16, v176
	v_and_b32_e32 v16, 0xffff0000, v177
	v_lshlrev_b32_e32 v17, 16, v177
	v_pk_mul_f32 v[18:19], v[250:251], v[14:15] op_sel_hi:[0,1]
	v_pk_mul_f32 v[20:21], v[250:251], v[16:17] op_sel_hi:[0,1]
	v_pk_fma_f32 v[10:11], v[250:251], v[14:15], v[10:11] op_sel_hi:[0,1,1]
	v_pk_fma_f32 v[12:13], v[250:251], v[16:17], v[12:13] op_sel_hi:[0,1,1]
	v_fma_f32 v26, s0, v11, -v19
	v_fma_f32 v27, s0, v10, -v18
	v_fma_f32 v28, s0, v13, -v21
	v_fma_f32 v29, s0, v12, -v20
	v_cvt_pk_bf16_f32 v26, v26, v27
	v_cvt_pk_bf16_f32 v27, v28, v29
	v_add_u32_e32 v33, 0x15800, v8
	global_store_dwordx2 v33, v[26:27], s[62:63]
	v_and_b32_e32 v14, 0xffff0000, v146
	v_lshlrev_b32_e32 v15, 16, v146
	v_and_b32_e32 v16, 0xffff0000, v147
	v_lshlrev_b32_e32 v17, 16, v147
	v_pk_fma_f32 v[10:11], v[234:235], v[14:15], v[10:11] op_sel:[1,0,0] op_sel_hi:[1,1,1] neg_lo:[1,0,0] neg_hi:[1,0,0]
	v_pk_fma_f32 v[12:13], v[234:235], v[16:17], v[12:13] op_sel:[1,0,0] op_sel_hi:[1,1,1] neg_lo:[1,0,0] neg_hi:[1,0,0]
	s_waitcnt vmcnt(47)
	v_and_b32_e32 v14, 0xffff0000, v178
	v_lshlrev_b32_e32 v15, 16, v178
	v_and_b32_e32 v16, 0xffff0000, v179
	v_lshlrev_b32_e32 v17, 16, v179
	v_pk_mul_f32 v[18:19], v[250:251], v[14:15] op_sel:[1,0] op_sel_hi:[1,1]
	v_pk_mul_f32 v[20:21], v[250:251], v[16:17] op_sel:[1,0] op_sel_hi:[1,1]
	v_pk_fma_f32 v[10:11], v[250:251], v[14:15], v[10:11] op_sel:[1,0,0] op_sel_hi:[1,1,1]
	v_pk_fma_f32 v[12:13], v[250:251], v[16:17], v[12:13] op_sel:[1,0,0] op_sel_hi:[1,1,1]
	v_fma_f32 v22, s0, v11, -v19
	v_fma_f32 v23, s0, v10, -v18
	v_fma_f32 v24, s0, v13, -v21
	v_fma_f32 v25, s0, v12, -v20
	v_cvt_pk_bf16_f32 v22, v22, v23
	v_cvt_pk_bf16_f32 v23, v24, v25
	v_add_u32_e32 v34, 0x16000, v8
	global_store_dwordx2 v34, v[22:23], s[62:63]
	v_and_b32_e32 v14, 0xffff0000, v148
	v_lshlrev_b32_e32 v15, 16, v148
	v_and_b32_e32 v16, 0xffff0000, v149
	v_lshlrev_b32_e32 v17, 16, v149
	v_pk_fma_f32 v[10:11], v[236:237], v[14:15], v[10:11] op_sel_hi:[0,1,1] neg_lo:[1,0,0] neg_hi:[1,0,0]
	v_pk_fma_f32 v[12:13], v[236:237], v[16:17], v[12:13] op_sel_hi:[0,1,1] neg_lo:[1,0,0] neg_hi:[1,0,0]
	s_waitcnt vmcnt(47)
	v_and_b32_e32 v14, 0xffff0000, v180
	v_lshlrev_b32_e32 v15, 16, v180
	v_and_b32_e32 v16, 0xffff0000, v181
	v_lshlrev_b32_e32 v17, 16, v181
	v_pk_mul_f32 v[18:19], v[252:253], v[14:15] op_sel_hi:[0,1]
	v_pk_mul_f32 v[20:21], v[252:253], v[16:17] op_sel_hi:[0,1]
	v_pk_fma_f32 v[10:11], v[252:253], v[14:15], v[10:11] op_sel_hi:[0,1,1]
	v_pk_fma_f32 v[12:13], v[252:253], v[16:17], v[12:13] op_sel_hi:[0,1,1]
	v_fma_f32 v26, s0, v11, -v19
	v_fma_f32 v27, s0, v10, -v18
	v_fma_f32 v28, s0, v13, -v21
	v_fma_f32 v29, s0, v12, -v20
	v_cvt_pk_bf16_f32 v26, v26, v27
	v_cvt_pk_bf16_f32 v27, v28, v29
	v_add_u32_e32 v35, 0x16800, v8
	global_store_dwordx2 v35, v[26:27], s[62:63]
	v_and_b32_e32 v14, 0xffff0000, v150
	v_lshlrev_b32_e32 v15, 16, v150
	v_and_b32_e32 v16, 0xffff0000, v151
	v_lshlrev_b32_e32 v17, 16, v151
	v_pk_fma_f32 v[10:11], v[236:237], v[14:15], v[10:11] op_sel:[1,0,0] op_sel_hi:[1,1,1] neg_lo:[1,0,0] neg_hi:[1,0,0]
	v_pk_fma_f32 v[12:13], v[236:237], v[16:17], v[12:13] op_sel:[1,0,0] op_sel_hi:[1,1,1] neg_lo:[1,0,0] neg_hi:[1,0,0]
	s_waitcnt vmcnt(47)
; __device__ __forceinline__ float bflo(unsigned u) { return __uint_as_float(u << 16); }
; __device__ __forceinline__ float bfhi(unsigned u) { return __uint_as_float(u & 0xffff0000u); }
; __device__ __forceinline__ void phase_pool(const Params& p, char* smraw) {
;     ...
;     for (int i = 1; i < win; ++i) {
;       const int pp = c0 - i;
;       if (pp >= 0) {
;         u32x2 v = *(const u32x2*)(base + (size_t)pp * D);
;         const float rs = rstd_s[15 - i];
;         s0 += bflo(v[0]) * rs; s1 += bfhi(v[0]) * rs; s2 += bflo(v[1]) * rs; s3 += bfhi(v[1]) * rs;
;       }
;     }
;     for (int t8 = 0; t8 < CH; t8 += 8) {
;       u32x2 cur[8], old[8];
; #pragma unroll
;       for (int k = 0; k < 8; ++k) {
;         const int pp = c0 + t8 + k;
;         cur[k] = *(const u32x2*)(base + (size_t)pp * D);
;         const int po = pp - win + 1;
;         old[k] = *(const u32x2*)(base + (size_t)(po >= 0 ? po : 0) * D);
;       }
; #pragma unroll
;       for (int k = 0; k < 8; ++k) {
;         const int tt = t8 + k, pp = c0 + tt;
;         const float rs = rstd_s[tt + 15];
;         const float x0 = bflo(cur[k][0]) * rs, x1 = bfhi(cur[k][0]) * rs, x2 = bflo(cur[k][1]) * rs, x3 = bfhi(cur[k][1]) * rs;
;         s0 += x0; s1 += x1; s2 += x2; s3 += x3;
;         const int cnt = (pp + 1 < win) ? pp + 1 : win;
;         const float inv = 1.f / (float)cnt;
;         u32x2 o; o[0] = cvtpk(s0 * inv - x0, s1 * inv - x1); o[1] = cvtpk(s2 * inv - x2, s3 * inv - x3);
;         *(u32x2*)(p.pooled + (size_t)(b * L + pp) * D + c) = o;
;         const int po = pp - win + 1;
;         if (po >= 0) {
;           const float ro = rstd_s[tt + 15 - win + 1];
;           s0 -= bflo(old[k][0]) * ro; s1 -= bfhi(old[k][0]) * ro; s2 -= bflo(old[k][1]) * ro; s3 -= bfhi(old[k][1]) * ro;
;         }
;       }
	v_and_b32_e32 v14, 0xffff0000, v182
	v_lshlrev_b32_e32 v15, 16, v182
	v_and_b32_e32 v16, 0xffff0000, v183
	v_lshlrev_b32_e32 v17, 16, v183
	v_pk_mul_f32 v[18:19], v[252:253], v[14:15] op_sel:[1,0] op_sel_hi:[1,1]
	v_pk_mul_f32 v[20:21], v[252:253], v[16:17] op_sel:[1,0] op_sel_hi:[1,1]
	v_pk_fma_f32 v[10:11], v[252:253], v[14:15], v[10:11] op_sel:[1,0,0] op_sel_hi:[1,1,1]
	v_pk_fma_f32 v[12:13], v[252:253], v[16:17], v[12:13] op_sel:[1,0,0] op_sel_hi:[1,1,1]
	v_fma_f32 v22, s0, v11, -v19
	v_fma_f32 v23, s0, v10, -v18
	v_fma_f32 v24, s0, v13, -v21
	v_fma_f32 v25, s0, v12, -v20
	v_cvt_pk_bf16_f32 v22, v22, v23
	v_cvt_pk_bf16_f32 v23, v24, v25
	v_add_u32_e32 v36, 0x17000, v8
	global_store_dwordx2 v36, v[22:23], s[62:63]
	v_and_b32_e32 v14, 0xffff0000, v152
	v_lshlrev_b32_e32 v15, 16, v152
	v_and_b32_e32 v16, 0xffff0000, v153
	v_lshlrev_b32_e32 v17, 16, v153
	v_pk_fma_f32 v[10:11], v[238:239], v[14:15], v[10:11] op_sel_hi:[0,1,1] neg_lo:[1,0,0] neg_hi:[1,0,0]
	v_pk_fma_f32 v[12:13], v[238:239], v[16:17], v[12:13] op_sel_hi:[0,1,1] neg_lo:[1,0,0] neg_hi:[1,0,0]
	s_waitcnt vmcnt(47)
	v_and_b32_e32 v14, 0xffff0000, v184
	v_lshlrev_b32_e32 v15, 16, v184
	v_and_b32_e32 v16, 0xffff0000, v185
	v_lshlrev_b32_e32 v17, 16, v185
	v_pk_mul_f32 v[18:19], v[186:187], v[14:15] op_sel_hi:[0,1]
	v_pk_mul_f32 v[20:21], v[186:187], v[16:17] op_sel_hi:[0,1]
	v_pk_fma_f32 v[10:11], v[186:187], v[14:15], v[10:11] op_sel_hi:[0,1,1]
	v_pk_fma_f32 v[12:13], v[186:187], v[16:17], v[12:13] op_sel_hi:[0,1,1]
	v_fma_f32 v26, s0, v11, -v19
	v_fma_f32 v27, s0, v10, -v18
	v_fma_f32 v28, s0, v13, -v21
	v_fma_f32 v29, s0, v12, -v20
	v_cvt_pk_bf16_f32 v26, v26, v27
	v_cvt_pk_bf16_f32 v27, v28, v29
	v_add_u32_e32 v37, 0x17800, v8
	global_store_dwordx2 v37, v[26:27], s[62:63]
	v_and_b32_e32 v14, 0xffff0000, v154
	v_lshlrev_b32_e32 v15, 16, v154
	v_and_b32_e32 v16, 0xffff0000, v155
	v_lshlrev_b32_e32 v17, 16, v155
	v_pk_fma_f32 v[10:11], v[238:239], v[14:15], v[10:11] op_sel:[1,0,0] op_sel_hi:[1,1,1] neg_lo:[1,0,0] neg_hi:[1,0,0]
	v_pk_fma_f32 v[12:13], v[238:239], v[16:17], v[12:13] op_sel:[1,0,0] op_sel_hi:[1,1,1] neg_lo:[1,0,0] neg_hi:[1,0,0]
	s_branch .Lmy_pool_next
.Lmy_pool_w2:
	s_mov_b32 s35, 0x3e000000
	ds_read_b128 v[192:195], v59 offset:0
	ds_read_b128 v[196:199], v59 offset:16
	ds_read_b128 v[200:203], v59 offset:32
	ds_read_b128 v[204:207], v59 offset:48
	ds_read_b128 v[208:211], v59 offset:64
	ds_read_b128 v[212:215], v59 offset:80
	ds_read_b128 v[216:219], v59 offset:96
	ds_read_b128 v[220:223], v59 offset:112
	ds_read_b128 v[224:227], v59 offset:128
	ds_read_b128 v[228:231], v59 offset:144
	ds_read_b128 v[232:235], v59 offset:160
	ds_read_b128 v[236:239], v59 offset:176
	ds_read_b128 v[240:243], v59 offset:192
	ds_read_b128 v[244:247], v59 offset:208
	ds_read_b128 v[248:251], v59 offset:224
	ds_read_b64 v[252:253], v59 offset:240
	ds_read_b32 v186, v59 offset:248
	s_add_i32 s1, s9, -7
	s_max_i32 s1, s1, 0
	s_add_u32 s1, s1, s27
	s_lshl_b32 s1, s1, 11
	v_add_u32_e32 v30, s1, v1
	global_load_dwordx2 v[76:77], v30, s[76:77]
	s_add_i32 s1, s9, -6
	s_max_i32 s1, s1, 0
	s_add_u32 s1, s1, s27
	s_lshl_b32 s1, s1, 11
	v_add_u32_e32 v31, s1, v1
	global_load_dwordx2 v[78:79], v31, s[76:77]
	s_add_i32 s1, s9, -5
	s_max_i32 s1, s1, 0
	s_add_u32 s1, s1, s27
	s_lshl_b32 s1, s1, 11
	v_add_u32_e32 v32, s1, v1
	global_load_dwordx2 v[80:81], v32, s[76:77]
	s_add_i32 s1, s9, -4
	s_max_i32 s1, s1, 0
	s_add_u32 s1, s1, s27
	s_lshl_b32 s1, s1, 11
	v_add_u32_e32 v33, s1, v1
	global_load_dwordx2 v[82:83], v33, s[76:77]
	s_add_i32 s1, s9, -3
	s_max_i32 s1, s1, 0
	s_add_u32 s1, s1, s27
	s_lshl_b32 s1, s1, 11
	v_add_u32_e32 v34, s1, v1
	global_load_dwordx2 v[84:85], v34, s[76:77]
	s_add_i32 s1, s9, -2
	s_max_i32 s1, s1, 0
	s_add_u32 s1, s1, s27
	s_lshl_b32 s1, s1, 11
	v_add_u32_e32 v35, s1, v1
	global_load_dwordx2 v[86:87], v35, s[76:77]
	s_add_i32 s1, s9, -1
	s_max_i32 s1, s1, 0
	s_add_u32 s1, s1, s27
	s_lshl_b32 s1, s1, 11
	v_add_u32_e32 v36, s1, v1
	global_load_dwordx2 v[88:89], v36, s[76:77]
	global_load_dwordx2 v[90:91], v8, s[76:77]
	v_add_u32_e32 v30, 0x800, v8
	global_load_dwordx2 v[92:93], v30, s[76:77]
	v_add_u32_e32 v31, 0x1000, v8
	global_load_dwordx2 v[94:95], v31, s[76:77]
	v_add_u32_e32 v32, 0x1800, v8
	global_load_dwordx2 v[96:97], v32, s[76:77]
	v_add_u32_e32 v33, 0x2000, v8
	global_load_dwordx2 v[98:99], v33, s[76:77]
	v_add_u32_e32 v34, 0x2800, v8
	global_load_dwordx2 v[100:101], v34, s[76:77]
	v_add_u32_e32 v35, 0x3000, v8
	global_load_dwordx2 v[102:103], v35, s[76:77]
	v_add_u32_e32 v36, 0x3800, v8
	global_load_dwordx2 v[104:105], v36, s[76:77]
	v_add_u32_e32 v37, 0x4000, v8
	global_load_dwordx2 v[106:107], v37, s[76:77]
	v_add_u32_e32 v30, 0x4800, v8
	global_load_dwordx2 v[108:109], v30, s[76:77]
	v_add_u32_e32 v31, 0x5000, v8
	global_load_dwordx2 v[110:111], v31, s[76:77]
	v_add_u32_e32 v32, 0x5800, v8
	global_load_dwordx2 v[112:113], v32, s[76:77]
	v_add_u32_e32 v33, 0x6000, v8
	global_load_dwordx2 v[114:115], v33, s[76:77]
	v_add_u32_e32 v34, 0x6800, v8
	global_load_dwordx2 v[116:117], v34, s[76:77]
	v_add_u32_e32 v35, 0x7000, v8
	global_load_dwordx2 v[118:119], v35, s[76:77]
	v_add_u32_e32 v36, 0x7800, v8
	global_load_dwordx2 v[120:121], v36, s[76:77]
	v_add_u32_e32 v37, 0x8000, v8
	global_load_dwordx2 v[122:123], v37, s[76:77]
	v_add_u32_e32 v30, 0x8800, v8
	global_load_dwordx2 v[124:125], v30, s[76:77]
	v_add_u32_e32 v31, 0x9000, v8
	global_load_dwordx2 v[126:127], v31, s[76:77]
	v_add_u32_e32 v32, 0x9800, v8
	global_load_dwordx2 v[128:129], v32, s[76:77]
	v_add_u32_e32 v33, 0xa000, v8
	global_load_dwordx2 v[130:131], v33, s[76:77]
	v_add_u32_e32 v34, 0xa800, v8
; __device__ __forceinline__ float bflo(unsigned u) { return __uint_as_float(u << 16); }
; __device__ __forceinline__ float bfhi(unsigned u) { return __uint_as_float(u & 0xffff0000u); }
; __device__ __forceinline__ void phase_pool(const Params& p, char* smraw) {
;     ...
;     for (int i = 1; i < win; ++i) {
;       const int pp = c0 - i;
;       if (pp >= 0) {
;         u32x2 v = *(const u32x2*)(base + (size_t)pp * D);
;         const float rs = rstd_s[15 - i];
;         s0 += bflo(v[0]) * rs; s1 += bfhi(v[0]) * rs; s2 += bflo(v[1]) * rs; s3 += bfhi(v[1]) * rs;
;       }
;     }
;     for (int t8 = 0; t8 < CH; t8 += 8) {
;       u32x2 cur[8], old[8];
; #pragma unroll
;       for (int k = 0; k < 8; ++k) {
;         const int pp = c0 + t8 + k;
;         cur[k] = *(const u32x2*)(base + (size_t)pp * D);
;         const int po = pp - win + 1;
;         old[k] = *(const u32x2*)(base + (size_t)(po >= 0 ? po : 0) * D);
;       }
; #pragma unroll
;       for (int k = 0; k < 8; ++k) {
;         const int tt = t8 + k, pp = c0 + tt;
;         const float rs = rstd_s[tt + 15];
;         const float x0 = bflo(cur[k][0]) * rs, x1 = bfhi(cur[k][0]) * rs, x2 = bflo(cur[k][1]) * rs, x3 = bfhi(cur[k][1]) * rs;
;         s0 += x0; s1 += x1; s2 += x2; s3 += x3;
;         const int cnt = (pp + 1 < win) ? pp + 1 : win;
;         const float inv = 1.f / (float)cnt;
;         u32x2 o; o[0] = cvtpk(s0 * inv - x0, s1 * inv - x1); o[1] = cvtpk(s2 * inv - x2, s3 * inv - x3);
;         *(u32x2*)(p.pooled + (size_t)(b * L + pp) * D + c) = o;
;         const int po = pp - win + 1;
;         if (po >= 0) {
;           const float ro = rstd_s[tt + 15 - win + 1];
;           s0 -= bflo(old[k][0]) * ro; s1 -= bfhi(old[k][0]) * ro; s2 -= bflo(old[k][1]) * ro; s3 -= bfhi(old[k][1]) * ro;
;         }
;       }
	global_load_dwordx2 v[132:133], v34, s[76:77]
	v_add_u32_e32 v35, 0xb000, v8
	global_load_dwordx2 v[134:135], v35, s[76:77]
	v_add_u32_e32 v36, 0xb800, v8
	global_load_dwordx2 v[136:137], v36, s[76:77]
	v_add_u32_e32 v37, 0xc000, v8
	global_load_dwordx2 v[138:139], v37, s[76:77]
	v_add_u32_e32 v30, 0xc800, v8
	global_load_dwordx2 v[140:141], v30, s[76:77]
	v_add_u32_e32 v31, 0xd000, v8
	global_load_dwordx2 v[142:143], v31, s[76:77]
	v_add_u32_e32 v32, 0xd800, v8
	global_load_dwordx2 v[144:145], v32, s[76:77]
	v_add_u32_e32 v33, 0xe000, v8
	global_load_dwordx2 v[146:147], v33, s[76:77]
	v_add_u32_e32 v34, 0xe800, v8
	global_load_dwordx2 v[148:149], v34, s[76:77]
	v_add_u32_e32 v35, 0xf000, v8
	global_load_dwordx2 v[150:151], v35, s[76:77]
	v_add_u32_e32 v36, 0xf800, v8
	global_load_dwordx2 v[152:153], v36, s[76:77]
	v_add_u32_e32 v37, 0x10000, v8
	global_load_dwordx2 v[154:155], v37, s[76:77]
	v_add_u32_e32 v30, 0x10800, v8
	global_load_dwordx2 v[156:157], v30, s[76:77]
	v_add_u32_e32 v31, 0x11000, v8
	global_load_dwordx2 v[158:159], v31, s[76:77]
	v_add_u32_e32 v32, 0x11800, v8
	global_load_dwordx2 v[160:161], v32, s[76:77]
	v_add_u32_e32 v33, 0x12000, v8
	global_load_dwordx2 v[162:163], v33, s[76:77]
	v_add_u32_e32 v34, 0x12800, v8
	global_load_dwordx2 v[164:165], v34, s[76:77]
	v_add_u32_e32 v35, 0x13000, v8
	global_load_dwordx2 v[166:167], v35, s[76:77]
	v_add_u32_e32 v36, 0x13800, v8
	global_load_dwordx2 v[168:169], v36, s[76:77]
	v_add_u32_e32 v37, 0x14000, v8
	global_load_dwordx2 v[170:171], v37, s[76:77]
	v_add_u32_e32 v30, 0x14800, v8
	global_load_dwordx2 v[172:173], v30, s[76:77]
	v_add_u32_e32 v31, 0x15000, v8
	global_load_dwordx2 v[174:175], v31, s[76:77]
	v_add_u32_e32 v32, 0x15800, v8
	global_load_dwordx2 v[176:177], v32, s[76:77]
	v_add_u32_e32 v33, 0x16000, v8
	global_load_dwordx2 v[178:179], v33, s[76:77]
	v_add_u32_e32 v34, 0x16800, v8
	global_load_dwordx2 v[180:181], v34, s[76:77]
	v_add_u32_e32 v35, 0x17000, v8
	global_load_dwordx2 v[182:183], v35, s[76:77]
	v_add_u32_e32 v36, 0x17800, v8
	global_load_dwordx2 v[184:185], v36, s[76:77]
	s_waitcnt lgkmcnt(0)
	s_cmp_lg_u32 s9, 0
	s_cbranch_scc1 .Lmy_pool_w2_nz
	v_mov_b32_e32 v192, 0
	v_mov_b32_e32 v193, 0
	v_mov_b32_e32 v194, 0
	v_mov_b32_e32 v195, 0
	v_mov_b32_e32 v196, 0
	v_mov_b32_e32 v197, 0
	v_mov_b32_e32 v198, 0
	v_mov_b32_e32 v199, 0
	v_mov_b32_e32 v200, 0
	v_mov_b32_e32 v201, 0
	v_mov_b32_e32 v202, 0
	v_mov_b32_e32 v203, 0
	v_mov_b32_e32 v204, 0
	v_mov_b32_e32 v205, 0
	v_mov_b32_e32 v206, 0
.Lmy_pool_w2_nz:
	v_mov_b32_e32 v10, 0
	v_mov_b32_e32 v11, 0
	v_mov_b32_e32 v12, 0
	v_mov_b32_e32 v13, 0
	s_waitcnt vmcnt(48)
	v_and_b32_e32 v14, 0xffff0000, v88
	v_lshlrev_b32_e32 v15, 16, v88
	v_and_b32_e32 v16, 0xffff0000, v89
	v_lshlrev_b32_e32 v17, 16, v89
	v_pk_fma_f32 v[10:11], v[206:207], v[14:15], v[10:11] op_sel_hi:[0,1,1]
	v_pk_fma_f32 v[12:13], v[206:207], v[16:17], v[12:13] op_sel_hi:[0,1,1]
	v_and_b32_e32 v14, 0xffff0000, v86
	v_lshlrev_b32_e32 v15, 16, v86
	v_and_b32_e32 v16, 0xffff0000, v87
	v_lshlrev_b32_e32 v17, 16, v87
	v_pk_fma_f32 v[10:11], v[204:205], v[14:15], v[10:11] op_sel:[1,0,0] op_sel_hi:[1,1,1]
	v_pk_fma_f32 v[12:13], v[204:205], v[16:17], v[12:13] op_sel:[1,0,0] op_sel_hi:[1,1,1]
	v_and_b32_e32 v14, 0xffff0000, v84
	v_lshlrev_b32_e32 v15, 16, v84
	v_and_b32_e32 v16, 0xffff0000, v85
	v_lshlrev_b32_e32 v17, 16, v85
	v_pk_fma_f32 v[10:11], v[204:205], v[14:15], v[10:11] op_sel_hi:[0,1,1]
	v_pk_fma_f32 v[12:13], v[204:205], v[16:17], v[12:13] op_sel_hi:[0,1,1]
	v_and_b32_e32 v14, 0xffff0000, v82
	v_lshlrev_b32_e32 v15, 16, v82
	v_and_b32_e32 v16, 0xffff0000, v83
	v_lshlrev_b32_e32 v17, 16, v83
	v_pk_fma_f32 v[10:11], v[202:203], v[14:15], v[10:11] op_sel:[1,0,0] op_sel_hi:[1,1,1]
	v_pk_fma_f32 v[12:13], v[202:203], v[16:17], v[12:13] op_sel:[1,0,0] op_sel_hi:[1,1,1]
	v_and_b32_e32 v14, 0xffff0000, v80
	v_lshlrev_b32_e32 v15, 16, v80
	v_and_b32_e32 v16, 0xffff0000, v81
	v_lshlrev_b32_e32 v17, 16, v81
	v_pk_fma_f32 v[10:11], v[202:203], v[14:15], v[10:11] op_sel_hi:[0,1,1]
	v_pk_fma_f32 v[12:13], v[202:203], v[16:17], v[12:13] op_sel_hi:[0,1,1]
	v_and_b32_e32 v14, 0xffff0000, v78
	v_lshlrev_b32_e32 v15, 16, v78
	v_and_b32_e32 v16, 0xffff0000, v79
	v_lshlrev_b32_e32 v17, 16, v79
	v_pk_fma_f32 v[10:11], v[200:201], v[14:15], v[10:11] op_sel:[1,0,0] op_sel_hi:[1,1,1]
	v_pk_fma_f32 v[12:13], v[200:201], v[16:17], v[12:13] op_sel:[1,0,0] op_sel_hi:[1,1,1]
	v_and_b32_e32 v14, 0xffff0000, v76
	v_lshlrev_b32_e32 v15, 16, v76
	v_and_b32_e32 v16, 0xffff0000, v77
	v_lshlrev_b32_e32 v17, 16, v77
	v_pk_fma_f32 v[10:11], v[200:201], v[14:15], v[10:11] op_sel_hi:[0,1,1]
	v_pk_fma_f32 v[12:13], v[200:201], v[16:17], v[12:13] op_sel_hi:[0,1,1]
	s_waitcnt vmcnt(47)
	v_and_b32_e32 v14, 0xffff0000, v90
	v_lshlrev_b32_e32 v15, 16, v90
	v_and_b32_e32 v16, 0xffff0000, v91
	v_lshlrev_b32_e32 v17, 16, v91
	v_pk_mul_f32 v[18:19], v[206:207], v[14:15] op_sel:[1,0] op_sel_hi:[1,1]
	v_pk_mul_f32 v[20:21], v[206:207], v[16:17] op_sel:[1,0] op_sel_hi:[1,1]
	v_pk_fma_f32 v[10:11], v[206:207], v[14:15], v[10:11] op_sel:[1,0,0] op_sel_hi:[1,1,1]
	v_pk_fma_f32 v[12:13], v[206:207], v[16:17], v[12:13] op_sel:[1,0,0] op_sel_hi:[1,1,1]
	s_cmp_eq_u32 s9, 0
	s_cselect_b32 s0, 0x3f800000, s35
	v_fma_f32 v22, s0, v11, -v19
	v_fma_f32 v23, s0, v10, -v18
	v_fma_f32 v24, s0, v13, -v21
	v_fma_f32 v25, s0, v12, -v20
	v_cvt_pk_bf16_f32 v22, v22, v23
	v_cvt_pk_bf16_f32 v23, v24, v25
	global_store_dwordx2 v8, v[22:23], s[62:63]
	v_and_b32_e32 v14, 0xffff0000, v76
	v_lshlrev_b32_e32 v15, 16, v76
	v_and_b32_e32 v16, 0xffff0000, v77
	v_lshlrev_b32_e32 v17, 16, v77
	v_pk_fma_f32 v[10:11], v[200:201], v[14:15], v[10:11] op_sel_hi:[0,1,1] neg_lo:[1,0,0] neg_hi:[1,0,0]
	v_pk_fma_f32 v[12:13], v[200:201], v[16:17], v[12:13] op_sel_hi:[0,1,1] neg_lo:[1,0,0] neg_hi:[1,0,0]
	s_waitcnt vmcnt(47)
; __device__ __forceinline__ float bflo(unsigned u) { return __uint_as_float(u << 16); }
; __device__ __forceinline__ float bfhi(unsigned u) { return __uint_as_float(u & 0xffff0000u); }
; __device__ __forceinline__ void phase_pool(const Params& p, char* smraw) {
;     ...
; #pragma unroll
;       for (int k = 0; k < 8; ++k) {
;         const int tt = t8 + k, pp = c0 + tt;
;         const float rs = rstd_s[tt + 15];
;         const float x0 = bflo(cur[k][0]) * rs, x1 = bfhi(cur[k][0]) * rs, x2 = bflo(cur[k][1]) * rs, x3 = bfhi(cur[k][1]) * rs;
;         s0 += x0; s1 += x1; s2 += x2; s3 += x3;
;         const int cnt = (pp + 1 < win) ? pp + 1 : win;
;         const float inv = 1.f / (float)cnt;
;         u32x2 o; o[0] = cvtpk(s0 * inv - x0, s1 * inv - x1); o[1] = cvtpk(s2 * inv - x2, s3 * inv - x3);
;         *(u32x2*)(p.pooled + (size_t)(b * L + pp) * D + c) = o;
;         const int po = pp - win + 1;
;         if (po >= 0) {
;           const float ro = rstd_s[tt + 15 - win + 1];
;           s0 -= bflo(old[k][0]) * ro; s1 -= bfhi(old[k][0]) * ro; s2 -= bflo(old[k][1]) * ro; s3 -= bfhi(old[k][1]) * ro;
;         }
;       }
	v_and_b32_e32 v14, 0xffff0000, v92
	v_lshlrev_b32_e32 v15, 16, v92
	v_and_b32_e32 v16, 0xffff0000, v93
	v_lshlrev_b32_e32 v17, 16, v93
	v_pk_mul_f32 v[18:19], v[208:209], v[14:15] op_sel_hi:[0,1]
	v_pk_mul_f32 v[20:21], v[208:209], v[16:17] op_sel_hi:[0,1]
	v_pk_fma_f32 v[10:11], v[208:209], v[14:15], v[10:11] op_sel_hi:[0,1,1]
	v_pk_fma_f32 v[12:13], v[208:209], v[16:17], v[12:13] op_sel_hi:[0,1,1]
	s_cmp_eq_u32 s9, 0
	s_cselect_b32 s0, 0x3f000000, s35
	v_fma_f32 v26, s0, v11, -v19
	v_fma_f32 v27, s0, v10, -v18
	v_fma_f32 v28, s0, v13, -v21
	v_fma_f32 v29, s0, v12, -v20
	v_cvt_pk_bf16_f32 v26, v26, v27
	v_cvt_pk_bf16_f32 v27, v28, v29
	v_add_u32_e32 v31, 0x800, v8
	global_store_dwordx2 v31, v[26:27], s[62:63]
	v_and_b32_e32 v14, 0xffff0000, v78
	v_lshlrev_b32_e32 v15, 16, v78
	v_and_b32_e32 v16, 0xffff0000, v79
	v_lshlrev_b32_e32 v17, 16, v79
	v_pk_fma_f32 v[10:11], v[200:201], v[14:15], v[10:11] op_sel:[1,0,0] op_sel_hi:[1,1,1] neg_lo:[1,0,0] neg_hi:[1,0,0]
	v_pk_fma_f32 v[12:13], v[200:201], v[16:17], v[12:13] op_sel:[1,0,0] op_sel_hi:[1,1,1] neg_lo:[1,0,0] neg_hi:[1,0,0]
	s_waitcnt vmcnt(47)
	v_and_b32_e32 v14, 0xffff0000, v94
	v_lshlrev_b32_e32 v15, 16, v94
	v_and_b32_e32 v16, 0xffff0000, v95
	v_lshlrev_b32_e32 v17, 16, v95
	v_pk_mul_f32 v[18:19], v[208:209], v[14:15] op_sel:[1,0] op_sel_hi:[1,1]
	v_pk_mul_f32 v[20:21], v[208:209], v[16:17] op_sel:[1,0] op_sel_hi:[1,1]
	v_pk_fma_f32 v[10:11], v[208:209], v[14:15], v[10:11] op_sel:[1,0,0] op_sel_hi:[1,1,1]
	v_pk_fma_f32 v[12:13], v[208:209], v[16:17], v[12:13] op_sel:[1,0,0] op_sel_hi:[1,1,1]
	s_cmp_eq_u32 s9, 0
	s_cselect_b32 s0, 0x3eaaaaab, s35
	v_fma_f32 v22, s0, v11, -v19
	v_fma_f32 v23, s0, v10, -v18
	v_fma_f32 v24, s0, v13, -v21
	v_fma_f32 v25, s0, v12, -v20
	v_cvt_pk_bf16_f32 v22, v22, v23
	v_cvt_pk_bf16_f32 v23, v24, v25
	v_add_u32_e32 v32, 0x1000, v8
	global_store_dwordx2 v32, v[22:23], s[62:63]
	v_and_b32_e32 v14, 0xffff0000, v80
	v_lshlrev_b32_e32 v15, 16, v80
	v_and_b32_e32 v16, 0xffff0000, v81
	v_lshlrev_b32_e32 v17, 16, v81
	v_pk_fma_f32 v[10:11], v[202:203], v[14:15], v[10:11] op_sel_hi:[0,1,1] neg_lo:[1,0,0] neg_hi:[1,0,0]
	v_pk_fma_f32 v[12:13], v[202:203], v[16:17], v[12:13] op_sel_hi:[0,1,1] neg_lo:[1,0,0] neg_hi:[1,0,0]
	s_waitcnt vmcnt(47)
	v_and_b32_e32 v14, 0xffff0000, v96
	v_lshlrev_b32_e32 v15, 16, v96
	v_and_b32_e32 v16, 0xffff0000, v97
	v_lshlrev_b32_e32 v17, 16, v97
	v_pk_mul_f32 v[18:19], v[210:211], v[14:15] op_sel_hi:[0,1]
	v_pk_mul_f32 v[20:21], v[210:211], v[16:17] op_sel_hi:[0,1]
	v_pk_fma_f32 v[10:11], v[210:211], v[14:15], v[10:11] op_sel_hi:[0,1,1]
	v_pk_fma_f32 v[12:13], v[210:211], v[16:17], v[12:13] op_sel_hi:[0,1,1]
	s_cmp_eq_u32 s9, 0
	s_cselect_b32 s0, 0x3e800000, s35
	v_fma_f32 v26, s0, v11, -v19
	v_fma_f32 v27, s0, v10, -v18
	v_fma_f32 v28, s0, v13, -v21
	v_fma_f32 v29, s0, v12, -v20
	v_cvt_pk_bf16_f32 v26, v26, v27
	v_cvt_pk_bf16_f32 v27, v28, v29
	v_add_u32_e32 v33, 0x1800, v8
	global_store_dwordx2 v33, v[26:27], s[62:63]
	v_and_b32_e32 v14, 0xffff0000, v82
	v_lshlrev_b32_e32 v15, 16, v82
	v_and_b32_e32 v16, 0xffff0000, v83
	v_lshlrev_b32_e32 v17, 16, v83
	v_pk_fma_f32 v[10:11], v[202:203], v[14:15], v[10:11] op_sel:[1,0,0] op_sel_hi:[1,1,1] neg_lo:[1,0,0] neg_hi:[1,0,0]
	v_pk_fma_f32 v[12:13], v[202:203], v[16:17], v[12:13] op_sel:[1,0,0] op_sel_hi:[1,1,1] neg_lo:[1,0,0] neg_hi:[1,0,0]
	s_waitcnt vmcnt(47)
	v_and_b32_e32 v14, 0xffff0000, v98
	v_lshlrev_b32_e32 v15, 16, v98
	v_and_b32_e32 v16, 0xffff0000, v99
	v_lshlrev_b32_e32 v17, 16, v99
	v_pk_mul_f32 v[18:19], v[210:211], v[14:15] op_sel:[1,0] op_sel_hi:[1,1]
	v_pk_mul_f32 v[20:21], v[210:211], v[16:17] op_sel:[1,0] op_sel_hi:[1,1]
	v_pk_fma_f32 v[10:11], v[210:211], v[14:15], v[10:11] op_sel:[1,0,0] op_sel_hi:[1,1,1]
	v_pk_fma_f32 v[12:13], v[210:211], v[16:17], v[12:13] op_sel:[1,0,0] op_sel_hi:[1,1,1]
	s_cmp_eq_u32 s9, 0
	s_cselect_b32 s0, 0x3e4ccccd, s35
	v_fma_f32 v22, s0, v11, -v19
	v_fma_f32 v23, s0, v10, -v18
	v_fma_f32 v24, s0, v13, -v21
	v_fma_f32 v25, s0, v12, -v20
	v_cvt_pk_bf16_f32 v22, v22, v23
	v_cvt_pk_bf16_f32 v23, v24, v25
	v_add_u32_e32 v34, 0x2000, v8
	global_store_dwordx2 v34, v[22:23], s[62:63]
	v_and_b32_e32 v14, 0xffff0000, v84
	v_lshlrev_b32_e32 v15, 16, v84
	v_and_b32_e32 v16, 0xffff0000, v85
	v_lshlrev_b32_e32 v17, 16, v85
	v_pk_fma_f32 v[10:11], v[204:205], v[14:15], v[10:11] op_sel_hi:[0,1,1] neg_lo:[1,0,0] neg_hi:[1,0,0]
	v_pk_fma_f32 v[12:13], v[204:205], v[16:17], v[12:13] op_sel_hi:[0,1,1] neg_lo:[1,0,0] neg_hi:[1,0,0]
	s_waitcnt vmcnt(47)
	v_and_b32_e32 v14, 0xffff0000, v100
	v_lshlrev_b32_e32 v15, 16, v100
	v_and_b32_e32 v16, 0xffff0000, v101
	v_lshlrev_b32_e32 v17, 16, v101
	v_pk_mul_f32 v[18:19], v[212:213], v[14:15] op_sel_hi:[0,1]
	v_pk_mul_f32 v[20:21], v[212:213], v[16:17] op_sel_hi:[0,1]
	v_pk_fma_f32 v[10:11], v[212:213], v[14:15], v[10:11] op_sel_hi:[0,1,1]
	v_pk_fma_f32 v[12:13], v[212:213], v[16:17], v[12:13] op_sel_hi:[0,1,1]
	s_cmp_eq_u32 s9, 0
	s_cselect_b32 s0, 0x3e2aaaab, s35
	v_fma_f32 v26, s0, v11, -v19
	v_fma_f32 v27, s0, v10, -v18
	v_fma_f32 v28, s0, v13, -v21
	v_fma_f32 v29, s0, v12, -v20
	v_cvt_pk_bf16_f32 v26, v26, v27
	v_cvt_pk_bf16_f32 v27, v28, v29
	v_add_u32_e32 v35, 0x2800, v8
	global_store_dwordx2 v35, v[26:27], s[62:63]
	v_and_b32_e32 v14, 0xffff0000, v86
	v_lshlrev_b32_e32 v15, 16, v86
	v_and_b32_e32 v16, 0xffff0000, v87
	v_lshlrev_b32_e32 v17, 16, v87
	v_pk_fma_f32 v[10:11], v[204:205], v[14:15], v[10:11] op_sel:[1,0,0] op_sel_hi:[1,1,1] neg_lo:[1,0,0] neg_hi:[1,0,0]
	v_pk_fma_f32 v[12:13], v[204:205], v[16:17], v[12:13] op_sel:[1,0,0] op_sel_hi:[1,1,1] neg_lo:[1,0,0] neg_hi:[1,0,0]
	s_waitcnt vmcnt(47)
; __device__ __forceinline__ float bflo(unsigned u) { return __uint_as_float(u << 16); }
; __device__ __forceinline__ float bfhi(unsigned u) { return __uint_as_float(u & 0xffff0000u); }
; __device__ __forceinline__ void phase_pool(const Params& p, char* smraw) {
;     ...
; #pragma unroll
;       for (int k = 0; k < 8; ++k) {
;         const int tt = t8 + k, pp = c0 + tt;
;         const float rs = rstd_s[tt + 15];
;         const float x0 = bflo(cur[k][0]) * rs, x1 = bfhi(cur[k][0]) * rs, x2 = bflo(cur[k][1]) * rs, x3 = bfhi(cur[k][1]) * rs;
;         s0 += x0; s1 += x1; s2 += x2; s3 += x3;
;         const int cnt = (pp + 1 < win) ? pp + 1 : win;
;         const float inv = 1.f / (float)cnt;
;         u32x2 o; o[0] = cvtpk(s0 * inv - x0, s1 * inv - x1); o[1] = cvtpk(s2 * inv - x2, s3 * inv - x3);
;         *(u32x2*)(p.pooled + (size_t)(b * L + pp) * D + c) = o;
;         const int po = pp - win + 1;
;         if (po >= 0) {
;           const float ro = rstd_s[tt + 15 - win + 1];
;           s0 -= bflo(old[k][0]) * ro; s1 -= bfhi(old[k][0]) * ro; s2 -= bflo(old[k][1]) * ro; s3 -= bfhi(old[k][1]) * ro;
;         }
;       }
	v_and_b32_e32 v14, 0xffff0000, v102
	v_lshlrev_b32_e32 v15, 16, v102
	v_and_b32_e32 v16, 0xffff0000, v103
	v_lshlrev_b32_e32 v17, 16, v103
	v_pk_mul_f32 v[18:19], v[212:213], v[14:15] op_sel:[1,0] op_sel_hi:[1,1]
	v_pk_mul_f32 v[20:21], v[212:213], v[16:17] op_sel:[1,0] op_sel_hi:[1,1]
	v_pk_fma_f32 v[10:11], v[212:213], v[14:15], v[10:11] op_sel:[1,0,0] op_sel_hi:[1,1,1]
	v_pk_fma_f32 v[12:13], v[212:213], v[16:17], v[12:13] op_sel:[1,0,0] op_sel_hi:[1,1,1]
	s_cmp_eq_u32 s9, 0
	s_cselect_b32 s0, 0x3e124925, s35
	v_fma_f32 v22, s0, v11, -v19
	v_fma_f32 v23, s0, v10, -v18
	v_fma_f32 v24, s0, v13, -v21
	v_fma_f32 v25, s0, v12, -v20
	v_cvt_pk_bf16_f32 v22, v22, v23
	v_cvt_pk_bf16_f32 v23, v24, v25
	v_add_u32_e32 v36, 0x3000, v8
	global_store_dwordx2 v36, v[22:23], s[62:63]
	v_and_b32_e32 v14, 0xffff0000, v88
	v_lshlrev_b32_e32 v15, 16, v88
	v_and_b32_e32 v16, 0xffff0000, v89
	v_lshlrev_b32_e32 v17, 16, v89
	v_pk_fma_f32 v[10:11], v[206:207], v[14:15], v[10:11] op_sel_hi:[0,1,1] neg_lo:[1,0,0] neg_hi:[1,0,0]
	v_pk_fma_f32 v[12:13], v[206:207], v[16:17], v[12:13] op_sel_hi:[0,1,1] neg_lo:[1,0,0] neg_hi:[1,0,0]
	s_waitcnt vmcnt(47)
	v_and_b32_e32 v14, 0xffff0000, v104
	v_lshlrev_b32_e32 v15, 16, v104
	v_and_b32_e32 v16, 0xffff0000, v105
	v_lshlrev_b32_e32 v17, 16, v105
	v_pk_mul_f32 v[18:19], v[214:215], v[14:15] op_sel_hi:[0,1]
	v_pk_mul_f32 v[20:21], v[214:215], v[16:17] op_sel_hi:[0,1]
	v_pk_fma_f32 v[10:11], v[214:215], v[14:15], v[10:11] op_sel_hi:[0,1,1]
	v_pk_fma_f32 v[12:13], v[214:215], v[16:17], v[12:13] op_sel_hi:[0,1,1]
	s_mov_b32 s0, s35
	v_fma_f32 v26, s0, v11, -v19
	v_fma_f32 v27, s0, v10, -v18
	v_fma_f32 v28, s0, v13, -v21
	v_fma_f32 v29, s0, v12, -v20
	v_cvt_pk_bf16_f32 v26, v26, v27
	v_cvt_pk_bf16_f32 v27, v28, v29
	v_add_u32_e32 v37, 0x3800, v8
	global_store_dwordx2 v37, v[26:27], s[62:63]
	v_and_b32_e32 v14, 0xffff0000, v90
	v_lshlrev_b32_e32 v15, 16, v90
	v_and_b32_e32 v16, 0xffff0000, v91
	v_lshlrev_b32_e32 v17, 16, v91
	v_pk_fma_f32 v[10:11], v[206:207], v[14:15], v[10:11] op_sel:[1,0,0] op_sel_hi:[1,1,1] neg_lo:[1,0,0] neg_hi:[1,0,0]
	v_pk_fma_f32 v[12:13], v[206:207], v[16:17], v[12:13] op_sel:[1,0,0] op_sel_hi:[1,1,1] neg_lo:[1,0,0] neg_hi:[1,0,0]
	s_waitcnt vmcnt(47)
	v_and_b32_e32 v14, 0xffff0000, v106
	v_lshlrev_b32_e32 v15, 16, v106
	v_and_b32_e32 v16, 0xffff0000, v107
	v_lshlrev_b32_e32 v17, 16, v107
	v_pk_mul_f32 v[18:19], v[214:215], v[14:15] op_sel:[1,0] op_sel_hi:[1,1]
	v_pk_mul_f32 v[20:21], v[214:215], v[16:17] op_sel:[1,0] op_sel_hi:[1,1]
	v_pk_fma_f32 v[10:11], v[214:215], v[14:15], v[10:11] op_sel:[1,0,0] op_sel_hi:[1,1,1]
	v_pk_fma_f32 v[12:13], v[214:215], v[16:17], v[12:13] op_sel:[1,0,0] op_sel_hi:[1,1,1]
	v_fma_f32 v22, s0, v11, -v19
	v_fma_f32 v23, s0, v10, -v18
	v_fma_f32 v24, s0, v13, -v21
	v_fma_f32 v25, s0, v12, -v20
	v_cvt_pk_bf16_f32 v22, v22, v23
	v_cvt_pk_bf16_f32 v23, v24, v25
	v_add_u32_e32 v30, 0x4000, v8
	global_store_dwordx2 v30, v[22:23], s[62:63]
	v_and_b32_e32 v14, 0xffff0000, v92
	v_lshlrev_b32_e32 v15, 16, v92
	v_and_b32_e32 v16, 0xffff0000, v93
	v_lshlrev_b32_e32 v17, 16, v93
	v_pk_fma_f32 v[10:11], v[208:209], v[14:15], v[10:11] op_sel_hi:[0,1,1] neg_lo:[1,0,0] neg_hi:[1,0,0]
	v_pk_fma_f32 v[12:13], v[208:209], v[16:17], v[12:13] op_sel_hi:[0,1,1] neg_lo:[1,0,0] neg_hi:[1,0,0]
	s_waitcnt vmcnt(47)
	v_and_b32_e32 v14, 0xffff0000, v108
	v_lshlrev_b32_e32 v15, 16, v108
	v_and_b32_e32 v16, 0xffff0000, v109
	v_lshlrev_b32_e32 v17, 16, v109
	v_pk_mul_f32 v[18:19], v[216:217], v[14:15] op_sel_hi:[0,1]
	v_pk_mul_f32 v[20:21], v[216:217], v[16:17] op_sel_hi:[0,1]
	v_pk_fma_f32 v[10:11], v[216:217], v[14:15], v[10:11] op_sel_hi:[0,1,1]
	v_pk_fma_f32 v[12:13], v[216:217], v[16:17], v[12:13] op_sel_hi:[0,1,1]
	v_fma_f32 v26, s0, v11, -v19
	v_fma_f32 v27, s0, v10, -v18
	v_fma_f32 v28, s0, v13, -v21
	v_fma_f32 v29, s0, v12, -v20
	v_cvt_pk_bf16_f32 v26, v26, v27
	v_cvt_pk_bf16_f32 v27, v28, v29
	v_add_u32_e32 v31, 0x4800, v8
	global_store_dwordx2 v31, v[26:27], s[62:63]
	v_and_b32_e32 v14, 0xffff0000, v94
	v_lshlrev_b32_e32 v15, 16, v94
	v_and_b32_e32 v16, 0xffff0000, v95
	v_lshlrev_b32_e32 v17, 16, v95
	v_pk_fma_f32 v[10:11], v[208:209], v[14:15], v[10:11] op_sel:[1,0,0] op_sel_hi:[1,1,1] neg_lo:[1,0,0] neg_hi:[1,0,0]
	v_pk_fma_f32 v[12:13], v[208:209], v[16:17], v[12:13] op_sel:[1,0,0] op_sel_hi:[1,1,1] neg_lo:[1,0,0] neg_hi:[1,0,0]
	s_waitcnt vmcnt(47)
	v_and_b32_e32 v14, 0xffff0000, v110
	v_lshlrev_b32_e32 v15, 16, v110
	v_and_b32_e32 v16, 0xffff0000, v111
	v_lshlrev_b32_e32 v17, 16, v111
	v_pk_mul_f32 v[18:19], v[216:217], v[14:15] op_sel:[1,0] op_sel_hi:[1,1]
	v_pk_mul_f32 v[20:21], v[216:217], v[16:17] op_sel:[1,0] op_sel_hi:[1,1]
	v_pk_fma_f32 v[10:11], v[216:217], v[14:15], v[10:11] op_sel:[1,0,0] op_sel_hi:[1,1,1]
	v_pk_fma_f32 v[12:13], v[216:217], v[16:17], v[12:13] op_sel:[1,0,0] op_sel_hi:[1,1,1]
	v_fma_f32 v22, s0, v11, -v19
	v_fma_f32 v23, s0, v10, -v18
	v_fma_f32 v24, s0, v13, -v21
	v_fma_f32 v25, s0, v12, -v20
	v_cvt_pk_bf16_f32 v22, v22, v23
	v_cvt_pk_bf16_f32 v23, v24, v25
	v_add_u32_e32 v32, 0x5000, v8
	global_store_dwordx2 v32, v[22:23], s[62:63]
	v_and_b32_e32 v14, 0xffff0000, v96
	v_lshlrev_b32_e32 v15, 16, v96
	v_and_b32_e32 v16, 0xffff0000, v97
	v_lshlrev_b32_e32 v17, 16, v97
	v_pk_fma_f32 v[10:11], v[210:211], v[14:15], v[10:11] op_sel_hi:[0,1,1] neg_lo:[1,0,0] neg_hi:[1,0,0]
	v_pk_fma_f32 v[12:13], v[210:211], v[16:17], v[12:13] op_sel_hi:[0,1,1] neg_lo:[1,0,0] neg_hi:[1,0,0]
	s_waitcnt vmcnt(47)
; __device__ __forceinline__ float bflo(unsigned u) { return __uint_as_float(u << 16); }
; __device__ __forceinline__ float bfhi(unsigned u) { return __uint_as_float(u & 0xffff0000u); }
; __device__ __forceinline__ void phase_pool(const Params& p, char* smraw) {
;     ...
; #pragma unroll
;       for (int k = 0; k < 8; ++k) {
;         const int tt = t8 + k, pp = c0 + tt;
;         const float rs = rstd_s[tt + 15];
;         const float x0 = bflo(cur[k][0]) * rs, x1 = bfhi(cur[k][0]) * rs, x2 = bflo(cur[k][1]) * rs, x3 = bfhi(cur[k][1]) * rs;
;         s0 += x0; s1 += x1; s2 += x2; s3 += x3;
;         const int cnt = (pp + 1 < win) ? pp + 1 : win;
;         const float inv = 1.f / (float)cnt;
;         u32x2 o; o[0] = cvtpk(s0 * inv - x0, s1 * inv - x1); o[1] = cvtpk(s2 * inv - x2, s3 * inv - x3);
;         *(u32x2*)(p.pooled + (size_t)(b * L + pp) * D + c) = o;
;         const int po = pp - win + 1;
;         if (po >= 0) {
;           const float ro = rstd_s[tt + 15 - win + 1];
;           s0 -= bflo(old[k][0]) * ro; s1 -= bfhi(old[k][0]) * ro; s2 -= bflo(old[k][1]) * ro; s3 -= bfhi(old[k][1]) * ro;
;         }
;       }
	v_and_b32_e32 v14, 0xffff0000, v112
	v_lshlrev_b32_e32 v15, 16, v112
	v_and_b32_e32 v16, 0xffff0000, v113
	v_lshlrev_b32_e32 v17, 16, v113
	v_pk_mul_f32 v[18:19], v[218:219], v[14:15] op_sel_hi:[0,1]
	v_pk_mul_f32 v[20:21], v[218:219], v[16:17] op_sel_hi:[0,1]
	v_pk_fma_f32 v[10:11], v[218:219], v[14:15], v[10:11] op_sel_hi:[0,1,1]
	v_pk_fma_f32 v[12:13], v[218:219], v[16:17], v[12:13] op_sel_hi:[0,1,1]
	v_fma_f32 v26, s0, v11, -v19
	v_fma_f32 v27, s0, v10, -v18
	v_fma_f32 v28, s0, v13, -v21
	v_fma_f32 v29, s0, v12, -v20
	v_cvt_pk_bf16_f32 v26, v26, v27
	v_cvt_pk_bf16_f32 v27, v28, v29
	v_add_u32_e32 v33, 0x5800, v8
	global_store_dwordx2 v33, v[26:27], s[62:63]
	v_and_b32_e32 v14, 0xffff0000, v98
	v_lshlrev_b32_e32 v15, 16, v98
	v_and_b32_e32 v16, 0xffff0000, v99
	v_lshlrev_b32_e32 v17, 16, v99
	v_pk_fma_f32 v[10:11], v[210:211], v[14:15], v[10:11] op_sel:[1,0,0] op_sel_hi:[1,1,1] neg_lo:[1,0,0] neg_hi:[1,0,0]
	v_pk_fma_f32 v[12:13], v[210:211], v[16:17], v[12:13] op_sel:[1,0,0] op_sel_hi:[1,1,1] neg_lo:[1,0,0] neg_hi:[1,0,0]
	s_waitcnt vmcnt(47)
	v_and_b32_e32 v14, 0xffff0000, v114
	v_lshlrev_b32_e32 v15, 16, v114
	v_and_b32_e32 v16, 0xffff0000, v115
	v_lshlrev_b32_e32 v17, 16, v115
	v_pk_mul_f32 v[18:19], v[218:219], v[14:15] op_sel:[1,0] op_sel_hi:[1,1]
	v_pk_mul_f32 v[20:21], v[218:219], v[16:17] op_sel:[1,0] op_sel_hi:[1,1]
	v_pk_fma_f32 v[10:11], v[218:219], v[14:15], v[10:11] op_sel:[1,0,0] op_sel_hi:[1,1,1]
	v_pk_fma_f32 v[12:13], v[218:219], v[16:17], v[12:13] op_sel:[1,0,0] op_sel_hi:[1,1,1]
	v_fma_f32 v22, s0, v11, -v19
	v_fma_f32 v23, s0, v10, -v18
	v_fma_f32 v24, s0, v13, -v21
	v_fma_f32 v25, s0, v12, -v20
	v_cvt_pk_bf16_f32 v22, v22, v23
	v_cvt_pk_bf16_f32 v23, v24, v25
	v_add_u32_e32 v34, 0x6000, v8
	global_store_dwordx2 v34, v[22:23], s[62:63]
	v_and_b32_e32 v14, 0xffff0000, v100
	v_lshlrev_b32_e32 v15, 16, v100
	v_and_b32_e32 v16, 0xffff0000, v101
	v_lshlrev_b32_e32 v17, 16, v101
	v_pk_fma_f32 v[10:11], v[212:213], v[14:15], v[10:11] op_sel_hi:[0,1,1] neg_lo:[1,0,0] neg_hi:[1,0,0]
	v_pk_fma_f32 v[12:13], v[212:213], v[16:17], v[12:13] op_sel_hi:[0,1,1] neg_lo:[1,0,0] neg_hi:[1,0,0]
	s_waitcnt vmcnt(47)
	v_and_b32_e32 v14, 0xffff0000, v116
	v_lshlrev_b32_e32 v15, 16, v116
	v_and_b32_e32 v16, 0xffff0000, v117
	v_lshlrev_b32_e32 v17, 16, v117
	v_pk_mul_f32 v[18:19], v[220:221], v[14:15] op_sel_hi:[0,1]
	v_pk_mul_f32 v[20:21], v[220:221], v[16:17] op_sel_hi:[0,1]
	v_pk_fma_f32 v[10:11], v[220:221], v[14:15], v[10:11] op_sel_hi:[0,1,1]
	v_pk_fma_f32 v[12:13], v[220:221], v[16:17], v[12:13] op_sel_hi:[0,1,1]
	v_fma_f32 v26, s0, v11, -v19
	v_fma_f32 v27, s0, v10, -v18
	v_fma_f32 v28, s0, v13, -v21
	v_fma_f32 v29, s0, v12, -v20
	v_cvt_pk_bf16_f32 v26, v26, v27
	v_cvt_pk_bf16_f32 v27, v28, v29
	v_add_u32_e32 v35, 0x6800, v8
	global_store_dwordx2 v35, v[26:27], s[62:63]
	v_and_b32_e32 v14, 0xffff0000, v102
	v_lshlrev_b32_e32 v15, 16, v102
	v_and_b32_e32 v16, 0xffff0000, v103
	v_lshlrev_b32_e32 v17, 16, v103
	v_pk_fma_f32 v[10:11], v[212:213], v[14:15], v[10:11] op_sel:[1,0,0] op_sel_hi:[1,1,1] neg_lo:[1,0,0] neg_hi:[1,0,0]
	v_pk_fma_f32 v[12:13], v[212:213], v[16:17], v[12:13] op_sel:[1,0,0] op_sel_hi:[1,1,1] neg_lo:[1,0,0] neg_hi:[1,0,0]
	s_waitcnt vmcnt(47)
	v_and_b32_e32 v14, 0xffff0000, v118
	v_lshlrev_b32_e32 v15, 16, v118
	v_and_b32_e32 v16, 0xffff0000, v119
	v_lshlrev_b32_e32 v17, 16, v119
	v_pk_mul_f32 v[18:19], v[220:221], v[14:15] op_sel:[1,0] op_sel_hi:[1,1]
	v_pk_mul_f32 v[20:21], v[220:221], v[16:17] op_sel:[1,0] op_sel_hi:[1,1]
	v_pk_fma_f32 v[10:11], v[220:221], v[14:15], v[10:11] op_sel:[1,0,0] op_sel_hi:[1,1,1]
	v_pk_fma_f32 v[12:13], v[220:221], v[16:17], v[12:13] op_sel:[1,0,0] op_sel_hi:[1,1,1]
	v_fma_f32 v22, s0, v11, -v19
	v_fma_f32 v23, s0, v10, -v18
	v_fma_f32 v24, s0, v13, -v21
	v_fma_f32 v25, s0, v12, -v20
	v_cvt_pk_bf16_f32 v22, v22, v23
	v_cvt_pk_bf16_f32 v23, v24, v25
	v_add_u32_e32 v36, 0x7000, v8
	global_store_dwordx2 v36, v[22:23], s[62:63]
	v_and_b32_e32 v14, 0xffff0000, v104
	v_lshlrev_b32_e32 v15, 16, v104
	v_and_b32_e32 v16, 0xffff0000, v105
	v_lshlrev_b32_e32 v17, 16, v105
	v_pk_fma_f32 v[10:11], v[214:215], v[14:15], v[10:11] op_sel_hi:[0,1,1] neg_lo:[1,0,0] neg_hi:[1,0,0]
	v_pk_fma_f32 v[12:13], v[214:215], v[16:17], v[12:13] op_sel_hi:[0,1,1] neg_lo:[1,0,0] neg_hi:[1,0,0]
	s_waitcnt vmcnt(47)
	v_and_b32_e32 v14, 0xffff0000, v120
	v_lshlrev_b32_e32 v15, 16, v120
	v_and_b32_e32 v16, 0xffff0000, v121
	v_lshlrev_b32_e32 v17, 16, v121
	v_pk_mul_f32 v[18:19], v[222:223], v[14:15] op_sel_hi:[0,1]
	v_pk_mul_f32 v[20:21], v[222:223], v[16:17] op_sel_hi:[0,1]
	v_pk_fma_f32 v[10:11], v[222:223], v[14:15], v[10:11] op_sel_hi:[0,1,1]
	v_pk_fma_f32 v[12:13], v[222:223], v[16:17], v[12:13] op_sel_hi:[0,1,1]
	v_fma_f32 v26, s0, v11, -v19
	v_fma_f32 v27, s0, v10, -v18
	v_fma_f32 v28, s0, v13, -v21
	v_fma_f32 v29, s0, v12, -v20
	v_cvt_pk_bf16_f32 v26, v26, v27
	v_cvt_pk_bf16_f32 v27, v28, v29
	v_add_u32_e32 v37, 0x7800, v8
	global_store_dwordx2 v37, v[26:27], s[62:63]
	v_and_b32_e32 v14, 0xffff0000, v106
	v_lshlrev_b32_e32 v15, 16, v106
	v_and_b32_e32 v16, 0xffff0000, v107
	v_lshlrev_b32_e32 v17, 16, v107
	v_pk_fma_f32 v[10:11], v[214:215], v[14:15], v[10:11] op_sel:[1,0,0] op_sel_hi:[1,1,1] neg_lo:[1,0,0] neg_hi:[1,0,0]
	v_pk_fma_f32 v[12:13], v[214:215], v[16:17], v[12:13] op_sel:[1,0,0] op_sel_hi:[1,1,1] neg_lo:[1,0,0] neg_hi:[1,0,0]
	s_waitcnt vmcnt(47)
; __device__ __forceinline__ float bflo(unsigned u) { return __uint_as_float(u << 16); }
; __device__ __forceinline__ float bfhi(unsigned u) { return __uint_as_float(u & 0xffff0000u); }
; __device__ __forceinline__ void phase_pool(const Params& p, char* smraw) {
;     ...
; #pragma unroll
;       for (int k = 0; k < 8; ++k) {
;         const int tt = t8 + k, pp = c0 + tt;
;         const float rs = rstd_s[tt + 15];
;         const float x0 = bflo(cur[k][0]) * rs, x1 = bfhi(cur[k][0]) * rs, x2 = bflo(cur[k][1]) * rs, x3 = bfhi(cur[k][1]) * rs;
;         s0 += x0; s1 += x1; s2 += x2; s3 += x3;
;         const int cnt = (pp + 1 < win) ? pp + 1 : win;
;         const float inv = 1.f / (float)cnt;
;         u32x2 o; o[0] = cvtpk(s0 * inv - x0, s1 * inv - x1); o[1] = cvtpk(s2 * inv - x2, s3 * inv - x3);
;         *(u32x2*)(p.pooled + (size_t)(b * L + pp) * D + c) = o;
;         const int po = pp - win + 1;
;         if (po >= 0) {
;           const float ro = rstd_s[tt + 15 - win + 1];
;           s0 -= bflo(old[k][0]) * ro; s1 -= bfhi(old[k][0]) * ro; s2 -= bflo(old[k][1]) * ro; s3 -= bfhi(old[k][1]) * ro;
;         }
;       }
	v_and_b32_e32 v14, 0xffff0000, v122
	v_lshlrev_b32_e32 v15, 16, v122
	v_and_b32_e32 v16, 0xffff0000, v123
	v_lshlrev_b32_e32 v17, 16, v123
	v_pk_mul_f32 v[18:19], v[222:223], v[14:15] op_sel:[1,0] op_sel_hi:[1,1]
	v_pk_mul_f32 v[20:21], v[222:223], v[16:17] op_sel:[1,0] op_sel_hi:[1,1]
	v_pk_fma_f32 v[10:11], v[222:223], v[14:15], v[10:11] op_sel:[1,0,0] op_sel_hi:[1,1,1]
	v_pk_fma_f32 v[12:13], v[222:223], v[16:17], v[12:13] op_sel:[1,0,0] op_sel_hi:[1,1,1]
	v_fma_f32 v22, s0, v11, -v19
	v_fma_f32 v23, s0, v10, -v18
	v_fma_f32 v24, s0, v13, -v21
	v_fma_f32 v25, s0, v12, -v20
	v_cvt_pk_bf16_f32 v22, v22, v23
	v_cvt_pk_bf16_f32 v23, v24, v25
	v_add_u32_e32 v30, 0x8000, v8
	global_store_dwordx2 v30, v[22:23], s[62:63]
	v_and_b32_e32 v14, 0xffff0000, v108
	v_lshlrev_b32_e32 v15, 16, v108
	v_and_b32_e32 v16, 0xffff0000, v109
	v_lshlrev_b32_e32 v17, 16, v109
	v_pk_fma_f32 v[10:11], v[216:217], v[14:15], v[10:11] op_sel_hi:[0,1,1] neg_lo:[1,0,0] neg_hi:[1,0,0]
	v_pk_fma_f32 v[12:13], v[216:217], v[16:17], v[12:13] op_sel_hi:[0,1,1] neg_lo:[1,0,0] neg_hi:[1,0,0]
	s_waitcnt vmcnt(47)
	v_and_b32_e32 v14, 0xffff0000, v124
	v_lshlrev_b32_e32 v15, 16, v124
	v_and_b32_e32 v16, 0xffff0000, v125
	v_lshlrev_b32_e32 v17, 16, v125
	v_pk_mul_f32 v[18:19], v[224:225], v[14:15] op_sel_hi:[0,1]
	v_pk_mul_f32 v[20:21], v[224:225], v[16:17] op_sel_hi:[0,1]
	v_pk_fma_f32 v[10:11], v[224:225], v[14:15], v[10:11] op_sel_hi:[0,1,1]
	v_pk_fma_f32 v[12:13], v[224:225], v[16:17], v[12:13] op_sel_hi:[0,1,1]
	v_fma_f32 v26, s0, v11, -v19
	v_fma_f32 v27, s0, v10, -v18
	v_fma_f32 v28, s0, v13, -v21
	v_fma_f32 v29, s0, v12, -v20
	v_cvt_pk_bf16_f32 v26, v26, v27
	v_cvt_pk_bf16_f32 v27, v28, v29
	v_add_u32_e32 v31, 0x8800, v8
	global_store_dwordx2 v31, v[26:27], s[62:63]
	v_and_b32_e32 v14, 0xffff0000, v110
	v_lshlrev_b32_e32 v15, 16, v110
	v_and_b32_e32 v16, 0xffff0000, v111
	v_lshlrev_b32_e32 v17, 16, v111
	v_pk_fma_f32 v[10:11], v[216:217], v[14:15], v[10:11] op_sel:[1,0,0] op_sel_hi:[1,1,1] neg_lo:[1,0,0] neg_hi:[1,0,0]
	v_pk_fma_f32 v[12:13], v[216:217], v[16:17], v[12:13] op_sel:[1,0,0] op_sel_hi:[1,1,1] neg_lo:[1,0,0] neg_hi:[1,0,0]
	s_waitcnt vmcnt(47)
	v_and_b32_e32 v14, 0xffff0000, v126
	v_lshlrev_b32_e32 v15, 16, v126
	v_and_b32_e32 v16, 0xffff0000, v127
	v_lshlrev_b32_e32 v17, 16, v127
	v_pk_mul_f32 v[18:19], v[224:225], v[14:15] op_sel:[1,0] op_sel_hi:[1,1]
	v_pk_mul_f32 v[20:21], v[224:225], v[16:17] op_sel:[1,0] op_sel_hi:[1,1]
	v_pk_fma_f32 v[10:11], v[224:225], v[14:15], v[10:11] op_sel:[1,0,0] op_sel_hi:[1,1,1]
	v_pk_fma_f32 v[12:13], v[224:225], v[16:17], v[12:13] op_sel:[1,0,0] op_sel_hi:[1,1,1]
	v_fma_f32 v22, s0, v11, -v19
	v_fma_f32 v23, s0, v10, -v18
	v_fma_f32 v24, s0, v13, -v21
	v_fma_f32 v25, s0, v12, -v20
	v_cvt_pk_bf16_f32 v22, v22, v23
	v_cvt_pk_bf16_f32 v23, v24, v25
	v_add_u32_e32 v32, 0x9000, v8
	global_store_dwordx2 v32, v[22:23], s[62:63]
	v_and_b32_e32 v14, 0xffff0000, v112
	v_lshlrev_b32_e32 v15, 16, v112
	v_and_b32_e32 v16, 0xffff0000, v113
	v_lshlrev_b32_e32 v17, 16, v113
	v_pk_fma_f32 v[10:11], v[218:219], v[14:15], v[10:11] op_sel_hi:[0,1,1] neg_lo:[1,0,0] neg_hi:[1,0,0]
	v_pk_fma_f32 v[12:13], v[218:219], v[16:17], v[12:13] op_sel_hi:[0,1,1] neg_lo:[1,0,0] neg_hi:[1,0,0]
	s_waitcnt vmcnt(47)
	v_and_b32_e32 v14, 0xffff0000, v128
	v_lshlrev_b32_e32 v15, 16, v128
	v_and_b32_e32 v16, 0xffff0000, v129
	v_lshlrev_b32_e32 v17, 16, v129
	v_pk_mul_f32 v[18:19], v[226:227], v[14:15] op_sel_hi:[0,1]
	v_pk_mul_f32 v[20:21], v[226:227], v[16:17] op_sel_hi:[0,1]
	v_pk_fma_f32 v[10:11], v[226:227], v[14:15], v[10:11] op_sel_hi:[0,1,1]
	v_pk_fma_f32 v[12:13], v[226:227], v[16:17], v[12:13] op_sel_hi:[0,1,1]
	v_fma_f32 v26, s0, v11, -v19
	v_fma_f32 v27, s0, v10, -v18
	v_fma_f32 v28, s0, v13, -v21
	v_fma_f32 v29, s0, v12, -v20
	v_cvt_pk_bf16_f32 v26, v26, v27
	v_cvt_pk_bf16_f32 v27, v28, v29
	v_add_u32_e32 v33, 0x9800, v8
	global_store_dwordx2 v33, v[26:27], s[62:63]
	v_and_b32_e32 v14, 0xffff0000, v114
	v_lshlrev_b32_e32 v15, 16, v114
	v_and_b32_e32 v16, 0xffff0000, v115
	v_lshlrev_b32_e32 v17, 16, v115
	v_pk_fma_f32 v[10:11], v[218:219], v[14:15], v[10:11] op_sel:[1,0,0] op_sel_hi:[1,1,1] neg_lo:[1,0,0] neg_hi:[1,0,0]
	v_pk_fma_f32 v[12:13], v[218:219], v[16:17], v[12:13] op_sel:[1,0,0] op_sel_hi:[1,1,1] neg_lo:[1,0,0] neg_hi:[1,0,0]
	s_waitcnt vmcnt(47)
	v_and_b32_e32 v14, 0xffff0000, v130
	v_lshlrev_b32_e32 v15, 16, v130
	v_and_b32_e32 v16, 0xffff0000, v131
	v_lshlrev_b32_e32 v17, 16, v131
	v_pk_mul_f32 v[18:19], v[226:227], v[14:15] op_sel:[1,0] op_sel_hi:[1,1]
	v_pk_mul_f32 v[20:21], v[226:227], v[16:17] op_sel:[1,0] op_sel_hi:[1,1]
	v_pk_fma_f32 v[10:11], v[226:227], v[14:15], v[10:11] op_sel:[1,0,0] op_sel_hi:[1,1,1]
	v_pk_fma_f32 v[12:13], v[226:227], v[16:17], v[12:13] op_sel:[1,0,0] op_sel_hi:[1,1,1]
	v_fma_f32 v22, s0, v11, -v19
	v_fma_f32 v23, s0, v10, -v18
	v_fma_f32 v24, s0, v13, -v21
	v_fma_f32 v25, s0, v12, -v20
	v_cvt_pk_bf16_f32 v22, v22, v23
	v_cvt_pk_bf16_f32 v23, v24, v25
	v_add_u32_e32 v34, 0xa000, v8
	global_store_dwordx2 v34, v[22:23], s[62:63]
	v_and_b32_e32 v14, 0xffff0000, v116
	v_lshlrev_b32_e32 v15, 16, v116
	v_and_b32_e32 v16, 0xffff0000, v117
	v_lshlrev_b32_e32 v17, 16, v117
	v_pk_fma_f32 v[10:11], v[220:221], v[14:15], v[10:11] op_sel_hi:[0,1,1] neg_lo:[1,0,0] neg_hi:[1,0,0]
	v_pk_fma_f32 v[12:13], v[220:221], v[16:17], v[12:13] op_sel_hi:[0,1,1] neg_lo:[1,0,0] neg_hi:[1,0,0]
	s_waitcnt vmcnt(47)
; __device__ __forceinline__ float bflo(unsigned u) { return __uint_as_float(u << 16); }
; __device__ __forceinline__ float bfhi(unsigned u) { return __uint_as_float(u & 0xffff0000u); }
; __device__ __forceinline__ void phase_pool(const Params& p, char* smraw) {
;     ...
; #pragma unroll
;       for (int k = 0; k < 8; ++k) {
;         const int tt = t8 + k, pp = c0 + tt;
;         const float rs = rstd_s[tt + 15];
;         const float x0 = bflo(cur[k][0]) * rs, x1 = bfhi(cur[k][0]) * rs, x2 = bflo(cur[k][1]) * rs, x3 = bfhi(cur[k][1]) * rs;
;         s0 += x0; s1 += x1; s2 += x2; s3 += x3;
;         const int cnt = (pp + 1 < win) ? pp + 1 : win;
;         const float inv = 1.f / (float)cnt;
;         u32x2 o; o[0] = cvtpk(s0 * inv - x0, s1 * inv - x1); o[1] = cvtpk(s2 * inv - x2, s3 * inv - x3);
;         *(u32x2*)(p.pooled + (size_t)(b * L + pp) * D + c) = o;
;         const int po = pp - win + 1;
;         if (po >= 0) {
;           const float ro = rstd_s[tt + 15 - win + 1];
;           s0 -= bflo(old[k][0]) * ro; s1 -= bfhi(old[k][0]) * ro; s2 -= bflo(old[k][1]) * ro; s3 -= bfhi(old[k][1]) * ro;
;         }
;       }
	v_and_b32_e32 v14, 0xffff0000, v132
	v_lshlrev_b32_e32 v15, 16, v132
	v_and_b32_e32 v16, 0xffff0000, v133
	v_lshlrev_b32_e32 v17, 16, v133
	v_pk_mul_f32 v[18:19], v[228:229], v[14:15] op_sel_hi:[0,1]
	v_pk_mul_f32 v[20:21], v[228:229], v[16:17] op_sel_hi:[0,1]
	v_pk_fma_f32 v[10:11], v[228:229], v[14:15], v[10:11] op_sel_hi:[0,1,1]
	v_pk_fma_f32 v[12:13], v[228:229], v[16:17], v[12:13] op_sel_hi:[0,1,1]
	v_fma_f32 v26, s0, v11, -v19
	v_fma_f32 v27, s0, v10, -v18
	v_fma_f32 v28, s0, v13, -v21
	v_fma_f32 v29, s0, v12, -v20
	v_cvt_pk_bf16_f32 v26, v26, v27
	v_cvt_pk_bf16_f32 v27, v28, v29
	v_add_u32_e32 v35, 0xa800, v8
	global_store_dwordx2 v35, v[26:27], s[62:63]
	v_and_b32_e32 v14, 0xffff0000, v118
	v_lshlrev_b32_e32 v15, 16, v118
	v_and_b32_e32 v16, 0xffff0000, v119
	v_lshlrev_b32_e32 v17, 16, v119
	v_pk_fma_f32 v[10:11], v[220:221], v[14:15], v[10:11] op_sel:[1,0,0] op_sel_hi:[1,1,1] neg_lo:[1,0,0] neg_hi:[1,0,0]
	v_pk_fma_f32 v[12:13], v[220:221], v[16:17], v[12:13] op_sel:[1,0,0] op_sel_hi:[1,1,1] neg_lo:[1,0,0] neg_hi:[1,0,0]
	s_waitcnt vmcnt(47)
	v_and_b32_e32 v14, 0xffff0000, v134
	v_lshlrev_b32_e32 v15, 16, v134
	v_and_b32_e32 v16, 0xffff0000, v135
	v_lshlrev_b32_e32 v17, 16, v135
	v_pk_mul_f32 v[18:19], v[228:229], v[14:15] op_sel:[1,0] op_sel_hi:[1,1]
	v_pk_mul_f32 v[20:21], v[228:229], v[16:17] op_sel:[1,0] op_sel_hi:[1,1]
	v_pk_fma_f32 v[10:11], v[228:229], v[14:15], v[10:11] op_sel:[1,0,0] op_sel_hi:[1,1,1]
	v_pk_fma_f32 v[12:13], v[228:229], v[16:17], v[12:13] op_sel:[1,0,0] op_sel_hi:[1,1,1]
	v_fma_f32 v22, s0, v11, -v19
	v_fma_f32 v23, s0, v10, -v18
	v_fma_f32 v24, s0, v13, -v21
	v_fma_f32 v25, s0, v12, -v20
	v_cvt_pk_bf16_f32 v22, v22, v23
	v_cvt_pk_bf16_f32 v23, v24, v25
	v_add_u32_e32 v36, 0xb000, v8
	global_store_dwordx2 v36, v[22:23], s[62:63]
	v_and_b32_e32 v14, 0xffff0000, v120
	v_lshlrev_b32_e32 v15, 16, v120
	v_and_b32_e32 v16, 0xffff0000, v121
	v_lshlrev_b32_e32 v17, 16, v121
	v_pk_fma_f32 v[10:11], v[222:223], v[14:15], v[10:11] op_sel_hi:[0,1,1] neg_lo:[1,0,0] neg_hi:[1,0,0]
	v_pk_fma_f32 v[12:13], v[222:223], v[16:17], v[12:13] op_sel_hi:[0,1,1] neg_lo:[1,0,0] neg_hi:[1,0,0]
	s_waitcnt vmcnt(47)
	v_and_b32_e32 v14, 0xffff0000, v136
	v_lshlrev_b32_e32 v15, 16, v136
	v_and_b32_e32 v16, 0xffff0000, v137
	v_lshlrev_b32_e32 v17, 16, v137
	v_pk_mul_f32 v[18:19], v[230:231], v[14:15] op_sel_hi:[0,1]
	v_pk_mul_f32 v[20:21], v[230:231], v[16:17] op_sel_hi:[0,1]
	v_pk_fma_f32 v[10:11], v[230:231], v[14:15], v[10:11] op_sel_hi:[0,1,1]
	v_pk_fma_f32 v[12:13], v[230:231], v[16:17], v[12:13] op_sel_hi:[0,1,1]
	v_fma_f32 v26, s0, v11, -v19
	v_fma_f32 v27, s0, v10, -v18
	v_fma_f32 v28, s0, v13, -v21
	v_fma_f32 v29, s0, v12, -v20
	v_cvt_pk_bf16_f32 v26, v26, v27
	v_cvt_pk_bf16_f32 v27, v28, v29
	v_add_u32_e32 v37, 0xb800, v8
	global_store_dwordx2 v37, v[26:27], s[62:63]
	v_and_b32_e32 v14, 0xffff0000, v122
	v_lshlrev_b32_e32 v15, 16, v122
	v_and_b32_e32 v16, 0xffff0000, v123
	v_lshlrev_b32_e32 v17, 16, v123
	v_pk_fma_f32 v[10:11], v[222:223], v[14:15], v[10:11] op_sel:[1,0,0] op_sel_hi:[1,1,1] neg_lo:[1,0,0] neg_hi:[1,0,0]
	v_pk_fma_f32 v[12:13], v[222:223], v[16:17], v[12:13] op_sel:[1,0,0] op_sel_hi:[1,1,1] neg_lo:[1,0,0] neg_hi:[1,0,0]
	s_waitcnt vmcnt(47)
	v_and_b32_e32 v14, 0xffff0000, v138
	v_lshlrev_b32_e32 v15, 16, v138
	v_and_b32_e32 v16, 0xffff0000, v139
	v_lshlrev_b32_e32 v17, 16, v139
	v_pk_mul_f32 v[18:19], v[230:231], v[14:15] op_sel:[1,0] op_sel_hi:[1,1]
	v_pk_mul_f32 v[20:21], v[230:231], v[16:17] op_sel:[1,0] op_sel_hi:[1,1]
	v_pk_fma_f32 v[10:11], v[230:231], v[14:15], v[10:11] op_sel:[1,0,0] op_sel_hi:[1,1,1]
	v_pk_fma_f32 v[12:13], v[230:231], v[16:17], v[12:13] op_sel:[1,0,0] op_sel_hi:[1,1,1]
	v_fma_f32 v22, s0, v11, -v19
	v_fma_f32 v23, s0, v10, -v18
	v_fma_f32 v24, s0, v13, -v21
	v_fma_f32 v25, s0, v12, -v20
	v_cvt_pk_bf16_f32 v22, v22, v23
	v_cvt_pk_bf16_f32 v23, v24, v25
	v_add_u32_e32 v30, 0xc000, v8
	global_store_dwordx2 v30, v[22:23], s[62:63]
	v_and_b32_e32 v14, 0xffff0000, v124
	v_lshlrev_b32_e32 v15, 16, v124
	v_and_b32_e32 v16, 0xffff0000, v125
	v_lshlrev_b32_e32 v17, 16, v125
	v_pk_fma_f32 v[10:11], v[224:225], v[14:15], v[10:11] op_sel_hi:[0,1,1] neg_lo:[1,0,0] neg_hi:[1,0,0]
	v_pk_fma_f32 v[12:13], v[224:225], v[16:17], v[12:13] op_sel_hi:[0,1,1] neg_lo:[1,0,0] neg_hi:[1,0,0]
	s_waitcnt vmcnt(47)
	v_and_b32_e32 v14, 0xffff0000, v140
	v_lshlrev_b32_e32 v15, 16, v140
	v_and_b32_e32 v16, 0xffff0000, v141
	v_lshlrev_b32_e32 v17, 16, v141
	v_pk_mul_f32 v[18:19], v[232:233], v[14:15] op_sel_hi:[0,1]
	v_pk_mul_f32 v[20:21], v[232:233], v[16:17] op_sel_hi:[0,1]
	v_pk_fma_f32 v[10:11], v[232:233], v[14:15], v[10:11] op_sel_hi:[0,1,1]
	v_pk_fma_f32 v[12:13], v[232:233], v[16:17], v[12:13] op_sel_hi:[0,1,1]
	v_fma_f32 v26, s0, v11, -v19
	v_fma_f32 v27, s0, v10, -v18
	v_fma_f32 v28, s0, v13, -v21
	v_fma_f32 v29, s0, v12, -v20
	v_cvt_pk_bf16_f32 v26, v26, v27
	v_cvt_pk_bf16_f32 v27, v28, v29
	v_add_u32_e32 v31, 0xc800, v8
	global_store_dwordx2 v31, v[26:27], s[62:63]
	v_and_b32_e32 v14, 0xffff0000, v126
	v_lshlrev_b32_e32 v15, 16, v126
	v_and_b32_e32 v16, 0xffff0000, v127
	v_lshlrev_b32_e32 v17, 16, v127
	v_pk_fma_f32 v[10:11], v[224:225], v[14:15], v[10:11] op_sel:[1,0,0] op_sel_hi:[1,1,1] neg_lo:[1,0,0] neg_hi:[1,0,0]
	v_pk_fma_f32 v[12:13], v[224:225], v[16:17], v[12:13] op_sel:[1,0,0] op_sel_hi:[1,1,1] neg_lo:[1,0,0] neg_hi:[1,0,0]
	s_waitcnt vmcnt(47)
; __device__ __forceinline__ float bflo(unsigned u) { return __uint_as_float(u << 16); }
; __device__ __forceinline__ float bfhi(unsigned u) { return __uint_as_float(u & 0xffff0000u); }
; __device__ __forceinline__ void phase_pool(const Params& p, char* smraw) {
;     ...
; #pragma unroll
;       for (int k = 0; k < 8; ++k) {
;         const int tt = t8 + k, pp = c0 + tt;
;         const float rs = rstd_s[tt + 15];
;         const float x0 = bflo(cur[k][0]) * rs, x1 = bfhi(cur[k][0]) * rs, x2 = bflo(cur[k][1]) * rs, x3 = bfhi(cur[k][1]) * rs;
;         s0 += x0; s1 += x1; s2 += x2; s3 += x3;
;         const int cnt = (pp + 1 < win) ? pp + 1 : win;
;         const float inv = 1.f / (float)cnt;
;         u32x2 o; o[0] = cvtpk(s0 * inv - x0, s1 * inv - x1); o[1] = cvtpk(s2 * inv - x2, s3 * inv - x3);
;         *(u32x2*)(p.pooled + (size_t)(b * L + pp) * D + c) = o;
;         const int po = pp - win + 1;
;         if (po >= 0) {
;           const float ro = rstd_s[tt + 15 - win + 1];
;           s0 -= bflo(old[k][0]) * ro; s1 -= bfhi(old[k][0]) * ro; s2 -= bflo(old[k][1]) * ro; s3 -= bfhi(old[k][1]) * ro;
;         }
;       }
	v_and_b32_e32 v14, 0xffff0000, v142
	v_lshlrev_b32_e32 v15, 16, v142
	v_and_b32_e32 v16, 0xffff0000, v143
	v_lshlrev_b32_e32 v17, 16, v143
	v_pk_mul_f32 v[18:19], v[232:233], v[14:15] op_sel:[1,0] op_sel_hi:[1,1]
	v_pk_mul_f32 v[20:21], v[232:233], v[16:17] op_sel:[1,0] op_sel_hi:[1,1]
	v_pk_fma_f32 v[10:11], v[232:233], v[14:15], v[10:11] op_sel:[1,0,0] op_sel_hi:[1,1,1]
	v_pk_fma_f32 v[12:13], v[232:233], v[16:17], v[12:13] op_sel:[1,0,0] op_sel_hi:[1,1,1]
	v_fma_f32 v22, s0, v11, -v19
	v_fma_f32 v23, s0, v10, -v18
	v_fma_f32 v24, s0, v13, -v21
	v_fma_f32 v25, s0, v12, -v20
	v_cvt_pk_bf16_f32 v22, v22, v23
	v_cvt_pk_bf16_f32 v23, v24, v25
	v_add_u32_e32 v32, 0xd000, v8
	global_store_dwordx2 v32, v[22:23], s[62:63]
	v_and_b32_e32 v14, 0xffff0000, v128
	v_lshlrev_b32_e32 v15, 16, v128
	v_and_b32_e32 v16, 0xffff0000, v129
	v_lshlrev_b32_e32 v17, 16, v129
	v_pk_fma_f32 v[10:11], v[226:227], v[14:15], v[10:11] op_sel_hi:[0,1,1] neg_lo:[1,0,0] neg_hi:[1,0,0]
	v_pk_fma_f32 v[12:13], v[226:227], v[16:17], v[12:13] op_sel_hi:[0,1,1] neg_lo:[1,0,0] neg_hi:[1,0,0]
	s_waitcnt vmcnt(47)
	v_and_b32_e32 v14, 0xffff0000, v144
	v_lshlrev_b32_e32 v15, 16, v144
	v_and_b32_e32 v16, 0xffff0000, v145
	v_lshlrev_b32_e32 v17, 16, v145
	v_pk_mul_f32 v[18:19], v[234:235], v[14:15] op_sel_hi:[0,1]
	v_pk_mul_f32 v[20:21], v[234:235], v[16:17] op_sel_hi:[0,1]
	v_pk_fma_f32 v[10:11], v[234:235], v[14:15], v[10:11] op_sel_hi:[0,1,1]
	v_pk_fma_f32 v[12:13], v[234:235], v[16:17], v[12:13] op_sel_hi:[0,1,1]
	v_fma_f32 v26, s0, v11, -v19
	v_fma_f32 v27, s0, v10, -v18
	v_fma_f32 v28, s0, v13, -v21
	v_fma_f32 v29, s0, v12, -v20
	v_cvt_pk_bf16_f32 v26, v26, v27
	v_cvt_pk_bf16_f32 v27, v28, v29
	v_add_u32_e32 v33, 0xd800, v8
	global_store_dwordx2 v33, v[26:27], s[62:63]
	v_and_b32_e32 v14, 0xffff0000, v130
	v_lshlrev_b32_e32 v15, 16, v130
	v_and_b32_e32 v16, 0xffff0000, v131
	v_lshlrev_b32_e32 v17, 16, v131
	v_pk_fma_f32 v[10:11], v[226:227], v[14:15], v[10:11] op_sel:[1,0,0] op_sel_hi:[1,1,1] neg_lo:[1,0,0] neg_hi:[1,0,0]
	v_pk_fma_f32 v[12:13], v[226:227], v[16:17], v[12:13] op_sel:[1,0,0] op_sel_hi:[1,1,1] neg_lo:[1,0,0] neg_hi:[1,0,0]
	s_waitcnt vmcnt(47)
	v_and_b32_e32 v14, 0xffff0000, v146
	v_lshlrev_b32_e32 v15, 16, v146
	v_and_b32_e32 v16, 0xffff0000, v147
	v_lshlrev_b32_e32 v17, 16, v147
	v_pk_mul_f32 v[18:19], v[234:235], v[14:15] op_sel:[1,0] op_sel_hi:[1,1]
	v_pk_mul_f32 v[20:21], v[234:235], v[16:17] op_sel:[1,0] op_sel_hi:[1,1]
	v_pk_fma_f32 v[10:11], v[234:235], v[14:15], v[10:11] op_sel:[1,0,0] op_sel_hi:[1,1,1]
	v_pk_fma_f32 v[12:13], v[234:235], v[16:17], v[12:13] op_sel:[1,0,0] op_sel_hi:[1,1,1]
	v_fma_f32 v22, s0, v11, -v19
	v_fma_f32 v23, s0, v10, -v18
	v_fma_f32 v24, s0, v13, -v21
	v_fma_f32 v25, s0, v12, -v20
	v_cvt_pk_bf16_f32 v22, v22, v23
	v_cvt_pk_bf16_f32 v23, v24, v25
	v_add_u32_e32 v34, 0xe000, v8
	global_store_dwordx2 v34, v[22:23], s[62:63]
	v_and_b32_e32 v14, 0xffff0000, v132
	v_lshlrev_b32_e32 v15, 16, v132
	v_and_b32_e32 v16, 0xffff0000, v133
	v_lshlrev_b32_e32 v17, 16, v133
	v_pk_fma_f32 v[10:11], v[228:229], v[14:15], v[10:11] op_sel_hi:[0,1,1] neg_lo:[1,0,0] neg_hi:[1,0,0]
	v_pk_fma_f32 v[12:13], v[228:229], v[16:17], v[12:13] op_sel_hi:[0,1,1] neg_lo:[1,0,0] neg_hi:[1,0,0]
	s_waitcnt vmcnt(47)
	v_and_b32_e32 v14, 0xffff0000, v148
	v_lshlrev_b32_e32 v15, 16, v148
	v_and_b32_e32 v16, 0xffff0000, v149
	v_lshlrev_b32_e32 v17, 16, v149
	v_pk_mul_f32 v[18:19], v[236:237], v[14:15] op_sel_hi:[0,1]
	v_pk_mul_f32 v[20:21], v[236:237], v[16:17] op_sel_hi:[0,1]
	v_pk_fma_f32 v[10:11], v[236:237], v[14:15], v[10:11] op_sel_hi:[0,1,1]
	v_pk_fma_f32 v[12:13], v[236:237], v[16:17], v[12:13] op_sel_hi:[0,1,1]
	v_fma_f32 v26, s0, v11, -v19
	v_fma_f32 v27, s0, v10, -v18
	v_fma_f32 v28, s0, v13, -v21
	v_fma_f32 v29, s0, v12, -v20
	v_cvt_pk_bf16_f32 v26, v26, v27
	v_cvt_pk_bf16_f32 v27, v28, v29
	v_add_u32_e32 v35, 0xe800, v8
	global_store_dwordx2 v35, v[26:27], s[62:63]
	v_and_b32_e32 v14, 0xffff0000, v134
	v_lshlrev_b32_e32 v15, 16, v134
	v_and_b32_e32 v16, 0xffff0000, v135
	v_lshlrev_b32_e32 v17, 16, v135
	v_pk_fma_f32 v[10:11], v[228:229], v[14:15], v[10:11] op_sel:[1,0,0] op_sel_hi:[1,1,1] neg_lo:[1,0,0] neg_hi:[1,0,0]
	v_pk_fma_f32 v[12:13], v[228:229], v[16:17], v[12:13] op_sel:[1,0,0] op_sel_hi:[1,1,1] neg_lo:[1,0,0] neg_hi:[1,0,0]
	s_waitcnt vmcnt(47)
	v_and_b32_e32 v14, 0xffff0000, v150
	v_lshlrev_b32_e32 v15, 16, v150
	v_and_b32_e32 v16, 0xffff0000, v151
	v_lshlrev_b32_e32 v17, 16, v151
	v_pk_mul_f32 v[18:19], v[236:237], v[14:15] op_sel:[1,0] op_sel_hi:[1,1]
	v_pk_mul_f32 v[20:21], v[236:237], v[16:17] op_sel:[1,0] op_sel_hi:[1,1]
	v_pk_fma_f32 v[10:11], v[236:237], v[14:15], v[10:11] op_sel:[1,0,0] op_sel_hi:[1,1,1]
	v_pk_fma_f32 v[12:13], v[236:237], v[16:17], v[12:13] op_sel:[1,0,0] op_sel_hi:[1,1,1]
	v_fma_f32 v22, s0, v11, -v19
	v_fma_f32 v23, s0, v10, -v18
	v_fma_f32 v24, s0, v13, -v21
	v_fma_f32 v25, s0, v12, -v20
	v_cvt_pk_bf16_f32 v22, v22, v23
	v_cvt_pk_bf16_f32 v23, v24, v25
	v_add_u32_e32 v36, 0xf000, v8
	global_store_dwordx2 v36, v[22:23], s[62:63]
	v_and_b32_e32 v14, 0xffff0000, v136
	v_lshlrev_b32_e32 v15, 16, v136
	v_and_b32_e32 v16, 0xffff0000, v137
	v_lshlrev_b32_e32 v17, 16, v137
	v_pk_fma_f32 v[10:11], v[230:231], v[14:15], v[10:11] op_sel_hi:[0,1,1] neg_lo:[1,0,0] neg_hi:[1,0,0]
	v_pk_fma_f32 v[12:13], v[230:231], v[16:17], v[12:13] op_sel_hi:[0,1,1] neg_lo:[1,0,0] neg_hi:[1,0,0]
	s_waitcnt vmcnt(47)
; __device__ __forceinline__ float bflo(unsigned u) { return __uint_as_float(u << 16); }
; __device__ __forceinline__ float bfhi(unsigned u) { return __uint_as_float(u & 0xffff0000u); }
; __device__ __forceinline__ void phase_pool(const Params& p, char* smraw) {
;     ...
; #pragma unroll
;       for (int k = 0; k < 8; ++k) {
;         const int tt = t8 + k, pp = c0 + tt;
;         const float rs = rstd_s[tt + 15];
;         const float x0 = bflo(cur[k][0]) * rs, x1 = bfhi(cur[k][0]) * rs, x2 = bflo(cur[k][1]) * rs, x3 = bfhi(cur[k][1]) * rs;
;         s0 += x0; s1 += x1; s2 += x2; s3 += x3;
;         const int cnt = (pp + 1 < win) ? pp + 1 : win;
;         const float inv = 1.f / (float)cnt;
;         u32x2 o; o[0] = cvtpk(s0 * inv - x0, s1 * inv - x1); o[1] = cvtpk(s2 * inv - x2, s3 * inv - x3);
;         *(u32x2*)(p.pooled + (size_t)(b * L + pp) * D + c) = o;
;         const int po = pp - win + 1;
;         if (po >= 0) {
;           const float ro = rstd_s[tt + 15 - win + 1];
;           s0 -= bflo(old[k][0]) * ro; s1 -= bfhi(old[k][0]) * ro; s2 -= bflo(old[k][1]) * ro; s3 -= bfhi(old[k][1]) * ro;
;         }
;       }
	v_and_b32_e32 v14, 0xffff0000, v152
	v_lshlrev_b32_e32 v15, 16, v152
	v_and_b32_e32 v16, 0xffff0000, v153
	v_lshlrev_b32_e32 v17, 16, v153
	v_pk_mul_f32 v[18:19], v[238:239], v[14:15] op_sel_hi:[0,1]
	v_pk_mul_f32 v[20:21], v[238:239], v[16:17] op_sel_hi:[0,1]
	v_pk_fma_f32 v[10:11], v[238:239], v[14:15], v[10:11] op_sel_hi:[0,1,1]
	v_pk_fma_f32 v[12:13], v[238:239], v[16:17], v[12:13] op_sel_hi:[0,1,1]
	v_fma_f32 v26, s0, v11, -v19
	v_fma_f32 v27, s0, v10, -v18
	v_fma_f32 v28, s0, v13, -v21
	v_fma_f32 v29, s0, v12, -v20
	v_cvt_pk_bf16_f32 v26, v26, v27
	v_cvt_pk_bf16_f32 v27, v28, v29
	v_add_u32_e32 v37, 0xf800, v8
	global_store_dwordx2 v37, v[26:27], s[62:63]
	v_and_b32_e32 v14, 0xffff0000, v138
	v_lshlrev_b32_e32 v15, 16, v138
	v_and_b32_e32 v16, 0xffff0000, v139
	v_lshlrev_b32_e32 v17, 16, v139
	v_pk_fma_f32 v[10:11], v[230:231], v[14:15], v[10:11] op_sel:[1,0,0] op_sel_hi:[1,1,1] neg_lo:[1,0,0] neg_hi:[1,0,0]
	v_pk_fma_f32 v[12:13], v[230:231], v[16:17], v[12:13] op_sel:[1,0,0] op_sel_hi:[1,1,1] neg_lo:[1,0,0] neg_hi:[1,0,0]
	s_waitcnt vmcnt(47)
	v_and_b32_e32 v14, 0xffff0000, v154
	v_lshlrev_b32_e32 v15, 16, v154
	v_and_b32_e32 v16, 0xffff0000, v155
	v_lshlrev_b32_e32 v17, 16, v155
	v_pk_mul_f32 v[18:19], v[238:239], v[14:15] op_sel:[1,0] op_sel_hi:[1,1]
	v_pk_mul_f32 v[20:21], v[238:239], v[16:17] op_sel:[1,0] op_sel_hi:[1,1]
	v_pk_fma_f32 v[10:11], v[238:239], v[14:15], v[10:11] op_sel:[1,0,0] op_sel_hi:[1,1,1]
	v_pk_fma_f32 v[12:13], v[238:239], v[16:17], v[12:13] op_sel:[1,0,0] op_sel_hi:[1,1,1]
	v_fma_f32 v22, s0, v11, -v19
	v_fma_f32 v23, s0, v10, -v18
	v_fma_f32 v24, s0, v13, -v21
	v_fma_f32 v25, s0, v12, -v20
	v_cvt_pk_bf16_f32 v22, v22, v23
	v_cvt_pk_bf16_f32 v23, v24, v25
	v_add_u32_e32 v30, 0x10000, v8
	global_store_dwordx2 v30, v[22:23], s[62:63]
	v_and_b32_e32 v14, 0xffff0000, v140
	v_lshlrev_b32_e32 v15, 16, v140
	v_and_b32_e32 v16, 0xffff0000, v141
	v_lshlrev_b32_e32 v17, 16, v141
	v_pk_fma_f32 v[10:11], v[232:233], v[14:15], v[10:11] op_sel_hi:[0,1,1] neg_lo:[1,0,0] neg_hi:[1,0,0]
	v_pk_fma_f32 v[12:13], v[232:233], v[16:17], v[12:13] op_sel_hi:[0,1,1] neg_lo:[1,0,0] neg_hi:[1,0,0]
	s_waitcnt vmcnt(47)
	v_and_b32_e32 v14, 0xffff0000, v156
	v_lshlrev_b32_e32 v15, 16, v156
	v_and_b32_e32 v16, 0xffff0000, v157
	v_lshlrev_b32_e32 v17, 16, v157
	v_pk_mul_f32 v[18:19], v[240:241], v[14:15] op_sel_hi:[0,1]
	v_pk_mul_f32 v[20:21], v[240:241], v[16:17] op_sel_hi:[0,1]
	v_pk_fma_f32 v[10:11], v[240:241], v[14:15], v[10:11] op_sel_hi:[0,1,1]
	v_pk_fma_f32 v[12:13], v[240:241], v[16:17], v[12:13] op_sel_hi:[0,1,1]
	v_fma_f32 v26, s0, v11, -v19
	v_fma_f32 v27, s0, v10, -v18
	v_fma_f32 v28, s0, v13, -v21
	v_fma_f32 v29, s0, v12, -v20
	v_cvt_pk_bf16_f32 v26, v26, v27
	v_cvt_pk_bf16_f32 v27, v28, v29
	v_add_u32_e32 v31, 0x10800, v8
	global_store_dwordx2 v31, v[26:27], s[62:63]
	v_and_b32_e32 v14, 0xffff0000, v142
	v_lshlrev_b32_e32 v15, 16, v142
	v_and_b32_e32 v16, 0xffff0000, v143
	v_lshlrev_b32_e32 v17, 16, v143
	v_pk_fma_f32 v[10:11], v[232:233], v[14:15], v[10:11] op_sel:[1,0,0] op_sel_hi:[1,1,1] neg_lo:[1,0,0] neg_hi:[1,0,0]
	v_pk_fma_f32 v[12:13], v[232:233], v[16:17], v[12:13] op_sel:[1,0,0] op_sel_hi:[1,1,1] neg_lo:[1,0,0] neg_hi:[1,0,0]
	s_waitcnt vmcnt(47)
	v_and_b32_e32 v14, 0xffff0000, v158
	v_lshlrev_b32_e32 v15, 16, v158
	v_and_b32_e32 v16, 0xffff0000, v159
	v_lshlrev_b32_e32 v17, 16, v159
	v_pk_mul_f32 v[18:19], v[240:241], v[14:15] op_sel:[1,0] op_sel_hi:[1,1]
	v_pk_mul_f32 v[20:21], v[240:241], v[16:17] op_sel:[1,0] op_sel_hi:[1,1]
	v_pk_fma_f32 v[10:11], v[240:241], v[14:15], v[10:11] op_sel:[1,0,0] op_sel_hi:[1,1,1]
	v_pk_fma_f32 v[12:13], v[240:241], v[16:17], v[12:13] op_sel:[1,0,0] op_sel_hi:[1,1,1]
	v_fma_f32 v22, s0, v11, -v19
	v_fma_f32 v23, s0, v10, -v18
	v_fma_f32 v24, s0, v13, -v21
	v_fma_f32 v25, s0, v12, -v20
	v_cvt_pk_bf16_f32 v22, v22, v23
	v_cvt_pk_bf16_f32 v23, v24, v25
	v_add_u32_e32 v32, 0x11000, v8
	global_store_dwordx2 v32, v[22:23], s[62:63]
	v_and_b32_e32 v14, 0xffff0000, v144
	v_lshlrev_b32_e32 v15, 16, v144
	v_and_b32_e32 v16, 0xffff0000, v145
	v_lshlrev_b32_e32 v17, 16, v145
	v_pk_fma_f32 v[10:11], v[234:235], v[14:15], v[10:11] op_sel_hi:[0,1,1] neg_lo:[1,0,0] neg_hi:[1,0,0]
	v_pk_fma_f32 v[12:13], v[234:235], v[16:17], v[12:13] op_sel_hi:[0,1,1] neg_lo:[1,0,0] neg_hi:[1,0,0]
	s_waitcnt vmcnt(47)
	v_and_b32_e32 v14, 0xffff0000, v160
	v_lshlrev_b32_e32 v15, 16, v160
	v_and_b32_e32 v16, 0xffff0000, v161
	v_lshlrev_b32_e32 v17, 16, v161
	v_pk_mul_f32 v[18:19], v[242:243], v[14:15] op_sel_hi:[0,1]
	v_pk_mul_f32 v[20:21], v[242:243], v[16:17] op_sel_hi:[0,1]
	v_pk_fma_f32 v[10:11], v[242:243], v[14:15], v[10:11] op_sel_hi:[0,1,1]
	v_pk_fma_f32 v[12:13], v[242:243], v[16:17], v[12:13] op_sel_hi:[0,1,1]
	v_fma_f32 v26, s0, v11, -v19
	v_fma_f32 v27, s0, v10, -v18
	v_fma_f32 v28, s0, v13, -v21
	v_fma_f32 v29, s0, v12, -v20
	v_cvt_pk_bf16_f32 v26, v26, v27
	v_cvt_pk_bf16_f32 v27, v28, v29
	v_add_u32_e32 v33, 0x11800, v8
	global_store_dwordx2 v33, v[26:27], s[62:63]
	v_and_b32_e32 v14, 0xffff0000, v146
	v_lshlrev_b32_e32 v15, 16, v146
	v_and_b32_e32 v16, 0xffff0000, v147
	v_lshlrev_b32_e32 v17, 16, v147
	v_pk_fma_f32 v[10:11], v[234:235], v[14:15], v[10:11] op_sel:[1,0,0] op_sel_hi:[1,1,1] neg_lo:[1,0,0] neg_hi:[1,0,0]
	v_pk_fma_f32 v[12:13], v[234:235], v[16:17], v[12:13] op_sel:[1,0,0] op_sel_hi:[1,1,1] neg_lo:[1,0,0] neg_hi:[1,0,0]
	s_waitcnt vmcnt(47)
; __device__ __forceinline__ float bflo(unsigned u) { return __uint_as_float(u << 16); }
; __device__ __forceinline__ float bfhi(unsigned u) { return __uint_as_float(u & 0xffff0000u); }
; __device__ __forceinline__ void phase_pool(const Params& p, char* smraw) {
;     ...
; #pragma unroll
;       for (int k = 0; k < 8; ++k) {
;         const int tt = t8 + k, pp = c0 + tt;
;         const float rs = rstd_s[tt + 15];
;         const float x0 = bflo(cur[k][0]) * rs, x1 = bfhi(cur[k][0]) * rs, x2 = bflo(cur[k][1]) * rs, x3 = bfhi(cur[k][1]) * rs;
;         s0 += x0; s1 += x1; s2 += x2; s3 += x3;
;         const int cnt = (pp + 1 < win) ? pp + 1 : win;
;         const float inv = 1.f / (float)cnt;
;         u32x2 o; o[0] = cvtpk(s0 * inv - x0, s1 * inv - x1); o[1] = cvtpk(s2 * inv - x2, s3 * inv - x3);
;         *(u32x2*)(p.pooled + (size_t)(b * L + pp) * D + c) = o;
;         const int po = pp - win + 1;
;         if (po >= 0) {
;           const float ro = rstd_s[tt + 15 - win + 1];
;           s0 -= bflo(old[k][0]) * ro; s1 -= bfhi(old[k][0]) * ro; s2 -= bflo(old[k][1]) * ro; s3 -= bfhi(old[k][1]) * ro;
;         }
;       }
	v_and_b32_e32 v14, 0xffff0000, v162
	v_lshlrev_b32_e32 v15, 16, v162
	v_and_b32_e32 v16, 0xffff0000, v163
	v_lshlrev_b32_e32 v17, 16, v163
	v_pk_mul_f32 v[18:19], v[242:243], v[14:15] op_sel:[1,0] op_sel_hi:[1,1]
	v_pk_mul_f32 v[20:21], v[242:243], v[16:17] op_sel:[1,0] op_sel_hi:[1,1]
	v_pk_fma_f32 v[10:11], v[242:243], v[14:15], v[10:11] op_sel:[1,0,0] op_sel_hi:[1,1,1]
	v_pk_fma_f32 v[12:13], v[242:243], v[16:17], v[12:13] op_sel:[1,0,0] op_sel_hi:[1,1,1]
	v_fma_f32 v22, s0, v11, -v19
	v_fma_f32 v23, s0, v10, -v18
	v_fma_f32 v24, s0, v13, -v21
	v_fma_f32 v25, s0, v12, -v20
	v_cvt_pk_bf16_f32 v22, v22, v23
	v_cvt_pk_bf16_f32 v23, v24, v25
	v_add_u32_e32 v34, 0x12000, v8
	global_store_dwordx2 v34, v[22:23], s[62:63]
	v_and_b32_e32 v14, 0xffff0000, v148
	v_lshlrev_b32_e32 v15, 16, v148
	v_and_b32_e32 v16, 0xffff0000, v149
	v_lshlrev_b32_e32 v17, 16, v149
	v_pk_fma_f32 v[10:11], v[236:237], v[14:15], v[10:11] op_sel_hi:[0,1,1] neg_lo:[1,0,0] neg_hi:[1,0,0]
	v_pk_fma_f32 v[12:13], v[236:237], v[16:17], v[12:13] op_sel_hi:[0,1,1] neg_lo:[1,0,0] neg_hi:[1,0,0]
	s_waitcnt vmcnt(47)
	v_and_b32_e32 v14, 0xffff0000, v164
	v_lshlrev_b32_e32 v15, 16, v164
	v_and_b32_e32 v16, 0xffff0000, v165
	v_lshlrev_b32_e32 v17, 16, v165
	v_pk_mul_f32 v[18:19], v[244:245], v[14:15] op_sel_hi:[0,1]
	v_pk_mul_f32 v[20:21], v[244:245], v[16:17] op_sel_hi:[0,1]
	v_pk_fma_f32 v[10:11], v[244:245], v[14:15], v[10:11] op_sel_hi:[0,1,1]
	v_pk_fma_f32 v[12:13], v[244:245], v[16:17], v[12:13] op_sel_hi:[0,1,1]
	v_fma_f32 v26, s0, v11, -v19
	v_fma_f32 v27, s0, v10, -v18
	v_fma_f32 v28, s0, v13, -v21
	v_fma_f32 v29, s0, v12, -v20
	v_cvt_pk_bf16_f32 v26, v26, v27
	v_cvt_pk_bf16_f32 v27, v28, v29
	v_add_u32_e32 v35, 0x12800, v8
	global_store_dwordx2 v35, v[26:27], s[62:63]
	v_and_b32_e32 v14, 0xffff0000, v150
	v_lshlrev_b32_e32 v15, 16, v150
	v_and_b32_e32 v16, 0xffff0000, v151
	v_lshlrev_b32_e32 v17, 16, v151
	v_pk_fma_f32 v[10:11], v[236:237], v[14:15], v[10:11] op_sel:[1,0,0] op_sel_hi:[1,1,1] neg_lo:[1,0,0] neg_hi:[1,0,0]
	v_pk_fma_f32 v[12:13], v[236:237], v[16:17], v[12:13] op_sel:[1,0,0] op_sel_hi:[1,1,1] neg_lo:[1,0,0] neg_hi:[1,0,0]
	s_waitcnt vmcnt(47)
	v_and_b32_e32 v14, 0xffff0000, v166
	v_lshlrev_b32_e32 v15, 16, v166
	v_and_b32_e32 v16, 0xffff0000, v167
	v_lshlrev_b32_e32 v17, 16, v167
	v_pk_mul_f32 v[18:19], v[244:245], v[14:15] op_sel:[1,0] op_sel_hi:[1,1]
	v_pk_mul_f32 v[20:21], v[244:245], v[16:17] op_sel:[1,0] op_sel_hi:[1,1]
	v_pk_fma_f32 v[10:11], v[244:245], v[14:15], v[10:11] op_sel:[1,0,0] op_sel_hi:[1,1,1]
	v_pk_fma_f32 v[12:13], v[244:245], v[16:17], v[12:13] op_sel:[1,0,0] op_sel_hi:[1,1,1]
	v_fma_f32 v22, s0, v11, -v19
	v_fma_f32 v23, s0, v10, -v18
	v_fma_f32 v24, s0, v13, -v21
	v_fma_f32 v25, s0, v12, -v20
	v_cvt_pk_bf16_f32 v22, v22, v23
	v_cvt_pk_bf16_f32 v23, v24, v25
	v_add_u32_e32 v36, 0x13000, v8
	global_store_dwordx2 v36, v[22:23], s[62:63]
	v_and_b32_e32 v14, 0xffff0000, v152
	v_lshlrev_b32_e32 v15, 16, v152
	v_and_b32_e32 v16, 0xffff0000, v153
	v_lshlrev_b32_e32 v17, 16, v153
	v_pk_fma_f32 v[10:11], v[238:239], v[14:15], v[10:11] op_sel_hi:[0,1,1] neg_lo:[1,0,0] neg_hi:[1,0,0]
	v_pk_fma_f32 v[12:13], v[238:239], v[16:17], v[12:13] op_sel_hi:[0,1,1] neg_lo:[1,0,0] neg_hi:[1,0,0]
	s_waitcnt vmcnt(47)
	v_and_b32_e32 v14, 0xffff0000, v168
	v_lshlrev_b32_e32 v15, 16, v168
	v_and_b32_e32 v16, 0xffff0000, v169
	v_lshlrev_b32_e32 v17, 16, v169
	v_pk_mul_f32 v[18:19], v[246:247], v[14:15] op_sel_hi:[0,1]
	v_pk_mul_f32 v[20:21], v[246:247], v[16:17] op_sel_hi:[0,1]
	v_pk_fma_f32 v[10:11], v[246:247], v[14:15], v[10:11] op_sel_hi:[0,1,1]
	v_pk_fma_f32 v[12:13], v[246:247], v[16:17], v[12:13] op_sel_hi:[0,1,1]
	v_fma_f32 v26, s0, v11, -v19
	v_fma_f32 v27, s0, v10, -v18
	v_fma_f32 v28, s0, v13, -v21
	v_fma_f32 v29, s0, v12, -v20
	v_cvt_pk_bf16_f32 v26, v26, v27
	v_cvt_pk_bf16_f32 v27, v28, v29
	v_add_u32_e32 v37, 0x13800, v8
	global_store_dwordx2 v37, v[26:27], s[62:63]
	v_and_b32_e32 v14, 0xffff0000, v154
	v_lshlrev_b32_e32 v15, 16, v154
	v_and_b32_e32 v16, 0xffff0000, v155
	v_lshlrev_b32_e32 v17, 16, v155
	v_pk_fma_f32 v[10:11], v[238:239], v[14:15], v[10:11] op_sel:[1,0,0] op_sel_hi:[1,1,1] neg_lo:[1,0,0] neg_hi:[1,0,0]
	v_pk_fma_f32 v[12:13], v[238:239], v[16:17], v[12:13] op_sel:[1,0,0] op_sel_hi:[1,1,1] neg_lo:[1,0,0] neg_hi:[1,0,0]
	s_waitcnt vmcnt(47)
	v_and_b32_e32 v14, 0xffff0000, v170
	v_lshlrev_b32_e32 v15, 16, v170
	v_and_b32_e32 v16, 0xffff0000, v171
	v_lshlrev_b32_e32 v17, 16, v171
	v_pk_mul_f32 v[18:19], v[246:247], v[14:15] op_sel:[1,0] op_sel_hi:[1,1]
	v_pk_mul_f32 v[20:21], v[246:247], v[16:17] op_sel:[1,0] op_sel_hi:[1,1]
	v_pk_fma_f32 v[10:11], v[246:247], v[14:15], v[10:11] op_sel:[1,0,0] op_sel_hi:[1,1,1]
	v_pk_fma_f32 v[12:13], v[246:247], v[16:17], v[12:13] op_sel:[1,0,0] op_sel_hi:[1,1,1]
	v_fma_f32 v22, s0, v11, -v19
	v_fma_f32 v23, s0, v10, -v18
	v_fma_f32 v24, s0, v13, -v21
	v_fma_f32 v25, s0, v12, -v20
	v_cvt_pk_bf16_f32 v22, v22, v23
	v_cvt_pk_bf16_f32 v23, v24, v25
	v_add_u32_e32 v30, 0x14000, v8
	global_store_dwordx2 v30, v[22:23], s[62:63]
	v_and_b32_e32 v14, 0xffff0000, v156
	v_lshlrev_b32_e32 v15, 16, v156
	v_and_b32_e32 v16, 0xffff0000, v157
	v_lshlrev_b32_e32 v17, 16, v157
	v_pk_fma_f32 v[10:11], v[240:241], v[14:15], v[10:11] op_sel_hi:[0,1,1] neg_lo:[1,0,0] neg_hi:[1,0,0]
	v_pk_fma_f32 v[12:13], v[240:241], v[16:17], v[12:13] op_sel_hi:[0,1,1] neg_lo:[1,0,0] neg_hi:[1,0,0]
	s_waitcnt vmcnt(47)
; __device__ __forceinline__ float bflo(unsigned u) { return __uint_as_float(u << 16); }
; __device__ __forceinline__ float bfhi(unsigned u) { return __uint_as_float(u & 0xffff0000u); }
; __device__ __forceinline__ void phase_pool(const Params& p, char* smraw) {
;     ...
; #pragma unroll
;       for (int k = 0; k < 8; ++k) {
;         const int tt = t8 + k, pp = c0 + tt;
;         const float rs = rstd_s[tt + 15];
;         const float x0 = bflo(cur[k][0]) * rs, x1 = bfhi(cur[k][0]) * rs, x2 = bflo(cur[k][1]) * rs, x3 = bfhi(cur[k][1]) * rs;
;         s0 += x0; s1 += x1; s2 += x2; s3 += x3;
;         const int cnt = (pp + 1 < win) ? pp + 1 : win;
;         const float inv = 1.f / (float)cnt;
;         u32x2 o; o[0] = cvtpk(s0 * inv - x0, s1 * inv - x1); o[1] = cvtpk(s2 * inv - x2, s3 * inv - x3);
;         *(u32x2*)(p.pooled + (size_t)(b * L + pp) * D + c) = o;
;         const int po = pp - win + 1;
;         if (po >= 0) {
;           const float ro = rstd_s[tt + 15 - win + 1];
;           s0 -= bflo(old[k][0]) * ro; s1 -= bfhi(old[k][0]) * ro; s2 -= bflo(old[k][1]) * ro; s3 -= bfhi(old[k][1]) * ro;
;         }
;       }
	v_and_b32_e32 v14, 0xffff0000, v172
	v_lshlrev_b32_e32 v15, 16, v172
	v_and_b32_e32 v16, 0xffff0000, v173
	v_lshlrev_b32_e32 v17, 16, v173
	v_pk_mul_f32 v[18:19], v[248:249], v[14:15] op_sel_hi:[0,1]
	v_pk_mul_f32 v[20:21], v[248:249], v[16:17] op_sel_hi:[0,1]
	v_pk_fma_f32 v[10:11], v[248:249], v[14:15], v[10:11] op_sel_hi:[0,1,1]
	v_pk_fma_f32 v[12:13], v[248:249], v[16:17], v[12:13] op_sel_hi:[0,1,1]
	v_fma_f32 v26, s0, v11, -v19
	v_fma_f32 v27, s0, v10, -v18
	v_fma_f32 v28, s0, v13, -v21
	v_fma_f32 v29, s0, v12, -v20
	v_cvt_pk_bf16_f32 v26, v26, v27
	v_cvt_pk_bf16_f32 v27, v28, v29
	v_add_u32_e32 v31, 0x14800, v8
	global_store_dwordx2 v31, v[26:27], s[62:63]
	v_and_b32_e32 v14, 0xffff0000, v158
	v_lshlrev_b32_e32 v15, 16, v158
	v_and_b32_e32 v16, 0xffff0000, v159
	v_lshlrev_b32_e32 v17, 16, v159
	v_pk_fma_f32 v[10:11], v[240:241], v[14:15], v[10:11] op_sel:[1,0,0] op_sel_hi:[1,1,1] neg_lo:[1,0,0] neg_hi:[1,0,0]
	v_pk_fma_f32 v[12:13], v[240:241], v[16:17], v[12:13] op_sel:[1,0,0] op_sel_hi:[1,1,1] neg_lo:[1,0,0] neg_hi:[1,0,0]
	s_waitcnt vmcnt(47)
	v_and_b32_e32 v14, 0xffff0000, v174
	v_lshlrev_b32_e32 v15, 16, v174
	v_and_b32_e32 v16, 0xffff0000, v175
	v_lshlrev_b32_e32 v17, 16, v175
	v_pk_mul_f32 v[18:19], v[248:249], v[14:15] op_sel:[1,0] op_sel_hi:[1,1]
	v_pk_mul_f32 v[20:21], v[248:249], v[16:17] op_sel:[1,0] op_sel_hi:[1,1]
	v_pk_fma_f32 v[10:11], v[248:249], v[14:15], v[10:11] op_sel:[1,0,0] op_sel_hi:[1,1,1]
	v_pk_fma_f32 v[12:13], v[248:249], v[16:17], v[12:13] op_sel:[1,0,0] op_sel_hi:[1,1,1]
	v_fma_f32 v22, s0, v11, -v19
	v_fma_f32 v23, s0, v10, -v18
	v_fma_f32 v24, s0, v13, -v21
	v_fma_f32 v25, s0, v12, -v20
	v_cvt_pk_bf16_f32 v22, v22, v23
	v_cvt_pk_bf16_f32 v23, v24, v25
	v_add_u32_e32 v32, 0x15000, v8
	global_store_dwordx2 v32, v[22:23], s[62:63]
	v_and_b32_e32 v14, 0xffff0000, v160
	v_lshlrev_b32_e32 v15, 16, v160
	v_and_b32_e32 v16, 0xffff0000, v161
	v_lshlrev_b32_e32 v17, 16, v161
	v_pk_fma_f32 v[10:11], v[242:243], v[14:15], v[10:11] op_sel_hi:[0,1,1] neg_lo:[1,0,0] neg_hi:[1,0,0]
	v_pk_fma_f32 v[12:13], v[242:243], v[16:17], v[12:13] op_sel_hi:[0,1,1] neg_lo:[1,0,0] neg_hi:[1,0,0]
	s_waitcnt vmcnt(47)
	v_and_b32_e32 v14, 0xffff0000, v176
	v_lshlrev_b32_e32 v15, 16, v176
	v_and_b32_e32 v16, 0xffff0000, v177
	v_lshlrev_b32_e32 v17, 16, v177
	v_pk_mul_f32 v[18:19], v[250:251], v[14:15] op_sel_hi:[0,1]
	v_pk_mul_f32 v[20:21], v[250:251], v[16:17] op_sel_hi:[0,1]
	v_pk_fma_f32 v[10:11], v[250:251], v[14:15], v[10:11] op_sel_hi:[0,1,1]
	v_pk_fma_f32 v[12:13], v[250:251], v[16:17], v[12:13] op_sel_hi:[0,1,1]
	v_fma_f32 v26, s0, v11, -v19
	v_fma_f32 v27, s0, v10, -v18
	v_fma_f32 v28, s0, v13, -v21
	v_fma_f32 v29, s0, v12, -v20
	v_cvt_pk_bf16_f32 v26, v26, v27
	v_cvt_pk_bf16_f32 v27, v28, v29
	v_add_u32_e32 v33, 0x15800, v8
	global_store_dwordx2 v33, v[26:27], s[62:63]
	v_and_b32_e32 v14, 0xffff0000, v162
	v_lshlrev_b32_e32 v15, 16, v162
	v_and_b32_e32 v16, 0xffff0000, v163
	v_lshlrev_b32_e32 v17, 16, v163
	v_pk_fma_f32 v[10:11], v[242:243], v[14:15], v[10:11] op_sel:[1,0,0] op_sel_hi:[1,1,1] neg_lo:[1,0,0] neg_hi:[1,0,0]
	v_pk_fma_f32 v[12:13], v[242:243], v[16:17], v[12:13] op_sel:[1,0,0] op_sel_hi:[1,1,1] neg_lo:[1,0,0] neg_hi:[1,0,0]
	s_waitcnt vmcnt(47)
	v_and_b32_e32 v14, 0xffff0000, v178
	v_lshlrev_b32_e32 v15, 16, v178
	v_and_b32_e32 v16, 0xffff0000, v179
	v_lshlrev_b32_e32 v17, 16, v179
	v_pk_mul_f32 v[18:19], v[250:251], v[14:15] op_sel:[1,0] op_sel_hi:[1,1]
	v_pk_mul_f32 v[20:21], v[250:251], v[16:17] op_sel:[1,0] op_sel_hi:[1,1]
	v_pk_fma_f32 v[10:11], v[250:251], v[14:15], v[10:11] op_sel:[1,0,0] op_sel_hi:[1,1,1]
	v_pk_fma_f32 v[12:13], v[250:251], v[16:17], v[12:13] op_sel:[1,0,0] op_sel_hi:[1,1,1]
	v_fma_f32 v22, s0, v11, -v19
	v_fma_f32 v23, s0, v10, -v18
	v_fma_f32 v24, s0, v13, -v21
	v_fma_f32 v25, s0, v12, -v20
	v_cvt_pk_bf16_f32 v22, v22, v23
	v_cvt_pk_bf16_f32 v23, v24, v25
	v_add_u32_e32 v34, 0x16000, v8
	global_store_dwordx2 v34, v[22:23], s[62:63]
	v_and_b32_e32 v14, 0xffff0000, v164
	v_lshlrev_b32_e32 v15, 16, v164
	v_and_b32_e32 v16, 0xffff0000, v165
	v_lshlrev_b32_e32 v17, 16, v165
	v_pk_fma_f32 v[10:11], v[244:245], v[14:15], v[10:11] op_sel_hi:[0,1,1] neg_lo:[1,0,0] neg_hi:[1,0,0]
	v_pk_fma_f32 v[12:13], v[244:245], v[16:17], v[12:13] op_sel_hi:[0,1,1] neg_lo:[1,0,0] neg_hi:[1,0,0]
	s_waitcnt vmcnt(47)
	v_and_b32_e32 v14, 0xffff0000, v180
	v_lshlrev_b32_e32 v15, 16, v180
	v_and_b32_e32 v16, 0xffff0000, v181
	v_lshlrev_b32_e32 v17, 16, v181
	v_pk_mul_f32 v[18:19], v[252:253], v[14:15] op_sel_hi:[0,1]
	v_pk_mul_f32 v[20:21], v[252:253], v[16:17] op_sel_hi:[0,1]
	v_pk_fma_f32 v[10:11], v[252:253], v[14:15], v[10:11] op_sel_hi:[0,1,1]
	v_pk_fma_f32 v[12:13], v[252:253], v[16:17], v[12:13] op_sel_hi:[0,1,1]
	v_fma_f32 v26, s0, v11, -v19
	v_fma_f32 v27, s0, v10, -v18
	v_fma_f32 v28, s0, v13, -v21
	v_fma_f32 v29, s0, v12, -v20
	v_cvt_pk_bf16_f32 v26, v26, v27
	v_cvt_pk_bf16_f32 v27, v28, v29
	v_add_u32_e32 v35, 0x16800, v8
	global_store_dwordx2 v35, v[26:27], s[62:63]
	v_and_b32_e32 v14, 0xffff0000, v166
	v_lshlrev_b32_e32 v15, 16, v166
	v_and_b32_e32 v16, 0xffff0000, v167
	v_lshlrev_b32_e32 v17, 16, v167
	v_pk_fma_f32 v[10:11], v[244:245], v[14:15], v[10:11] op_sel:[1,0,0] op_sel_hi:[1,1,1] neg_lo:[1,0,0] neg_hi:[1,0,0]
	v_pk_fma_f32 v[12:13], v[244:245], v[16:17], v[12:13] op_sel:[1,0,0] op_sel_hi:[1,1,1] neg_lo:[1,0,0] neg_hi:[1,0,0]
	s_waitcnt vmcnt(47)
; __device__ __forceinline__ float bflo(unsigned u) { return __uint_as_float(u << 16); }
; __device__ __forceinline__ float bfhi(unsigned u) { return __uint_as_float(u & 0xffff0000u); }
; __device__ __forceinline__ void phase_pool(const Params& p, char* smraw) {
;     ...
;     for (int i = 1; i < win; ++i) {
;       const int pp = c0 - i;
;       if (pp >= 0) {
;         u32x2 v = *(const u32x2*)(base + (size_t)pp * D);
;         const float rs = rstd_s[15 - i];
;         s0 += bflo(v[0]) * rs; s1 += bfhi(v[0]) * rs; s2 += bflo(v[1]) * rs; s3 += bfhi(v[1]) * rs;
;       }
;     }
;     for (int t8 = 0; t8 < CH; t8 += 8) {
;       u32x2 cur[8], old[8];
; #pragma unroll
;       for (int k = 0; k < 8; ++k) {
;         const int pp = c0 + t8 + k;
;         cur[k] = *(const u32x2*)(base + (size_t)pp * D);
;         const int po = pp - win + 1;
;         old[k] = *(const u32x2*)(base + (size_t)(po >= 0 ? po : 0) * D);
;       }
; #pragma unroll
;       for (int k = 0; k < 8; ++k) {
;         const int tt = t8 + k, pp = c0 + tt;
;         const float rs = rstd_s[tt + 15];
;         const float x0 = bflo(cur[k][0]) * rs, x1 = bfhi(cur[k][0]) * rs, x2 = bflo(cur[k][1]) * rs, x3 = bfhi(cur[k][1]) * rs;
;         s0 += x0; s1 += x1; s2 += x2; s3 += x3;
;         const int cnt = (pp + 1 < win) ? pp + 1 : win;
;         const float inv = 1.f / (float)cnt;
;         u32x2 o; o[0] = cvtpk(s0 * inv - x0, s1 * inv - x1); o[1] = cvtpk(s2 * inv - x2, s3 * inv - x3);
;         *(u32x2*)(p.pooled + (size_t)(b * L + pp) * D + c) = o;
;         const int po = pp - win + 1;
;         if (po >= 0) {
;           const float ro = rstd_s[tt + 15 - win + 1];
;           s0 -= bflo(old[k][0]) * ro; s1 -= bfhi(old[k][0]) * ro; s2 -= bflo(old[k][1]) * ro; s3 -= bfhi(old[k][1]) * ro;
;         }
;       }
	v_and_b32_e32 v14, 0xffff0000, v182
	v_lshlrev_b32_e32 v15, 16, v182
	v_and_b32_e32 v16, 0xffff0000, v183
	v_lshlrev_b32_e32 v17, 16, v183
	v_pk_mul_f32 v[18:19], v[252:253], v[14:15] op_sel:[1,0] op_sel_hi:[1,1]
	v_pk_mul_f32 v[20:21], v[252:253], v[16:17] op_sel:[1,0] op_sel_hi:[1,1]
	v_pk_fma_f32 v[10:11], v[252:253], v[14:15], v[10:11] op_sel:[1,0,0] op_sel_hi:[1,1,1]
	v_pk_fma_f32 v[12:13], v[252:253], v[16:17], v[12:13] op_sel:[1,0,0] op_sel_hi:[1,1,1]
	v_fma_f32 v22, s0, v11, -v19
	v_fma_f32 v23, s0, v10, -v18
	v_fma_f32 v24, s0, v13, -v21
	v_fma_f32 v25, s0, v12, -v20
	v_cvt_pk_bf16_f32 v22, v22, v23
	v_cvt_pk_bf16_f32 v23, v24, v25
	v_add_u32_e32 v36, 0x17000, v8
	global_store_dwordx2 v36, v[22:23], s[62:63]
	v_and_b32_e32 v14, 0xffff0000, v168
	v_lshlrev_b32_e32 v15, 16, v168
	v_and_b32_e32 v16, 0xffff0000, v169
	v_lshlrev_b32_e32 v17, 16, v169
	v_pk_fma_f32 v[10:11], v[246:247], v[14:15], v[10:11] op_sel_hi:[0,1,1] neg_lo:[1,0,0] neg_hi:[1,0,0]
	v_pk_fma_f32 v[12:13], v[246:247], v[16:17], v[12:13] op_sel_hi:[0,1,1] neg_lo:[1,0,0] neg_hi:[1,0,0]
	s_waitcnt vmcnt(47)
	v_and_b32_e32 v14, 0xffff0000, v184
	v_lshlrev_b32_e32 v15, 16, v184
	v_and_b32_e32 v16, 0xffff0000, v185
	v_lshlrev_b32_e32 v17, 16, v185
	v_pk_mul_f32 v[18:19], v[186:187], v[14:15] op_sel_hi:[0,1]
	v_pk_mul_f32 v[20:21], v[186:187], v[16:17] op_sel_hi:[0,1]
	v_pk_fma_f32 v[10:11], v[186:187], v[14:15], v[10:11] op_sel_hi:[0,1,1]
	v_pk_fma_f32 v[12:13], v[186:187], v[16:17], v[12:13] op_sel_hi:[0,1,1]
	v_fma_f32 v26, s0, v11, -v19
	v_fma_f32 v27, s0, v10, -v18
	v_fma_f32 v28, s0, v13, -v21
	v_fma_f32 v29, s0, v12, -v20
	v_cvt_pk_bf16_f32 v26, v26, v27
	v_cvt_pk_bf16_f32 v27, v28, v29
	v_add_u32_e32 v37, 0x17800, v8
	global_store_dwordx2 v37, v[26:27], s[62:63]
	v_and_b32_e32 v14, 0xffff0000, v170
	v_lshlrev_b32_e32 v15, 16, v170
	v_and_b32_e32 v16, 0xffff0000, v171
	v_lshlrev_b32_e32 v17, 16, v171
	v_pk_fma_f32 v[10:11], v[246:247], v[14:15], v[10:11] op_sel:[1,0,0] op_sel_hi:[1,1,1] neg_lo:[1,0,0] neg_hi:[1,0,0]
	v_pk_fma_f32 v[12:13], v[246:247], v[16:17], v[12:13] op_sel:[1,0,0] op_sel_hi:[1,1,1] neg_lo:[1,0,0] neg_hi:[1,0,0]
	s_branch .Lmy_pool_next
.Lmy_pool_w1:
	s_mov_b32 s35, 0x3e800000
	ds_read_b128 v[192:195], v59 offset:0
	ds_read_b128 v[196:199], v59 offset:16
	ds_read_b128 v[200:203], v59 offset:32
	ds_read_b128 v[204:207], v59 offset:48
	ds_read_b128 v[208:211], v59 offset:64
	ds_read_b128 v[212:215], v59 offset:80
	ds_read_b128 v[216:219], v59 offset:96
	ds_read_b128 v[220:223], v59 offset:112
	ds_read_b128 v[224:227], v59 offset:128
	ds_read_b128 v[228:231], v59 offset:144
	ds_read_b128 v[232:235], v59 offset:160
	ds_read_b128 v[236:239], v59 offset:176
	ds_read_b128 v[240:243], v59 offset:192
	ds_read_b128 v[244:247], v59 offset:208
	ds_read_b128 v[248:251], v59 offset:224
	ds_read_b64 v[252:253], v59 offset:240
	ds_read_b32 v186, v59 offset:248
	s_add_i32 s1, s9, -3
	s_max_i32 s1, s1, 0
	s_add_u32 s1, s1, s27
	s_lshl_b32 s1, s1, 11
	v_add_u32_e32 v34, s1, v1
	global_load_dwordx2 v[84:85], v34, s[76:77]
	s_add_i32 s1, s9, -2
	s_max_i32 s1, s1, 0
	s_add_u32 s1, s1, s27
	s_lshl_b32 s1, s1, 11
	v_add_u32_e32 v35, s1, v1
	global_load_dwordx2 v[86:87], v35, s[76:77]
	s_add_i32 s1, s9, -1
	s_max_i32 s1, s1, 0
	s_add_u32 s1, s1, s27
	s_lshl_b32 s1, s1, 11
	v_add_u32_e32 v36, s1, v1
	global_load_dwordx2 v[88:89], v36, s[76:77]
	global_load_dwordx2 v[90:91], v8, s[76:77]
	v_add_u32_e32 v30, 0x800, v8
	global_load_dwordx2 v[92:93], v30, s[76:77]
	v_add_u32_e32 v31, 0x1000, v8
	global_load_dwordx2 v[94:95], v31, s[76:77]
	v_add_u32_e32 v32, 0x1800, v8
	global_load_dwordx2 v[96:97], v32, s[76:77]
	v_add_u32_e32 v33, 0x2000, v8
	global_load_dwordx2 v[98:99], v33, s[76:77]
	v_add_u32_e32 v34, 0x2800, v8
	global_load_dwordx2 v[100:101], v34, s[76:77]
	v_add_u32_e32 v35, 0x3000, v8
	global_load_dwordx2 v[102:103], v35, s[76:77]
	v_add_u32_e32 v36, 0x3800, v8
	global_load_dwordx2 v[104:105], v36, s[76:77]
	v_add_u32_e32 v37, 0x4000, v8
	global_load_dwordx2 v[106:107], v37, s[76:77]
	v_add_u32_e32 v30, 0x4800, v8
	global_load_dwordx2 v[108:109], v30, s[76:77]
	v_add_u32_e32 v31, 0x5000, v8
	global_load_dwordx2 v[110:111], v31, s[76:77]
	v_add_u32_e32 v32, 0x5800, v8
	global_load_dwordx2 v[112:113], v32, s[76:77]
	v_add_u32_e32 v33, 0x6000, v8
	global_load_dwordx2 v[114:115], v33, s[76:77]
	v_add_u32_e32 v34, 0x6800, v8
	global_load_dwordx2 v[116:117], v34, s[76:77]
	v_add_u32_e32 v35, 0x7000, v8
	global_load_dwordx2 v[118:119], v35, s[76:77]
	v_add_u32_e32 v36, 0x7800, v8
	global_load_dwordx2 v[120:121], v36, s[76:77]
	v_add_u32_e32 v37, 0x8000, v8
	global_load_dwordx2 v[122:123], v37, s[76:77]
	v_add_u32_e32 v30, 0x8800, v8
	global_load_dwordx2 v[124:125], v30, s[76:77]
	v_add_u32_e32 v31, 0x9000, v8
	global_load_dwordx2 v[126:127], v31, s[76:77]
	v_add_u32_e32 v32, 0x9800, v8
	global_load_dwordx2 v[128:129], v32, s[76:77]
	v_add_u32_e32 v33, 0xa000, v8
	global_load_dwordx2 v[130:131], v33, s[76:77]
	v_add_u32_e32 v34, 0xa800, v8
	global_load_dwordx2 v[132:133], v34, s[76:77]
	v_add_u32_e32 v35, 0xb000, v8
	global_load_dwordx2 v[134:135], v35, s[76:77]
	v_add_u32_e32 v36, 0xb800, v8
	global_load_dwordx2 v[136:137], v36, s[76:77]
	v_add_u32_e32 v37, 0xc000, v8
	global_load_dwordx2 v[138:139], v37, s[76:77]
	v_add_u32_e32 v30, 0xc800, v8
	global_load_dwordx2 v[140:141], v30, s[76:77]
	v_add_u32_e32 v31, 0xd000, v8
	global_load_dwordx2 v[142:143], v31, s[76:77]
	v_add_u32_e32 v32, 0xd800, v8
	global_load_dwordx2 v[144:145], v32, s[76:77]
	v_add_u32_e32 v33, 0xe000, v8
	global_load_dwordx2 v[146:147], v33, s[76:77]
	v_add_u32_e32 v34, 0xe800, v8
; __device__ __forceinline__ float bflo(unsigned u) { return __uint_as_float(u << 16); }
; __device__ __forceinline__ float bfhi(unsigned u) { return __uint_as_float(u & 0xffff0000u); }
; __device__ __forceinline__ void phase_pool(const Params& p, char* smraw) {
;     ...
;     for (int i = 1; i < win; ++i) {
;       const int pp = c0 - i;
;       if (pp >= 0) {
;         u32x2 v = *(const u32x2*)(base + (size_t)pp * D);
;         const float rs = rstd_s[15 - i];
;         s0 += bflo(v[0]) * rs; s1 += bfhi(v[0]) * rs; s2 += bflo(v[1]) * rs; s3 += bfhi(v[1]) * rs;
;       }
;     }
;     for (int t8 = 0; t8 < CH; t8 += 8) {
;       u32x2 cur[8], old[8];
; #pragma unroll
;       for (int k = 0; k < 8; ++k) {
;         const int pp = c0 + t8 + k;
;         cur[k] = *(const u32x2*)(base + (size_t)pp * D);
;         const int po = pp - win + 1;
;         old[k] = *(const u32x2*)(base + (size_t)(po >= 0 ? po : 0) * D);
;       }
; #pragma unroll
;       for (int k = 0; k < 8; ++k) {
;         const int tt = t8 + k, pp = c0 + tt;
;         const float rs = rstd_s[tt + 15];
;         const float x0 = bflo(cur[k][0]) * rs, x1 = bfhi(cur[k][0]) * rs, x2 = bflo(cur[k][1]) * rs, x3 = bfhi(cur[k][1]) * rs;
;         s0 += x0; s1 += x1; s2 += x2; s3 += x3;
;         const int cnt = (pp + 1 < win) ? pp + 1 : win;
;         const float inv = 1.f / (float)cnt;
;         u32x2 o; o[0] = cvtpk(s0 * inv - x0, s1 * inv - x1); o[1] = cvtpk(s2 * inv - x2, s3 * inv - x3);
;         *(u32x2*)(p.pooled + (size_t)(b * L + pp) * D + c) = o;
;         const int po = pp - win + 1;
;         if (po >= 0) {
;           const float ro = rstd_s[tt + 15 - win + 1];
;           s0 -= bflo(old[k][0]) * ro; s1 -= bfhi(old[k][0]) * ro; s2 -= bflo(old[k][1]) * ro; s3 -= bfhi(old[k][1]) * ro;
;         }
;       }
	global_load_dwordx2 v[148:149], v34, s[76:77]
	v_add_u32_e32 v35, 0xf000, v8
	global_load_dwordx2 v[150:151], v35, s[76:77]
	v_add_u32_e32 v36, 0xf800, v8
	global_load_dwordx2 v[152:153], v36, s[76:77]
	v_add_u32_e32 v37, 0x10000, v8
	global_load_dwordx2 v[154:155], v37, s[76:77]
	v_add_u32_e32 v30, 0x10800, v8
	global_load_dwordx2 v[156:157], v30, s[76:77]
	v_add_u32_e32 v31, 0x11000, v8
	global_load_dwordx2 v[158:159], v31, s[76:77]
	v_add_u32_e32 v32, 0x11800, v8
	global_load_dwordx2 v[160:161], v32, s[76:77]
	v_add_u32_e32 v33, 0x12000, v8
	global_load_dwordx2 v[162:163], v33, s[76:77]
	v_add_u32_e32 v34, 0x12800, v8
	global_load_dwordx2 v[164:165], v34, s[76:77]
	v_add_u32_e32 v35, 0x13000, v8
	global_load_dwordx2 v[166:167], v35, s[76:77]
	v_add_u32_e32 v36, 0x13800, v8
	global_load_dwordx2 v[168:169], v36, s[76:77]
	v_add_u32_e32 v37, 0x14000, v8
	global_load_dwordx2 v[170:171], v37, s[76:77]
	v_add_u32_e32 v30, 0x14800, v8
	global_load_dwordx2 v[172:173], v30, s[76:77]
	v_add_u32_e32 v31, 0x15000, v8
	global_load_dwordx2 v[174:175], v31, s[76:77]
	v_add_u32_e32 v32, 0x15800, v8
	global_load_dwordx2 v[176:177], v32, s[76:77]
	v_add_u32_e32 v33, 0x16000, v8
	global_load_dwordx2 v[178:179], v33, s[76:77]
	v_add_u32_e32 v34, 0x16800, v8
	global_load_dwordx2 v[180:181], v34, s[76:77]
	v_add_u32_e32 v35, 0x17000, v8
	global_load_dwordx2 v[182:183], v35, s[76:77]
	v_add_u32_e32 v36, 0x17800, v8
	global_load_dwordx2 v[184:185], v36, s[76:77]
	s_waitcnt lgkmcnt(0)
	s_cmp_lg_u32 s9, 0
	s_cbranch_scc1 .Lmy_pool_w1_nz
	v_mov_b32_e32 v192, 0
	v_mov_b32_e32 v193, 0
	v_mov_b32_e32 v194, 0
	v_mov_b32_e32 v195, 0
	v_mov_b32_e32 v196, 0
	v_mov_b32_e32 v197, 0
	v_mov_b32_e32 v198, 0
	v_mov_b32_e32 v199, 0
	v_mov_b32_e32 v200, 0
	v_mov_b32_e32 v201, 0
	v_mov_b32_e32 v202, 0
	v_mov_b32_e32 v203, 0
	v_mov_b32_e32 v204, 0
	v_mov_b32_e32 v205, 0
	v_mov_b32_e32 v206, 0
.Lmy_pool_w1_nz:
	v_mov_b32_e32 v10, 0
	v_mov_b32_e32 v11, 0
	v_mov_b32_e32 v12, 0
	v_mov_b32_e32 v13, 0
	s_waitcnt vmcnt(48)
	v_and_b32_e32 v14, 0xffff0000, v88
	v_lshlrev_b32_e32 v15, 16, v88
	v_and_b32_e32 v16, 0xffff0000, v89
	v_lshlrev_b32_e32 v17, 16, v89
	v_pk_fma_f32 v[10:11], v[206:207], v[14:15], v[10:11] op_sel_hi:[0,1,1]
	v_pk_fma_f32 v[12:13], v[206:207], v[16:17], v[12:13] op_sel_hi:[0,1,1]
	v_and_b32_e32 v14, 0xffff0000, v86
	v_lshlrev_b32_e32 v15, 16, v86
	v_and_b32_e32 v16, 0xffff0000, v87
	v_lshlrev_b32_e32 v17, 16, v87
	v_pk_fma_f32 v[10:11], v[204:205], v[14:15], v[10:11] op_sel:[1,0,0] op_sel_hi:[1,1,1]
	v_pk_fma_f32 v[12:13], v[204:205], v[16:17], v[12:13] op_sel:[1,0,0] op_sel_hi:[1,1,1]
	v_and_b32_e32 v14, 0xffff0000, v84
	v_lshlrev_b32_e32 v15, 16, v84
	v_and_b32_e32 v16, 0xffff0000, v85
	v_lshlrev_b32_e32 v17, 16, v85
	v_pk_fma_f32 v[10:11], v[204:205], v[14:15], v[10:11] op_sel_hi:[0,1,1]
	v_pk_fma_f32 v[12:13], v[204:205], v[16:17], v[12:13] op_sel_hi:[0,1,1]
	s_waitcnt vmcnt(47)
	v_and_b32_e32 v14, 0xffff0000, v90
	v_lshlrev_b32_e32 v15, 16, v90
	v_and_b32_e32 v16, 0xffff0000, v91
	v_lshlrev_b32_e32 v17, 16, v91
	v_pk_mul_f32 v[18:19], v[206:207], v[14:15] op_sel:[1,0] op_sel_hi:[1,1]
	v_pk_mul_f32 v[20:21], v[206:207], v[16:17] op_sel:[1,0] op_sel_hi:[1,1]
	v_pk_fma_f32 v[10:11], v[206:207], v[14:15], v[10:11] op_sel:[1,0,0] op_sel_hi:[1,1,1]
	v_pk_fma_f32 v[12:13], v[206:207], v[16:17], v[12:13] op_sel:[1,0,0] op_sel_hi:[1,1,1]
	s_cmp_eq_u32 s9, 0
	s_cselect_b32 s0, 0x3f800000, s35
	v_fma_f32 v22, s0, v11, -v19
	v_fma_f32 v23, s0, v10, -v18
	v_fma_f32 v24, s0, v13, -v21
	v_fma_f32 v25, s0, v12, -v20
	v_cvt_pk_bf16_f32 v22, v22, v23
	v_cvt_pk_bf16_f32 v23, v24, v25
	global_store_dwordx2 v8, v[22:23], s[62:63]
	v_and_b32_e32 v14, 0xffff0000, v84
	v_lshlrev_b32_e32 v15, 16, v84
	v_and_b32_e32 v16, 0xffff0000, v85
	v_lshlrev_b32_e32 v17, 16, v85
	v_pk_fma_f32 v[10:11], v[204:205], v[14:15], v[10:11] op_sel_hi:[0,1,1] neg_lo:[1,0,0] neg_hi:[1,0,0]
	v_pk_fma_f32 v[12:13], v[204:205], v[16:17], v[12:13] op_sel_hi:[0,1,1] neg_lo:[1,0,0] neg_hi:[1,0,0]
	s_waitcnt vmcnt(47)
	v_and_b32_e32 v14, 0xffff0000, v92
	v_lshlrev_b32_e32 v15, 16, v92
	v_and_b32_e32 v16, 0xffff0000, v93
	v_lshlrev_b32_e32 v17, 16, v93
	v_pk_mul_f32 v[18:19], v[208:209], v[14:15] op_sel_hi:[0,1]
	v_pk_mul_f32 v[20:21], v[208:209], v[16:17] op_sel_hi:[0,1]
	v_pk_fma_f32 v[10:11], v[208:209], v[14:15], v[10:11] op_sel_hi:[0,1,1]
	v_pk_fma_f32 v[12:13], v[208:209], v[16:17], v[12:13] op_sel_hi:[0,1,1]
	s_cmp_eq_u32 s9, 0
	s_cselect_b32 s0, 0x3f000000, s35
	v_fma_f32 v26, s0, v11, -v19
	v_fma_f32 v27, s0, v10, -v18
	v_fma_f32 v28, s0, v13, -v21
	v_fma_f32 v29, s0, v12, -v20
	v_cvt_pk_bf16_f32 v26, v26, v27
	v_cvt_pk_bf16_f32 v27, v28, v29
	v_add_u32_e32 v31, 0x800, v8
	global_store_dwordx2 v31, v[26:27], s[62:63]
	v_and_b32_e32 v14, 0xffff0000, v86
	v_lshlrev_b32_e32 v15, 16, v86
	v_and_b32_e32 v16, 0xffff0000, v87
	v_lshlrev_b32_e32 v17, 16, v87
	v_pk_fma_f32 v[10:11], v[204:205], v[14:15], v[10:11] op_sel:[1,0,0] op_sel_hi:[1,1,1] neg_lo:[1,0,0] neg_hi:[1,0,0]
	v_pk_fma_f32 v[12:13], v[204:205], v[16:17], v[12:13] op_sel:[1,0,0] op_sel_hi:[1,1,1] neg_lo:[1,0,0] neg_hi:[1,0,0]
	s_waitcnt vmcnt(47)
; __device__ __forceinline__ float bflo(unsigned u) { return __uint_as_float(u << 16); }
; __device__ __forceinline__ float bfhi(unsigned u) { return __uint_as_float(u & 0xffff0000u); }
; __device__ __forceinline__ void phase_pool(const Params& p, char* smraw) {
;     ...
; #pragma unroll
;       for (int k = 0; k < 8; ++k) {
;         const int tt = t8 + k, pp = c0 + tt;
;         const float rs = rstd_s[tt + 15];
;         const float x0 = bflo(cur[k][0]) * rs, x1 = bfhi(cur[k][0]) * rs, x2 = bflo(cur[k][1]) * rs, x3 = bfhi(cur[k][1]) * rs;
;         s0 += x0; s1 += x1; s2 += x2; s3 += x3;
;         const int cnt = (pp + 1 < win) ? pp + 1 : win;
;         const float inv = 1.f / (float)cnt;
;         u32x2 o; o[0] = cvtpk(s0 * inv - x0, s1 * inv - x1); o[1] = cvtpk(s2 * inv - x2, s3 * inv - x3);
;         *(u32x2*)(p.pooled + (size_t)(b * L + pp) * D + c) = o;
;         const int po = pp - win + 1;
;         if (po >= 0) {
;           const float ro = rstd_s[tt + 15 - win + 1];
;           s0 -= bflo(old[k][0]) * ro; s1 -= bfhi(old[k][0]) * ro; s2 -= bflo(old[k][1]) * ro; s3 -= bfhi(old[k][1]) * ro;
;         }
;       }
	v_and_b32_e32 v14, 0xffff0000, v94
	v_lshlrev_b32_e32 v15, 16, v94
	v_and_b32_e32 v16, 0xffff0000, v95
	v_lshlrev_b32_e32 v17, 16, v95
	v_pk_mul_f32 v[18:19], v[208:209], v[14:15] op_sel:[1,0] op_sel_hi:[1,1]
	v_pk_mul_f32 v[20:21], v[208:209], v[16:17] op_sel:[1,0] op_sel_hi:[1,1]
	v_pk_fma_f32 v[10:11], v[208:209], v[14:15], v[10:11] op_sel:[1,0,0] op_sel_hi:[1,1,1]
	v_pk_fma_f32 v[12:13], v[208:209], v[16:17], v[12:13] op_sel:[1,0,0] op_sel_hi:[1,1,1]
	s_cmp_eq_u32 s9, 0
	s_cselect_b32 s0, 0x3eaaaaab, s35
	v_fma_f32 v22, s0, v11, -v19
	v_fma_f32 v23, s0, v10, -v18
	v_fma_f32 v24, s0, v13, -v21
	v_fma_f32 v25, s0, v12, -v20
	v_cvt_pk_bf16_f32 v22, v22, v23
	v_cvt_pk_bf16_f32 v23, v24, v25
	v_add_u32_e32 v32, 0x1000, v8
	global_store_dwordx2 v32, v[22:23], s[62:63]
	v_and_b32_e32 v14, 0xffff0000, v88
	v_lshlrev_b32_e32 v15, 16, v88
	v_and_b32_e32 v16, 0xffff0000, v89
	v_lshlrev_b32_e32 v17, 16, v89
	v_pk_fma_f32 v[10:11], v[206:207], v[14:15], v[10:11] op_sel_hi:[0,1,1] neg_lo:[1,0,0] neg_hi:[1,0,0]
	v_pk_fma_f32 v[12:13], v[206:207], v[16:17], v[12:13] op_sel_hi:[0,1,1] neg_lo:[1,0,0] neg_hi:[1,0,0]
	s_waitcnt vmcnt(47)
	v_and_b32_e32 v14, 0xffff0000, v96
	v_lshlrev_b32_e32 v15, 16, v96
	v_and_b32_e32 v16, 0xffff0000, v97
	v_lshlrev_b32_e32 v17, 16, v97
	v_pk_mul_f32 v[18:19], v[210:211], v[14:15] op_sel_hi:[0,1]
	v_pk_mul_f32 v[20:21], v[210:211], v[16:17] op_sel_hi:[0,1]
	v_pk_fma_f32 v[10:11], v[210:211], v[14:15], v[10:11] op_sel_hi:[0,1,1]
	v_pk_fma_f32 v[12:13], v[210:211], v[16:17], v[12:13] op_sel_hi:[0,1,1]
	s_mov_b32 s0, s35
	v_fma_f32 v26, s0, v11, -v19
	v_fma_f32 v27, s0, v10, -v18
	v_fma_f32 v28, s0, v13, -v21
	v_fma_f32 v29, s0, v12, -v20
	v_cvt_pk_bf16_f32 v26, v26, v27
	v_cvt_pk_bf16_f32 v27, v28, v29
	v_add_u32_e32 v33, 0x1800, v8
	global_store_dwordx2 v33, v[26:27], s[62:63]
	v_and_b32_e32 v14, 0xffff0000, v90
	v_lshlrev_b32_e32 v15, 16, v90
	v_and_b32_e32 v16, 0xffff0000, v91
	v_lshlrev_b32_e32 v17, 16, v91
	v_pk_fma_f32 v[10:11], v[206:207], v[14:15], v[10:11] op_sel:[1,0,0] op_sel_hi:[1,1,1] neg_lo:[1,0,0] neg_hi:[1,0,0]
	v_pk_fma_f32 v[12:13], v[206:207], v[16:17], v[12:13] op_sel:[1,0,0] op_sel_hi:[1,1,1] neg_lo:[1,0,0] neg_hi:[1,0,0]
	s_waitcnt vmcnt(47)
	v_and_b32_e32 v14, 0xffff0000, v98
	v_lshlrev_b32_e32 v15, 16, v98
	v_and_b32_e32 v16, 0xffff0000, v99
	v_lshlrev_b32_e32 v17, 16, v99
	v_pk_mul_f32 v[18:19], v[210:211], v[14:15] op_sel:[1,0] op_sel_hi:[1,1]
	v_pk_mul_f32 v[20:21], v[210:211], v[16:17] op_sel:[1,0] op_sel_hi:[1,1]
	v_pk_fma_f32 v[10:11], v[210:211], v[14:15], v[10:11] op_sel:[1,0,0] op_sel_hi:[1,1,1]
	v_pk_fma_f32 v[12:13], v[210:211], v[16:17], v[12:13] op_sel:[1,0,0] op_sel_hi:[1,1,1]
	v_fma_f32 v22, s0, v11, -v19
	v_fma_f32 v23, s0, v10, -v18
	v_fma_f32 v24, s0, v13, -v21
	v_fma_f32 v25, s0, v12, -v20
	v_cvt_pk_bf16_f32 v22, v22, v23
	v_cvt_pk_bf16_f32 v23, v24, v25
	v_add_u32_e32 v34, 0x2000, v8
	global_store_dwordx2 v34, v[22:23], s[62:63]
	v_and_b32_e32 v14, 0xffff0000, v92
	v_lshlrev_b32_e32 v15, 16, v92
	v_and_b32_e32 v16, 0xffff0000, v93
	v_lshlrev_b32_e32 v17, 16, v93
	v_pk_fma_f32 v[10:11], v[208:209], v[14:15], v[10:11] op_sel_hi:[0,1,1] neg_lo:[1,0,0] neg_hi:[1,0,0]
	v_pk_fma_f32 v[12:13], v[208:209], v[16:17], v[12:13] op_sel_hi:[0,1,1] neg_lo:[1,0,0] neg_hi:[1,0,0]
	s_waitcnt vmcnt(47)
	v_and_b32_e32 v14, 0xffff0000, v100
	v_lshlrev_b32_e32 v15, 16, v100
	v_and_b32_e32 v16, 0xffff0000, v101
	v_lshlrev_b32_e32 v17, 16, v101
	v_pk_mul_f32 v[18:19], v[212:213], v[14:15] op_sel_hi:[0,1]
	v_pk_mul_f32 v[20:21], v[212:213], v[16:17] op_sel_hi:[0,1]
	v_pk_fma_f32 v[10:11], v[212:213], v[14:15], v[10:11] op_sel_hi:[0,1,1]
	v_pk_fma_f32 v[12:13], v[212:213], v[16:17], v[12:13] op_sel_hi:[0,1,1]
	v_fma_f32 v26, s0, v11, -v19
	v_fma_f32 v27, s0, v10, -v18
	v_fma_f32 v28, s0, v13, -v21
	v_fma_f32 v29, s0, v12, -v20
	v_cvt_pk_bf16_f32 v26, v26, v27
	v_cvt_pk_bf16_f32 v27, v28, v29
	v_add_u32_e32 v35, 0x2800, v8
	global_store_dwordx2 v35, v[26:27], s[62:63]
	v_and_b32_e32 v14, 0xffff0000, v94
	v_lshlrev_b32_e32 v15, 16, v94
	v_and_b32_e32 v16, 0xffff0000, v95
	v_lshlrev_b32_e32 v17, 16, v95
	v_pk_fma_f32 v[10:11], v[208:209], v[14:15], v[10:11] op_sel:[1,0,0] op_sel_hi:[1,1,1] neg_lo:[1,0,0] neg_hi:[1,0,0]
	v_pk_fma_f32 v[12:13], v[208:209], v[16:17], v[12:13] op_sel:[1,0,0] op_sel_hi:[1,1,1] neg_lo:[1,0,0] neg_hi:[1,0,0]
	s_waitcnt vmcnt(47)
	v_and_b32_e32 v14, 0xffff0000, v102
	v_lshlrev_b32_e32 v15, 16, v102
	v_and_b32_e32 v16, 0xffff0000, v103
	v_lshlrev_b32_e32 v17, 16, v103
	v_pk_mul_f32 v[18:19], v[212:213], v[14:15] op_sel:[1,0] op_sel_hi:[1,1]
	v_pk_mul_f32 v[20:21], v[212:213], v[16:17] op_sel:[1,0] op_sel_hi:[1,1]
	v_pk_fma_f32 v[10:11], v[212:213], v[14:15], v[10:11] op_sel:[1,0,0] op_sel_hi:[1,1,1]
	v_pk_fma_f32 v[12:13], v[212:213], v[16:17], v[12:13] op_sel:[1,0,0] op_sel_hi:[1,1,1]
	v_fma_f32 v22, s0, v11, -v19
	v_fma_f32 v23, s0, v10, -v18
	v_fma_f32 v24, s0, v13, -v21
	v_fma_f32 v25, s0, v12, -v20
	v_cvt_pk_bf16_f32 v22, v22, v23
	v_cvt_pk_bf16_f32 v23, v24, v25
	v_add_u32_e32 v36, 0x3000, v8
	global_store_dwordx2 v36, v[22:23], s[62:63]
	v_and_b32_e32 v14, 0xffff0000, v96
	v_lshlrev_b32_e32 v15, 16, v96
	v_and_b32_e32 v16, 0xffff0000, v97
	v_lshlrev_b32_e32 v17, 16, v97
	v_pk_fma_f32 v[10:11], v[210:211], v[14:15], v[10:11] op_sel_hi:[0,1,1] neg_lo:[1,0,0] neg_hi:[1,0,0]
	v_pk_fma_f32 v[12:13], v[210:211], v[16:17], v[12:13] op_sel_hi:[0,1,1] neg_lo:[1,0,0] neg_hi:[1,0,0]
	s_waitcnt vmcnt(47)
; __device__ __forceinline__ float bflo(unsigned u) { return __uint_as_float(u << 16); }
; __device__ __forceinline__ float bfhi(unsigned u) { return __uint_as_float(u & 0xffff0000u); }
; __device__ __forceinline__ void phase_pool(const Params& p, char* smraw) {
;     ...
; #pragma unroll
;       for (int k = 0; k < 8; ++k) {
;         const int tt = t8 + k, pp = c0 + tt;
;         const float rs = rstd_s[tt + 15];
;         const float x0 = bflo(cur[k][0]) * rs, x1 = bfhi(cur[k][0]) * rs, x2 = bflo(cur[k][1]) * rs, x3 = bfhi(cur[k][1]) * rs;
;         s0 += x0; s1 += x1; s2 += x2; s3 += x3;
;         const int cnt = (pp + 1 < win) ? pp + 1 : win;
;         const float inv = 1.f / (float)cnt;
;         u32x2 o; o[0] = cvtpk(s0 * inv - x0, s1 * inv - x1); o[1] = cvtpk(s2 * inv - x2, s3 * inv - x3);
;         *(u32x2*)(p.pooled + (size_t)(b * L + pp) * D + c) = o;
;         const int po = pp - win + 1;
;         if (po >= 0) {
;           const float ro = rstd_s[tt + 15 - win + 1];
;           s0 -= bflo(old[k][0]) * ro; s1 -= bfhi(old[k][0]) * ro; s2 -= bflo(old[k][1]) * ro; s3 -= bfhi(old[k][1]) * ro;
;         }
;       }
	v_and_b32_e32 v14, 0xffff0000, v104
	v_lshlrev_b32_e32 v15, 16, v104
	v_and_b32_e32 v16, 0xffff0000, v105
	v_lshlrev_b32_e32 v17, 16, v105
	v_pk_mul_f32 v[18:19], v[214:215], v[14:15] op_sel_hi:[0,1]
	v_pk_mul_f32 v[20:21], v[214:215], v[16:17] op_sel_hi:[0,1]
	v_pk_fma_f32 v[10:11], v[214:215], v[14:15], v[10:11] op_sel_hi:[0,1,1]
	v_pk_fma_f32 v[12:13], v[214:215], v[16:17], v[12:13] op_sel_hi:[0,1,1]
	v_fma_f32 v26, s0, v11, -v19
	v_fma_f32 v27, s0, v10, -v18
	v_fma_f32 v28, s0, v13, -v21
	v_fma_f32 v29, s0, v12, -v20
	v_cvt_pk_bf16_f32 v26, v26, v27
	v_cvt_pk_bf16_f32 v27, v28, v29
	v_add_u32_e32 v37, 0x3800, v8
	global_store_dwordx2 v37, v[26:27], s[62:63]
	v_and_b32_e32 v14, 0xffff0000, v98
	v_lshlrev_b32_e32 v15, 16, v98
	v_and_b32_e32 v16, 0xffff0000, v99
	v_lshlrev_b32_e32 v17, 16, v99
	v_pk_fma_f32 v[10:11], v[210:211], v[14:15], v[10:11] op_sel:[1,0,0] op_sel_hi:[1,1,1] neg_lo:[1,0,0] neg_hi:[1,0,0]
	v_pk_fma_f32 v[12:13], v[210:211], v[16:17], v[12:13] op_sel:[1,0,0] op_sel_hi:[1,1,1] neg_lo:[1,0,0] neg_hi:[1,0,0]
	s_waitcnt vmcnt(47)
	v_and_b32_e32 v14, 0xffff0000, v106
	v_lshlrev_b32_e32 v15, 16, v106
	v_and_b32_e32 v16, 0xffff0000, v107
	v_lshlrev_b32_e32 v17, 16, v107
	v_pk_mul_f32 v[18:19], v[214:215], v[14:15] op_sel:[1,0] op_sel_hi:[1,1]
	v_pk_mul_f32 v[20:21], v[214:215], v[16:17] op_sel:[1,0] op_sel_hi:[1,1]
	v_pk_fma_f32 v[10:11], v[214:215], v[14:15], v[10:11] op_sel:[1,0,0] op_sel_hi:[1,1,1]
	v_pk_fma_f32 v[12:13], v[214:215], v[16:17], v[12:13] op_sel:[1,0,0] op_sel_hi:[1,1,1]
	v_fma_f32 v22, s0, v11, -v19
	v_fma_f32 v23, s0, v10, -v18
	v_fma_f32 v24, s0, v13, -v21
	v_fma_f32 v25, s0, v12, -v20
	v_cvt_pk_bf16_f32 v22, v22, v23
	v_cvt_pk_bf16_f32 v23, v24, v25
	v_add_u32_e32 v30, 0x4000, v8
	global_store_dwordx2 v30, v[22:23], s[62:63]
	v_and_b32_e32 v14, 0xffff0000, v100
	v_lshlrev_b32_e32 v15, 16, v100
	v_and_b32_e32 v16, 0xffff0000, v101
	v_lshlrev_b32_e32 v17, 16, v101
	v_pk_fma_f32 v[10:11], v[212:213], v[14:15], v[10:11] op_sel_hi:[0,1,1] neg_lo:[1,0,0] neg_hi:[1,0,0]
	v_pk_fma_f32 v[12:13], v[212:213], v[16:17], v[12:13] op_sel_hi:[0,1,1] neg_lo:[1,0,0] neg_hi:[1,0,0]
	s_waitcnt vmcnt(47)
	v_and_b32_e32 v14, 0xffff0000, v108
	v_lshlrev_b32_e32 v15, 16, v108
	v_and_b32_e32 v16, 0xffff0000, v109
	v_lshlrev_b32_e32 v17, 16, v109
	v_pk_mul_f32 v[18:19], v[216:217], v[14:15] op_sel_hi:[0,1]
	v_pk_mul_f32 v[20:21], v[216:217], v[16:17] op_sel_hi:[0,1]
	v_pk_fma_f32 v[10:11], v[216:217], v[14:15], v[10:11] op_sel_hi:[0,1,1]
	v_pk_fma_f32 v[12:13], v[216:217], v[16:17], v[12:13] op_sel_hi:[0,1,1]
	v_fma_f32 v26, s0, v11, -v19
	v_fma_f32 v27, s0, v10, -v18
	v_fma_f32 v28, s0, v13, -v21
	v_fma_f32 v29, s0, v12, -v20
	v_cvt_pk_bf16_f32 v26, v26, v27
	v_cvt_pk_bf16_f32 v27, v28, v29
	v_add_u32_e32 v31, 0x4800, v8
	global_store_dwordx2 v31, v[26:27], s[62:63]
	v_and_b32_e32 v14, 0xffff0000, v102
	v_lshlrev_b32_e32 v15, 16, v102
	v_and_b32_e32 v16, 0xffff0000, v103
	v_lshlrev_b32_e32 v17, 16, v103
	v_pk_fma_f32 v[10:11], v[212:213], v[14:15], v[10:11] op_sel:[1,0,0] op_sel_hi:[1,1,1] neg_lo:[1,0,0] neg_hi:[1,0,0]
	v_pk_fma_f32 v[12:13], v[212:213], v[16:17], v[12:13] op_sel:[1,0,0] op_sel_hi:[1,1,1] neg_lo:[1,0,0] neg_hi:[1,0,0]
	s_waitcnt vmcnt(47)
	v_and_b32_e32 v14, 0xffff0000, v110
	v_lshlrev_b32_e32 v15, 16, v110
	v_and_b32_e32 v16, 0xffff0000, v111
	v_lshlrev_b32_e32 v17, 16, v111
	v_pk_mul_f32 v[18:19], v[216:217], v[14:15] op_sel:[1,0] op_sel_hi:[1,1]
	v_pk_mul_f32 v[20:21], v[216:217], v[16:17] op_sel:[1,0] op_sel_hi:[1,1]
	v_pk_fma_f32 v[10:11], v[216:217], v[14:15], v[10:11] op_sel:[1,0,0] op_sel_hi:[1,1,1]
	v_pk_fma_f32 v[12:13], v[216:217], v[16:17], v[12:13] op_sel:[1,0,0] op_sel_hi:[1,1,1]
	v_fma_f32 v22, s0, v11, -v19
	v_fma_f32 v23, s0, v10, -v18
	v_fma_f32 v24, s0, v13, -v21
	v_fma_f32 v25, s0, v12, -v20
	v_cvt_pk_bf16_f32 v22, v22, v23
	v_cvt_pk_bf16_f32 v23, v24, v25
	v_add_u32_e32 v32, 0x5000, v8
	global_store_dwordx2 v32, v[22:23], s[62:63]
	v_and_b32_e32 v14, 0xffff0000, v104
	v_lshlrev_b32_e32 v15, 16, v104
	v_and_b32_e32 v16, 0xffff0000, v105
	v_lshlrev_b32_e32 v17, 16, v105
	v_pk_fma_f32 v[10:11], v[214:215], v[14:15], v[10:11] op_sel_hi:[0,1,1] neg_lo:[1,0,0] neg_hi:[1,0,0]
	v_pk_fma_f32 v[12:13], v[214:215], v[16:17], v[12:13] op_sel_hi:[0,1,1] neg_lo:[1,0,0] neg_hi:[1,0,0]
	s_waitcnt vmcnt(47)
	v_and_b32_e32 v14, 0xffff0000, v112
	v_lshlrev_b32_e32 v15, 16, v112
	v_and_b32_e32 v16, 0xffff0000, v113
	v_lshlrev_b32_e32 v17, 16, v113
	v_pk_mul_f32 v[18:19], v[218:219], v[14:15] op_sel_hi:[0,1]
	v_pk_mul_f32 v[20:21], v[218:219], v[16:17] op_sel_hi:[0,1]
	v_pk_fma_f32 v[10:11], v[218:219], v[14:15], v[10:11] op_sel_hi:[0,1,1]
	v_pk_fma_f32 v[12:13], v[218:219], v[16:17], v[12:13] op_sel_hi:[0,1,1]
	v_fma_f32 v26, s0, v11, -v19
	v_fma_f32 v27, s0, v10, -v18
	v_fma_f32 v28, s0, v13, -v21
	v_fma_f32 v29, s0, v12, -v20
	v_cvt_pk_bf16_f32 v26, v26, v27
	v_cvt_pk_bf16_f32 v27, v28, v29
	v_add_u32_e32 v33, 0x5800, v8
	global_store_dwordx2 v33, v[26:27], s[62:63]
	v_and_b32_e32 v14, 0xffff0000, v106
	v_lshlrev_b32_e32 v15, 16, v106
	v_and_b32_e32 v16, 0xffff0000, v107
	v_lshlrev_b32_e32 v17, 16, v107
	v_pk_fma_f32 v[10:11], v[214:215], v[14:15], v[10:11] op_sel:[1,0,0] op_sel_hi:[1,1,1] neg_lo:[1,0,0] neg_hi:[1,0,0]
	v_pk_fma_f32 v[12:13], v[214:215], v[16:17], v[12:13] op_sel:[1,0,0] op_sel_hi:[1,1,1] neg_lo:[1,0,0] neg_hi:[1,0,0]
	s_waitcnt vmcnt(47)
; __device__ __forceinline__ float bflo(unsigned u) { return __uint_as_float(u << 16); }
; __device__ __forceinline__ float bfhi(unsigned u) { return __uint_as_float(u & 0xffff0000u); }
; __device__ __forceinline__ void phase_pool(const Params& p, char* smraw) {
;     ...
; #pragma unroll
;       for (int k = 0; k < 8; ++k) {
;         const int tt = t8 + k, pp = c0 + tt;
;         const float rs = rstd_s[tt + 15];
;         const float x0 = bflo(cur[k][0]) * rs, x1 = bfhi(cur[k][0]) * rs, x2 = bflo(cur[k][1]) * rs, x3 = bfhi(cur[k][1]) * rs;
;         s0 += x0; s1 += x1; s2 += x2; s3 += x3;
;         const int cnt = (pp + 1 < win) ? pp + 1 : win;
;         const float inv = 1.f / (float)cnt;
;         u32x2 o; o[0] = cvtpk(s0 * inv - x0, s1 * inv - x1); o[1] = cvtpk(s2 * inv - x2, s3 * inv - x3);
;         *(u32x2*)(p.pooled + (size_t)(b * L + pp) * D + c) = o;
;         const int po = pp - win + 1;
;         if (po >= 0) {
;           const float ro = rstd_s[tt + 15 - win + 1];
;           s0 -= bflo(old[k][0]) * ro; s1 -= bfhi(old[k][0]) * ro; s2 -= bflo(old[k][1]) * ro; s3 -= bfhi(old[k][1]) * ro;
;         }
;       }
	v_and_b32_e32 v14, 0xffff0000, v114
	v_lshlrev_b32_e32 v15, 16, v114
	v_and_b32_e32 v16, 0xffff0000, v115
	v_lshlrev_b32_e32 v17, 16, v115
	v_pk_mul_f32 v[18:19], v[218:219], v[14:15] op_sel:[1,0] op_sel_hi:[1,1]
	v_pk_mul_f32 v[20:21], v[218:219], v[16:17] op_sel:[1,0] op_sel_hi:[1,1]
	v_pk_fma_f32 v[10:11], v[218:219], v[14:15], v[10:11] op_sel:[1,0,0] op_sel_hi:[1,1,1]
	v_pk_fma_f32 v[12:13], v[218:219], v[16:17], v[12:13] op_sel:[1,0,0] op_sel_hi:[1,1,1]
	v_fma_f32 v22, s0, v11, -v19
	v_fma_f32 v23, s0, v10, -v18
	v_fma_f32 v24, s0, v13, -v21
	v_fma_f32 v25, s0, v12, -v20
	v_cvt_pk_bf16_f32 v22, v22, v23
	v_cvt_pk_bf16_f32 v23, v24, v25
	v_add_u32_e32 v34, 0x6000, v8
	global_store_dwordx2 v34, v[22:23], s[62:63]
	v_and_b32_e32 v14, 0xffff0000, v108
	v_lshlrev_b32_e32 v15, 16, v108
	v_and_b32_e32 v16, 0xffff0000, v109
	v_lshlrev_b32_e32 v17, 16, v109
	v_pk_fma_f32 v[10:11], v[216:217], v[14:15], v[10:11] op_sel_hi:[0,1,1] neg_lo:[1,0,0] neg_hi:[1,0,0]
	v_pk_fma_f32 v[12:13], v[216:217], v[16:17], v[12:13] op_sel_hi:[0,1,1] neg_lo:[1,0,0] neg_hi:[1,0,0]
	s_waitcnt vmcnt(47)
	v_and_b32_e32 v14, 0xffff0000, v116
	v_lshlrev_b32_e32 v15, 16, v116
	v_and_b32_e32 v16, 0xffff0000, v117
	v_lshlrev_b32_e32 v17, 16, v117
	v_pk_mul_f32 v[18:19], v[220:221], v[14:15] op_sel_hi:[0,1]
	v_pk_mul_f32 v[20:21], v[220:221], v[16:17] op_sel_hi:[0,1]
	v_pk_fma_f32 v[10:11], v[220:221], v[14:15], v[10:11] op_sel_hi:[0,1,1]
	v_pk_fma_f32 v[12:13], v[220:221], v[16:17], v[12:13] op_sel_hi:[0,1,1]
	v_fma_f32 v26, s0, v11, -v19
	v_fma_f32 v27, s0, v10, -v18
	v_fma_f32 v28, s0, v13, -v21
	v_fma_f32 v29, s0, v12, -v20
	v_cvt_pk_bf16_f32 v26, v26, v27
	v_cvt_pk_bf16_f32 v27, v28, v29
	v_add_u32_e32 v35, 0x6800, v8
	global_store_dwordx2 v35, v[26:27], s[62:63]
	v_and_b32_e32 v14, 0xffff0000, v110
	v_lshlrev_b32_e32 v15, 16, v110
	v_and_b32_e32 v16, 0xffff0000, v111
	v_lshlrev_b32_e32 v17, 16, v111
	v_pk_fma_f32 v[10:11], v[216:217], v[14:15], v[10:11] op_sel:[1,0,0] op_sel_hi:[1,1,1] neg_lo:[1,0,0] neg_hi:[1,0,0]
	v_pk_fma_f32 v[12:13], v[216:217], v[16:17], v[12:13] op_sel:[1,0,0] op_sel_hi:[1,1,1] neg_lo:[1,0,0] neg_hi:[1,0,0]
	s_waitcnt vmcnt(47)
	v_and_b32_e32 v14, 0xffff0000, v118
	v_lshlrev_b32_e32 v15, 16, v118
	v_and_b32_e32 v16, 0xffff0000, v119
	v_lshlrev_b32_e32 v17, 16, v119
	v_pk_mul_f32 v[18:19], v[220:221], v[14:15] op_sel:[1,0] op_sel_hi:[1,1]
	v_pk_mul_f32 v[20:21], v[220:221], v[16:17] op_sel:[1,0] op_sel_hi:[1,1]
	v_pk_fma_f32 v[10:11], v[220:221], v[14:15], v[10:11] op_sel:[1,0,0] op_sel_hi:[1,1,1]
	v_pk_fma_f32 v[12:13], v[220:221], v[16:17], v[12:13] op_sel:[1,0,0] op_sel_hi:[1,1,1]
	v_fma_f32 v22, s0, v11, -v19
	v_fma_f32 v23, s0, v10, -v18
	v_fma_f32 v24, s0, v13, -v21
	v_fma_f32 v25, s0, v12, -v20
	v_cvt_pk_bf16_f32 v22, v22, v23
	v_cvt_pk_bf16_f32 v23, v24, v25
	v_add_u32_e32 v36, 0x7000, v8
	global_store_dwordx2 v36, v[22:23], s[62:63]
	v_and_b32_e32 v14, 0xffff0000, v112
	v_lshlrev_b32_e32 v15, 16, v112
	v_and_b32_e32 v16, 0xffff0000, v113
	v_lshlrev_b32_e32 v17, 16, v113
	v_pk_fma_f32 v[10:11], v[218:219], v[14:15], v[10:11] op_sel_hi:[0,1,1] neg_lo:[1,0,0] neg_hi:[1,0,0]
	v_pk_fma_f32 v[12:13], v[218:219], v[16:17], v[12:13] op_sel_hi:[0,1,1] neg_lo:[1,0,0] neg_hi:[1,0,0]
	s_waitcnt vmcnt(47)
	v_and_b32_e32 v14, 0xffff0000, v120
	v_lshlrev_b32_e32 v15, 16, v120
	v_and_b32_e32 v16, 0xffff0000, v121
	v_lshlrev_b32_e32 v17, 16, v121
	v_pk_mul_f32 v[18:19], v[222:223], v[14:15] op_sel_hi:[0,1]
	v_pk_mul_f32 v[20:21], v[222:223], v[16:17] op_sel_hi:[0,1]
	v_pk_fma_f32 v[10:11], v[222:223], v[14:15], v[10:11] op_sel_hi:[0,1,1]
	v_pk_fma_f32 v[12:13], v[222:223], v[16:17], v[12:13] op_sel_hi:[0,1,1]
	v_fma_f32 v26, s0, v11, -v19
	v_fma_f32 v27, s0, v10, -v18
	v_fma_f32 v28, s0, v13, -v21
	v_fma_f32 v29, s0, v12, -v20
	v_cvt_pk_bf16_f32 v26, v26, v27
	v_cvt_pk_bf16_f32 v27, v28, v29
	v_add_u32_e32 v37, 0x7800, v8
	global_store_dwordx2 v37, v[26:27], s[62:63]
	v_and_b32_e32 v14, 0xffff0000, v114
	v_lshlrev_b32_e32 v15, 16, v114
	v_and_b32_e32 v16, 0xffff0000, v115
	v_lshlrev_b32_e32 v17, 16, v115
	v_pk_fma_f32 v[10:11], v[218:219], v[14:15], v[10:11] op_sel:[1,0,0] op_sel_hi:[1,1,1] neg_lo:[1,0,0] neg_hi:[1,0,0]
	v_pk_fma_f32 v[12:13], v[218:219], v[16:17], v[12:13] op_sel:[1,0,0] op_sel_hi:[1,1,1] neg_lo:[1,0,0] neg_hi:[1,0,0]
	s_waitcnt vmcnt(47)
	v_and_b32_e32 v14, 0xffff0000, v122
	v_lshlrev_b32_e32 v15, 16, v122
	v_and_b32_e32 v16, 0xffff0000, v123
	v_lshlrev_b32_e32 v17, 16, v123
	v_pk_mul_f32 v[18:19], v[222:223], v[14:15] op_sel:[1,0] op_sel_hi:[1,1]
	v_pk_mul_f32 v[20:21], v[222:223], v[16:17] op_sel:[1,0] op_sel_hi:[1,1]
	v_pk_fma_f32 v[10:11], v[222:223], v[14:15], v[10:11] op_sel:[1,0,0] op_sel_hi:[1,1,1]
	v_pk_fma_f32 v[12:13], v[222:223], v[16:17], v[12:13] op_sel:[1,0,0] op_sel_hi:[1,1,1]
	v_fma_f32 v22, s0, v11, -v19
	v_fma_f32 v23, s0, v10, -v18
	v_fma_f32 v24, s0, v13, -v21
	v_fma_f32 v25, s0, v12, -v20
	v_cvt_pk_bf16_f32 v22, v22, v23
	v_cvt_pk_bf16_f32 v23, v24, v25
	v_add_u32_e32 v30, 0x8000, v8
	global_store_dwordx2 v30, v[22:23], s[62:63]
	v_and_b32_e32 v14, 0xffff0000, v116
	v_lshlrev_b32_e32 v15, 16, v116
	v_and_b32_e32 v16, 0xffff0000, v117
	v_lshlrev_b32_e32 v17, 16, v117
	v_pk_fma_f32 v[10:11], v[220:221], v[14:15], v[10:11] op_sel_hi:[0,1,1] neg_lo:[1,0,0] neg_hi:[1,0,0]
	v_pk_fma_f32 v[12:13], v[220:221], v[16:17], v[12:13] op_sel_hi:[0,1,1] neg_lo:[1,0,0] neg_hi:[1,0,0]
	s_waitcnt vmcnt(47)
; __device__ __forceinline__ float bflo(unsigned u) { return __uint_as_float(u << 16); }
; __device__ __forceinline__ float bfhi(unsigned u) { return __uint_as_float(u & 0xffff0000u); }
; __device__ __forceinline__ void phase_pool(const Params& p, char* smraw) {
;     ...
; #pragma unroll
;       for (int k = 0; k < 8; ++k) {
;         const int tt = t8 + k, pp = c0 + tt;
;         const float rs = rstd_s[tt + 15];
;         const float x0 = bflo(cur[k][0]) * rs, x1 = bfhi(cur[k][0]) * rs, x2 = bflo(cur[k][1]) * rs, x3 = bfhi(cur[k][1]) * rs;
;         s0 += x0; s1 += x1; s2 += x2; s3 += x3;
;         const int cnt = (pp + 1 < win) ? pp + 1 : win;
;         const float inv = 1.f / (float)cnt;
;         u32x2 o; o[0] = cvtpk(s0 * inv - x0, s1 * inv - x1); o[1] = cvtpk(s2 * inv - x2, s3 * inv - x3);
;         *(u32x2*)(p.pooled + (size_t)(b * L + pp) * D + c) = o;
;         const int po = pp - win + 1;
;         if (po >= 0) {
;           const float ro = rstd_s[tt + 15 - win + 1];
;           s0 -= bflo(old[k][0]) * ro; s1 -= bfhi(old[k][0]) * ro; s2 -= bflo(old[k][1]) * ro; s3 -= bfhi(old[k][1]) * ro;
;         }
;       }
	v_and_b32_e32 v14, 0xffff0000, v124
	v_lshlrev_b32_e32 v15, 16, v124
	v_and_b32_e32 v16, 0xffff0000, v125
	v_lshlrev_b32_e32 v17, 16, v125
	v_pk_mul_f32 v[18:19], v[224:225], v[14:15] op_sel_hi:[0,1]
	v_pk_mul_f32 v[20:21], v[224:225], v[16:17] op_sel_hi:[0,1]
	v_pk_fma_f32 v[10:11], v[224:225], v[14:15], v[10:11] op_sel_hi:[0,1,1]
	v_pk_fma_f32 v[12:13], v[224:225], v[16:17], v[12:13] op_sel_hi:[0,1,1]
	v_fma_f32 v26, s0, v11, -v19
	v_fma_f32 v27, s0, v10, -v18
	v_fma_f32 v28, s0, v13, -v21
	v_fma_f32 v29, s0, v12, -v20
	v_cvt_pk_bf16_f32 v26, v26, v27
	v_cvt_pk_bf16_f32 v27, v28, v29
	v_add_u32_e32 v31, 0x8800, v8
	global_store_dwordx2 v31, v[26:27], s[62:63]
	v_and_b32_e32 v14, 0xffff0000, v118
	v_lshlrev_b32_e32 v15, 16, v118
	v_and_b32_e32 v16, 0xffff0000, v119
	v_lshlrev_b32_e32 v17, 16, v119
	v_pk_fma_f32 v[10:11], v[220:221], v[14:15], v[10:11] op_sel:[1,0,0] op_sel_hi:[1,1,1] neg_lo:[1,0,0] neg_hi:[1,0,0]
	v_pk_fma_f32 v[12:13], v[220:221], v[16:17], v[12:13] op_sel:[1,0,0] op_sel_hi:[1,1,1] neg_lo:[1,0,0] neg_hi:[1,0,0]
	s_waitcnt vmcnt(47)
	v_and_b32_e32 v14, 0xffff0000, v126
	v_lshlrev_b32_e32 v15, 16, v126
	v_and_b32_e32 v16, 0xffff0000, v127
	v_lshlrev_b32_e32 v17, 16, v127
	v_pk_mul_f32 v[18:19], v[224:225], v[14:15] op_sel:[1,0] op_sel_hi:[1,1]
	v_pk_mul_f32 v[20:21], v[224:225], v[16:17] op_sel:[1,0] op_sel_hi:[1,1]
	v_pk_fma_f32 v[10:11], v[224:225], v[14:15], v[10:11] op_sel:[1,0,0] op_sel_hi:[1,1,1]
	v_pk_fma_f32 v[12:13], v[224:225], v[16:17], v[12:13] op_sel:[1,0,0] op_sel_hi:[1,1,1]
	v_fma_f32 v22, s0, v11, -v19
	v_fma_f32 v23, s0, v10, -v18
	v_fma_f32 v24, s0, v13, -v21
	v_fma_f32 v25, s0, v12, -v20
	v_cvt_pk_bf16_f32 v22, v22, v23
	v_cvt_pk_bf16_f32 v23, v24, v25
	v_add_u32_e32 v32, 0x9000, v8
	global_store_dwordx2 v32, v[22:23], s[62:63]
	v_and_b32_e32 v14, 0xffff0000, v120
	v_lshlrev_b32_e32 v15, 16, v120
	v_and_b32_e32 v16, 0xffff0000, v121
	v_lshlrev_b32_e32 v17, 16, v121
	v_pk_fma_f32 v[10:11], v[222:223], v[14:15], v[10:11] op_sel_hi:[0,1,1] neg_lo:[1,0,0] neg_hi:[1,0,0]
	v_pk_fma_f32 v[12:13], v[222:223], v[16:17], v[12:13] op_sel_hi:[0,1,1] neg_lo:[1,0,0] neg_hi:[1,0,0]
	s_waitcnt vmcnt(47)
	v_and_b32_e32 v14, 0xffff0000, v128
	v_lshlrev_b32_e32 v15, 16, v128
	v_and_b32_e32 v16, 0xffff0000, v129
	v_lshlrev_b32_e32 v17, 16, v129
	v_pk_mul_f32 v[18:19], v[226:227], v[14:15] op_sel_hi:[0,1]
	v_pk_mul_f32 v[20:21], v[226:227], v[16:17] op_sel_hi:[0,1]
	v_pk_fma_f32 v[10:11], v[226:227], v[14:15], v[10:11] op_sel_hi:[0,1,1]
	v_pk_fma_f32 v[12:13], v[226:227], v[16:17], v[12:13] op_sel_hi:[0,1,1]
	v_fma_f32 v26, s0, v11, -v19
	v_fma_f32 v27, s0, v10, -v18
	v_fma_f32 v28, s0, v13, -v21
	v_fma_f32 v29, s0, v12, -v20
	v_cvt_pk_bf16_f32 v26, v26, v27
	v_cvt_pk_bf16_f32 v27, v28, v29
	v_add_u32_e32 v33, 0x9800, v8
	global_store_dwordx2 v33, v[26:27], s[62:63]
	v_and_b32_e32 v14, 0xffff0000, v122
	v_lshlrev_b32_e32 v15, 16, v122
	v_and_b32_e32 v16, 0xffff0000, v123
	v_lshlrev_b32_e32 v17, 16, v123
	v_pk_fma_f32 v[10:11], v[222:223], v[14:15], v[10:11] op_sel:[1,0,0] op_sel_hi:[1,1,1] neg_lo:[1,0,0] neg_hi:[1,0,0]
	v_pk_fma_f32 v[12:13], v[222:223], v[16:17], v[12:13] op_sel:[1,0,0] op_sel_hi:[1,1,1] neg_lo:[1,0,0] neg_hi:[1,0,0]
	s_waitcnt vmcnt(47)
	v_and_b32_e32 v14, 0xffff0000, v130
	v_lshlrev_b32_e32 v15, 16, v130
	v_and_b32_e32 v16, 0xffff0000, v131
	v_lshlrev_b32_e32 v17, 16, v131
	v_pk_mul_f32 v[18:19], v[226:227], v[14:15] op_sel:[1,0] op_sel_hi:[1,1]
	v_pk_mul_f32 v[20:21], v[226:227], v[16:17] op_sel:[1,0] op_sel_hi:[1,1]
	v_pk_fma_f32 v[10:11], v[226:227], v[14:15], v[10:11] op_sel:[1,0,0] op_sel_hi:[1,1,1]
	v_pk_fma_f32 v[12:13], v[226:227], v[16:17], v[12:13] op_sel:[1,0,0] op_sel_hi:[1,1,1]
	v_fma_f32 v22, s0, v11, -v19
	v_fma_f32 v23, s0, v10, -v18
	v_fma_f32 v24, s0, v13, -v21
	v_fma_f32 v25, s0, v12, -v20
	v_cvt_pk_bf16_f32 v22, v22, v23
	v_cvt_pk_bf16_f32 v23, v24, v25
	v_add_u32_e32 v34, 0xa000, v8
	global_store_dwordx2 v34, v[22:23], s[62:63]
	v_and_b32_e32 v14, 0xffff0000, v124
	v_lshlrev_b32_e32 v15, 16, v124
	v_and_b32_e32 v16, 0xffff0000, v125
	v_lshlrev_b32_e32 v17, 16, v125
	v_pk_fma_f32 v[10:11], v[224:225], v[14:15], v[10:11] op_sel_hi:[0,1,1] neg_lo:[1,0,0] neg_hi:[1,0,0]
	v_pk_fma_f32 v[12:13], v[224:225], v[16:17], v[12:13] op_sel_hi:[0,1,1] neg_lo:[1,0,0] neg_hi:[1,0,0]
	s_waitcnt vmcnt(47)
	v_and_b32_e32 v14, 0xffff0000, v132
	v_lshlrev_b32_e32 v15, 16, v132
	v_and_b32_e32 v16, 0xffff0000, v133
	v_lshlrev_b32_e32 v17, 16, v133
	v_pk_mul_f32 v[18:19], v[228:229], v[14:15] op_sel_hi:[0,1]
	v_pk_mul_f32 v[20:21], v[228:229], v[16:17] op_sel_hi:[0,1]
	v_pk_fma_f32 v[10:11], v[228:229], v[14:15], v[10:11] op_sel_hi:[0,1,1]
	v_pk_fma_f32 v[12:13], v[228:229], v[16:17], v[12:13] op_sel_hi:[0,1,1]
	v_fma_f32 v26, s0, v11, -v19
	v_fma_f32 v27, s0, v10, -v18
	v_fma_f32 v28, s0, v13, -v21
	v_fma_f32 v29, s0, v12, -v20
	v_cvt_pk_bf16_f32 v26, v26, v27
	v_cvt_pk_bf16_f32 v27, v28, v29
	v_add_u32_e32 v35, 0xa800, v8
	global_store_dwordx2 v35, v[26:27], s[62:63]
	v_and_b32_e32 v14, 0xffff0000, v126
	v_lshlrev_b32_e32 v15, 16, v126
	v_and_b32_e32 v16, 0xffff0000, v127
	v_lshlrev_b32_e32 v17, 16, v127
	v_pk_fma_f32 v[10:11], v[224:225], v[14:15], v[10:11] op_sel:[1,0,0] op_sel_hi:[1,1,1] neg_lo:[1,0,0] neg_hi:[1,0,0]
	v_pk_fma_f32 v[12:13], v[224:225], v[16:17], v[12:13] op_sel:[1,0,0] op_sel_hi:[1,1,1] neg_lo:[1,0,0] neg_hi:[1,0,0]
	s_waitcnt vmcnt(47)
; __device__ __forceinline__ float bflo(unsigned u) { return __uint_as_float(u << 16); }
; __device__ __forceinline__ float bfhi(unsigned u) { return __uint_as_float(u & 0xffff0000u); }
; __device__ __forceinline__ void phase_pool(const Params& p, char* smraw) {
;     ...
; #pragma unroll
;       for (int k = 0; k < 8; ++k) {
;         const int tt = t8 + k, pp = c0 + tt;
;         const float rs = rstd_s[tt + 15];
;         const float x0 = bflo(cur[k][0]) * rs, x1 = bfhi(cur[k][0]) * rs, x2 = bflo(cur[k][1]) * rs, x3 = bfhi(cur[k][1]) * rs;
;         s0 += x0; s1 += x1; s2 += x2; s3 += x3;
;         const int cnt = (pp + 1 < win) ? pp + 1 : win;
;         const float inv = 1.f / (float)cnt;
;         u32x2 o; o[0] = cvtpk(s0 * inv - x0, s1 * inv - x1); o[1] = cvtpk(s2 * inv - x2, s3 * inv - x3);
;         *(u32x2*)(p.pooled + (size_t)(b * L + pp) * D + c) = o;
;         const int po = pp - win + 1;
;         if (po >= 0) {
;           const float ro = rstd_s[tt + 15 - win + 1];
;           s0 -= bflo(old[k][0]) * ro; s1 -= bfhi(old[k][0]) * ro; s2 -= bflo(old[k][1]) * ro; s3 -= bfhi(old[k][1]) * ro;
;         }
;       }
	v_and_b32_e32 v14, 0xffff0000, v134
	v_lshlrev_b32_e32 v15, 16, v134
	v_and_b32_e32 v16, 0xffff0000, v135
	v_lshlrev_b32_e32 v17, 16, v135
	v_pk_mul_f32 v[18:19], v[228:229], v[14:15] op_sel:[1,0] op_sel_hi:[1,1]
	v_pk_mul_f32 v[20:21], v[228:229], v[16:17] op_sel:[1,0] op_sel_hi:[1,1]
	v_pk_fma_f32 v[10:11], v[228:229], v[14:15], v[10:11] op_sel:[1,0,0] op_sel_hi:[1,1,1]
	v_pk_fma_f32 v[12:13], v[228:229], v[16:17], v[12:13] op_sel:[1,0,0] op_sel_hi:[1,1,1]
	v_fma_f32 v22, s0, v11, -v19
	v_fma_f32 v23, s0, v10, -v18
	v_fma_f32 v24, s0, v13, -v21
	v_fma_f32 v25, s0, v12, -v20
	v_cvt_pk_bf16_f32 v22, v22, v23
	v_cvt_pk_bf16_f32 v23, v24, v25
	v_add_u32_e32 v36, 0xb000, v8
	global_store_dwordx2 v36, v[22:23], s[62:63]
	v_and_b32_e32 v14, 0xffff0000, v128
	v_lshlrev_b32_e32 v15, 16, v128
	v_and_b32_e32 v16, 0xffff0000, v129
	v_lshlrev_b32_e32 v17, 16, v129
	v_pk_fma_f32 v[10:11], v[226:227], v[14:15], v[10:11] op_sel_hi:[0,1,1] neg_lo:[1,0,0] neg_hi:[1,0,0]
	v_pk_fma_f32 v[12:13], v[226:227], v[16:17], v[12:13] op_sel_hi:[0,1,1] neg_lo:[1,0,0] neg_hi:[1,0,0]
	s_waitcnt vmcnt(47)
	v_and_b32_e32 v14, 0xffff0000, v136
	v_lshlrev_b32_e32 v15, 16, v136
	v_and_b32_e32 v16, 0xffff0000, v137
	v_lshlrev_b32_e32 v17, 16, v137
	v_pk_mul_f32 v[18:19], v[230:231], v[14:15] op_sel_hi:[0,1]
	v_pk_mul_f32 v[20:21], v[230:231], v[16:17] op_sel_hi:[0,1]
	v_pk_fma_f32 v[10:11], v[230:231], v[14:15], v[10:11] op_sel_hi:[0,1,1]
	v_pk_fma_f32 v[12:13], v[230:231], v[16:17], v[12:13] op_sel_hi:[0,1,1]
	v_fma_f32 v26, s0, v11, -v19
	v_fma_f32 v27, s0, v10, -v18
	v_fma_f32 v28, s0, v13, -v21
	v_fma_f32 v29, s0, v12, -v20
	v_cvt_pk_bf16_f32 v26, v26, v27
	v_cvt_pk_bf16_f32 v27, v28, v29
	v_add_u32_e32 v37, 0xb800, v8
	global_store_dwordx2 v37, v[26:27], s[62:63]
	v_and_b32_e32 v14, 0xffff0000, v130
	v_lshlrev_b32_e32 v15, 16, v130
	v_and_b32_e32 v16, 0xffff0000, v131
	v_lshlrev_b32_e32 v17, 16, v131
	v_pk_fma_f32 v[10:11], v[226:227], v[14:15], v[10:11] op_sel:[1,0,0] op_sel_hi:[1,1,1] neg_lo:[1,0,0] neg_hi:[1,0,0]
	v_pk_fma_f32 v[12:13], v[226:227], v[16:17], v[12:13] op_sel:[1,0,0] op_sel_hi:[1,1,1] neg_lo:[1,0,0] neg_hi:[1,0,0]
	s_waitcnt vmcnt(47)
	v_and_b32_e32 v14, 0xffff0000, v138
	v_lshlrev_b32_e32 v15, 16, v138
	v_and_b32_e32 v16, 0xffff0000, v139
	v_lshlrev_b32_e32 v17, 16, v139
	v_pk_mul_f32 v[18:19], v[230:231], v[14:15] op_sel:[1,0] op_sel_hi:[1,1]
	v_pk_mul_f32 v[20:21], v[230:231], v[16:17] op_sel:[1,0] op_sel_hi:[1,1]
	v_pk_fma_f32 v[10:11], v[230:231], v[14:15], v[10:11] op_sel:[1,0,0] op_sel_hi:[1,1,1]
	v_pk_fma_f32 v[12:13], v[230:231], v[16:17], v[12:13] op_sel:[1,0,0] op_sel_hi:[1,1,1]
	v_fma_f32 v22, s0, v11, -v19
	v_fma_f32 v23, s0, v10, -v18
	v_fma_f32 v24, s0, v13, -v21
	v_fma_f32 v25, s0, v12, -v20
	v_cvt_pk_bf16_f32 v22, v22, v23
	v_cvt_pk_bf16_f32 v23, v24, v25
	v_add_u32_e32 v30, 0xc000, v8
	global_store_dwordx2 v30, v[22:23], s[62:63]
	v_and_b32_e32 v14, 0xffff0000, v132
	v_lshlrev_b32_e32 v15, 16, v132
	v_and_b32_e32 v16, 0xffff0000, v133
	v_lshlrev_b32_e32 v17, 16, v133
	v_pk_fma_f32 v[10:11], v[228:229], v[14:15], v[10:11] op_sel_hi:[0,1,1] neg_lo:[1,0,0] neg_hi:[1,0,0]
	v_pk_fma_f32 v[12:13], v[228:229], v[16:17], v[12:13] op_sel_hi:[0,1,1] neg_lo:[1,0,0] neg_hi:[1,0,0]
	s_waitcnt vmcnt(47)
	v_and_b32_e32 v14, 0xffff0000, v140
	v_lshlrev_b32_e32 v15, 16, v140
	v_and_b32_e32 v16, 0xffff0000, v141
	v_lshlrev_b32_e32 v17, 16, v141
	v_pk_mul_f32 v[18:19], v[232:233], v[14:15] op_sel_hi:[0,1]
	v_pk_mul_f32 v[20:21], v[232:233], v[16:17] op_sel_hi:[0,1]
	v_pk_fma_f32 v[10:11], v[232:233], v[14:15], v[10:11] op_sel_hi:[0,1,1]
	v_pk_fma_f32 v[12:13], v[232:233], v[16:17], v[12:13] op_sel_hi:[0,1,1]
	v_fma_f32 v26, s0, v11, -v19
	v_fma_f32 v27, s0, v10, -v18
	v_fma_f32 v28, s0, v13, -v21
	v_fma_f32 v29, s0, v12, -v20
	v_cvt_pk_bf16_f32 v26, v26, v27
	v_cvt_pk_bf16_f32 v27, v28, v29
	v_add_u32_e32 v31, 0xc800, v8
	global_store_dwordx2 v31, v[26:27], s[62:63]
	v_and_b32_e32 v14, 0xffff0000, v134
	v_lshlrev_b32_e32 v15, 16, v134
	v_and_b32_e32 v16, 0xffff0000, v135
	v_lshlrev_b32_e32 v17, 16, v135
	v_pk_fma_f32 v[10:11], v[228:229], v[14:15], v[10:11] op_sel:[1,0,0] op_sel_hi:[1,1,1] neg_lo:[1,0,0] neg_hi:[1,0,0]
	v_pk_fma_f32 v[12:13], v[228:229], v[16:17], v[12:13] op_sel:[1,0,0] op_sel_hi:[1,1,1] neg_lo:[1,0,0] neg_hi:[1,0,0]
	s_waitcnt vmcnt(47)
	v_and_b32_e32 v14, 0xffff0000, v142
	v_lshlrev_b32_e32 v15, 16, v142
	v_and_b32_e32 v16, 0xffff0000, v143
	v_lshlrev_b32_e32 v17, 16, v143
	v_pk_mul_f32 v[18:19], v[232:233], v[14:15] op_sel:[1,0] op_sel_hi:[1,1]
	v_pk_mul_f32 v[20:21], v[232:233], v[16:17] op_sel:[1,0] op_sel_hi:[1,1]
	v_pk_fma_f32 v[10:11], v[232:233], v[14:15], v[10:11] op_sel:[1,0,0] op_sel_hi:[1,1,1]
	v_pk_fma_f32 v[12:13], v[232:233], v[16:17], v[12:13] op_sel:[1,0,0] op_sel_hi:[1,1,1]
	v_fma_f32 v22, s0, v11, -v19
	v_fma_f32 v23, s0, v10, -v18
	v_fma_f32 v24, s0, v13, -v21
	v_fma_f32 v25, s0, v12, -v20
	v_cvt_pk_bf16_f32 v22, v22, v23
	v_cvt_pk_bf16_f32 v23, v24, v25
	v_add_u32_e32 v32, 0xd000, v8
	global_store_dwordx2 v32, v[22:23], s[62:63]
	v_and_b32_e32 v14, 0xffff0000, v136
	v_lshlrev_b32_e32 v15, 16, v136
	v_and_b32_e32 v16, 0xffff0000, v137
	v_lshlrev_b32_e32 v17, 16, v137
	v_pk_fma_f32 v[10:11], v[230:231], v[14:15], v[10:11] op_sel_hi:[0,1,1] neg_lo:[1,0,0] neg_hi:[1,0,0]
	v_pk_fma_f32 v[12:13], v[230:231], v[16:17], v[12:13] op_sel_hi:[0,1,1] neg_lo:[1,0,0] neg_hi:[1,0,0]
	s_waitcnt vmcnt(47)
; __device__ __forceinline__ float bflo(unsigned u) { return __uint_as_float(u << 16); }
; __device__ __forceinline__ float bfhi(unsigned u) { return __uint_as_float(u & 0xffff0000u); }
; __device__ __forceinline__ void phase_pool(const Params& p, char* smraw) {
;     ...
; #pragma unroll
;       for (int k = 0; k < 8; ++k) {
;         const int tt = t8 + k, pp = c0 + tt;
;         const float rs = rstd_s[tt + 15];
;         const float x0 = bflo(cur[k][0]) * rs, x1 = bfhi(cur[k][0]) * rs, x2 = bflo(cur[k][1]) * rs, x3 = bfhi(cur[k][1]) * rs;
;         s0 += x0; s1 += x1; s2 += x2; s3 += x3;
;         const int cnt = (pp + 1 < win) ? pp + 1 : win;
;         const float inv = 1.f / (float)cnt;
;         u32x2 o; o[0] = cvtpk(s0 * inv - x0, s1 * inv - x1); o[1] = cvtpk(s2 * inv - x2, s3 * inv - x3);
;         *(u32x2*)(p.pooled + (size_t)(b * L + pp) * D + c) = o;
;         const int po = pp - win + 1;
;         if (po >= 0) {
;           const float ro = rstd_s[tt + 15 - win + 1];
;           s0 -= bflo(old[k][0]) * ro; s1 -= bfhi(old[k][0]) * ro; s2 -= bflo(old[k][1]) * ro; s3 -= bfhi(old[k][1]) * ro;
;         }
;       }
	v_and_b32_e32 v14, 0xffff0000, v144
	v_lshlrev_b32_e32 v15, 16, v144
	v_and_b32_e32 v16, 0xffff0000, v145
	v_lshlrev_b32_e32 v17, 16, v145
	v_pk_mul_f32 v[18:19], v[234:235], v[14:15] op_sel_hi:[0,1]
	v_pk_mul_f32 v[20:21], v[234:235], v[16:17] op_sel_hi:[0,1]
	v_pk_fma_f32 v[10:11], v[234:235], v[14:15], v[10:11] op_sel_hi:[0,1,1]
	v_pk_fma_f32 v[12:13], v[234:235], v[16:17], v[12:13] op_sel_hi:[0,1,1]
	v_fma_f32 v26, s0, v11, -v19
	v_fma_f32 v27, s0, v10, -v18
	v_fma_f32 v28, s0, v13, -v21
	v_fma_f32 v29, s0, v12, -v20
	v_cvt_pk_bf16_f32 v26, v26, v27
	v_cvt_pk_bf16_f32 v27, v28, v29
	v_add_u32_e32 v33, 0xd800, v8
	global_store_dwordx2 v33, v[26:27], s[62:63]
	v_and_b32_e32 v14, 0xffff0000, v138
	v_lshlrev_b32_e32 v15, 16, v138
	v_and_b32_e32 v16, 0xffff0000, v139
	v_lshlrev_b32_e32 v17, 16, v139
	v_pk_fma_f32 v[10:11], v[230:231], v[14:15], v[10:11] op_sel:[1,0,0] op_sel_hi:[1,1,1] neg_lo:[1,0,0] neg_hi:[1,0,0]
	v_pk_fma_f32 v[12:13], v[230:231], v[16:17], v[12:13] op_sel:[1,0,0] op_sel_hi:[1,1,1] neg_lo:[1,0,0] neg_hi:[1,0,0]
	s_waitcnt vmcnt(47)
	v_and_b32_e32 v14, 0xffff0000, v146
	v_lshlrev_b32_e32 v15, 16, v146
	v_and_b32_e32 v16, 0xffff0000, v147
	v_lshlrev_b32_e32 v17, 16, v147
	v_pk_mul_f32 v[18:19], v[234:235], v[14:15] op_sel:[1,0] op_sel_hi:[1,1]
	v_pk_mul_f32 v[20:21], v[234:235], v[16:17] op_sel:[1,0] op_sel_hi:[1,1]
	v_pk_fma_f32 v[10:11], v[234:235], v[14:15], v[10:11] op_sel:[1,0,0] op_sel_hi:[1,1,1]
	v_pk_fma_f32 v[12:13], v[234:235], v[16:17], v[12:13] op_sel:[1,0,0] op_sel_hi:[1,1,1]
	v_fma_f32 v22, s0, v11, -v19
	v_fma_f32 v23, s0, v10, -v18
	v_fma_f32 v24, s0, v13, -v21
	v_fma_f32 v25, s0, v12, -v20
	v_cvt_pk_bf16_f32 v22, v22, v23
	v_cvt_pk_bf16_f32 v23, v24, v25
	v_add_u32_e32 v34, 0xe000, v8
	global_store_dwordx2 v34, v[22:23], s[62:63]
	v_and_b32_e32 v14, 0xffff0000, v140
	v_lshlrev_b32_e32 v15, 16, v140
	v_and_b32_e32 v16, 0xffff0000, v141
	v_lshlrev_b32_e32 v17, 16, v141
	v_pk_fma_f32 v[10:11], v[232:233], v[14:15], v[10:11] op_sel_hi:[0,1,1] neg_lo:[1,0,0] neg_hi:[1,0,0]
	v_pk_fma_f32 v[12:13], v[232:233], v[16:17], v[12:13] op_sel_hi:[0,1,1] neg_lo:[1,0,0] neg_hi:[1,0,0]
	s_waitcnt vmcnt(47)
	v_and_b32_e32 v14, 0xffff0000, v148
	v_lshlrev_b32_e32 v15, 16, v148
	v_and_b32_e32 v16, 0xffff0000, v149
	v_lshlrev_b32_e32 v17, 16, v149
	v_pk_mul_f32 v[18:19], v[236:237], v[14:15] op_sel_hi:[0,1]
	v_pk_mul_f32 v[20:21], v[236:237], v[16:17] op_sel_hi:[0,1]
	v_pk_fma_f32 v[10:11], v[236:237], v[14:15], v[10:11] op_sel_hi:[0,1,1]
	v_pk_fma_f32 v[12:13], v[236:237], v[16:17], v[12:13] op_sel_hi:[0,1,1]
	v_fma_f32 v26, s0, v11, -v19
	v_fma_f32 v27, s0, v10, -v18
	v_fma_f32 v28, s0, v13, -v21
	v_fma_f32 v29, s0, v12, -v20
	v_cvt_pk_bf16_f32 v26, v26, v27
	v_cvt_pk_bf16_f32 v27, v28, v29
	v_add_u32_e32 v35, 0xe800, v8
	global_store_dwordx2 v35, v[26:27], s[62:63]
	v_and_b32_e32 v14, 0xffff0000, v142
	v_lshlrev_b32_e32 v15, 16, v142
	v_and_b32_e32 v16, 0xffff0000, v143
	v_lshlrev_b32_e32 v17, 16, v143
	v_pk_fma_f32 v[10:11], v[232:233], v[14:15], v[10:11] op_sel:[1,0,0] op_sel_hi:[1,1,1] neg_lo:[1,0,0] neg_hi:[1,0,0]
	v_pk_fma_f32 v[12:13], v[232:233], v[16:17], v[12:13] op_sel:[1,0,0] op_sel_hi:[1,1,1] neg_lo:[1,0,0] neg_hi:[1,0,0]
	s_waitcnt vmcnt(47)
	v_and_b32_e32 v14, 0xffff0000, v150
	v_lshlrev_b32_e32 v15, 16, v150
	v_and_b32_e32 v16, 0xffff0000, v151
	v_lshlrev_b32_e32 v17, 16, v151
	v_pk_mul_f32 v[18:19], v[236:237], v[14:15] op_sel:[1,0] op_sel_hi:[1,1]
	v_pk_mul_f32 v[20:21], v[236:237], v[16:17] op_sel:[1,0] op_sel_hi:[1,1]
	v_pk_fma_f32 v[10:11], v[236:237], v[14:15], v[10:11] op_sel:[1,0,0] op_sel_hi:[1,1,1]
	v_pk_fma_f32 v[12:13], v[236:237], v[16:17], v[12:13] op_sel:[1,0,0] op_sel_hi:[1,1,1]
	v_fma_f32 v22, s0, v11, -v19
	v_fma_f32 v23, s0, v10, -v18
	v_fma_f32 v24, s0, v13, -v21
	v_fma_f32 v25, s0, v12, -v20
	v_cvt_pk_bf16_f32 v22, v22, v23
	v_cvt_pk_bf16_f32 v23, v24, v25
	v_add_u32_e32 v36, 0xf000, v8
	global_store_dwordx2 v36, v[22:23], s[62:63]
	v_and_b32_e32 v14, 0xffff0000, v144
	v_lshlrev_b32_e32 v15, 16, v144
	v_and_b32_e32 v16, 0xffff0000, v145
	v_lshlrev_b32_e32 v17, 16, v145
	v_pk_fma_f32 v[10:11], v[234:235], v[14:15], v[10:11] op_sel_hi:[0,1,1] neg_lo:[1,0,0] neg_hi:[1,0,0]
	v_pk_fma_f32 v[12:13], v[234:235], v[16:17], v[12:13] op_sel_hi:[0,1,1] neg_lo:[1,0,0] neg_hi:[1,0,0]
	s_waitcnt vmcnt(47)
	v_and_b32_e32 v14, 0xffff0000, v152
	v_lshlrev_b32_e32 v15, 16, v152
	v_and_b32_e32 v16, 0xffff0000, v153
	v_lshlrev_b32_e32 v17, 16, v153
	v_pk_mul_f32 v[18:19], v[238:239], v[14:15] op_sel_hi:[0,1]
	v_pk_mul_f32 v[20:21], v[238:239], v[16:17] op_sel_hi:[0,1]
	v_pk_fma_f32 v[10:11], v[238:239], v[14:15], v[10:11] op_sel_hi:[0,1,1]
	v_pk_fma_f32 v[12:13], v[238:239], v[16:17], v[12:13] op_sel_hi:[0,1,1]
	v_fma_f32 v26, s0, v11, -v19
	v_fma_f32 v27, s0, v10, -v18
	v_fma_f32 v28, s0, v13, -v21
	v_fma_f32 v29, s0, v12, -v20
	v_cvt_pk_bf16_f32 v26, v26, v27
	v_cvt_pk_bf16_f32 v27, v28, v29
	v_add_u32_e32 v37, 0xf800, v8
	global_store_dwordx2 v37, v[26:27], s[62:63]
	v_and_b32_e32 v14, 0xffff0000, v146
	v_lshlrev_b32_e32 v15, 16, v146
	v_and_b32_e32 v16, 0xffff0000, v147
	v_lshlrev_b32_e32 v17, 16, v147
	v_pk_fma_f32 v[10:11], v[234:235], v[14:15], v[10:11] op_sel:[1,0,0] op_sel_hi:[1,1,1] neg_lo:[1,0,0] neg_hi:[1,0,0]
	v_pk_fma_f32 v[12:13], v[234:235], v[16:17], v[12:13] op_sel:[1,0,0] op_sel_hi:[1,1,1] neg_lo:[1,0,0] neg_hi:[1,0,0]
	s_waitcnt vmcnt(47)
; __device__ __forceinline__ float bflo(unsigned u) { return __uint_as_float(u << 16); }
; __device__ __forceinline__ float bfhi(unsigned u) { return __uint_as_float(u & 0xffff0000u); }
; __device__ __forceinline__ void phase_pool(const Params& p, char* smraw) {
;     ...
; #pragma unroll
;       for (int k = 0; k < 8; ++k) {
;         const int tt = t8 + k, pp = c0 + tt;
;         const float rs = rstd_s[tt + 15];
;         const float x0 = bflo(cur[k][0]) * rs, x1 = bfhi(cur[k][0]) * rs, x2 = bflo(cur[k][1]) * rs, x3 = bfhi(cur[k][1]) * rs;
;         s0 += x0; s1 += x1; s2 += x2; s3 += x3;
;         const int cnt = (pp + 1 < win) ? pp + 1 : win;
;         const float inv = 1.f / (float)cnt;
;         u32x2 o; o[0] = cvtpk(s0 * inv - x0, s1 * inv - x1); o[1] = cvtpk(s2 * inv - x2, s3 * inv - x3);
;         *(u32x2*)(p.pooled + (size_t)(b * L + pp) * D + c) = o;
;         const int po = pp - win + 1;
;         if (po >= 0) {
;           const float ro = rstd_s[tt + 15 - win + 1];
;           s0 -= bflo(old[k][0]) * ro; s1 -= bfhi(old[k][0]) * ro; s2 -= bflo(old[k][1]) * ro; s3 -= bfhi(old[k][1]) * ro;
;         }
;       }
	v_and_b32_e32 v14, 0xffff0000, v154
	v_lshlrev_b32_e32 v15, 16, v154
	v_and_b32_e32 v16, 0xffff0000, v155
	v_lshlrev_b32_e32 v17, 16, v155
	v_pk_mul_f32 v[18:19], v[238:239], v[14:15] op_sel:[1,0] op_sel_hi:[1,1]
	v_pk_mul_f32 v[20:21], v[238:239], v[16:17] op_sel:[1,0] op_sel_hi:[1,1]
	v_pk_fma_f32 v[10:11], v[238:239], v[14:15], v[10:11] op_sel:[1,0,0] op_sel_hi:[1,1,1]
	v_pk_fma_f32 v[12:13], v[238:239], v[16:17], v[12:13] op_sel:[1,0,0] op_sel_hi:[1,1,1]
	v_fma_f32 v22, s0, v11, -v19
	v_fma_f32 v23, s0, v10, -v18
	v_fma_f32 v24, s0, v13, -v21
	v_fma_f32 v25, s0, v12, -v20
	v_cvt_pk_bf16_f32 v22, v22, v23
	v_cvt_pk_bf16_f32 v23, v24, v25
	v_add_u32_e32 v30, 0x10000, v8
	global_store_dwordx2 v30, v[22:23], s[62:63]
	v_and_b32_e32 v14, 0xffff0000, v148
	v_lshlrev_b32_e32 v15, 16, v148
	v_and_b32_e32 v16, 0xffff0000, v149
	v_lshlrev_b32_e32 v17, 16, v149
	v_pk_fma_f32 v[10:11], v[236:237], v[14:15], v[10:11] op_sel_hi:[0,1,1] neg_lo:[1,0,0] neg_hi:[1,0,0]
	v_pk_fma_f32 v[12:13], v[236:237], v[16:17], v[12:13] op_sel_hi:[0,1,1] neg_lo:[1,0,0] neg_hi:[1,0,0]
	s_waitcnt vmcnt(47)
	v_and_b32_e32 v14, 0xffff0000, v156
	v_lshlrev_b32_e32 v15, 16, v156
	v_and_b32_e32 v16, 0xffff0000, v157
	v_lshlrev_b32_e32 v17, 16, v157
	v_pk_mul_f32 v[18:19], v[240:241], v[14:15] op_sel_hi:[0,1]
	v_pk_mul_f32 v[20:21], v[240:241], v[16:17] op_sel_hi:[0,1]
	v_pk_fma_f32 v[10:11], v[240:241], v[14:15], v[10:11] op_sel_hi:[0,1,1]
	v_pk_fma_f32 v[12:13], v[240:241], v[16:17], v[12:13] op_sel_hi:[0,1,1]
	v_fma_f32 v26, s0, v11, -v19
	v_fma_f32 v27, s0, v10, -v18
	v_fma_f32 v28, s0, v13, -v21
	v_fma_f32 v29, s0, v12, -v20
	v_cvt_pk_bf16_f32 v26, v26, v27
	v_cvt_pk_bf16_f32 v27, v28, v29
	v_add_u32_e32 v31, 0x10800, v8
	global_store_dwordx2 v31, v[26:27], s[62:63]
	v_and_b32_e32 v14, 0xffff0000, v150
	v_lshlrev_b32_e32 v15, 16, v150
	v_and_b32_e32 v16, 0xffff0000, v151
	v_lshlrev_b32_e32 v17, 16, v151
	v_pk_fma_f32 v[10:11], v[236:237], v[14:15], v[10:11] op_sel:[1,0,0] op_sel_hi:[1,1,1] neg_lo:[1,0,0] neg_hi:[1,0,0]
	v_pk_fma_f32 v[12:13], v[236:237], v[16:17], v[12:13] op_sel:[1,0,0] op_sel_hi:[1,1,1] neg_lo:[1,0,0] neg_hi:[1,0,0]
	s_waitcnt vmcnt(47)
	v_and_b32_e32 v14, 0xffff0000, v158
	v_lshlrev_b32_e32 v15, 16, v158
	v_and_b32_e32 v16, 0xffff0000, v159
	v_lshlrev_b32_e32 v17, 16, v159
	v_pk_mul_f32 v[18:19], v[240:241], v[14:15] op_sel:[1,0] op_sel_hi:[1,1]
	v_pk_mul_f32 v[20:21], v[240:241], v[16:17] op_sel:[1,0] op_sel_hi:[1,1]
	v_pk_fma_f32 v[10:11], v[240:241], v[14:15], v[10:11] op_sel:[1,0,0] op_sel_hi:[1,1,1]
	v_pk_fma_f32 v[12:13], v[240:241], v[16:17], v[12:13] op_sel:[1,0,0] op_sel_hi:[1,1,1]
	v_fma_f32 v22, s0, v11, -v19
	v_fma_f32 v23, s0, v10, -v18
	v_fma_f32 v24, s0, v13, -v21
	v_fma_f32 v25, s0, v12, -v20
	v_cvt_pk_bf16_f32 v22, v22, v23
	v_cvt_pk_bf16_f32 v23, v24, v25
	v_add_u32_e32 v32, 0x11000, v8
	global_store_dwordx2 v32, v[22:23], s[62:63]
	v_and_b32_e32 v14, 0xffff0000, v152
	v_lshlrev_b32_e32 v15, 16, v152
	v_and_b32_e32 v16, 0xffff0000, v153
	v_lshlrev_b32_e32 v17, 16, v153
	v_pk_fma_f32 v[10:11], v[238:239], v[14:15], v[10:11] op_sel_hi:[0,1,1] neg_lo:[1,0,0] neg_hi:[1,0,0]
	v_pk_fma_f32 v[12:13], v[238:239], v[16:17], v[12:13] op_sel_hi:[0,1,1] neg_lo:[1,0,0] neg_hi:[1,0,0]
	s_waitcnt vmcnt(47)
	v_and_b32_e32 v14, 0xffff0000, v160
	v_lshlrev_b32_e32 v15, 16, v160
	v_and_b32_e32 v16, 0xffff0000, v161
	v_lshlrev_b32_e32 v17, 16, v161
	v_pk_mul_f32 v[18:19], v[242:243], v[14:15] op_sel_hi:[0,1]
	v_pk_mul_f32 v[20:21], v[242:243], v[16:17] op_sel_hi:[0,1]
	v_pk_fma_f32 v[10:11], v[242:243], v[14:15], v[10:11] op_sel_hi:[0,1,1]
	v_pk_fma_f32 v[12:13], v[242:243], v[16:17], v[12:13] op_sel_hi:[0,1,1]
	v_fma_f32 v26, s0, v11, -v19
	v_fma_f32 v27, s0, v10, -v18
	v_fma_f32 v28, s0, v13, -v21
	v_fma_f32 v29, s0, v12, -v20
	v_cvt_pk_bf16_f32 v26, v26, v27
	v_cvt_pk_bf16_f32 v27, v28, v29
	v_add_u32_e32 v33, 0x11800, v8
	global_store_dwordx2 v33, v[26:27], s[62:63]
	v_and_b32_e32 v14, 0xffff0000, v154
	v_lshlrev_b32_e32 v15, 16, v154
	v_and_b32_e32 v16, 0xffff0000, v155
	v_lshlrev_b32_e32 v17, 16, v155
	v_pk_fma_f32 v[10:11], v[238:239], v[14:15], v[10:11] op_sel:[1,0,0] op_sel_hi:[1,1,1] neg_lo:[1,0,0] neg_hi:[1,0,0]
	v_pk_fma_f32 v[12:13], v[238:239], v[16:17], v[12:13] op_sel:[1,0,0] op_sel_hi:[1,1,1] neg_lo:[1,0,0] neg_hi:[1,0,0]
	s_waitcnt vmcnt(47)
	v_and_b32_e32 v14, 0xffff0000, v162
	v_lshlrev_b32_e32 v15, 16, v162
	v_and_b32_e32 v16, 0xffff0000, v163
	v_lshlrev_b32_e32 v17, 16, v163
	v_pk_mul_f32 v[18:19], v[242:243], v[14:15] op_sel:[1,0] op_sel_hi:[1,1]
	v_pk_mul_f32 v[20:21], v[242:243], v[16:17] op_sel:[1,0] op_sel_hi:[1,1]
	v_pk_fma_f32 v[10:11], v[242:243], v[14:15], v[10:11] op_sel:[1,0,0] op_sel_hi:[1,1,1]
	v_pk_fma_f32 v[12:13], v[242:243], v[16:17], v[12:13] op_sel:[1,0,0] op_sel_hi:[1,1,1]
	v_fma_f32 v22, s0, v11, -v19
	v_fma_f32 v23, s0, v10, -v18
	v_fma_f32 v24, s0, v13, -v21
	v_fma_f32 v25, s0, v12, -v20
	v_cvt_pk_bf16_f32 v22, v22, v23
	v_cvt_pk_bf16_f32 v23, v24, v25
	v_add_u32_e32 v34, 0x12000, v8
	global_store_dwordx2 v34, v[22:23], s[62:63]
	v_and_b32_e32 v14, 0xffff0000, v156
	v_lshlrev_b32_e32 v15, 16, v156
	v_and_b32_e32 v16, 0xffff0000, v157
	v_lshlrev_b32_e32 v17, 16, v157
	v_pk_fma_f32 v[10:11], v[240:241], v[14:15], v[10:11] op_sel_hi:[0,1,1] neg_lo:[1,0,0] neg_hi:[1,0,0]
	v_pk_fma_f32 v[12:13], v[240:241], v[16:17], v[12:13] op_sel_hi:[0,1,1] neg_lo:[1,0,0] neg_hi:[1,0,0]
	s_waitcnt vmcnt(47)
; __device__ __forceinline__ float bflo(unsigned u) { return __uint_as_float(u << 16); }
; __device__ __forceinline__ float bfhi(unsigned u) { return __uint_as_float(u & 0xffff0000u); }
; __device__ __forceinline__ void phase_pool(const Params& p, char* smraw) {
;     ...
; #pragma unroll
;       for (int k = 0; k < 8; ++k) {
;         const int tt = t8 + k, pp = c0 + tt;
;         const float rs = rstd_s[tt + 15];
;         const float x0 = bflo(cur[k][0]) * rs, x1 = bfhi(cur[k][0]) * rs, x2 = bflo(cur[k][1]) * rs, x3 = bfhi(cur[k][1]) * rs;
;         s0 += x0; s1 += x1; s2 += x2; s3 += x3;
;         const int cnt = (pp + 1 < win) ? pp + 1 : win;
;         const float inv = 1.f / (float)cnt;
;         u32x2 o; o[0] = cvtpk(s0 * inv - x0, s1 * inv - x1); o[1] = cvtpk(s2 * inv - x2, s3 * inv - x3);
;         *(u32x2*)(p.pooled + (size_t)(b * L + pp) * D + c) = o;
;         const int po = pp - win + 1;
;         if (po >= 0) {
;           const float ro = rstd_s[tt + 15 - win + 1];
;           s0 -= bflo(old[k][0]) * ro; s1 -= bfhi(old[k][0]) * ro; s2 -= bflo(old[k][1]) * ro; s3 -= bfhi(old[k][1]) * ro;
;         }
;       }
	v_and_b32_e32 v14, 0xffff0000, v164
	v_lshlrev_b32_e32 v15, 16, v164
	v_and_b32_e32 v16, 0xffff0000, v165
	v_lshlrev_b32_e32 v17, 16, v165
	v_pk_mul_f32 v[18:19], v[244:245], v[14:15] op_sel_hi:[0,1]
	v_pk_mul_f32 v[20:21], v[244:245], v[16:17] op_sel_hi:[0,1]
	v_pk_fma_f32 v[10:11], v[244:245], v[14:15], v[10:11] op_sel_hi:[0,1,1]
	v_pk_fma_f32 v[12:13], v[244:245], v[16:17], v[12:13] op_sel_hi:[0,1,1]
	v_fma_f32 v26, s0, v11, -v19
	v_fma_f32 v27, s0, v10, -v18
	v_fma_f32 v28, s0, v13, -v21
	v_fma_f32 v29, s0, v12, -v20
	v_cvt_pk_bf16_f32 v26, v26, v27
	v_cvt_pk_bf16_f32 v27, v28, v29
	v_add_u32_e32 v35, 0x12800, v8
	global_store_dwordx2 v35, v[26:27], s[62:63]
	v_and_b32_e32 v14, 0xffff0000, v158
	v_lshlrev_b32_e32 v15, 16, v158
	v_and_b32_e32 v16, 0xffff0000, v159
	v_lshlrev_b32_e32 v17, 16, v159
	v_pk_fma_f32 v[10:11], v[240:241], v[14:15], v[10:11] op_sel:[1,0,0] op_sel_hi:[1,1,1] neg_lo:[1,0,0] neg_hi:[1,0,0]
	v_pk_fma_f32 v[12:13], v[240:241], v[16:17], v[12:13] op_sel:[1,0,0] op_sel_hi:[1,1,1] neg_lo:[1,0,0] neg_hi:[1,0,0]
	s_waitcnt vmcnt(47)
	v_and_b32_e32 v14, 0xffff0000, v166
	v_lshlrev_b32_e32 v15, 16, v166
	v_and_b32_e32 v16, 0xffff0000, v167
	v_lshlrev_b32_e32 v17, 16, v167
	v_pk_mul_f32 v[18:19], v[244:245], v[14:15] op_sel:[1,0] op_sel_hi:[1,1]
	v_pk_mul_f32 v[20:21], v[244:245], v[16:17] op_sel:[1,0] op_sel_hi:[1,1]
	v_pk_fma_f32 v[10:11], v[244:245], v[14:15], v[10:11] op_sel:[1,0,0] op_sel_hi:[1,1,1]
	v_pk_fma_f32 v[12:13], v[244:245], v[16:17], v[12:13] op_sel:[1,0,0] op_sel_hi:[1,1,1]
	v_fma_f32 v22, s0, v11, -v19
	v_fma_f32 v23, s0, v10, -v18
	v_fma_f32 v24, s0, v13, -v21
	v_fma_f32 v25, s0, v12, -v20
	v_cvt_pk_bf16_f32 v22, v22, v23
	v_cvt_pk_bf16_f32 v23, v24, v25
	v_add_u32_e32 v36, 0x13000, v8
	global_store_dwordx2 v36, v[22:23], s[62:63]
	v_and_b32_e32 v14, 0xffff0000, v160
	v_lshlrev_b32_e32 v15, 16, v160
	v_and_b32_e32 v16, 0xffff0000, v161
	v_lshlrev_b32_e32 v17, 16, v161
	v_pk_fma_f32 v[10:11], v[242:243], v[14:15], v[10:11] op_sel_hi:[0,1,1] neg_lo:[1,0,0] neg_hi:[1,0,0]
	v_pk_fma_f32 v[12:13], v[242:243], v[16:17], v[12:13] op_sel_hi:[0,1,1] neg_lo:[1,0,0] neg_hi:[1,0,0]
	s_waitcnt vmcnt(47)
	v_and_b32_e32 v14, 0xffff0000, v168
	v_lshlrev_b32_e32 v15, 16, v168
	v_and_b32_e32 v16, 0xffff0000, v169
	v_lshlrev_b32_e32 v17, 16, v169
	v_pk_mul_f32 v[18:19], v[246:247], v[14:15] op_sel_hi:[0,1]
	v_pk_mul_f32 v[20:21], v[246:247], v[16:17] op_sel_hi:[0,1]
	v_pk_fma_f32 v[10:11], v[246:247], v[14:15], v[10:11] op_sel_hi:[0,1,1]
	v_pk_fma_f32 v[12:13], v[246:247], v[16:17], v[12:13] op_sel_hi:[0,1,1]
	v_fma_f32 v26, s0, v11, -v19
	v_fma_f32 v27, s0, v10, -v18
	v_fma_f32 v28, s0, v13, -v21
	v_fma_f32 v29, s0, v12, -v20
	v_cvt_pk_bf16_f32 v26, v26, v27
	v_cvt_pk_bf16_f32 v27, v28, v29
	v_add_u32_e32 v37, 0x13800, v8
	global_store_dwordx2 v37, v[26:27], s[62:63]
	v_and_b32_e32 v14, 0xffff0000, v162
	v_lshlrev_b32_e32 v15, 16, v162
	v_and_b32_e32 v16, 0xffff0000, v163
	v_lshlrev_b32_e32 v17, 16, v163
	v_pk_fma_f32 v[10:11], v[242:243], v[14:15], v[10:11] op_sel:[1,0,0] op_sel_hi:[1,1,1] neg_lo:[1,0,0] neg_hi:[1,0,0]
	v_pk_fma_f32 v[12:13], v[242:243], v[16:17], v[12:13] op_sel:[1,0,0] op_sel_hi:[1,1,1] neg_lo:[1,0,0] neg_hi:[1,0,0]
	s_waitcnt vmcnt(47)
	v_and_b32_e32 v14, 0xffff0000, v170
	v_lshlrev_b32_e32 v15, 16, v170
	v_and_b32_e32 v16, 0xffff0000, v171
	v_lshlrev_b32_e32 v17, 16, v171
	v_pk_mul_f32 v[18:19], v[246:247], v[14:15] op_sel:[1,0] op_sel_hi:[1,1]
	v_pk_mul_f32 v[20:21], v[246:247], v[16:17] op_sel:[1,0] op_sel_hi:[1,1]
	v_pk_fma_f32 v[10:11], v[246:247], v[14:15], v[10:11] op_sel:[1,0,0] op_sel_hi:[1,1,1]
	v_pk_fma_f32 v[12:13], v[246:247], v[16:17], v[12:13] op_sel:[1,0,0] op_sel_hi:[1,1,1]
	v_fma_f32 v22, s0, v11, -v19
	v_fma_f32 v23, s0, v10, -v18
	v_fma_f32 v24, s0, v13, -v21
	v_fma_f32 v25, s0, v12, -v20
	v_cvt_pk_bf16_f32 v22, v22, v23
	v_cvt_pk_bf16_f32 v23, v24, v25
	v_add_u32_e32 v30, 0x14000, v8
	global_store_dwordx2 v30, v[22:23], s[62:63]
	v_and_b32_e32 v14, 0xffff0000, v164
	v_lshlrev_b32_e32 v15, 16, v164
	v_and_b32_e32 v16, 0xffff0000, v165
	v_lshlrev_b32_e32 v17, 16, v165
	v_pk_fma_f32 v[10:11], v[244:245], v[14:15], v[10:11] op_sel_hi:[0,1,1] neg_lo:[1,0,0] neg_hi:[1,0,0]
	v_pk_fma_f32 v[12:13], v[244:245], v[16:17], v[12:13] op_sel_hi:[0,1,1] neg_lo:[1,0,0] neg_hi:[1,0,0]
	s_waitcnt vmcnt(47)
	v_and_b32_e32 v14, 0xffff0000, v172
	v_lshlrev_b32_e32 v15, 16, v172
	v_and_b32_e32 v16, 0xffff0000, v173
	v_lshlrev_b32_e32 v17, 16, v173
	v_pk_mul_f32 v[18:19], v[248:249], v[14:15] op_sel_hi:[0,1]
	v_pk_mul_f32 v[20:21], v[248:249], v[16:17] op_sel_hi:[0,1]
	v_pk_fma_f32 v[10:11], v[248:249], v[14:15], v[10:11] op_sel_hi:[0,1,1]
	v_pk_fma_f32 v[12:13], v[248:249], v[16:17], v[12:13] op_sel_hi:[0,1,1]
	v_fma_f32 v26, s0, v11, -v19
	v_fma_f32 v27, s0, v10, -v18
	v_fma_f32 v28, s0, v13, -v21
	v_fma_f32 v29, s0, v12, -v20
	v_cvt_pk_bf16_f32 v26, v26, v27
	v_cvt_pk_bf16_f32 v27, v28, v29
	v_add_u32_e32 v31, 0x14800, v8
	global_store_dwordx2 v31, v[26:27], s[62:63]
	v_and_b32_e32 v14, 0xffff0000, v166
	v_lshlrev_b32_e32 v15, 16, v166
	v_and_b32_e32 v16, 0xffff0000, v167
	v_lshlrev_b32_e32 v17, 16, v167
	v_pk_fma_f32 v[10:11], v[244:245], v[14:15], v[10:11] op_sel:[1,0,0] op_sel_hi:[1,1,1] neg_lo:[1,0,0] neg_hi:[1,0,0]
	v_pk_fma_f32 v[12:13], v[244:245], v[16:17], v[12:13] op_sel:[1,0,0] op_sel_hi:[1,1,1] neg_lo:[1,0,0] neg_hi:[1,0,0]
	s_waitcnt vmcnt(47)
; __device__ __forceinline__ float bflo(unsigned u) { return __uint_as_float(u << 16); }
; __device__ __forceinline__ float bfhi(unsigned u) { return __uint_as_float(u & 0xffff0000u); }
; __device__ __forceinline__ void phase_pool(const Params& p, char* smraw) {
;     ...
; #pragma unroll
;       for (int k = 0; k < 8; ++k) {
;         const int tt = t8 + k, pp = c0 + tt;
;         const float rs = rstd_s[tt + 15];
;         const float x0 = bflo(cur[k][0]) * rs, x1 = bfhi(cur[k][0]) * rs, x2 = bflo(cur[k][1]) * rs, x3 = bfhi(cur[k][1]) * rs;
;         s0 += x0; s1 += x1; s2 += x2; s3 += x3;
;         const int cnt = (pp + 1 < win) ? pp + 1 : win;
;         const float inv = 1.f / (float)cnt;
;         u32x2 o; o[0] = cvtpk(s0 * inv - x0, s1 * inv - x1); o[1] = cvtpk(s2 * inv - x2, s3 * inv - x3);
;         *(u32x2*)(p.pooled + (size_t)(b * L + pp) * D + c) = o;
;         const int po = pp - win + 1;
;         if (po >= 0) {
;           const float ro = rstd_s[tt + 15 - win + 1];
;           s0 -= bflo(old[k][0]) * ro; s1 -= bfhi(old[k][0]) * ro; s2 -= bflo(old[k][1]) * ro; s3 -= bfhi(old[k][1]) * ro;
;         }
;       }
	v_and_b32_e32 v14, 0xffff0000, v174
	v_lshlrev_b32_e32 v15, 16, v174
	v_and_b32_e32 v16, 0xffff0000, v175
	v_lshlrev_b32_e32 v17, 16, v175
	v_pk_mul_f32 v[18:19], v[248:249], v[14:15] op_sel:[1,0] op_sel_hi:[1,1]
	v_pk_mul_f32 v[20:21], v[248:249], v[16:17] op_sel:[1,0] op_sel_hi:[1,1]
	v_pk_fma_f32 v[10:11], v[248:249], v[14:15], v[10:11] op_sel:[1,0,0] op_sel_hi:[1,1,1]
	v_pk_fma_f32 v[12:13], v[248:249], v[16:17], v[12:13] op_sel:[1,0,0] op_sel_hi:[1,1,1]
	v_fma_f32 v22, s0, v11, -v19
	v_fma_f32 v23, s0, v10, -v18
	v_fma_f32 v24, s0, v13, -v21
	v_fma_f32 v25, s0, v12, -v20
	v_cvt_pk_bf16_f32 v22, v22, v23
	v_cvt_pk_bf16_f32 v23, v24, v25
	v_add_u32_e32 v32, 0x15000, v8
	global_store_dwordx2 v32, v[22:23], s[62:63]
	v_and_b32_e32 v14, 0xffff0000, v168
	v_lshlrev_b32_e32 v15, 16, v168
	v_and_b32_e32 v16, 0xffff0000, v169
	v_lshlrev_b32_e32 v17, 16, v169
	v_pk_fma_f32 v[10:11], v[246:247], v[14:15], v[10:11] op_sel_hi:[0,1,1] neg_lo:[1,0,0] neg_hi:[1,0,0]
	v_pk_fma_f32 v[12:13], v[246:247], v[16:17], v[12:13] op_sel_hi:[0,1,1] neg_lo:[1,0,0] neg_hi:[1,0,0]
	s_waitcnt vmcnt(47)
	v_and_b32_e32 v14, 0xffff0000, v176
	v_lshlrev_b32_e32 v15, 16, v176
	v_and_b32_e32 v16, 0xffff0000, v177
	v_lshlrev_b32_e32 v17, 16, v177
	v_pk_mul_f32 v[18:19], v[250:251], v[14:15] op_sel_hi:[0,1]
	v_pk_mul_f32 v[20:21], v[250:251], v[16:17] op_sel_hi:[0,1]
	v_pk_fma_f32 v[10:11], v[250:251], v[14:15], v[10:11] op_sel_hi:[0,1,1]
	v_pk_fma_f32 v[12:13], v[250:251], v[16:17], v[12:13] op_sel_hi:[0,1,1]
	v_fma_f32 v26, s0, v11, -v19
	v_fma_f32 v27, s0, v10, -v18
	v_fma_f32 v28, s0, v13, -v21
	v_fma_f32 v29, s0, v12, -v20
	v_cvt_pk_bf16_f32 v26, v26, v27
	v_cvt_pk_bf16_f32 v27, v28, v29
	v_add_u32_e32 v33, 0x15800, v8
	global_store_dwordx2 v33, v[26:27], s[62:63]
	v_and_b32_e32 v14, 0xffff0000, v170
	v_lshlrev_b32_e32 v15, 16, v170
	v_and_b32_e32 v16, 0xffff0000, v171
	v_lshlrev_b32_e32 v17, 16, v171
	v_pk_fma_f32 v[10:11], v[246:247], v[14:15], v[10:11] op_sel:[1,0,0] op_sel_hi:[1,1,1] neg_lo:[1,0,0] neg_hi:[1,0,0]
	v_pk_fma_f32 v[12:13], v[246:247], v[16:17], v[12:13] op_sel:[1,0,0] op_sel_hi:[1,1,1] neg_lo:[1,0,0] neg_hi:[1,0,0]
	s_waitcnt vmcnt(47)
	v_and_b32_e32 v14, 0xffff0000, v178
	v_lshlrev_b32_e32 v15, 16, v178
	v_and_b32_e32 v16, 0xffff0000, v179
	v_lshlrev_b32_e32 v17, 16, v179
	v_pk_mul_f32 v[18:19], v[250:251], v[14:15] op_sel:[1,0] op_sel_hi:[1,1]
	v_pk_mul_f32 v[20:21], v[250:251], v[16:17] op_sel:[1,0] op_sel_hi:[1,1]
	v_pk_fma_f32 v[10:11], v[250:251], v[14:15], v[10:11] op_sel:[1,0,0] op_sel_hi:[1,1,1]
	v_pk_fma_f32 v[12:13], v[250:251], v[16:17], v[12:13] op_sel:[1,0,0] op_sel_hi:[1,1,1]
	v_fma_f32 v22, s0, v11, -v19
	v_fma_f32 v23, s0, v10, -v18
	v_fma_f32 v24, s0, v13, -v21
	v_fma_f32 v25, s0, v12, -v20
	v_cvt_pk_bf16_f32 v22, v22, v23
	v_cvt_pk_bf16_f32 v23, v24, v25
	v_add_u32_e32 v34, 0x16000, v8
	global_store_dwordx2 v34, v[22:23], s[62:63]
	v_and_b32_e32 v14, 0xffff0000, v172
	v_lshlrev_b32_e32 v15, 16, v172
	v_and_b32_e32 v16, 0xffff0000, v173
	v_lshlrev_b32_e32 v17, 16, v173
	v_pk_fma_f32 v[10:11], v[248:249], v[14:15], v[10:11] op_sel_hi:[0,1,1] neg_lo:[1,0,0] neg_hi:[1,0,0]
	v_pk_fma_f32 v[12:13], v[248:249], v[16:17], v[12:13] op_sel_hi:[0,1,1] neg_lo:[1,0,0] neg_hi:[1,0,0]
	s_waitcnt vmcnt(47)
	v_and_b32_e32 v14, 0xffff0000, v180
	v_lshlrev_b32_e32 v15, 16, v180
	v_and_b32_e32 v16, 0xffff0000, v181
	v_lshlrev_b32_e32 v17, 16, v181
	v_pk_mul_f32 v[18:19], v[252:253], v[14:15] op_sel_hi:[0,1]
	v_pk_mul_f32 v[20:21], v[252:253], v[16:17] op_sel_hi:[0,1]
	v_pk_fma_f32 v[10:11], v[252:253], v[14:15], v[10:11] op_sel_hi:[0,1,1]
	v_pk_fma_f32 v[12:13], v[252:253], v[16:17], v[12:13] op_sel_hi:[0,1,1]
	v_fma_f32 v26, s0, v11, -v19
	v_fma_f32 v27, s0, v10, -v18
	v_fma_f32 v28, s0, v13, -v21
	v_fma_f32 v29, s0, v12, -v20
	v_cvt_pk_bf16_f32 v26, v26, v27
	v_cvt_pk_bf16_f32 v27, v28, v29
	v_add_u32_e32 v35, 0x16800, v8
	global_store_dwordx2 v35, v[26:27], s[62:63]
	v_and_b32_e32 v14, 0xffff0000, v174
	v_lshlrev_b32_e32 v15, 16, v174
	v_and_b32_e32 v16, 0xffff0000, v175
	v_lshlrev_b32_e32 v17, 16, v175
	v_pk_fma_f32 v[10:11], v[248:249], v[14:15], v[10:11] op_sel:[1,0,0] op_sel_hi:[1,1,1] neg_lo:[1,0,0] neg_hi:[1,0,0]
	v_pk_fma_f32 v[12:13], v[248:249], v[16:17], v[12:13] op_sel:[1,0,0] op_sel_hi:[1,1,1] neg_lo:[1,0,0] neg_hi:[1,0,0]
	s_waitcnt vmcnt(47)
	v_and_b32_e32 v14, 0xffff0000, v182
	v_lshlrev_b32_e32 v15, 16, v182
	v_and_b32_e32 v16, 0xffff0000, v183
	v_lshlrev_b32_e32 v17, 16, v183
	v_pk_mul_f32 v[18:19], v[252:253], v[14:15] op_sel:[1,0] op_sel_hi:[1,1]
	v_pk_mul_f32 v[20:21], v[252:253], v[16:17] op_sel:[1,0] op_sel_hi:[1,1]
	v_pk_fma_f32 v[10:11], v[252:253], v[14:15], v[10:11] op_sel:[1,0,0] op_sel_hi:[1,1,1]
	v_pk_fma_f32 v[12:13], v[252:253], v[16:17], v[12:13] op_sel:[1,0,0] op_sel_hi:[1,1,1]
	v_fma_f32 v22, s0, v11, -v19
	v_fma_f32 v23, s0, v10, -v18
	v_fma_f32 v24, s0, v13, -v21
	v_fma_f32 v25, s0, v12, -v20
	v_cvt_pk_bf16_f32 v22, v22, v23
	v_cvt_pk_bf16_f32 v23, v24, v25
	v_add_u32_e32 v36, 0x17000, v8
	global_store_dwordx2 v36, v[22:23], s[62:63]
	v_and_b32_e32 v14, 0xffff0000, v176
	v_lshlrev_b32_e32 v15, 16, v176
	v_and_b32_e32 v16, 0xffff0000, v177
	v_lshlrev_b32_e32 v17, 16, v177
	v_pk_fma_f32 v[10:11], v[250:251], v[14:15], v[10:11] op_sel_hi:[0,1,1] neg_lo:[1,0,0] neg_hi:[1,0,0]
	v_pk_fma_f32 v[12:13], v[250:251], v[16:17], v[12:13] op_sel_hi:[0,1,1] neg_lo:[1,0,0] neg_hi:[1,0,0]
	s_waitcnt vmcnt(47)
	v_and_b32_e32 v14, 0xffff0000, v184
	v_lshlrev_b32_e32 v15, 16, v184
	v_and_b32_e32 v16, 0xffff0000, v185
	v_lshlrev_b32_e32 v17, 16, v185
	v_pk_mul_f32 v[18:19], v[186:187], v[14:15] op_sel_hi:[0,1]
	v_pk_mul_f32 v[20:21], v[186:187], v[16:17] op_sel_hi:[0,1]
	v_pk_fma_f32 v[10:11], v[186:187], v[14:15], v[10:11] op_sel_hi:[0,1,1]
	v_pk_fma_f32 v[12:13], v[186:187], v[16:17], v[12:13] op_sel_hi:[0,1,1]
	v_fma_f32 v26, s0, v11, -v19
	v_fma_f32 v27, s0, v10, -v18
	v_fma_f32 v28, s0, v13, -v21
	v_fma_f32 v29, s0, v12, -v20
	v_cvt_pk_bf16_f32 v26, v26, v27
	v_cvt_pk_bf16_f32 v27, v28, v29
	v_add_u32_e32 v37, 0x17800, v8
	global_store_dwordx2 v37, v[26:27], s[62:63]
	v_and_b32_e32 v14, 0xffff0000, v178
	v_lshlrev_b32_e32 v15, 16, v178
	v_and_b32_e32 v16, 0xffff0000, v179
	v_lshlrev_b32_e32 v17, 16, v179
	v_pk_fma_f32 v[10:11], v[250:251], v[14:15], v[10:11] op_sel:[1,0,0] op_sel_hi:[1,1,1] neg_lo:[1,0,0] neg_hi:[1,0,0]
	v_pk_fma_f32 v[12:13], v[250:251], v[16:17], v[12:13] op_sel:[1,0,0] op_sel_hi:[1,1,1] neg_lo:[1,0,0] neg_hi:[1,0,0]
	s_branch .Lmy_pool_next
; __device__ __forceinline__ float bflo(unsigned u) { return __uint_as_float(u << 16); }
; __device__ __forceinline__ float bfhi(unsigned u) { return __uint_as_float(u & 0xffff0000u); }
; __device__ __forceinline__ void phase_pool(const Params& p, char* smraw) {
;     ...
;     const int c = tid * 4;
;     const int win = 2 << (tid >> 6);
;     const u16* base = p.hb + (size_t)(b * L) * D + c;
;     float s0 = 0.f, s1 = 0.f, s2 = 0.f, s3 = 0.f;
;     for (int i = 1; i < win; ++i) {
;       const int pp = c0 - i;
;       if (pp >= 0) {
;         u32x2 v = *(const u32x2*)(base + (size_t)pp * D);
;         const float rs = rstd_s[15 - i];
;         s0 += bflo(v[0]) * rs; s1 += bfhi(v[0]) * rs; s2 += bflo(v[1]) * rs; s3 += bfhi(v[1]) * rs;
;       }
;     }
;     for (int t8 = 0; t8 < CH; t8 += 8) {
;       u32x2 cur[8], old[8];
; #pragma unroll
;       for (int k = 0; k < 8; ++k) {
;         const int pp = c0 + t8 + k;
;         cur[k] = *(const u32x2*)(base + (size_t)pp * D);
;         const int po = pp - win + 1;
;         old[k] = *(const u32x2*)(base + (size_t)(po >= 0 ? po : 0) * D);
;       }
.Lmy_pool_w0:
	s_mov_b32 s35, 0x3f000000
	ds_read_b128 v[192:195], v59 offset:0
	ds_read_b128 v[196:199], v59 offset:16
	ds_read_b128 v[200:203], v59 offset:32
	ds_read_b128 v[204:207], v59 offset:48
	ds_read_b128 v[208:211], v59 offset:64
	ds_read_b128 v[212:215], v59 offset:80
	ds_read_b128 v[216:219], v59 offset:96
	ds_read_b128 v[220:223], v59 offset:112
	ds_read_b128 v[224:227], v59 offset:128
	ds_read_b128 v[228:231], v59 offset:144
	ds_read_b128 v[232:235], v59 offset:160
	ds_read_b128 v[236:239], v59 offset:176
	ds_read_b128 v[240:243], v59 offset:192
	ds_read_b128 v[244:247], v59 offset:208
	ds_read_b128 v[248:251], v59 offset:224
	ds_read_b64 v[252:253], v59 offset:240
	ds_read_b32 v186, v59 offset:248
	s_add_i32 s1, s9, -1
	s_max_i32 s1, s1, 0
	s_add_u32 s1, s1, s27
	s_lshl_b32 s1, s1, 11
	v_add_u32_e32 v36, s1, v1
	global_load_dwordx2 v[88:89], v36, s[76:77]
	global_load_dwordx2 v[90:91], v8, s[76:77]
	v_add_u32_e32 v30, 0x800, v8
	global_load_dwordx2 v[92:93], v30, s[76:77]
	v_add_u32_e32 v31, 0x1000, v8
	global_load_dwordx2 v[94:95], v31, s[76:77]
	v_add_u32_e32 v32, 0x1800, v8
	global_load_dwordx2 v[96:97], v32, s[76:77]
	v_add_u32_e32 v33, 0x2000, v8
	global_load_dwordx2 v[98:99], v33, s[76:77]
	v_add_u32_e32 v34, 0x2800, v8
	global_load_dwordx2 v[100:101], v34, s[76:77]
	v_add_u32_e32 v35, 0x3000, v8
	global_load_dwordx2 v[102:103], v35, s[76:77]
	v_add_u32_e32 v36, 0x3800, v8
	global_load_dwordx2 v[104:105], v36, s[76:77]
	v_add_u32_e32 v37, 0x4000, v8
	global_load_dwordx2 v[106:107], v37, s[76:77]
	v_add_u32_e32 v30, 0x4800, v8
	global_load_dwordx2 v[108:109], v30, s[76:77]
	v_add_u32_e32 v31, 0x5000, v8
	global_load_dwordx2 v[110:111], v31, s[76:77]
	v_add_u32_e32 v32, 0x5800, v8
	global_load_dwordx2 v[112:113], v32, s[76:77]
	v_add_u32_e32 v33, 0x6000, v8
	global_load_dwordx2 v[114:115], v33, s[76:77]
	v_add_u32_e32 v34, 0x6800, v8
	global_load_dwordx2 v[116:117], v34, s[76:77]
	v_add_u32_e32 v35, 0x7000, v8
	global_load_dwordx2 v[118:119], v35, s[76:77]
	v_add_u32_e32 v36, 0x7800, v8
	global_load_dwordx2 v[120:121], v36, s[76:77]
	v_add_u32_e32 v37, 0x8000, v8
	global_load_dwordx2 v[122:123], v37, s[76:77]
	v_add_u32_e32 v30, 0x8800, v8
	global_load_dwordx2 v[124:125], v30, s[76:77]
	v_add_u32_e32 v31, 0x9000, v8
	global_load_dwordx2 v[126:127], v31, s[76:77]
	v_add_u32_e32 v32, 0x9800, v8
	global_load_dwordx2 v[128:129], v32, s[76:77]
	v_add_u32_e32 v33, 0xa000, v8
	global_load_dwordx2 v[130:131], v33, s[76:77]
	v_add_u32_e32 v34, 0xa800, v8
	global_load_dwordx2 v[132:133], v34, s[76:77]
	v_add_u32_e32 v35, 0xb000, v8
	global_load_dwordx2 v[134:135], v35, s[76:77]
	v_add_u32_e32 v36, 0xb800, v8
	global_load_dwordx2 v[136:137], v36, s[76:77]
	v_add_u32_e32 v37, 0xc000, v8
	global_load_dwordx2 v[138:139], v37, s[76:77]
	v_add_u32_e32 v30, 0xc800, v8
	global_load_dwordx2 v[140:141], v30, s[76:77]
	v_add_u32_e32 v31, 0xd000, v8
	global_load_dwordx2 v[142:143], v31, s[76:77]
	v_add_u32_e32 v32, 0xd800, v8
	global_load_dwordx2 v[144:145], v32, s[76:77]
	v_add_u32_e32 v33, 0xe000, v8
	global_load_dwordx2 v[146:147], v33, s[76:77]
	v_add_u32_e32 v34, 0xe800, v8
	global_load_dwordx2 v[148:149], v34, s[76:77]
	v_add_u32_e32 v35, 0xf000, v8
	global_load_dwordx2 v[150:151], v35, s[76:77]
	v_add_u32_e32 v36, 0xf800, v8
	global_load_dwordx2 v[152:153], v36, s[76:77]
	v_add_u32_e32 v37, 0x10000, v8
	global_load_dwordx2 v[154:155], v37, s[76:77]
	v_add_u32_e32 v30, 0x10800, v8
	global_load_dwordx2 v[156:157], v30, s[76:77]
	v_add_u32_e32 v31, 0x11000, v8
	global_load_dwordx2 v[158:159], v31, s[76:77]
	v_add_u32_e32 v32, 0x11800, v8
	global_load_dwordx2 v[160:161], v32, s[76:77]
	v_add_u32_e32 v33, 0x12000, v8
	global_load_dwordx2 v[162:163], v33, s[76:77]
	v_add_u32_e32 v34, 0x12800, v8
	global_load_dwordx2 v[164:165], v34, s[76:77]
	v_add_u32_e32 v35, 0x13000, v8
	global_load_dwordx2 v[166:167], v35, s[76:77]
	v_add_u32_e32 v36, 0x13800, v8
	global_load_dwordx2 v[168:169], v36, s[76:77]
	v_add_u32_e32 v37, 0x14000, v8
	global_load_dwordx2 v[170:171], v37, s[76:77]
	v_add_u32_e32 v30, 0x14800, v8
	global_load_dwordx2 v[172:173], v30, s[76:77]
	v_add_u32_e32 v31, 0x15000, v8
	global_load_dwordx2 v[174:175], v31, s[76:77]
	v_add_u32_e32 v32, 0x15800, v8
	global_load_dwordx2 v[176:177], v32, s[76:77]
	v_add_u32_e32 v33, 0x16000, v8
	global_load_dwordx2 v[178:179], v33, s[76:77]
	v_add_u32_e32 v34, 0x16800, v8
	global_load_dwordx2 v[180:181], v34, s[76:77]
	v_add_u32_e32 v35, 0x17000, v8
	global_load_dwordx2 v[182:183], v35, s[76:77]
	v_add_u32_e32 v36, 0x17800, v8
	global_load_dwordx2 v[184:185], v36, s[76:77]
	s_waitcnt lgkmcnt(0)
	s_cmp_lg_u32 s9, 0
	s_cbranch_scc1 .Lmy_pool_w0_nz
	v_mov_b32_e32 v192, 0
	v_mov_b32_e32 v193, 0
	v_mov_b32_e32 v194, 0
	v_mov_b32_e32 v195, 0
	v_mov_b32_e32 v196, 0
	v_mov_b32_e32 v197, 0
	v_mov_b32_e32 v198, 0
	v_mov_b32_e32 v199, 0
	v_mov_b32_e32 v200, 0
	v_mov_b32_e32 v201, 0
	v_mov_b32_e32 v202, 0
	v_mov_b32_e32 v203, 0
	v_mov_b32_e32 v204, 0
	v_mov_b32_e32 v205, 0
	v_mov_b32_e32 v206, 0
; __device__ __forceinline__ float bflo(unsigned u) { return __uint_as_float(u << 16); }
; __device__ __forceinline__ float bfhi(unsigned u) { return __uint_as_float(u & 0xffff0000u); }
; __device__ __forceinline__ void phase_pool(const Params& p, char* smraw) {
;     ...
;     for (int i = 1; i < win; ++i) {
;       const int pp = c0 - i;
;       if (pp >= 0) {
;         u32x2 v = *(const u32x2*)(base + (size_t)pp * D);
;         const float rs = rstd_s[15 - i];
;         s0 += bflo(v[0]) * rs; s1 += bfhi(v[0]) * rs; s2 += bflo(v[1]) * rs; s3 += bfhi(v[1]) * rs;
;       }
;     }
;     ...
;       for (int k = 0; k < 8; ++k) {
;         const int tt = t8 + k, pp = c0 + tt;
;         const float rs = rstd_s[tt + 15];
;         const float x0 = bflo(cur[k][0]) * rs, x1 = bfhi(cur[k][0]) * rs, x2 = bflo(cur[k][1]) * rs, x3 = bfhi(cur[k][1]) * rs;
;         s0 += x0; s1 += x1; s2 += x2; s3 += x3;
;         const int cnt = (pp + 1 < win) ? pp + 1 : win;
;         const float inv = 1.f / (float)cnt;
;         u32x2 o; o[0] = cvtpk(s0 * inv - x0, s1 * inv - x1); o[1] = cvtpk(s2 * inv - x2, s3 * inv - x3);
;         *(u32x2*)(p.pooled + (size_t)(b * L + pp) * D + c) = o;
;         const int po = pp - win + 1;
;         if (po >= 0) {
;           const float ro = rstd_s[tt + 15 - win + 1];
;           s0 -= bflo(old[k][0]) * ro; s1 -= bfhi(old[k][0]) * ro; s2 -= bflo(old[k][1]) * ro; s3 -= bfhi(old[k][1]) * ro;
;         }
;       }
.Lmy_pool_w0_nz:
	v_mov_b32_e32 v10, 0
	v_mov_b32_e32 v11, 0
	v_mov_b32_e32 v12, 0
	v_mov_b32_e32 v13, 0
	s_waitcnt vmcnt(48)
	v_and_b32_e32 v14, 0xffff0000, v88
	v_lshlrev_b32_e32 v15, 16, v88
	v_and_b32_e32 v16, 0xffff0000, v89
	v_lshlrev_b32_e32 v17, 16, v89
	v_pk_fma_f32 v[10:11], v[206:207], v[14:15], v[10:11] op_sel_hi:[0,1,1]
	v_pk_fma_f32 v[12:13], v[206:207], v[16:17], v[12:13] op_sel_hi:[0,1,1]
	s_waitcnt vmcnt(47)
	v_and_b32_e32 v14, 0xffff0000, v90
	v_lshlrev_b32_e32 v15, 16, v90
	v_and_b32_e32 v16, 0xffff0000, v91
	v_lshlrev_b32_e32 v17, 16, v91
	v_pk_mul_f32 v[18:19], v[206:207], v[14:15] op_sel:[1,0] op_sel_hi:[1,1]
	v_pk_mul_f32 v[20:21], v[206:207], v[16:17] op_sel:[1,0] op_sel_hi:[1,1]
	v_pk_fma_f32 v[10:11], v[206:207], v[14:15], v[10:11] op_sel:[1,0,0] op_sel_hi:[1,1,1]
	v_pk_fma_f32 v[12:13], v[206:207], v[16:17], v[12:13] op_sel:[1,0,0] op_sel_hi:[1,1,1]
	s_cmp_eq_u32 s9, 0
	s_cselect_b32 s0, 0x3f800000, s35
	v_fma_f32 v22, s0, v11, -v19
	v_fma_f32 v23, s0, v10, -v18
	v_fma_f32 v24, s0, v13, -v21
	v_fma_f32 v25, s0, v12, -v20
	v_cvt_pk_bf16_f32 v22, v22, v23
	v_cvt_pk_bf16_f32 v23, v24, v25
	global_store_dwordx2 v8, v[22:23], s[62:63]
	v_and_b32_e32 v14, 0xffff0000, v88
	v_lshlrev_b32_e32 v15, 16, v88
	v_and_b32_e32 v16, 0xffff0000, v89
	v_lshlrev_b32_e32 v17, 16, v89
	v_pk_fma_f32 v[10:11], v[206:207], v[14:15], v[10:11] op_sel_hi:[0,1,1] neg_lo:[1,0,0] neg_hi:[1,0,0]
	v_pk_fma_f32 v[12:13], v[206:207], v[16:17], v[12:13] op_sel_hi:[0,1,1] neg_lo:[1,0,0] neg_hi:[1,0,0]
	s_waitcnt vmcnt(47)
	v_and_b32_e32 v14, 0xffff0000, v92
	v_lshlrev_b32_e32 v15, 16, v92
	v_and_b32_e32 v16, 0xffff0000, v93
	v_lshlrev_b32_e32 v17, 16, v93
	v_pk_mul_f32 v[18:19], v[208:209], v[14:15] op_sel_hi:[0,1]
	v_pk_mul_f32 v[20:21], v[208:209], v[16:17] op_sel_hi:[0,1]
	v_pk_fma_f32 v[10:11], v[208:209], v[14:15], v[10:11] op_sel_hi:[0,1,1]
	v_pk_fma_f32 v[12:13], v[208:209], v[16:17], v[12:13] op_sel_hi:[0,1,1]
	s_mov_b32 s0, s35
	v_fma_f32 v26, s0, v11, -v19
	v_fma_f32 v27, s0, v10, -v18
	v_fma_f32 v28, s0, v13, -v21
	v_fma_f32 v29, s0, v12, -v20
	v_cvt_pk_bf16_f32 v26, v26, v27
	v_cvt_pk_bf16_f32 v27, v28, v29
	v_add_u32_e32 v31, 0x800, v8
	global_store_dwordx2 v31, v[26:27], s[62:63]
	v_and_b32_e32 v14, 0xffff0000, v90
	v_lshlrev_b32_e32 v15, 16, v90
	v_and_b32_e32 v16, 0xffff0000, v91
	v_lshlrev_b32_e32 v17, 16, v91
	v_pk_fma_f32 v[10:11], v[206:207], v[14:15], v[10:11] op_sel:[1,0,0] op_sel_hi:[1,1,1] neg_lo:[1,0,0] neg_hi:[1,0,0]
	v_pk_fma_f32 v[12:13], v[206:207], v[16:17], v[12:13] op_sel:[1,0,0] op_sel_hi:[1,1,1] neg_lo:[1,0,0] neg_hi:[1,0,0]
	s_waitcnt vmcnt(47)
	v_and_b32_e32 v14, 0xffff0000, v94
	v_lshlrev_b32_e32 v15, 16, v94
	v_and_b32_e32 v16, 0xffff0000, v95
	v_lshlrev_b32_e32 v17, 16, v95
	v_pk_mul_f32 v[18:19], v[208:209], v[14:15] op_sel:[1,0] op_sel_hi:[1,1]
	v_pk_mul_f32 v[20:21], v[208:209], v[16:17] op_sel:[1,0] op_sel_hi:[1,1]
	v_pk_fma_f32 v[10:11], v[208:209], v[14:15], v[10:11] op_sel:[1,0,0] op_sel_hi:[1,1,1]
	v_pk_fma_f32 v[12:13], v[208:209], v[16:17], v[12:13] op_sel:[1,0,0] op_sel_hi:[1,1,1]
	v_fma_f32 v22, s0, v11, -v19
	v_fma_f32 v23, s0, v10, -v18
	v_fma_f32 v24, s0, v13, -v21
	v_fma_f32 v25, s0, v12, -v20
	v_cvt_pk_bf16_f32 v22, v22, v23
	v_cvt_pk_bf16_f32 v23, v24, v25
	v_add_u32_e32 v32, 0x1000, v8
	global_store_dwordx2 v32, v[22:23], s[62:63]
	v_and_b32_e32 v14, 0xffff0000, v92
	v_lshlrev_b32_e32 v15, 16, v92
	v_and_b32_e32 v16, 0xffff0000, v93
	v_lshlrev_b32_e32 v17, 16, v93
	v_pk_fma_f32 v[10:11], v[208:209], v[14:15], v[10:11] op_sel_hi:[0,1,1] neg_lo:[1,0,0] neg_hi:[1,0,0]
	v_pk_fma_f32 v[12:13], v[208:209], v[16:17], v[12:13] op_sel_hi:[0,1,1] neg_lo:[1,0,0] neg_hi:[1,0,0]
	s_waitcnt vmcnt(47)
	v_and_b32_e32 v14, 0xffff0000, v96
	v_lshlrev_b32_e32 v15, 16, v96
	v_and_b32_e32 v16, 0xffff0000, v97
	v_lshlrev_b32_e32 v17, 16, v97
	v_pk_mul_f32 v[18:19], v[210:211], v[14:15] op_sel_hi:[0,1]
	v_pk_mul_f32 v[20:21], v[210:211], v[16:17] op_sel_hi:[0,1]
	v_pk_fma_f32 v[10:11], v[210:211], v[14:15], v[10:11] op_sel_hi:[0,1,1]
	v_pk_fma_f32 v[12:13], v[210:211], v[16:17], v[12:13] op_sel_hi:[0,1,1]
	v_fma_f32 v26, s0, v11, -v19
	v_fma_f32 v27, s0, v10, -v18
	v_fma_f32 v28, s0, v13, -v21
	v_fma_f32 v29, s0, v12, -v20
	v_cvt_pk_bf16_f32 v26, v26, v27
	v_cvt_pk_bf16_f32 v27, v28, v29
	v_add_u32_e32 v33, 0x1800, v8
	global_store_dwordx2 v33, v[26:27], s[62:63]
	v_and_b32_e32 v14, 0xffff0000, v94
	v_lshlrev_b32_e32 v15, 16, v94
	v_and_b32_e32 v16, 0xffff0000, v95
	v_lshlrev_b32_e32 v17, 16, v95
	v_pk_fma_f32 v[10:11], v[208:209], v[14:15], v[10:11] op_sel:[1,0,0] op_sel_hi:[1,1,1] neg_lo:[1,0,0] neg_hi:[1,0,0]
	v_pk_fma_f32 v[12:13], v[208:209], v[16:17], v[12:13] op_sel:[1,0,0] op_sel_hi:[1,1,1] neg_lo:[1,0,0] neg_hi:[1,0,0]
	s_waitcnt vmcnt(47)
	v_and_b32_e32 v14, 0xffff0000, v98
	v_lshlrev_b32_e32 v15, 16, v98
	v_and_b32_e32 v16, 0xffff0000, v99
	v_lshlrev_b32_e32 v17, 16, v99
	v_pk_mul_f32 v[18:19], v[210:211], v[14:15] op_sel:[1,0] op_sel_hi:[1,1]
	v_pk_mul_f32 v[20:21], v[210:211], v[16:17] op_sel:[1,0] op_sel_hi:[1,1]
	v_pk_fma_f32 v[10:11], v[210:211], v[14:15], v[10:11] op_sel:[1,0,0] op_sel_hi:[1,1,1]
	v_pk_fma_f32 v[12:13], v[210:211], v[16:17], v[12:13] op_sel:[1,0,0] op_sel_hi:[1,1,1]
	v_fma_f32 v22, s0, v11, -v19
	v_fma_f32 v23, s0, v10, -v18
	v_fma_f32 v24, s0, v13, -v21
	v_fma_f32 v25, s0, v12, -v20
	v_cvt_pk_bf16_f32 v22, v22, v23
	v_cvt_pk_bf16_f32 v23, v24, v25
	v_add_u32_e32 v34, 0x2000, v8
	global_store_dwordx2 v34, v[22:23], s[62:63]
	v_and_b32_e32 v14, 0xffff0000, v96
	v_lshlrev_b32_e32 v15, 16, v96
	v_and_b32_e32 v16, 0xffff0000, v97
	v_lshlrev_b32_e32 v17, 16, v97
	v_pk_fma_f32 v[10:11], v[210:211], v[14:15], v[10:11] op_sel_hi:[0,1,1] neg_lo:[1,0,0] neg_hi:[1,0,0]
	v_pk_fma_f32 v[12:13], v[210:211], v[16:17], v[12:13] op_sel_hi:[0,1,1] neg_lo:[1,0,0] neg_hi:[1,0,0]
	s_waitcnt vmcnt(47)
; __device__ __forceinline__ float bflo(unsigned u) { return __uint_as_float(u << 16); }
; __device__ __forceinline__ float bfhi(unsigned u) { return __uint_as_float(u & 0xffff0000u); }
; __device__ __forceinline__ void phase_pool(const Params& p, char* smraw) {
;     ...
;       for (int k = 0; k < 8; ++k) {
;         const int tt = t8 + k, pp = c0 + tt;
;         const float rs = rstd_s[tt + 15];
;         const float x0 = bflo(cur[k][0]) * rs, x1 = bfhi(cur[k][0]) * rs, x2 = bflo(cur[k][1]) * rs, x3 = bfhi(cur[k][1]) * rs;
;         s0 += x0; s1 += x1; s2 += x2; s3 += x3;
;         const int cnt = (pp + 1 < win) ? pp + 1 : win;
;         const float inv = 1.f / (float)cnt;
;         u32x2 o; o[0] = cvtpk(s0 * inv - x0, s1 * inv - x1); o[1] = cvtpk(s2 * inv - x2, s3 * inv - x3);
;         *(u32x2*)(p.pooled + (size_t)(b * L + pp) * D + c) = o;
;         const int po = pp - win + 1;
;         if (po >= 0) {
;           const float ro = rstd_s[tt + 15 - win + 1];
;           s0 -= bflo(old[k][0]) * ro; s1 -= bfhi(old[k][0]) * ro; s2 -= bflo(old[k][1]) * ro; s3 -= bfhi(old[k][1]) * ro;
;         }
;       }
	v_and_b32_e32 v14, 0xffff0000, v100
	v_lshlrev_b32_e32 v15, 16, v100
	v_and_b32_e32 v16, 0xffff0000, v101
	v_lshlrev_b32_e32 v17, 16, v101
	v_pk_mul_f32 v[18:19], v[212:213], v[14:15] op_sel_hi:[0,1]
	v_pk_mul_f32 v[20:21], v[212:213], v[16:17] op_sel_hi:[0,1]
	v_pk_fma_f32 v[10:11], v[212:213], v[14:15], v[10:11] op_sel_hi:[0,1,1]
	v_pk_fma_f32 v[12:13], v[212:213], v[16:17], v[12:13] op_sel_hi:[0,1,1]
	v_fma_f32 v26, s0, v11, -v19
	v_fma_f32 v27, s0, v10, -v18
	v_fma_f32 v28, s0, v13, -v21
	v_fma_f32 v29, s0, v12, -v20
	v_cvt_pk_bf16_f32 v26, v26, v27
	v_cvt_pk_bf16_f32 v27, v28, v29
	v_add_u32_e32 v35, 0x2800, v8
	global_store_dwordx2 v35, v[26:27], s[62:63]
	v_and_b32_e32 v14, 0xffff0000, v98
	v_lshlrev_b32_e32 v15, 16, v98
	v_and_b32_e32 v16, 0xffff0000, v99
	v_lshlrev_b32_e32 v17, 16, v99
	v_pk_fma_f32 v[10:11], v[210:211], v[14:15], v[10:11] op_sel:[1,0,0] op_sel_hi:[1,1,1] neg_lo:[1,0,0] neg_hi:[1,0,0]
	v_pk_fma_f32 v[12:13], v[210:211], v[16:17], v[12:13] op_sel:[1,0,0] op_sel_hi:[1,1,1] neg_lo:[1,0,0] neg_hi:[1,0,0]
	s_waitcnt vmcnt(47)
	v_and_b32_e32 v14, 0xffff0000, v102
	v_lshlrev_b32_e32 v15, 16, v102
	v_and_b32_e32 v16, 0xffff0000, v103
	v_lshlrev_b32_e32 v17, 16, v103
	v_pk_mul_f32 v[18:19], v[212:213], v[14:15] op_sel:[1,0] op_sel_hi:[1,1]
	v_pk_mul_f32 v[20:21], v[212:213], v[16:17] op_sel:[1,0] op_sel_hi:[1,1]
	v_pk_fma_f32 v[10:11], v[212:213], v[14:15], v[10:11] op_sel:[1,0,0] op_sel_hi:[1,1,1]
	v_pk_fma_f32 v[12:13], v[212:213], v[16:17], v[12:13] op_sel:[1,0,0] op_sel_hi:[1,1,1]
	v_fma_f32 v22, s0, v11, -v19
	v_fma_f32 v23, s0, v10, -v18
	v_fma_f32 v24, s0, v13, -v21
	v_fma_f32 v25, s0, v12, -v20
	v_cvt_pk_bf16_f32 v22, v22, v23
	v_cvt_pk_bf16_f32 v23, v24, v25
	v_add_u32_e32 v36, 0x3000, v8
	global_store_dwordx2 v36, v[22:23], s[62:63]
	v_and_b32_e32 v14, 0xffff0000, v100
	v_lshlrev_b32_e32 v15, 16, v100
	v_and_b32_e32 v16, 0xffff0000, v101
	v_lshlrev_b32_e32 v17, 16, v101
	v_pk_fma_f32 v[10:11], v[212:213], v[14:15], v[10:11] op_sel_hi:[0,1,1] neg_lo:[1,0,0] neg_hi:[1,0,0]
	v_pk_fma_f32 v[12:13], v[212:213], v[16:17], v[12:13] op_sel_hi:[0,1,1] neg_lo:[1,0,0] neg_hi:[1,0,0]
	s_waitcnt vmcnt(47)
	v_and_b32_e32 v14, 0xffff0000, v104
	v_lshlrev_b32_e32 v15, 16, v104
	v_and_b32_e32 v16, 0xffff0000, v105
	v_lshlrev_b32_e32 v17, 16, v105
	v_pk_mul_f32 v[18:19], v[214:215], v[14:15] op_sel_hi:[0,1]
	v_pk_mul_f32 v[20:21], v[214:215], v[16:17] op_sel_hi:[0,1]
	v_pk_fma_f32 v[10:11], v[214:215], v[14:15], v[10:11] op_sel_hi:[0,1,1]
	v_pk_fma_f32 v[12:13], v[214:215], v[16:17], v[12:13] op_sel_hi:[0,1,1]
	v_fma_f32 v26, s0, v11, -v19
	v_fma_f32 v27, s0, v10, -v18
	v_fma_f32 v28, s0, v13, -v21
	v_fma_f32 v29, s0, v12, -v20
	v_cvt_pk_bf16_f32 v26, v26, v27
	v_cvt_pk_bf16_f32 v27, v28, v29
	v_add_u32_e32 v37, 0x3800, v8
	global_store_dwordx2 v37, v[26:27], s[62:63]
	v_and_b32_e32 v14, 0xffff0000, v102
	v_lshlrev_b32_e32 v15, 16, v102
	v_and_b32_e32 v16, 0xffff0000, v103
	v_lshlrev_b32_e32 v17, 16, v103
	v_pk_fma_f32 v[10:11], v[212:213], v[14:15], v[10:11] op_sel:[1,0,0] op_sel_hi:[1,1,1] neg_lo:[1,0,0] neg_hi:[1,0,0]
	v_pk_fma_f32 v[12:13], v[212:213], v[16:17], v[12:13] op_sel:[1,0,0] op_sel_hi:[1,1,1] neg_lo:[1,0,0] neg_hi:[1,0,0]
	s_waitcnt vmcnt(47)
	v_and_b32_e32 v14, 0xffff0000, v106
	v_lshlrev_b32_e32 v15, 16, v106
	v_and_b32_e32 v16, 0xffff0000, v107
	v_lshlrev_b32_e32 v17, 16, v107
	v_pk_mul_f32 v[18:19], v[214:215], v[14:15] op_sel:[1,0] op_sel_hi:[1,1]
	v_pk_mul_f32 v[20:21], v[214:215], v[16:17] op_sel:[1,0] op_sel_hi:[1,1]
	v_pk_fma_f32 v[10:11], v[214:215], v[14:15], v[10:11] op_sel:[1,0,0] op_sel_hi:[1,1,1]
	v_pk_fma_f32 v[12:13], v[214:215], v[16:17], v[12:13] op_sel:[1,0,0] op_sel_hi:[1,1,1]
	v_fma_f32 v22, s0, v11, -v19
	v_fma_f32 v23, s0, v10, -v18
	v_fma_f32 v24, s0, v13, -v21
	v_fma_f32 v25, s0, v12, -v20
	v_cvt_pk_bf16_f32 v22, v22, v23
	v_cvt_pk_bf16_f32 v23, v24, v25
	v_add_u32_e32 v30, 0x4000, v8
	global_store_dwordx2 v30, v[22:23], s[62:63]
	v_and_b32_e32 v14, 0xffff0000, v104
	v_lshlrev_b32_e32 v15, 16, v104
	v_and_b32_e32 v16, 0xffff0000, v105
	v_lshlrev_b32_e32 v17, 16, v105
	v_pk_fma_f32 v[10:11], v[214:215], v[14:15], v[10:11] op_sel_hi:[0,1,1] neg_lo:[1,0,0] neg_hi:[1,0,0]
	v_pk_fma_f32 v[12:13], v[214:215], v[16:17], v[12:13] op_sel_hi:[0,1,1] neg_lo:[1,0,0] neg_hi:[1,0,0]
	s_waitcnt vmcnt(47)
	v_and_b32_e32 v14, 0xffff0000, v108
	v_lshlrev_b32_e32 v15, 16, v108
	v_and_b32_e32 v16, 0xffff0000, v109
	v_lshlrev_b32_e32 v17, 16, v109
	v_pk_mul_f32 v[18:19], v[216:217], v[14:15] op_sel_hi:[0,1]
	v_pk_mul_f32 v[20:21], v[216:217], v[16:17] op_sel_hi:[0,1]
	v_pk_fma_f32 v[10:11], v[216:217], v[14:15], v[10:11] op_sel_hi:[0,1,1]
	v_pk_fma_f32 v[12:13], v[216:217], v[16:17], v[12:13] op_sel_hi:[0,1,1]
	v_fma_f32 v26, s0, v11, -v19
	v_fma_f32 v27, s0, v10, -v18
	v_fma_f32 v28, s0, v13, -v21
	v_fma_f32 v29, s0, v12, -v20
	v_cvt_pk_bf16_f32 v26, v26, v27
	v_cvt_pk_bf16_f32 v27, v28, v29
	v_add_u32_e32 v31, 0x4800, v8
	global_store_dwordx2 v31, v[26:27], s[62:63]
	v_and_b32_e32 v14, 0xffff0000, v106
	v_lshlrev_b32_e32 v15, 16, v106
	v_and_b32_e32 v16, 0xffff0000, v107
	v_lshlrev_b32_e32 v17, 16, v107
	v_pk_fma_f32 v[10:11], v[214:215], v[14:15], v[10:11] op_sel:[1,0,0] op_sel_hi:[1,1,1] neg_lo:[1,0,0] neg_hi:[1,0,0]
	v_pk_fma_f32 v[12:13], v[214:215], v[16:17], v[12:13] op_sel:[1,0,0] op_sel_hi:[1,1,1] neg_lo:[1,0,0] neg_hi:[1,0,0]
	s_waitcnt vmcnt(47)
; __device__ __forceinline__ float bflo(unsigned u) { return __uint_as_float(u << 16); }
; __device__ __forceinline__ float bfhi(unsigned u) { return __uint_as_float(u & 0xffff0000u); }
; __device__ __forceinline__ void phase_pool(const Params& p, char* smraw) {
;     ...
;       for (int k = 0; k < 8; ++k) {
;         const int tt = t8 + k, pp = c0 + tt;
;         const float rs = rstd_s[tt + 15];
;         const float x0 = bflo(cur[k][0]) * rs, x1 = bfhi(cur[k][0]) * rs, x2 = bflo(cur[k][1]) * rs, x3 = bfhi(cur[k][1]) * rs;
;         s0 += x0; s1 += x1; s2 += x2; s3 += x3;
;         const int cnt = (pp + 1 < win) ? pp + 1 : win;
;         const float inv = 1.f / (float)cnt;
;         u32x2 o; o[0] = cvtpk(s0 * inv - x0, s1 * inv - x1); o[1] = cvtpk(s2 * inv - x2, s3 * inv - x3);
;         *(u32x2*)(p.pooled + (size_t)(b * L + pp) * D + c) = o;
;         const int po = pp - win + 1;
;         if (po >= 0) {
;           const float ro = rstd_s[tt + 15 - win + 1];
;           s0 -= bflo(old[k][0]) * ro; s1 -= bfhi(old[k][0]) * ro; s2 -= bflo(old[k][1]) * ro; s3 -= bfhi(old[k][1]) * ro;
;         }
;       }
	v_and_b32_e32 v14, 0xffff0000, v110
	v_lshlrev_b32_e32 v15, 16, v110
	v_and_b32_e32 v16, 0xffff0000, v111
	v_lshlrev_b32_e32 v17, 16, v111
	v_pk_mul_f32 v[18:19], v[216:217], v[14:15] op_sel:[1,0] op_sel_hi:[1,1]
	v_pk_mul_f32 v[20:21], v[216:217], v[16:17] op_sel:[1,0] op_sel_hi:[1,1]
	v_pk_fma_f32 v[10:11], v[216:217], v[14:15], v[10:11] op_sel:[1,0,0] op_sel_hi:[1,1,1]
	v_pk_fma_f32 v[12:13], v[216:217], v[16:17], v[12:13] op_sel:[1,0,0] op_sel_hi:[1,1,1]
	v_fma_f32 v22, s0, v11, -v19
	v_fma_f32 v23, s0, v10, -v18
	v_fma_f32 v24, s0, v13, -v21
	v_fma_f32 v25, s0, v12, -v20
	v_cvt_pk_bf16_f32 v22, v22, v23
	v_cvt_pk_bf16_f32 v23, v24, v25
	v_add_u32_e32 v32, 0x5000, v8
	global_store_dwordx2 v32, v[22:23], s[62:63]
	v_and_b32_e32 v14, 0xffff0000, v108
	v_lshlrev_b32_e32 v15, 16, v108
	v_and_b32_e32 v16, 0xffff0000, v109
	v_lshlrev_b32_e32 v17, 16, v109
	v_pk_fma_f32 v[10:11], v[216:217], v[14:15], v[10:11] op_sel_hi:[0,1,1] neg_lo:[1,0,0] neg_hi:[1,0,0]
	v_pk_fma_f32 v[12:13], v[216:217], v[16:17], v[12:13] op_sel_hi:[0,1,1] neg_lo:[1,0,0] neg_hi:[1,0,0]
	s_waitcnt vmcnt(47)
	v_and_b32_e32 v14, 0xffff0000, v112
	v_lshlrev_b32_e32 v15, 16, v112
	v_and_b32_e32 v16, 0xffff0000, v113
	v_lshlrev_b32_e32 v17, 16, v113
	v_pk_mul_f32 v[18:19], v[218:219], v[14:15] op_sel_hi:[0,1]
	v_pk_mul_f32 v[20:21], v[218:219], v[16:17] op_sel_hi:[0,1]
	v_pk_fma_f32 v[10:11], v[218:219], v[14:15], v[10:11] op_sel_hi:[0,1,1]
	v_pk_fma_f32 v[12:13], v[218:219], v[16:17], v[12:13] op_sel_hi:[0,1,1]
	v_fma_f32 v26, s0, v11, -v19
	v_fma_f32 v27, s0, v10, -v18
	v_fma_f32 v28, s0, v13, -v21
	v_fma_f32 v29, s0, v12, -v20
	v_cvt_pk_bf16_f32 v26, v26, v27
	v_cvt_pk_bf16_f32 v27, v28, v29
	v_add_u32_e32 v33, 0x5800, v8
	global_store_dwordx2 v33, v[26:27], s[62:63]
	v_and_b32_e32 v14, 0xffff0000, v110
	v_lshlrev_b32_e32 v15, 16, v110
	v_and_b32_e32 v16, 0xffff0000, v111
	v_lshlrev_b32_e32 v17, 16, v111
	v_pk_fma_f32 v[10:11], v[216:217], v[14:15], v[10:11] op_sel:[1,0,0] op_sel_hi:[1,1,1] neg_lo:[1,0,0] neg_hi:[1,0,0]
	v_pk_fma_f32 v[12:13], v[216:217], v[16:17], v[12:13] op_sel:[1,0,0] op_sel_hi:[1,1,1] neg_lo:[1,0,0] neg_hi:[1,0,0]
	s_waitcnt vmcnt(47)
	v_and_b32_e32 v14, 0xffff0000, v114
	v_lshlrev_b32_e32 v15, 16, v114
	v_and_b32_e32 v16, 0xffff0000, v115
	v_lshlrev_b32_e32 v17, 16, v115
	v_pk_mul_f32 v[18:19], v[218:219], v[14:15] op_sel:[1,0] op_sel_hi:[1,1]
	v_pk_mul_f32 v[20:21], v[218:219], v[16:17] op_sel:[1,0] op_sel_hi:[1,1]
	v_pk_fma_f32 v[10:11], v[218:219], v[14:15], v[10:11] op_sel:[1,0,0] op_sel_hi:[1,1,1]
	v_pk_fma_f32 v[12:13], v[218:219], v[16:17], v[12:13] op_sel:[1,0,0] op_sel_hi:[1,1,1]
	v_fma_f32 v22, s0, v11, -v19
	v_fma_f32 v23, s0, v10, -v18
	v_fma_f32 v24, s0, v13, -v21
	v_fma_f32 v25, s0, v12, -v20
	v_cvt_pk_bf16_f32 v22, v22, v23
	v_cvt_pk_bf16_f32 v23, v24, v25
	v_add_u32_e32 v34, 0x6000, v8
	global_store_dwordx2 v34, v[22:23], s[62:63]
	v_and_b32_e32 v14, 0xffff0000, v112
	v_lshlrev_b32_e32 v15, 16, v112
	v_and_b32_e32 v16, 0xffff0000, v113
	v_lshlrev_b32_e32 v17, 16, v113
	v_pk_fma_f32 v[10:11], v[218:219], v[14:15], v[10:11] op_sel_hi:[0,1,1] neg_lo:[1,0,0] neg_hi:[1,0,0]
	v_pk_fma_f32 v[12:13], v[218:219], v[16:17], v[12:13] op_sel_hi:[0,1,1] neg_lo:[1,0,0] neg_hi:[1,0,0]
	s_waitcnt vmcnt(47)
	v_and_b32_e32 v14, 0xffff0000, v116
	v_lshlrev_b32_e32 v15, 16, v116
	v_and_b32_e32 v16, 0xffff0000, v117
	v_lshlrev_b32_e32 v17, 16, v117
	v_pk_mul_f32 v[18:19], v[220:221], v[14:15] op_sel_hi:[0,1]
	v_pk_mul_f32 v[20:21], v[220:221], v[16:17] op_sel_hi:[0,1]
	v_pk_fma_f32 v[10:11], v[220:221], v[14:15], v[10:11] op_sel_hi:[0,1,1]
	v_pk_fma_f32 v[12:13], v[220:221], v[16:17], v[12:13] op_sel_hi:[0,1,1]
	v_fma_f32 v26, s0, v11, -v19
	v_fma_f32 v27, s0, v10, -v18
	v_fma_f32 v28, s0, v13, -v21
	v_fma_f32 v29, s0, v12, -v20
	v_cvt_pk_bf16_f32 v26, v26, v27
	v_cvt_pk_bf16_f32 v27, v28, v29
	v_add_u32_e32 v35, 0x6800, v8
	global_store_dwordx2 v35, v[26:27], s[62:63]
	v_and_b32_e32 v14, 0xffff0000, v114
	v_lshlrev_b32_e32 v15, 16, v114
	v_and_b32_e32 v16, 0xffff0000, v115
	v_lshlrev_b32_e32 v17, 16, v115
	v_pk_fma_f32 v[10:11], v[218:219], v[14:15], v[10:11] op_sel:[1,0,0] op_sel_hi:[1,1,1] neg_lo:[1,0,0] neg_hi:[1,0,0]
	v_pk_fma_f32 v[12:13], v[218:219], v[16:17], v[12:13] op_sel:[1,0,0] op_sel_hi:[1,1,1] neg_lo:[1,0,0] neg_hi:[1,0,0]
	s_waitcnt vmcnt(47)
	v_and_b32_e32 v14, 0xffff0000, v118
	v_lshlrev_b32_e32 v15, 16, v118
	v_and_b32_e32 v16, 0xffff0000, v119
	v_lshlrev_b32_e32 v17, 16, v119
	v_pk_mul_f32 v[18:19], v[220:221], v[14:15] op_sel:[1,0] op_sel_hi:[1,1]
	v_pk_mul_f32 v[20:21], v[220:221], v[16:17] op_sel:[1,0] op_sel_hi:[1,1]
	v_pk_fma_f32 v[10:11], v[220:221], v[14:15], v[10:11] op_sel:[1,0,0] op_sel_hi:[1,1,1]
	v_pk_fma_f32 v[12:13], v[220:221], v[16:17], v[12:13] op_sel:[1,0,0] op_sel_hi:[1,1,1]
	v_fma_f32 v22, s0, v11, -v19
	v_fma_f32 v23, s0, v10, -v18
	v_fma_f32 v24, s0, v13, -v21
	v_fma_f32 v25, s0, v12, -v20
	v_cvt_pk_bf16_f32 v22, v22, v23
	v_cvt_pk_bf16_f32 v23, v24, v25
	v_add_u32_e32 v36, 0x7000, v8
	global_store_dwordx2 v36, v[22:23], s[62:63]
	v_and_b32_e32 v14, 0xffff0000, v116
	v_lshlrev_b32_e32 v15, 16, v116
	v_and_b32_e32 v16, 0xffff0000, v117
	v_lshlrev_b32_e32 v17, 16, v117
	v_pk_fma_f32 v[10:11], v[220:221], v[14:15], v[10:11] op_sel_hi:[0,1,1] neg_lo:[1,0,0] neg_hi:[1,0,0]
	v_pk_fma_f32 v[12:13], v[220:221], v[16:17], v[12:13] op_sel_hi:[0,1,1] neg_lo:[1,0,0] neg_hi:[1,0,0]
	s_waitcnt vmcnt(47)
; __device__ __forceinline__ float bflo(unsigned u) { return __uint_as_float(u << 16); }
; __device__ __forceinline__ float bfhi(unsigned u) { return __uint_as_float(u & 0xffff0000u); }
; __device__ __forceinline__ void phase_pool(const Params& p, char* smraw) {
;     ...
;       for (int k = 0; k < 8; ++k) {
;         const int tt = t8 + k, pp = c0 + tt;
;         const float rs = rstd_s[tt + 15];
;         const float x0 = bflo(cur[k][0]) * rs, x1 = bfhi(cur[k][0]) * rs, x2 = bflo(cur[k][1]) * rs, x3 = bfhi(cur[k][1]) * rs;
;         s0 += x0; s1 += x1; s2 += x2; s3 += x3;
;         const int cnt = (pp + 1 < win) ? pp + 1 : win;
;         const float inv = 1.f / (float)cnt;
;         u32x2 o; o[0] = cvtpk(s0 * inv - x0, s1 * inv - x1); o[1] = cvtpk(s2 * inv - x2, s3 * inv - x3);
;         *(u32x2*)(p.pooled + (size_t)(b * L + pp) * D + c) = o;
;         const int po = pp - win + 1;
;         if (po >= 0) {
;           const float ro = rstd_s[tt + 15 - win + 1];
;           s0 -= bflo(old[k][0]) * ro; s1 -= bfhi(old[k][0]) * ro; s2 -= bflo(old[k][1]) * ro; s3 -= bfhi(old[k][1]) * ro;
;         }
;       }
	v_and_b32_e32 v14, 0xffff0000, v120
	v_lshlrev_b32_e32 v15, 16, v120
	v_and_b32_e32 v16, 0xffff0000, v121
	v_lshlrev_b32_e32 v17, 16, v121
	v_pk_mul_f32 v[18:19], v[222:223], v[14:15] op_sel_hi:[0,1]
	v_pk_mul_f32 v[20:21], v[222:223], v[16:17] op_sel_hi:[0,1]
	v_pk_fma_f32 v[10:11], v[222:223], v[14:15], v[10:11] op_sel_hi:[0,1,1]
	v_pk_fma_f32 v[12:13], v[222:223], v[16:17], v[12:13] op_sel_hi:[0,1,1]
	v_fma_f32 v26, s0, v11, -v19
	v_fma_f32 v27, s0, v10, -v18
	v_fma_f32 v28, s0, v13, -v21
	v_fma_f32 v29, s0, v12, -v20
	v_cvt_pk_bf16_f32 v26, v26, v27
	v_cvt_pk_bf16_f32 v27, v28, v29
	v_add_u32_e32 v37, 0x7800, v8
	global_store_dwordx2 v37, v[26:27], s[62:63]
	v_and_b32_e32 v14, 0xffff0000, v118
	v_lshlrev_b32_e32 v15, 16, v118
	v_and_b32_e32 v16, 0xffff0000, v119
	v_lshlrev_b32_e32 v17, 16, v119
	v_pk_fma_f32 v[10:11], v[220:221], v[14:15], v[10:11] op_sel:[1,0,0] op_sel_hi:[1,1,1] neg_lo:[1,0,0] neg_hi:[1,0,0]
	v_pk_fma_f32 v[12:13], v[220:221], v[16:17], v[12:13] op_sel:[1,0,0] op_sel_hi:[1,1,1] neg_lo:[1,0,0] neg_hi:[1,0,0]
	s_waitcnt vmcnt(47)
	v_and_b32_e32 v14, 0xffff0000, v122
	v_lshlrev_b32_e32 v15, 16, v122
	v_and_b32_e32 v16, 0xffff0000, v123
	v_lshlrev_b32_e32 v17, 16, v123
	v_pk_mul_f32 v[18:19], v[222:223], v[14:15] op_sel:[1,0] op_sel_hi:[1,1]
	v_pk_mul_f32 v[20:21], v[222:223], v[16:17] op_sel:[1,0] op_sel_hi:[1,1]
	v_pk_fma_f32 v[10:11], v[222:223], v[14:15], v[10:11] op_sel:[1,0,0] op_sel_hi:[1,1,1]
	v_pk_fma_f32 v[12:13], v[222:223], v[16:17], v[12:13] op_sel:[1,0,0] op_sel_hi:[1,1,1]
	v_fma_f32 v22, s0, v11, -v19
	v_fma_f32 v23, s0, v10, -v18
	v_fma_f32 v24, s0, v13, -v21
	v_fma_f32 v25, s0, v12, -v20
	v_cvt_pk_bf16_f32 v22, v22, v23
	v_cvt_pk_bf16_f32 v23, v24, v25
	v_add_u32_e32 v30, 0x8000, v8
	global_store_dwordx2 v30, v[22:23], s[62:63]
	v_and_b32_e32 v14, 0xffff0000, v120
	v_lshlrev_b32_e32 v15, 16, v120
	v_and_b32_e32 v16, 0xffff0000, v121
	v_lshlrev_b32_e32 v17, 16, v121
	v_pk_fma_f32 v[10:11], v[222:223], v[14:15], v[10:11] op_sel_hi:[0,1,1] neg_lo:[1,0,0] neg_hi:[1,0,0]
	v_pk_fma_f32 v[12:13], v[222:223], v[16:17], v[12:13] op_sel_hi:[0,1,1] neg_lo:[1,0,0] neg_hi:[1,0,0]
	s_waitcnt vmcnt(47)
	v_and_b32_e32 v14, 0xffff0000, v124
	v_lshlrev_b32_e32 v15, 16, v124
	v_and_b32_e32 v16, 0xffff0000, v125
	v_lshlrev_b32_e32 v17, 16, v125
	v_pk_mul_f32 v[18:19], v[224:225], v[14:15] op_sel_hi:[0,1]
	v_pk_mul_f32 v[20:21], v[224:225], v[16:17] op_sel_hi:[0,1]
	v_pk_fma_f32 v[10:11], v[224:225], v[14:15], v[10:11] op_sel_hi:[0,1,1]
	v_pk_fma_f32 v[12:13], v[224:225], v[16:17], v[12:13] op_sel_hi:[0,1,1]
	v_fma_f32 v26, s0, v11, -v19
	v_fma_f32 v27, s0, v10, -v18
	v_fma_f32 v28, s0, v13, -v21
	v_fma_f32 v29, s0, v12, -v20
	v_cvt_pk_bf16_f32 v26, v26, v27
	v_cvt_pk_bf16_f32 v27, v28, v29
	v_add_u32_e32 v31, 0x8800, v8
	global_store_dwordx2 v31, v[26:27], s[62:63]
	v_and_b32_e32 v14, 0xffff0000, v122
	v_lshlrev_b32_e32 v15, 16, v122
	v_and_b32_e32 v16, 0xffff0000, v123
	v_lshlrev_b32_e32 v17, 16, v123
	v_pk_fma_f32 v[10:11], v[222:223], v[14:15], v[10:11] op_sel:[1,0,0] op_sel_hi:[1,1,1] neg_lo:[1,0,0] neg_hi:[1,0,0]
	v_pk_fma_f32 v[12:13], v[222:223], v[16:17], v[12:13] op_sel:[1,0,0] op_sel_hi:[1,1,1] neg_lo:[1,0,0] neg_hi:[1,0,0]
	s_waitcnt vmcnt(47)
	v_and_b32_e32 v14, 0xffff0000, v126
	v_lshlrev_b32_e32 v15, 16, v126
	v_and_b32_e32 v16, 0xffff0000, v127
	v_lshlrev_b32_e32 v17, 16, v127
	v_pk_mul_f32 v[18:19], v[224:225], v[14:15] op_sel:[1,0] op_sel_hi:[1,1]
	v_pk_mul_f32 v[20:21], v[224:225], v[16:17] op_sel:[1,0] op_sel_hi:[1,1]
	v_pk_fma_f32 v[10:11], v[224:225], v[14:15], v[10:11] op_sel:[1,0,0] op_sel_hi:[1,1,1]
	v_pk_fma_f32 v[12:13], v[224:225], v[16:17], v[12:13] op_sel:[1,0,0] op_sel_hi:[1,1,1]
	v_fma_f32 v22, s0, v11, -v19
	v_fma_f32 v23, s0, v10, -v18
	v_fma_f32 v24, s0, v13, -v21
	v_fma_f32 v25, s0, v12, -v20
	v_cvt_pk_bf16_f32 v22, v22, v23
	v_cvt_pk_bf16_f32 v23, v24, v25
	v_add_u32_e32 v32, 0x9000, v8
	global_store_dwordx2 v32, v[22:23], s[62:63]
	v_and_b32_e32 v14, 0xffff0000, v124
	v_lshlrev_b32_e32 v15, 16, v124
	v_and_b32_e32 v16, 0xffff0000, v125
	v_lshlrev_b32_e32 v17, 16, v125
	v_pk_fma_f32 v[10:11], v[224:225], v[14:15], v[10:11] op_sel_hi:[0,1,1] neg_lo:[1,0,0] neg_hi:[1,0,0]
	v_pk_fma_f32 v[12:13], v[224:225], v[16:17], v[12:13] op_sel_hi:[0,1,1] neg_lo:[1,0,0] neg_hi:[1,0,0]
	s_waitcnt vmcnt(47)
	v_and_b32_e32 v14, 0xffff0000, v128
	v_lshlrev_b32_e32 v15, 16, v128
	v_and_b32_e32 v16, 0xffff0000, v129
	v_lshlrev_b32_e32 v17, 16, v129
	v_pk_mul_f32 v[18:19], v[226:227], v[14:15] op_sel_hi:[0,1]
	v_pk_mul_f32 v[20:21], v[226:227], v[16:17] op_sel_hi:[0,1]
	v_pk_fma_f32 v[10:11], v[226:227], v[14:15], v[10:11] op_sel_hi:[0,1,1]
	v_pk_fma_f32 v[12:13], v[226:227], v[16:17], v[12:13] op_sel_hi:[0,1,1]
	v_fma_f32 v26, s0, v11, -v19
	v_fma_f32 v27, s0, v10, -v18
	v_fma_f32 v28, s0, v13, -v21
	v_fma_f32 v29, s0, v12, -v20
	v_cvt_pk_bf16_f32 v26, v26, v27
	v_cvt_pk_bf16_f32 v27, v28, v29
	v_add_u32_e32 v33, 0x9800, v8
	global_store_dwordx2 v33, v[26:27], s[62:63]
	v_and_b32_e32 v14, 0xffff0000, v126
	v_lshlrev_b32_e32 v15, 16, v126
	v_and_b32_e32 v16, 0xffff0000, v127
	v_lshlrev_b32_e32 v17, 16, v127
	v_pk_fma_f32 v[10:11], v[224:225], v[14:15], v[10:11] op_sel:[1,0,0] op_sel_hi:[1,1,1] neg_lo:[1,0,0] neg_hi:[1,0,0]
	v_pk_fma_f32 v[12:13], v[224:225], v[16:17], v[12:13] op_sel:[1,0,0] op_sel_hi:[1,1,1] neg_lo:[1,0,0] neg_hi:[1,0,0]
	s_waitcnt vmcnt(47)
; __device__ __forceinline__ float bflo(unsigned u) { return __uint_as_float(u << 16); }
; __device__ __forceinline__ float bfhi(unsigned u) { return __uint_as_float(u & 0xffff0000u); }
; __device__ __forceinline__ void phase_pool(const Params& p, char* smraw) {
;     ...
;       for (int k = 0; k < 8; ++k) {
;         const int tt = t8 + k, pp = c0 + tt;
;         const float rs = rstd_s[tt + 15];
;         const float x0 = bflo(cur[k][0]) * rs, x1 = bfhi(cur[k][0]) * rs, x2 = bflo(cur[k][1]) * rs, x3 = bfhi(cur[k][1]) * rs;
;         s0 += x0; s1 += x1; s2 += x2; s3 += x3;
;         const int cnt = (pp + 1 < win) ? pp + 1 : win;
;         const float inv = 1.f / (float)cnt;
;         u32x2 o; o[0] = cvtpk(s0 * inv - x0, s1 * inv - x1); o[1] = cvtpk(s2 * inv - x2, s3 * inv - x3);
;         *(u32x2*)(p.pooled + (size_t)(b * L + pp) * D + c) = o;
;         const int po = pp - win + 1;
;         if (po >= 0) {
;           const float ro = rstd_s[tt + 15 - win + 1];
;           s0 -= bflo(old[k][0]) * ro; s1 -= bfhi(old[k][0]) * ro; s2 -= bflo(old[k][1]) * ro; s3 -= bfhi(old[k][1]) * ro;
;         }
;       }
	v_and_b32_e32 v14, 0xffff0000, v130
	v_lshlrev_b32_e32 v15, 16, v130
	v_and_b32_e32 v16, 0xffff0000, v131
	v_lshlrev_b32_e32 v17, 16, v131
	v_pk_mul_f32 v[18:19], v[226:227], v[14:15] op_sel:[1,0] op_sel_hi:[1,1]
	v_pk_mul_f32 v[20:21], v[226:227], v[16:17] op_sel:[1,0] op_sel_hi:[1,1]
	v_pk_fma_f32 v[10:11], v[226:227], v[14:15], v[10:11] op_sel:[1,0,0] op_sel_hi:[1,1,1]
	v_pk_fma_f32 v[12:13], v[226:227], v[16:17], v[12:13] op_sel:[1,0,0] op_sel_hi:[1,1,1]
	v_fma_f32 v22, s0, v11, -v19
	v_fma_f32 v23, s0, v10, -v18
	v_fma_f32 v24, s0, v13, -v21
	v_fma_f32 v25, s0, v12, -v20
	v_cvt_pk_bf16_f32 v22, v22, v23
	v_cvt_pk_bf16_f32 v23, v24, v25
	v_add_u32_e32 v34, 0xa000, v8
	global_store_dwordx2 v34, v[22:23], s[62:63]
	v_and_b32_e32 v14, 0xffff0000, v128
	v_lshlrev_b32_e32 v15, 16, v128
	v_and_b32_e32 v16, 0xffff0000, v129
	v_lshlrev_b32_e32 v17, 16, v129
	v_pk_fma_f32 v[10:11], v[226:227], v[14:15], v[10:11] op_sel_hi:[0,1,1] neg_lo:[1,0,0] neg_hi:[1,0,0]
	v_pk_fma_f32 v[12:13], v[226:227], v[16:17], v[12:13] op_sel_hi:[0,1,1] neg_lo:[1,0,0] neg_hi:[1,0,0]
	s_waitcnt vmcnt(47)
	v_and_b32_e32 v14, 0xffff0000, v132
	v_lshlrev_b32_e32 v15, 16, v132
	v_and_b32_e32 v16, 0xffff0000, v133
	v_lshlrev_b32_e32 v17, 16, v133
	v_pk_mul_f32 v[18:19], v[228:229], v[14:15] op_sel_hi:[0,1]
	v_pk_mul_f32 v[20:21], v[228:229], v[16:17] op_sel_hi:[0,1]
	v_pk_fma_f32 v[10:11], v[228:229], v[14:15], v[10:11] op_sel_hi:[0,1,1]
	v_pk_fma_f32 v[12:13], v[228:229], v[16:17], v[12:13] op_sel_hi:[0,1,1]
	v_fma_f32 v26, s0, v11, -v19
	v_fma_f32 v27, s0, v10, -v18
	v_fma_f32 v28, s0, v13, -v21
	v_fma_f32 v29, s0, v12, -v20
	v_cvt_pk_bf16_f32 v26, v26, v27
	v_cvt_pk_bf16_f32 v27, v28, v29
	v_add_u32_e32 v35, 0xa800, v8
	global_store_dwordx2 v35, v[26:27], s[62:63]
	v_and_b32_e32 v14, 0xffff0000, v130
	v_lshlrev_b32_e32 v15, 16, v130
	v_and_b32_e32 v16, 0xffff0000, v131
	v_lshlrev_b32_e32 v17, 16, v131
	v_pk_fma_f32 v[10:11], v[226:227], v[14:15], v[10:11] op_sel:[1,0,0] op_sel_hi:[1,1,1] neg_lo:[1,0,0] neg_hi:[1,0,0]
	v_pk_fma_f32 v[12:13], v[226:227], v[16:17], v[12:13] op_sel:[1,0,0] op_sel_hi:[1,1,1] neg_lo:[1,0,0] neg_hi:[1,0,0]
	s_waitcnt vmcnt(47)
	v_and_b32_e32 v14, 0xffff0000, v134
	v_lshlrev_b32_e32 v15, 16, v134
	v_and_b32_e32 v16, 0xffff0000, v135
	v_lshlrev_b32_e32 v17, 16, v135
	v_pk_mul_f32 v[18:19], v[228:229], v[14:15] op_sel:[1,0] op_sel_hi:[1,1]
	v_pk_mul_f32 v[20:21], v[228:229], v[16:17] op_sel:[1,0] op_sel_hi:[1,1]
	v_pk_fma_f32 v[10:11], v[228:229], v[14:15], v[10:11] op_sel:[1,0,0] op_sel_hi:[1,1,1]
	v_pk_fma_f32 v[12:13], v[228:229], v[16:17], v[12:13] op_sel:[1,0,0] op_sel_hi:[1,1,1]
	v_fma_f32 v22, s0, v11, -v19
	v_fma_f32 v23, s0, v10, -v18
	v_fma_f32 v24, s0, v13, -v21
	v_fma_f32 v25, s0, v12, -v20
	v_cvt_pk_bf16_f32 v22, v22, v23
	v_cvt_pk_bf16_f32 v23, v24, v25
	v_add_u32_e32 v36, 0xb000, v8
	global_store_dwordx2 v36, v[22:23], s[62:63]
	v_and_b32_e32 v14, 0xffff0000, v132
	v_lshlrev_b32_e32 v15, 16, v132
	v_and_b32_e32 v16, 0xffff0000, v133
	v_lshlrev_b32_e32 v17, 16, v133
	v_pk_fma_f32 v[10:11], v[228:229], v[14:15], v[10:11] op_sel_hi:[0,1,1] neg_lo:[1,0,0] neg_hi:[1,0,0]
	v_pk_fma_f32 v[12:13], v[228:229], v[16:17], v[12:13] op_sel_hi:[0,1,1] neg_lo:[1,0,0] neg_hi:[1,0,0]
	s_waitcnt vmcnt(47)
	v_and_b32_e32 v14, 0xffff0000, v136
	v_lshlrev_b32_e32 v15, 16, v136
	v_and_b32_e32 v16, 0xffff0000, v137
	v_lshlrev_b32_e32 v17, 16, v137
	v_pk_mul_f32 v[18:19], v[230:231], v[14:15] op_sel_hi:[0,1]
	v_pk_mul_f32 v[20:21], v[230:231], v[16:17] op_sel_hi:[0,1]
	v_pk_fma_f32 v[10:11], v[230:231], v[14:15], v[10:11] op_sel_hi:[0,1,1]
	v_pk_fma_f32 v[12:13], v[230:231], v[16:17], v[12:13] op_sel_hi:[0,1,1]
	v_fma_f32 v26, s0, v11, -v19
	v_fma_f32 v27, s0, v10, -v18
	v_fma_f32 v28, s0, v13, -v21
	v_fma_f32 v29, s0, v12, -v20
	v_cvt_pk_bf16_f32 v26, v26, v27
	v_cvt_pk_bf16_f32 v27, v28, v29
	v_add_u32_e32 v37, 0xb800, v8
	global_store_dwordx2 v37, v[26:27], s[62:63]
	v_and_b32_e32 v14, 0xffff0000, v134
	v_lshlrev_b32_e32 v15, 16, v134
	v_and_b32_e32 v16, 0xffff0000, v135
	v_lshlrev_b32_e32 v17, 16, v135
	v_pk_fma_f32 v[10:11], v[228:229], v[14:15], v[10:11] op_sel:[1,0,0] op_sel_hi:[1,1,1] neg_lo:[1,0,0] neg_hi:[1,0,0]
	v_pk_fma_f32 v[12:13], v[228:229], v[16:17], v[12:13] op_sel:[1,0,0] op_sel_hi:[1,1,1] neg_lo:[1,0,0] neg_hi:[1,0,0]
	s_waitcnt vmcnt(47)
	v_and_b32_e32 v14, 0xffff0000, v138
	v_lshlrev_b32_e32 v15, 16, v138
	v_and_b32_e32 v16, 0xffff0000, v139
	v_lshlrev_b32_e32 v17, 16, v139
	v_pk_mul_f32 v[18:19], v[230:231], v[14:15] op_sel:[1,0] op_sel_hi:[1,1]
	v_pk_mul_f32 v[20:21], v[230:231], v[16:17] op_sel:[1,0] op_sel_hi:[1,1]
	v_pk_fma_f32 v[10:11], v[230:231], v[14:15], v[10:11] op_sel:[1,0,0] op_sel_hi:[1,1,1]
	v_pk_fma_f32 v[12:13], v[230:231], v[16:17], v[12:13] op_sel:[1,0,0] op_sel_hi:[1,1,1]
	v_fma_f32 v22, s0, v11, -v19
	v_fma_f32 v23, s0, v10, -v18
	v_fma_f32 v24, s0, v13, -v21
	v_fma_f32 v25, s0, v12, -v20
	v_cvt_pk_bf16_f32 v22, v22, v23
	v_cvt_pk_bf16_f32 v23, v24, v25
	v_add_u32_e32 v30, 0xc000, v8
	global_store_dwordx2 v30, v[22:23], s[62:63]
	v_and_b32_e32 v14, 0xffff0000, v136
	v_lshlrev_b32_e32 v15, 16, v136
	v_and_b32_e32 v16, 0xffff0000, v137
	v_lshlrev_b32_e32 v17, 16, v137
	v_pk_fma_f32 v[10:11], v[230:231], v[14:15], v[10:11] op_sel_hi:[0,1,1] neg_lo:[1,0,0] neg_hi:[1,0,0]
	v_pk_fma_f32 v[12:13], v[230:231], v[16:17], v[12:13] op_sel_hi:[0,1,1] neg_lo:[1,0,0] neg_hi:[1,0,0]
	s_waitcnt vmcnt(47)
; __device__ __forceinline__ float bflo(unsigned u) { return __uint_as_float(u << 16); }
; __device__ __forceinline__ float bfhi(unsigned u) { return __uint_as_float(u & 0xffff0000u); }
; __device__ __forceinline__ void phase_pool(const Params& p, char* smraw) {
;     ...
;       for (int k = 0; k < 8; ++k) {
;         const int tt = t8 + k, pp = c0 + tt;
;         const float rs = rstd_s[tt + 15];
;         const float x0 = bflo(cur[k][0]) * rs, x1 = bfhi(cur[k][0]) * rs, x2 = bflo(cur[k][1]) * rs, x3 = bfhi(cur[k][1]) * rs;
;         s0 += x0; s1 += x1; s2 += x2; s3 += x3;
;         const int cnt = (pp + 1 < win) ? pp + 1 : win;
;         const float inv = 1.f / (float)cnt;
;         u32x2 o; o[0] = cvtpk(s0 * inv - x0, s1 * inv - x1); o[1] = cvtpk(s2 * inv - x2, s3 * inv - x3);
;         *(u32x2*)(p.pooled + (size_t)(b * L + pp) * D + c) = o;
;         const int po = pp - win + 1;
;         if (po >= 0) {
;           const float ro = rstd_s[tt + 15 - win + 1];
;           s0 -= bflo(old[k][0]) * ro; s1 -= bfhi(old[k][0]) * ro; s2 -= bflo(old[k][1]) * ro; s3 -= bfhi(old[k][1]) * ro;
;         }
;       }
	v_and_b32_e32 v14, 0xffff0000, v140
	v_lshlrev_b32_e32 v15, 16, v140
	v_and_b32_e32 v16, 0xffff0000, v141
	v_lshlrev_b32_e32 v17, 16, v141
	v_pk_mul_f32 v[18:19], v[232:233], v[14:15] op_sel_hi:[0,1]
	v_pk_mul_f32 v[20:21], v[232:233], v[16:17] op_sel_hi:[0,1]
	v_pk_fma_f32 v[10:11], v[232:233], v[14:15], v[10:11] op_sel_hi:[0,1,1]
	v_pk_fma_f32 v[12:13], v[232:233], v[16:17], v[12:13] op_sel_hi:[0,1,1]
	v_fma_f32 v26, s0, v11, -v19
	v_fma_f32 v27, s0, v10, -v18
	v_fma_f32 v28, s0, v13, -v21
	v_fma_f32 v29, s0, v12, -v20
	v_cvt_pk_bf16_f32 v26, v26, v27
	v_cvt_pk_bf16_f32 v27, v28, v29
	v_add_u32_e32 v31, 0xc800, v8
	global_store_dwordx2 v31, v[26:27], s[62:63]
	v_and_b32_e32 v14, 0xffff0000, v138
	v_lshlrev_b32_e32 v15, 16, v138
	v_and_b32_e32 v16, 0xffff0000, v139
	v_lshlrev_b32_e32 v17, 16, v139
	v_pk_fma_f32 v[10:11], v[230:231], v[14:15], v[10:11] op_sel:[1,0,0] op_sel_hi:[1,1,1] neg_lo:[1,0,0] neg_hi:[1,0,0]
	v_pk_fma_f32 v[12:13], v[230:231], v[16:17], v[12:13] op_sel:[1,0,0] op_sel_hi:[1,1,1] neg_lo:[1,0,0] neg_hi:[1,0,0]
	s_waitcnt vmcnt(47)
	v_and_b32_e32 v14, 0xffff0000, v142
	v_lshlrev_b32_e32 v15, 16, v142
	v_and_b32_e32 v16, 0xffff0000, v143
	v_lshlrev_b32_e32 v17, 16, v143
	v_pk_mul_f32 v[18:19], v[232:233], v[14:15] op_sel:[1,0] op_sel_hi:[1,1]
	v_pk_mul_f32 v[20:21], v[232:233], v[16:17] op_sel:[1,0] op_sel_hi:[1,1]
	v_pk_fma_f32 v[10:11], v[232:233], v[14:15], v[10:11] op_sel:[1,0,0] op_sel_hi:[1,1,1]
	v_pk_fma_f32 v[12:13], v[232:233], v[16:17], v[12:13] op_sel:[1,0,0] op_sel_hi:[1,1,1]
	v_fma_f32 v22, s0, v11, -v19
	v_fma_f32 v23, s0, v10, -v18
	v_fma_f32 v24, s0, v13, -v21
	v_fma_f32 v25, s0, v12, -v20
	v_cvt_pk_bf16_f32 v22, v22, v23
	v_cvt_pk_bf16_f32 v23, v24, v25
	v_add_u32_e32 v32, 0xd000, v8
	global_store_dwordx2 v32, v[22:23], s[62:63]
	v_and_b32_e32 v14, 0xffff0000, v140
	v_lshlrev_b32_e32 v15, 16, v140
	v_and_b32_e32 v16, 0xffff0000, v141
	v_lshlrev_b32_e32 v17, 16, v141
	v_pk_fma_f32 v[10:11], v[232:233], v[14:15], v[10:11] op_sel_hi:[0,1,1] neg_lo:[1,0,0] neg_hi:[1,0,0]
	v_pk_fma_f32 v[12:13], v[232:233], v[16:17], v[12:13] op_sel_hi:[0,1,1] neg_lo:[1,0,0] neg_hi:[1,0,0]
	s_waitcnt vmcnt(47)
	v_and_b32_e32 v14, 0xffff0000, v144
	v_lshlrev_b32_e32 v15, 16, v144
	v_and_b32_e32 v16, 0xffff0000, v145
	v_lshlrev_b32_e32 v17, 16, v145
	v_pk_mul_f32 v[18:19], v[234:235], v[14:15] op_sel_hi:[0,1]
	v_pk_mul_f32 v[20:21], v[234:235], v[16:17] op_sel_hi:[0,1]
	v_pk_fma_f32 v[10:11], v[234:235], v[14:15], v[10:11] op_sel_hi:[0,1,1]
	v_pk_fma_f32 v[12:13], v[234:235], v[16:17], v[12:13] op_sel_hi:[0,1,1]
	v_fma_f32 v26, s0, v11, -v19
	v_fma_f32 v27, s0, v10, -v18
	v_fma_f32 v28, s0, v13, -v21
	v_fma_f32 v29, s0, v12, -v20
	v_cvt_pk_bf16_f32 v26, v26, v27
	v_cvt_pk_bf16_f32 v27, v28, v29
	v_add_u32_e32 v33, 0xd800, v8
	global_store_dwordx2 v33, v[26:27], s[62:63]
	v_and_b32_e32 v14, 0xffff0000, v142
	v_lshlrev_b32_e32 v15, 16, v142
	v_and_b32_e32 v16, 0xffff0000, v143
	v_lshlrev_b32_e32 v17, 16, v143
	v_pk_fma_f32 v[10:11], v[232:233], v[14:15], v[10:11] op_sel:[1,0,0] op_sel_hi:[1,1,1] neg_lo:[1,0,0] neg_hi:[1,0,0]
	v_pk_fma_f32 v[12:13], v[232:233], v[16:17], v[12:13] op_sel:[1,0,0] op_sel_hi:[1,1,1] neg_lo:[1,0,0] neg_hi:[1,0,0]
	s_waitcnt vmcnt(47)
	v_and_b32_e32 v14, 0xffff0000, v146
	v_lshlrev_b32_e32 v15, 16, v146
	v_and_b32_e32 v16, 0xffff0000, v147
	v_lshlrev_b32_e32 v17, 16, v147
	v_pk_mul_f32 v[18:19], v[234:235], v[14:15] op_sel:[1,0] op_sel_hi:[1,1]
	v_pk_mul_f32 v[20:21], v[234:235], v[16:17] op_sel:[1,0] op_sel_hi:[1,1]
	v_pk_fma_f32 v[10:11], v[234:235], v[14:15], v[10:11] op_sel:[1,0,0] op_sel_hi:[1,1,1]
	v_pk_fma_f32 v[12:13], v[234:235], v[16:17], v[12:13] op_sel:[1,0,0] op_sel_hi:[1,1,1]
	v_fma_f32 v22, s0, v11, -v19
	v_fma_f32 v23, s0, v10, -v18
	v_fma_f32 v24, s0, v13, -v21
	v_fma_f32 v25, s0, v12, -v20
	v_cvt_pk_bf16_f32 v22, v22, v23
	v_cvt_pk_bf16_f32 v23, v24, v25
	v_add_u32_e32 v34, 0xe000, v8
	global_store_dwordx2 v34, v[22:23], s[62:63]
	v_and_b32_e32 v14, 0xffff0000, v144
	v_lshlrev_b32_e32 v15, 16, v144
	v_and_b32_e32 v16, 0xffff0000, v145
	v_lshlrev_b32_e32 v17, 16, v145
	v_pk_fma_f32 v[10:11], v[234:235], v[14:15], v[10:11] op_sel_hi:[0,1,1] neg_lo:[1,0,0] neg_hi:[1,0,0]
	v_pk_fma_f32 v[12:13], v[234:235], v[16:17], v[12:13] op_sel_hi:[0,1,1] neg_lo:[1,0,0] neg_hi:[1,0,0]
	s_waitcnt vmcnt(47)
	v_and_b32_e32 v14, 0xffff0000, v148
	v_lshlrev_b32_e32 v15, 16, v148
	v_and_b32_e32 v16, 0xffff0000, v149
	v_lshlrev_b32_e32 v17, 16, v149
	v_pk_mul_f32 v[18:19], v[236:237], v[14:15] op_sel_hi:[0,1]
	v_pk_mul_f32 v[20:21], v[236:237], v[16:17] op_sel_hi:[0,1]
	v_pk_fma_f32 v[10:11], v[236:237], v[14:15], v[10:11] op_sel_hi:[0,1,1]
	v_pk_fma_f32 v[12:13], v[236:237], v[16:17], v[12:13] op_sel_hi:[0,1,1]
	v_fma_f32 v26, s0, v11, -v19
	v_fma_f32 v27, s0, v10, -v18
	v_fma_f32 v28, s0, v13, -v21
	v_fma_f32 v29, s0, v12, -v20
	v_cvt_pk_bf16_f32 v26, v26, v27
	v_cvt_pk_bf16_f32 v27, v28, v29
	v_add_u32_e32 v35, 0xe800, v8
	global_store_dwordx2 v35, v[26:27], s[62:63]
	v_and_b32_e32 v14, 0xffff0000, v146
	v_lshlrev_b32_e32 v15, 16, v146
	v_and_b32_e32 v16, 0xffff0000, v147
	v_lshlrev_b32_e32 v17, 16, v147
	v_pk_fma_f32 v[10:11], v[234:235], v[14:15], v[10:11] op_sel:[1,0,0] op_sel_hi:[1,1,1] neg_lo:[1,0,0] neg_hi:[1,0,0]
	v_pk_fma_f32 v[12:13], v[234:235], v[16:17], v[12:13] op_sel:[1,0,0] op_sel_hi:[1,1,1] neg_lo:[1,0,0] neg_hi:[1,0,0]
	s_waitcnt vmcnt(47)
; __device__ __forceinline__ float bflo(unsigned u) { return __uint_as_float(u << 16); }
; __device__ __forceinline__ float bfhi(unsigned u) { return __uint_as_float(u & 0xffff0000u); }
; __device__ __forceinline__ void phase_pool(const Params& p, char* smraw) {
;     ...
;       for (int k = 0; k < 8; ++k) {
;         const int tt = t8 + k, pp = c0 + tt;
;         const float rs = rstd_s[tt + 15];
;         const float x0 = bflo(cur[k][0]) * rs, x1 = bfhi(cur[k][0]) * rs, x2 = bflo(cur[k][1]) * rs, x3 = bfhi(cur[k][1]) * rs;
;         s0 += x0; s1 += x1; s2 += x2; s3 += x3;
;         const int cnt = (pp + 1 < win) ? pp + 1 : win;
;         const float inv = 1.f / (float)cnt;
;         u32x2 o; o[0] = cvtpk(s0 * inv - x0, s1 * inv - x1); o[1] = cvtpk(s2 * inv - x2, s3 * inv - x3);
;         *(u32x2*)(p.pooled + (size_t)(b * L + pp) * D + c) = o;
;         const int po = pp - win + 1;
;         if (po >= 0) {
;           const float ro = rstd_s[tt + 15 - win + 1];
;           s0 -= bflo(old[k][0]) * ro; s1 -= bfhi(old[k][0]) * ro; s2 -= bflo(old[k][1]) * ro; s3 -= bfhi(old[k][1]) * ro;
;         }
;       }
	v_and_b32_e32 v14, 0xffff0000, v150
	v_lshlrev_b32_e32 v15, 16, v150
	v_and_b32_e32 v16, 0xffff0000, v151
	v_lshlrev_b32_e32 v17, 16, v151
	v_pk_mul_f32 v[18:19], v[236:237], v[14:15] op_sel:[1,0] op_sel_hi:[1,1]
	v_pk_mul_f32 v[20:21], v[236:237], v[16:17] op_sel:[1,0] op_sel_hi:[1,1]
	v_pk_fma_f32 v[10:11], v[236:237], v[14:15], v[10:11] op_sel:[1,0,0] op_sel_hi:[1,1,1]
	v_pk_fma_f32 v[12:13], v[236:237], v[16:17], v[12:13] op_sel:[1,0,0] op_sel_hi:[1,1,1]
	v_fma_f32 v22, s0, v11, -v19
	v_fma_f32 v23, s0, v10, -v18
	v_fma_f32 v24, s0, v13, -v21
	v_fma_f32 v25, s0, v12, -v20
	v_cvt_pk_bf16_f32 v22, v22, v23
	v_cvt_pk_bf16_f32 v23, v24, v25
	v_add_u32_e32 v36, 0xf000, v8
	global_store_dwordx2 v36, v[22:23], s[62:63]
	v_and_b32_e32 v14, 0xffff0000, v148
	v_lshlrev_b32_e32 v15, 16, v148
	v_and_b32_e32 v16, 0xffff0000, v149
	v_lshlrev_b32_e32 v17, 16, v149
	v_pk_fma_f32 v[10:11], v[236:237], v[14:15], v[10:11] op_sel_hi:[0,1,1] neg_lo:[1,0,0] neg_hi:[1,0,0]
	v_pk_fma_f32 v[12:13], v[236:237], v[16:17], v[12:13] op_sel_hi:[0,1,1] neg_lo:[1,0,0] neg_hi:[1,0,0]
	s_waitcnt vmcnt(47)
	v_and_b32_e32 v14, 0xffff0000, v152
	v_lshlrev_b32_e32 v15, 16, v152
	v_and_b32_e32 v16, 0xffff0000, v153
	v_lshlrev_b32_e32 v17, 16, v153
	v_pk_mul_f32 v[18:19], v[238:239], v[14:15] op_sel_hi:[0,1]
	v_pk_mul_f32 v[20:21], v[238:239], v[16:17] op_sel_hi:[0,1]
	v_pk_fma_f32 v[10:11], v[238:239], v[14:15], v[10:11] op_sel_hi:[0,1,1]
	v_pk_fma_f32 v[12:13], v[238:239], v[16:17], v[12:13] op_sel_hi:[0,1,1]
	v_fma_f32 v26, s0, v11, -v19
	v_fma_f32 v27, s0, v10, -v18
	v_fma_f32 v28, s0, v13, -v21
	v_fma_f32 v29, s0, v12, -v20
	v_cvt_pk_bf16_f32 v26, v26, v27
	v_cvt_pk_bf16_f32 v27, v28, v29
	v_add_u32_e32 v37, 0xf800, v8
	global_store_dwordx2 v37, v[26:27], s[62:63]
	v_and_b32_e32 v14, 0xffff0000, v150
	v_lshlrev_b32_e32 v15, 16, v150
	v_and_b32_e32 v16, 0xffff0000, v151
	v_lshlrev_b32_e32 v17, 16, v151
	v_pk_fma_f32 v[10:11], v[236:237], v[14:15], v[10:11] op_sel:[1,0,0] op_sel_hi:[1,1,1] neg_lo:[1,0,0] neg_hi:[1,0,0]
	v_pk_fma_f32 v[12:13], v[236:237], v[16:17], v[12:13] op_sel:[1,0,0] op_sel_hi:[1,1,1] neg_lo:[1,0,0] neg_hi:[1,0,0]
	s_waitcnt vmcnt(47)
	v_and_b32_e32 v14, 0xffff0000, v154
	v_lshlrev_b32_e32 v15, 16, v154
	v_and_b32_e32 v16, 0xffff0000, v155
	v_lshlrev_b32_e32 v17, 16, v155
	v_pk_mul_f32 v[18:19], v[238:239], v[14:15] op_sel:[1,0] op_sel_hi:[1,1]
	v_pk_mul_f32 v[20:21], v[238:239], v[16:17] op_sel:[1,0] op_sel_hi:[1,1]
	v_pk_fma_f32 v[10:11], v[238:239], v[14:15], v[10:11] op_sel:[1,0,0] op_sel_hi:[1,1,1]
	v_pk_fma_f32 v[12:13], v[238:239], v[16:17], v[12:13] op_sel:[1,0,0] op_sel_hi:[1,1,1]
	v_fma_f32 v22, s0, v11, -v19
	v_fma_f32 v23, s0, v10, -v18
	v_fma_f32 v24, s0, v13, -v21
	v_fma_f32 v25, s0, v12, -v20
	v_cvt_pk_bf16_f32 v22, v22, v23
	v_cvt_pk_bf16_f32 v23, v24, v25
	v_add_u32_e32 v30, 0x10000, v8
	global_store_dwordx2 v30, v[22:23], s[62:63]
	v_and_b32_e32 v14, 0xffff0000, v152
	v_lshlrev_b32_e32 v15, 16, v152
	v_and_b32_e32 v16, 0xffff0000, v153
	v_lshlrev_b32_e32 v17, 16, v153
	v_pk_fma_f32 v[10:11], v[238:239], v[14:15], v[10:11] op_sel_hi:[0,1,1] neg_lo:[1,0,0] neg_hi:[1,0,0]
	v_pk_fma_f32 v[12:13], v[238:239], v[16:17], v[12:13] op_sel_hi:[0,1,1] neg_lo:[1,0,0] neg_hi:[1,0,0]
	s_waitcnt vmcnt(47)
	v_and_b32_e32 v14, 0xffff0000, v156
	v_lshlrev_b32_e32 v15, 16, v156
	v_and_b32_e32 v16, 0xffff0000, v157
	v_lshlrev_b32_e32 v17, 16, v157
	v_pk_mul_f32 v[18:19], v[240:241], v[14:15] op_sel_hi:[0,1]
	v_pk_mul_f32 v[20:21], v[240:241], v[16:17] op_sel_hi:[0,1]
	v_pk_fma_f32 v[10:11], v[240:241], v[14:15], v[10:11] op_sel_hi:[0,1,1]
	v_pk_fma_f32 v[12:13], v[240:241], v[16:17], v[12:13] op_sel_hi:[0,1,1]
	v_fma_f32 v26, s0, v11, -v19
	v_fma_f32 v27, s0, v10, -v18
	v_fma_f32 v28, s0, v13, -v21
	v_fma_f32 v29, s0, v12, -v20
	v_cvt_pk_bf16_f32 v26, v26, v27
	v_cvt_pk_bf16_f32 v27, v28, v29
	v_add_u32_e32 v31, 0x10800, v8
	global_store_dwordx2 v31, v[26:27], s[62:63]
	v_and_b32_e32 v14, 0xffff0000, v154
	v_lshlrev_b32_e32 v15, 16, v154
	v_and_b32_e32 v16, 0xffff0000, v155
	v_lshlrev_b32_e32 v17, 16, v155
	v_pk_fma_f32 v[10:11], v[238:239], v[14:15], v[10:11] op_sel:[1,0,0] op_sel_hi:[1,1,1] neg_lo:[1,0,0] neg_hi:[1,0,0]
	v_pk_fma_f32 v[12:13], v[238:239], v[16:17], v[12:13] op_sel:[1,0,0] op_sel_hi:[1,1,1] neg_lo:[1,0,0] neg_hi:[1,0,0]
	s_waitcnt vmcnt(47)
	v_and_b32_e32 v14, 0xffff0000, v158
	v_lshlrev_b32_e32 v15, 16, v158
	v_and_b32_e32 v16, 0xffff0000, v159
	v_lshlrev_b32_e32 v17, 16, v159
	v_pk_mul_f32 v[18:19], v[240:241], v[14:15] op_sel:[1,0] op_sel_hi:[1,1]
	v_pk_mul_f32 v[20:21], v[240:241], v[16:17] op_sel:[1,0] op_sel_hi:[1,1]
	v_pk_fma_f32 v[10:11], v[240:241], v[14:15], v[10:11] op_sel:[1,0,0] op_sel_hi:[1,1,1]
	v_pk_fma_f32 v[12:13], v[240:241], v[16:17], v[12:13] op_sel:[1,0,0] op_sel_hi:[1,1,1]
	v_fma_f32 v22, s0, v11, -v19
	v_fma_f32 v23, s0, v10, -v18
	v_fma_f32 v24, s0, v13, -v21
	v_fma_f32 v25, s0, v12, -v20
	v_cvt_pk_bf16_f32 v22, v22, v23
	v_cvt_pk_bf16_f32 v23, v24, v25
	v_add_u32_e32 v32, 0x11000, v8
	global_store_dwordx2 v32, v[22:23], s[62:63]
	v_and_b32_e32 v14, 0xffff0000, v156
	v_lshlrev_b32_e32 v15, 16, v156
	v_and_b32_e32 v16, 0xffff0000, v157
	v_lshlrev_b32_e32 v17, 16, v157
	v_pk_fma_f32 v[10:11], v[240:241], v[14:15], v[10:11] op_sel_hi:[0,1,1] neg_lo:[1,0,0] neg_hi:[1,0,0]
	v_pk_fma_f32 v[12:13], v[240:241], v[16:17], v[12:13] op_sel_hi:[0,1,1] neg_lo:[1,0,0] neg_hi:[1,0,0]
	s_waitcnt vmcnt(47)
; __device__ __forceinline__ float bflo(unsigned u) { return __uint_as_float(u << 16); }
; __device__ __forceinline__ float bfhi(unsigned u) { return __uint_as_float(u & 0xffff0000u); }
; __device__ __forceinline__ void phase_pool(const Params& p, char* smraw) {
;     ...
;       for (int k = 0; k < 8; ++k) {
;         const int tt = t8 + k, pp = c0 + tt;
;         const float rs = rstd_s[tt + 15];
;         const float x0 = bflo(cur[k][0]) * rs, x1 = bfhi(cur[k][0]) * rs, x2 = bflo(cur[k][1]) * rs, x3 = bfhi(cur[k][1]) * rs;
;         s0 += x0; s1 += x1; s2 += x2; s3 += x3;
;         const int cnt = (pp + 1 < win) ? pp + 1 : win;
;         const float inv = 1.f / (float)cnt;
;         u32x2 o; o[0] = cvtpk(s0 * inv - x0, s1 * inv - x1); o[1] = cvtpk(s2 * inv - x2, s3 * inv - x3);
;         *(u32x2*)(p.pooled + (size_t)(b * L + pp) * D + c) = o;
;         const int po = pp - win + 1;
;         if (po >= 0) {
;           const float ro = rstd_s[tt + 15 - win + 1];
;           s0 -= bflo(old[k][0]) * ro; s1 -= bfhi(old[k][0]) * ro; s2 -= bflo(old[k][1]) * ro; s3 -= bfhi(old[k][1]) * ro;
;         }
;       }
	v_and_b32_e32 v14, 0xffff0000, v160
	v_lshlrev_b32_e32 v15, 16, v160
	v_and_b32_e32 v16, 0xffff0000, v161
	v_lshlrev_b32_e32 v17, 16, v161
	v_pk_mul_f32 v[18:19], v[242:243], v[14:15] op_sel_hi:[0,1]
	v_pk_mul_f32 v[20:21], v[242:243], v[16:17] op_sel_hi:[0,1]
	v_pk_fma_f32 v[10:11], v[242:243], v[14:15], v[10:11] op_sel_hi:[0,1,1]
	v_pk_fma_f32 v[12:13], v[242:243], v[16:17], v[12:13] op_sel_hi:[0,1,1]
	v_fma_f32 v26, s0, v11, -v19
	v_fma_f32 v27, s0, v10, -v18
	v_fma_f32 v28, s0, v13, -v21
	v_fma_f32 v29, s0, v12, -v20
	v_cvt_pk_bf16_f32 v26, v26, v27
	v_cvt_pk_bf16_f32 v27, v28, v29
	v_add_u32_e32 v33, 0x11800, v8
	global_store_dwordx2 v33, v[26:27], s[62:63]
	v_and_b32_e32 v14, 0xffff0000, v158
	v_lshlrev_b32_e32 v15, 16, v158
	v_and_b32_e32 v16, 0xffff0000, v159
	v_lshlrev_b32_e32 v17, 16, v159
	v_pk_fma_f32 v[10:11], v[240:241], v[14:15], v[10:11] op_sel:[1,0,0] op_sel_hi:[1,1,1] neg_lo:[1,0,0] neg_hi:[1,0,0]
	v_pk_fma_f32 v[12:13], v[240:241], v[16:17], v[12:13] op_sel:[1,0,0] op_sel_hi:[1,1,1] neg_lo:[1,0,0] neg_hi:[1,0,0]
	s_waitcnt vmcnt(47)
	v_and_b32_e32 v14, 0xffff0000, v162
	v_lshlrev_b32_e32 v15, 16, v162
	v_and_b32_e32 v16, 0xffff0000, v163
	v_lshlrev_b32_e32 v17, 16, v163
	v_pk_mul_f32 v[18:19], v[242:243], v[14:15] op_sel:[1,0] op_sel_hi:[1,1]
	v_pk_mul_f32 v[20:21], v[242:243], v[16:17] op_sel:[1,0] op_sel_hi:[1,1]
	v_pk_fma_f32 v[10:11], v[242:243], v[14:15], v[10:11] op_sel:[1,0,0] op_sel_hi:[1,1,1]
	v_pk_fma_f32 v[12:13], v[242:243], v[16:17], v[12:13] op_sel:[1,0,0] op_sel_hi:[1,1,1]
	v_fma_f32 v22, s0, v11, -v19
	v_fma_f32 v23, s0, v10, -v18
	v_fma_f32 v24, s0, v13, -v21
	v_fma_f32 v25, s0, v12, -v20
	v_cvt_pk_bf16_f32 v22, v22, v23
	v_cvt_pk_bf16_f32 v23, v24, v25
	v_add_u32_e32 v34, 0x12000, v8
	global_store_dwordx2 v34, v[22:23], s[62:63]
	v_and_b32_e32 v14, 0xffff0000, v160
	v_lshlrev_b32_e32 v15, 16, v160
	v_and_b32_e32 v16, 0xffff0000, v161
	v_lshlrev_b32_e32 v17, 16, v161
	v_pk_fma_f32 v[10:11], v[242:243], v[14:15], v[10:11] op_sel_hi:[0,1,1] neg_lo:[1,0,0] neg_hi:[1,0,0]
	v_pk_fma_f32 v[12:13], v[242:243], v[16:17], v[12:13] op_sel_hi:[0,1,1] neg_lo:[1,0,0] neg_hi:[1,0,0]
	s_waitcnt vmcnt(47)
	v_and_b32_e32 v14, 0xffff0000, v164
	v_lshlrev_b32_e32 v15, 16, v164
	v_and_b32_e32 v16, 0xffff0000, v165
	v_lshlrev_b32_e32 v17, 16, v165
	v_pk_mul_f32 v[18:19], v[244:245], v[14:15] op_sel_hi:[0,1]
	v_pk_mul_f32 v[20:21], v[244:245], v[16:17] op_sel_hi:[0,1]
	v_pk_fma_f32 v[10:11], v[244:245], v[14:15], v[10:11] op_sel_hi:[0,1,1]
	v_pk_fma_f32 v[12:13], v[244:245], v[16:17], v[12:13] op_sel_hi:[0,1,1]
	v_fma_f32 v26, s0, v11, -v19
	v_fma_f32 v27, s0, v10, -v18
	v_fma_f32 v28, s0, v13, -v21
	v_fma_f32 v29, s0, v12, -v20
	v_cvt_pk_bf16_f32 v26, v26, v27
	v_cvt_pk_bf16_f32 v27, v28, v29
	v_add_u32_e32 v35, 0x12800, v8
	global_store_dwordx2 v35, v[26:27], s[62:63]
	v_and_b32_e32 v14, 0xffff0000, v162
	v_lshlrev_b32_e32 v15, 16, v162
	v_and_b32_e32 v16, 0xffff0000, v163
	v_lshlrev_b32_e32 v17, 16, v163
	v_pk_fma_f32 v[10:11], v[242:243], v[14:15], v[10:11] op_sel:[1,0,0] op_sel_hi:[1,1,1] neg_lo:[1,0,0] neg_hi:[1,0,0]
	v_pk_fma_f32 v[12:13], v[242:243], v[16:17], v[12:13] op_sel:[1,0,0] op_sel_hi:[1,1,1] neg_lo:[1,0,0] neg_hi:[1,0,0]
	s_waitcnt vmcnt(47)
	v_and_b32_e32 v14, 0xffff0000, v166
	v_lshlrev_b32_e32 v15, 16, v166
	v_and_b32_e32 v16, 0xffff0000, v167
	v_lshlrev_b32_e32 v17, 16, v167
	v_pk_mul_f32 v[18:19], v[244:245], v[14:15] op_sel:[1,0] op_sel_hi:[1,1]
	v_pk_mul_f32 v[20:21], v[244:245], v[16:17] op_sel:[1,0] op_sel_hi:[1,1]
	v_pk_fma_f32 v[10:11], v[244:245], v[14:15], v[10:11] op_sel:[1,0,0] op_sel_hi:[1,1,1]
	v_pk_fma_f32 v[12:13], v[244:245], v[16:17], v[12:13] op_sel:[1,0,0] op_sel_hi:[1,1,1]
	v_fma_f32 v22, s0, v11, -v19
	v_fma_f32 v23, s0, v10, -v18
	v_fma_f32 v24, s0, v13, -v21
	v_fma_f32 v25, s0, v12, -v20
	v_cvt_pk_bf16_f32 v22, v22, v23
	v_cvt_pk_bf16_f32 v23, v24, v25
	v_add_u32_e32 v36, 0x13000, v8
	global_store_dwordx2 v36, v[22:23], s[62:63]
	v_and_b32_e32 v14, 0xffff0000, v164
	v_lshlrev_b32_e32 v15, 16, v164
	v_and_b32_e32 v16, 0xffff0000, v165
	v_lshlrev_b32_e32 v17, 16, v165
	v_pk_fma_f32 v[10:11], v[244:245], v[14:15], v[10:11] op_sel_hi:[0,1,1] neg_lo:[1,0,0] neg_hi:[1,0,0]
	v_pk_fma_f32 v[12:13], v[244:245], v[16:17], v[12:13] op_sel_hi:[0,1,1] neg_lo:[1,0,0] neg_hi:[1,0,0]
	s_waitcnt vmcnt(47)
	v_and_b32_e32 v14, 0xffff0000, v168
	v_lshlrev_b32_e32 v15, 16, v168
	v_and_b32_e32 v16, 0xffff0000, v169
	v_lshlrev_b32_e32 v17, 16, v169
	v_pk_mul_f32 v[18:19], v[246:247], v[14:15] op_sel_hi:[0,1]
	v_pk_mul_f32 v[20:21], v[246:247], v[16:17] op_sel_hi:[0,1]
	v_pk_fma_f32 v[10:11], v[246:247], v[14:15], v[10:11] op_sel_hi:[0,1,1]
	v_pk_fma_f32 v[12:13], v[246:247], v[16:17], v[12:13] op_sel_hi:[0,1,1]
	v_fma_f32 v26, s0, v11, -v19
	v_fma_f32 v27, s0, v10, -v18
	v_fma_f32 v28, s0, v13, -v21
	v_fma_f32 v29, s0, v12, -v20
	v_cvt_pk_bf16_f32 v26, v26, v27
	v_cvt_pk_bf16_f32 v27, v28, v29
	v_add_u32_e32 v37, 0x13800, v8
	global_store_dwordx2 v37, v[26:27], s[62:63]
	v_and_b32_e32 v14, 0xffff0000, v166
	v_lshlrev_b32_e32 v15, 16, v166
	v_and_b32_e32 v16, 0xffff0000, v167
	v_lshlrev_b32_e32 v17, 16, v167
	v_pk_fma_f32 v[10:11], v[244:245], v[14:15], v[10:11] op_sel:[1,0,0] op_sel_hi:[1,1,1] neg_lo:[1,0,0] neg_hi:[1,0,0]
	v_pk_fma_f32 v[12:13], v[244:245], v[16:17], v[12:13] op_sel:[1,0,0] op_sel_hi:[1,1,1] neg_lo:[1,0,0] neg_hi:[1,0,0]
	s_waitcnt vmcnt(47)
; __device__ __forceinline__ float bflo(unsigned u) { return __uint_as_float(u << 16); }
; __device__ __forceinline__ float bfhi(unsigned u) { return __uint_as_float(u & 0xffff0000u); }
; __device__ __forceinline__ void phase_pool(const Params& p, char* smraw) {
;     ...
;       for (int k = 0; k < 8; ++k) {
;         const int tt = t8 + k, pp = c0 + tt;
;         const float rs = rstd_s[tt + 15];
;         const float x0 = bflo(cur[k][0]) * rs, x1 = bfhi(cur[k][0]) * rs, x2 = bflo(cur[k][1]) * rs, x3 = bfhi(cur[k][1]) * rs;
;         s0 += x0; s1 += x1; s2 += x2; s3 += x3;
;         const int cnt = (pp + 1 < win) ? pp + 1 : win;
;         const float inv = 1.f / (float)cnt;
;         u32x2 o; o[0] = cvtpk(s0 * inv - x0, s1 * inv - x1); o[1] = cvtpk(s2 * inv - x2, s3 * inv - x3);
;         *(u32x2*)(p.pooled + (size_t)(b * L + pp) * D + c) = o;
;         const int po = pp - win + 1;
;         if (po >= 0) {
;           const float ro = rstd_s[tt + 15 - win + 1];
;           s0 -= bflo(old[k][0]) * ro; s1 -= bfhi(old[k][0]) * ro; s2 -= bflo(old[k][1]) * ro; s3 -= bfhi(old[k][1]) * ro;
;         }
;       }
	v_and_b32_e32 v14, 0xffff0000, v170
	v_lshlrev_b32_e32 v15, 16, v170
	v_and_b32_e32 v16, 0xffff0000, v171
	v_lshlrev_b32_e32 v17, 16, v171
	v_pk_mul_f32 v[18:19], v[246:247], v[14:15] op_sel:[1,0] op_sel_hi:[1,1]
	v_pk_mul_f32 v[20:21], v[246:247], v[16:17] op_sel:[1,0] op_sel_hi:[1,1]
	v_pk_fma_f32 v[10:11], v[246:247], v[14:15], v[10:11] op_sel:[1,0,0] op_sel_hi:[1,1,1]
	v_pk_fma_f32 v[12:13], v[246:247], v[16:17], v[12:13] op_sel:[1,0,0] op_sel_hi:[1,1,1]
	v_fma_f32 v22, s0, v11, -v19
	v_fma_f32 v23, s0, v10, -v18
	v_fma_f32 v24, s0, v13, -v21
	v_fma_f32 v25, s0, v12, -v20
	v_cvt_pk_bf16_f32 v22, v22, v23
	v_cvt_pk_bf16_f32 v23, v24, v25
	v_add_u32_e32 v30, 0x14000, v8
	global_store_dwordx2 v30, v[22:23], s[62:63]
	v_and_b32_e32 v14, 0xffff0000, v168
	v_lshlrev_b32_e32 v15, 16, v168
	v_and_b32_e32 v16, 0xffff0000, v169
	v_lshlrev_b32_e32 v17, 16, v169
	v_pk_fma_f32 v[10:11], v[246:247], v[14:15], v[10:11] op_sel_hi:[0,1,1] neg_lo:[1,0,0] neg_hi:[1,0,0]
	v_pk_fma_f32 v[12:13], v[246:247], v[16:17], v[12:13] op_sel_hi:[0,1,1] neg_lo:[1,0,0] neg_hi:[1,0,0]
	s_waitcnt vmcnt(47)
	v_and_b32_e32 v14, 0xffff0000, v172
	v_lshlrev_b32_e32 v15, 16, v172
	v_and_b32_e32 v16, 0xffff0000, v173
	v_lshlrev_b32_e32 v17, 16, v173
	v_pk_mul_f32 v[18:19], v[248:249], v[14:15] op_sel_hi:[0,1]
	v_pk_mul_f32 v[20:21], v[248:249], v[16:17] op_sel_hi:[0,1]
	v_pk_fma_f32 v[10:11], v[248:249], v[14:15], v[10:11] op_sel_hi:[0,1,1]
	v_pk_fma_f32 v[12:13], v[248:249], v[16:17], v[12:13] op_sel_hi:[0,1,1]
	v_fma_f32 v26, s0, v11, -v19
	v_fma_f32 v27, s0, v10, -v18
	v_fma_f32 v28, s0, v13, -v21
	v_fma_f32 v29, s0, v12, -v20
	v_cvt_pk_bf16_f32 v26, v26, v27
	v_cvt_pk_bf16_f32 v27, v28, v29
	v_add_u32_e32 v31, 0x14800, v8
	global_store_dwordx2 v31, v[26:27], s[62:63]
	v_and_b32_e32 v14, 0xffff0000, v170
	v_lshlrev_b32_e32 v15, 16, v170
	v_and_b32_e32 v16, 0xffff0000, v171
	v_lshlrev_b32_e32 v17, 16, v171
	v_pk_fma_f32 v[10:11], v[246:247], v[14:15], v[10:11] op_sel:[1,0,0] op_sel_hi:[1,1,1] neg_lo:[1,0,0] neg_hi:[1,0,0]
	v_pk_fma_f32 v[12:13], v[246:247], v[16:17], v[12:13] op_sel:[1,0,0] op_sel_hi:[1,1,1] neg_lo:[1,0,0] neg_hi:[1,0,0]
	s_waitcnt vmcnt(47)
	v_and_b32_e32 v14, 0xffff0000, v174
	v_lshlrev_b32_e32 v15, 16, v174
	v_and_b32_e32 v16, 0xffff0000, v175
	v_lshlrev_b32_e32 v17, 16, v175
	v_pk_mul_f32 v[18:19], v[248:249], v[14:15] op_sel:[1,0] op_sel_hi:[1,1]
	v_pk_mul_f32 v[20:21], v[248:249], v[16:17] op_sel:[1,0] op_sel_hi:[1,1]
	v_pk_fma_f32 v[10:11], v[248:249], v[14:15], v[10:11] op_sel:[1,0,0] op_sel_hi:[1,1,1]
	v_pk_fma_f32 v[12:13], v[248:249], v[16:17], v[12:13] op_sel:[1,0,0] op_sel_hi:[1,1,1]
	v_fma_f32 v22, s0, v11, -v19
	v_fma_f32 v23, s0, v10, -v18
	v_fma_f32 v24, s0, v13, -v21
	v_fma_f32 v25, s0, v12, -v20
	v_cvt_pk_bf16_f32 v22, v22, v23
	v_cvt_pk_bf16_f32 v23, v24, v25
	v_add_u32_e32 v32, 0x15000, v8
	global_store_dwordx2 v32, v[22:23], s[62:63]
	v_and_b32_e32 v14, 0xffff0000, v172
	v_lshlrev_b32_e32 v15, 16, v172
	v_and_b32_e32 v16, 0xffff0000, v173
	v_lshlrev_b32_e32 v17, 16, v173
	v_pk_fma_f32 v[10:11], v[248:249], v[14:15], v[10:11] op_sel_hi:[0,1,1] neg_lo:[1,0,0] neg_hi:[1,0,0]
	v_pk_fma_f32 v[12:13], v[248:249], v[16:17], v[12:13] op_sel_hi:[0,1,1] neg_lo:[1,0,0] neg_hi:[1,0,0]
	s_waitcnt vmcnt(47)
	v_and_b32_e32 v14, 0xffff0000, v176
	v_lshlrev_b32_e32 v15, 16, v176
	v_and_b32_e32 v16, 0xffff0000, v177
	v_lshlrev_b32_e32 v17, 16, v177
	v_pk_mul_f32 v[18:19], v[250:251], v[14:15] op_sel_hi:[0,1]
	v_pk_mul_f32 v[20:21], v[250:251], v[16:17] op_sel_hi:[0,1]
	v_pk_fma_f32 v[10:11], v[250:251], v[14:15], v[10:11] op_sel_hi:[0,1,1]
	v_pk_fma_f32 v[12:13], v[250:251], v[16:17], v[12:13] op_sel_hi:[0,1,1]
	v_fma_f32 v26, s0, v11, -v19
	v_fma_f32 v27, s0, v10, -v18
	v_fma_f32 v28, s0, v13, -v21
	v_fma_f32 v29, s0, v12, -v20
	v_cvt_pk_bf16_f32 v26, v26, v27
	v_cvt_pk_bf16_f32 v27, v28, v29
	v_add_u32_e32 v33, 0x15800, v8
	global_store_dwordx2 v33, v[26:27], s[62:63]
	v_and_b32_e32 v14, 0xffff0000, v174
	v_lshlrev_b32_e32 v15, 16, v174
	v_and_b32_e32 v16, 0xffff0000, v175
	v_lshlrev_b32_e32 v17, 16, v175
	v_pk_fma_f32 v[10:11], v[248:249], v[14:15], v[10:11] op_sel:[1,0,0] op_sel_hi:[1,1,1] neg_lo:[1,0,0] neg_hi:[1,0,0]
	v_pk_fma_f32 v[12:13], v[248:249], v[16:17], v[12:13] op_sel:[1,0,0] op_sel_hi:[1,1,1] neg_lo:[1,0,0] neg_hi:[1,0,0]
	s_waitcnt vmcnt(47)
; __device__ __forceinline__ float bflo(unsigned u) { return __uint_as_float(u << 16); }
; __device__ __forceinline__ float bfhi(unsigned u) { return __uint_as_float(u & 0xffff0000u); }
; __device__ __forceinline__ void phase_pool(const Params& p, char* smraw) {
;     ...
;   for (int item = blockIdx.x; item < Bn * NCH; item += gridDim.x) {
;     const int b = item / NCH, c0 = (item - b * NCH) * CH;
;     ...
;       for (int k = 0; k < 8; ++k) {
;         const int tt = t8 + k, pp = c0 + tt;
;         const float rs = rstd_s[tt + 15];
;         const float x0 = bflo(cur[k][0]) * rs, x1 = bfhi(cur[k][0]) * rs, x2 = bflo(cur[k][1]) * rs, x3 = bfhi(cur[k][1]) * rs;
;         s0 += x0; s1 += x1; s2 += x2; s3 += x3;
;         const int cnt = (pp + 1 < win) ? pp + 1 : win;
;         const float inv = 1.f / (float)cnt;
;         u32x2 o; o[0] = cvtpk(s0 * inv - x0, s1 * inv - x1); o[1] = cvtpk(s2 * inv - x2, s3 * inv - x3);
;         *(u32x2*)(p.pooled + (size_t)(b * L + pp) * D + c) = o;
;         const int po = pp - win + 1;
;         if (po >= 0) {
;           const float ro = rstd_s[tt + 15 - win + 1];
;           s0 -= bflo(old[k][0]) * ro; s1 -= bfhi(old[k][0]) * ro; s2 -= bflo(old[k][1]) * ro; s3 -= bfhi(old[k][1]) * ro;
;         }
;       }
	v_and_b32_e32 v14, 0xffff0000, v178
	v_lshlrev_b32_e32 v15, 16, v178
	v_and_b32_e32 v16, 0xffff0000, v179
	v_lshlrev_b32_e32 v17, 16, v179
	v_pk_mul_f32 v[18:19], v[250:251], v[14:15] op_sel:[1,0] op_sel_hi:[1,1]
	v_pk_mul_f32 v[20:21], v[250:251], v[16:17] op_sel:[1,0] op_sel_hi:[1,1]
	v_pk_fma_f32 v[10:11], v[250:251], v[14:15], v[10:11] op_sel:[1,0,0] op_sel_hi:[1,1,1]
	v_pk_fma_f32 v[12:13], v[250:251], v[16:17], v[12:13] op_sel:[1,0,0] op_sel_hi:[1,1,1]
	v_fma_f32 v22, s0, v11, -v19
	v_fma_f32 v23, s0, v10, -v18
	v_fma_f32 v24, s0, v13, -v21
	v_fma_f32 v25, s0, v12, -v20
	v_cvt_pk_bf16_f32 v22, v22, v23
	v_cvt_pk_bf16_f32 v23, v24, v25
	v_add_u32_e32 v34, 0x16000, v8
	global_store_dwordx2 v34, v[22:23], s[62:63]
	v_and_b32_e32 v14, 0xffff0000, v176
	v_lshlrev_b32_e32 v15, 16, v176
	v_and_b32_e32 v16, 0xffff0000, v177
	v_lshlrev_b32_e32 v17, 16, v177
	v_pk_fma_f32 v[10:11], v[250:251], v[14:15], v[10:11] op_sel_hi:[0,1,1] neg_lo:[1,0,0] neg_hi:[1,0,0]
	v_pk_fma_f32 v[12:13], v[250:251], v[16:17], v[12:13] op_sel_hi:[0,1,1] neg_lo:[1,0,0] neg_hi:[1,0,0]
	s_waitcnt vmcnt(47)
	v_and_b32_e32 v14, 0xffff0000, v180
	v_lshlrev_b32_e32 v15, 16, v180
	v_and_b32_e32 v16, 0xffff0000, v181
	v_lshlrev_b32_e32 v17, 16, v181
	v_pk_mul_f32 v[18:19], v[252:253], v[14:15] op_sel_hi:[0,1]
	v_pk_mul_f32 v[20:21], v[252:253], v[16:17] op_sel_hi:[0,1]
	v_pk_fma_f32 v[10:11], v[252:253], v[14:15], v[10:11] op_sel_hi:[0,1,1]
	v_pk_fma_f32 v[12:13], v[252:253], v[16:17], v[12:13] op_sel_hi:[0,1,1]
	v_fma_f32 v26, s0, v11, -v19
	v_fma_f32 v27, s0, v10, -v18
	v_fma_f32 v28, s0, v13, -v21
	v_fma_f32 v29, s0, v12, -v20
	v_cvt_pk_bf16_f32 v26, v26, v27
	v_cvt_pk_bf16_f32 v27, v28, v29
	v_add_u32_e32 v35, 0x16800, v8
	global_store_dwordx2 v35, v[26:27], s[62:63]
	v_and_b32_e32 v14, 0xffff0000, v178
	v_lshlrev_b32_e32 v15, 16, v178
	v_and_b32_e32 v16, 0xffff0000, v179
	v_lshlrev_b32_e32 v17, 16, v179
	v_pk_fma_f32 v[10:11], v[250:251], v[14:15], v[10:11] op_sel:[1,0,0] op_sel_hi:[1,1,1] neg_lo:[1,0,0] neg_hi:[1,0,0]
	v_pk_fma_f32 v[12:13], v[250:251], v[16:17], v[12:13] op_sel:[1,0,0] op_sel_hi:[1,1,1] neg_lo:[1,0,0] neg_hi:[1,0,0]
	s_waitcnt vmcnt(47)
	v_and_b32_e32 v14, 0xffff0000, v182
	v_lshlrev_b32_e32 v15, 16, v182
	v_and_b32_e32 v16, 0xffff0000, v183
	v_lshlrev_b32_e32 v17, 16, v183
	v_pk_mul_f32 v[18:19], v[252:253], v[14:15] op_sel:[1,0] op_sel_hi:[1,1]
	v_pk_mul_f32 v[20:21], v[252:253], v[16:17] op_sel:[1,0] op_sel_hi:[1,1]
	v_pk_fma_f32 v[10:11], v[252:253], v[14:15], v[10:11] op_sel:[1,0,0] op_sel_hi:[1,1,1]
	v_pk_fma_f32 v[12:13], v[252:253], v[16:17], v[12:13] op_sel:[1,0,0] op_sel_hi:[1,1,1]
	v_fma_f32 v22, s0, v11, -v19
	v_fma_f32 v23, s0, v10, -v18
	v_fma_f32 v24, s0, v13, -v21
	v_fma_f32 v25, s0, v12, -v20
	v_cvt_pk_bf16_f32 v22, v22, v23
	v_cvt_pk_bf16_f32 v23, v24, v25
	v_add_u32_e32 v36, 0x17000, v8
	global_store_dwordx2 v36, v[22:23], s[62:63]
	v_and_b32_e32 v14, 0xffff0000, v180
	v_lshlrev_b32_e32 v15, 16, v180
	v_and_b32_e32 v16, 0xffff0000, v181
	v_lshlrev_b32_e32 v17, 16, v181
	v_pk_fma_f32 v[10:11], v[252:253], v[14:15], v[10:11] op_sel_hi:[0,1,1] neg_lo:[1,0,0] neg_hi:[1,0,0]
	v_pk_fma_f32 v[12:13], v[252:253], v[16:17], v[12:13] op_sel_hi:[0,1,1] neg_lo:[1,0,0] neg_hi:[1,0,0]
	s_waitcnt vmcnt(47)
	v_and_b32_e32 v14, 0xffff0000, v184
	v_lshlrev_b32_e32 v15, 16, v184
	v_and_b32_e32 v16, 0xffff0000, v185
	v_lshlrev_b32_e32 v17, 16, v185
	v_pk_mul_f32 v[18:19], v[186:187], v[14:15] op_sel_hi:[0,1]
	v_pk_mul_f32 v[20:21], v[186:187], v[16:17] op_sel_hi:[0,1]
	v_pk_fma_f32 v[10:11], v[186:187], v[14:15], v[10:11] op_sel_hi:[0,1,1]
	v_pk_fma_f32 v[12:13], v[186:187], v[16:17], v[12:13] op_sel_hi:[0,1,1]
	v_fma_f32 v26, s0, v11, -v19
	v_fma_f32 v27, s0, v10, -v18
	v_fma_f32 v28, s0, v13, -v21
	v_fma_f32 v29, s0, v12, -v20
	v_cvt_pk_bf16_f32 v26, v26, v27
	v_cvt_pk_bf16_f32 v27, v28, v29
	v_add_u32_e32 v37, 0x17800, v8
	global_store_dwordx2 v37, v[26:27], s[62:63]
	v_and_b32_e32 v14, 0xffff0000, v182
	v_lshlrev_b32_e32 v15, 16, v182
	v_and_b32_e32 v16, 0xffff0000, v183
	v_lshlrev_b32_e32 v17, 16, v183
	v_pk_fma_f32 v[10:11], v[252:253], v[14:15], v[10:11] op_sel:[1,0,0] op_sel_hi:[1,1,1] neg_lo:[1,0,0] neg_hi:[1,0,0]
	v_pk_fma_f32 v[12:13], v[252:253], v[16:17], v[12:13] op_sel:[1,0,0] op_sel_hi:[1,1,1] neg_lo:[1,0,0] neg_hi:[1,0,0]
.Lmy_pool_next:
	s_add_i32 s26, s26, s96
	s_add_i32 s3, s3, s24
	s_cmpk_lt_i32 s26, 0x2ac
	s_cbranch_scc1 .Lmy_pool_item
